# v25 with the 72 redundant second s_waitcnt lgkmcnt(0) after the GEMM-loop barriers removed
# speedup vs baseline: 1.0081x; 1.0081x over previous
; #define PG8_STAGE(bufoff, gbase, voff) do { _Pragma("unroll") for (int _i = 0; _i < 2; ++_i) \
;         __builtin_amdgcn_global_load_lds((const unsigned*)((const char*)(gbase) + (voff)[_i]), (PG8_LAS unsigned*)(lds + (bufoff) + ldsw + _i * 8192), 16, 0, 0); } while (0)
; #define PG8_LDA(dst, b, h) do { _Pragma("unroll") for (int m = 0; m < 4; ++m) _Pragma("unroll") for (int k = 0; k < 2; ++k) dst[m][k] = *(const PG8_LAS bf16x8*)(lds + PG8_SA(b, h) + aoff + m * 2048 + k * 1024); } while (0)
; #define PG8_MMA(ai, bj, At, Bt) do { __builtin_amdgcn_s_setprio(1); _Pragma("unroll") for (int m = 0; m < 4; ++m) _Pragma("unroll") for (int n = 0; n < 2; ++n) _Pragma("unroll") for (int k = 0; k < 2; ++k) \
;         acc[ai][bj][m][n] = mma16<F16>(Bt[n][k], At[m][k], acc[ai][bj][m][n]); __builtin_amdgcn_s_setprio(0); } while (0)
; #define PG8_WAIT_V(n) asm volatile("s_waitcnt vmcnt(" #n ")" ::: "memory")
; #define PG8_WAIT_L(n) asm volatile("s_waitcnt lgkmcnt(" #n ")" ::: "memory")
; #define PG8_BAR __builtin_amdgcn_s_barrier()
; #define PG8_SCHED __builtin_amdgcn_sched_barrier(0)
; template <class Epi, class Sched, bool ALIGN_EPI = false, bool SP2 = false, bool F16 = false, bool TOKPERM = false>
; __device__ __forceinline__ void gemm_phase(PG8_LAS unsigned char* lds, const Gemm g, const Sched& S, const Epi& E, int wv) {
;     ...
;             PG8_WAIT_V(8); PG8_WAIT_L(0); PG8_BAR; PG8_MMA(0, 0, At, B0); PG8_MMA(0, 1, At, B1); PG8_BAR; PG8_SCHED;
;             PG8_LDA(At, 0, 1); PG8_STAGE(PG8_SB(0, 0), b2, voffB); PG8_STAGE(PG8_SB(0, 1), b2 + hstep, voffB); PG8_STAGE(PG8_SA(0, 0), a2, voffA);
;             PG8_WAIT_V(8); PG8_WAIT_L(0); PG8_BAR; PG8_MMA(1, 0, At, B0); PG8_MMA(1, 1, At, B1); PG8_BAR; PG8_SCHED;
.Lvmw_181_0:
	s_waitcnt lgkmcnt(0)
	s_barrier
	s_setprio 1
	v_mfma_f32_16x16x32_f16 v[124:127], v[172:175], v[204:207], 0
	v_mfma_f32_16x16x32_f16 v[116:119], v[180:183], v[204:207], 0
	v_mfma_f32_16x16x32_f16 v[108:111], v[172:175], v[212:215], 0
	v_mfma_f32_16x16x32_f16 v[104:107], v[180:183], v[212:215], 0
	v_mfma_f32_16x16x32_f16 v[92:95], v[172:175], v[220:223], 0
	v_mfma_f32_16x16x32_f16 v[88:91], v[180:183], v[220:223], 0
	v_mfma_f32_16x16x32_f16 v[76:79], v[172:175], v[232:235], 0
	v_mfma_f32_16x16x32_f16 v[72:75], v[180:183], v[232:235], 0
	v_mfma_f32_16x16x32_f16 v[124:127], v[176:179], v[208:211], v[124:127]
	v_mfma_f32_16x16x32_f16 v[116:119], v[184:187], v[208:211], v[116:119]
	v_mfma_f32_16x16x32_f16 v[108:111], v[176:179], v[216:219], v[108:111]
	v_mfma_f32_16x16x32_f16 v[104:107], v[184:187], v[216:219], v[104:107]
	v_mfma_f32_16x16x32_f16 v[92:95], v[176:179], v[228:231], v[92:95]
	v_mfma_f32_16x16x32_f16 v[88:91], v[184:187], v[228:231], v[88:91]
	v_mfma_f32_16x16x32_f16 v[76:79], v[176:179], v[236:239], v[76:79]
	v_mfma_f32_16x16x32_f16 v[72:75], v[184:187], v[236:239], v[72:75]
	s_setprio 0
	s_setprio 1
	v_mfma_f32_16x16x32_f16 v[120:123], v[188:191], v[204:207], 0
	v_mfma_f32_16x16x32_f16 v[112:115], v[196:199], v[204:207], 0
	v_mfma_f32_16x16x32_f16 v[100:103], v[188:191], v[212:215], 0
	v_mfma_f32_16x16x32_f16 v[96:99], v[196:199], v[212:215], 0
	v_mfma_f32_16x16x32_f16 v[84:87], v[188:191], v[220:223], 0
	v_mfma_f32_16x16x32_f16 v[80:83], v[196:199], v[220:223], 0
	v_mfma_f32_16x16x32_f16 v[68:71], v[188:191], v[232:235], 0
	v_mfma_f32_16x16x32_f16 v[64:67], v[196:199], v[232:235], 0
	v_mfma_f32_16x16x32_f16 v[120:123], v[192:195], v[208:211], v[120:123]
	v_mfma_f32_16x16x32_f16 v[112:115], v[200:203], v[208:211], v[112:115]
	v_mfma_f32_16x16x32_f16 v[100:103], v[192:195], v[216:219], v[100:103]
	v_mfma_f32_16x16x32_f16 v[96:99], v[200:203], v[216:219], v[96:99]
	v_mfma_f32_16x16x32_f16 v[84:87], v[192:195], v[228:231], v[84:87]
	v_mfma_f32_16x16x32_f16 v[80:83], v[200:203], v[228:231], v[80:83]
	v_mfma_f32_16x16x32_f16 v[68:71], v[192:195], v[236:239], v[68:71]
	v_mfma_f32_16x16x32_f16 v[64:67], v[200:203], v[236:239], v[64:67]
	s_setprio 0
	s_barrier
	s_mov_b32 m0, s37
	v_lshl_add_u64 v[148:149], s[8:9], 0, v[132:133]
	s_add_u32 s82, s8, 0x40000
	ds_read_b128 v[204:207], v153 offset:16384
	ds_read_b128 v[208:211], v153 offset:17408
	ds_read_b128 v[212:215], v153 offset:18432
	ds_read_b128 v[216:219], v153 offset:19456
	ds_read_b128 v[220:223], v153 offset:20480
	ds_read_b128 v[228:231], v153 offset:21504
	ds_read_b128 v[232:235], v153 offset:22528
	ds_read_b128 v[236:239], v153 offset:23552
	global_load_lds_dwordx4 v[148:149], off
	v_lshl_add_u64 v[224:225], s[8:9], 0, v[128:129]
	s_mov_b32 m0, s45
	s_addc_u32 s83, s9, 0
	global_load_lds_dwordx4 v[224:225], off
	v_lshl_add_u64 v[240:241], s[82:83], 0, v[132:133]
	s_mov_b32 m0, s58
	v_lshl_add_u64 v[242:243], s[56:57], 0, v[130:131]
	global_load_lds_dwordx4 v[240:241], off
	v_lshl_add_u64 v[240:241], s[82:83], 0, v[128:129]
	s_mov_b32 m0, s59
	s_nop 0
	global_load_lds_dwordx4 v[240:241], off
	v_lshl_add_u64 v[240:241], s[56:57], 0, v[134:135]
	s_mov_b32 m0, s20
	s_nop 0
	global_load_lds_dwordx4 v[240:241], off
	s_mov_b32 m0, s60
	s_nop 0
	global_load_lds_dwordx4 v[242:243], off
	s_waitcnt vmcnt(16)
	s_cmp_lg_u32 s99, -1
	s_cbranch_scc1 .Lvmw_181_1
	s_waitcnt vmcnt(8)
.Lvmw_181_1:
	s_waitcnt lgkmcnt(0)
	s_barrier
	s_setprio 1
	v_mfma_f32_16x16x32_f16 v[60:63], v[172:175], v[204:207], 0
	v_mfma_f32_16x16x32_f16 v[56:59], v[180:183], v[204:207], 0
	v_mfma_f32_16x16x32_f16 v[44:47], v[172:175], v[212:215], 0
	v_mfma_f32_16x16x32_f16 v[40:43], v[180:183], v[212:215], 0
	v_mfma_f32_16x16x32_f16 v[28:31], v[172:175], v[220:223], 0
	v_mfma_f32_16x16x32_f16 v[24:27], v[180:183], v[220:223], 0
	v_mfma_f32_16x16x32_f16 v[12:15], v[172:175], v[232:235], 0
	v_mfma_f32_16x16x32_f16 v[8:11], v[180:183], v[232:235], 0
	v_mfma_f32_16x16x32_f16 v[60:63], v[176:179], v[208:211], v[60:63]
	v_mfma_f32_16x16x32_f16 v[56:59], v[184:187], v[208:211], v[56:59]
	v_mfma_f32_16x16x32_f16 v[44:47], v[176:179], v[216:219], v[44:47]
	v_mfma_f32_16x16x32_f16 v[40:43], v[184:187], v[216:219], v[40:43]
	v_mfma_f32_16x16x32_f16 v[28:31], v[176:179], v[228:231], v[28:31]
	v_mfma_f32_16x16x32_f16 v[24:27], v[184:187], v[228:231], v[24:27]
	v_mfma_f32_16x16x32_f16 v[12:15], v[176:179], v[236:239], v[12:15]
	v_mfma_f32_16x16x32_f16 v[8:11], v[184:187], v[236:239], v[8:11]
	s_setprio 0
	s_setprio 1
	v_mfma_f32_16x16x32_f16 v[52:55], v[188:191], v[204:207], 0
	v_mfma_f32_16x16x32_f16 v[48:51], v[196:199], v[204:207], 0
	v_mfma_f32_16x16x32_f16 v[36:39], v[188:191], v[212:215], 0
	v_mfma_f32_16x16x32_f16 v[32:35], v[196:199], v[212:215], 0
	v_mfma_f32_16x16x32_f16 v[20:23], v[188:191], v[220:223], 0
	v_mfma_f32_16x16x32_f16 v[16:19], v[196:199], v[220:223], 0
	v_mfma_f32_16x16x32_f16 v[4:7], v[188:191], v[232:235], 0
	v_mfma_f32_16x16x32_f16 v[0:3], v[196:199], v[232:235], 0
	v_mfma_f32_16x16x32_f16 v[52:55], v[192:195], v[208:211], v[52:55]
	v_mfma_f32_16x16x32_f16 v[48:51], v[200:203], v[208:211], v[48:51]
	v_mfma_f32_16x16x32_f16 v[36:39], v[192:195], v[216:219], v[36:39]
	v_mfma_f32_16x16x32_f16 v[32:35], v[200:203], v[216:219], v[32:35]
	v_mfma_f32_16x16x32_f16 v[20:23], v[192:195], v[228:231], v[20:23]
	v_mfma_f32_16x16x32_f16 v[16:19], v[200:203], v[228:231], v[16:19]
	v_mfma_f32_16x16x32_f16 v[4:7], v[192:195], v[236:239], v[4:7]
	v_mfma_f32_16x16x32_f16 v[0:3], v[200:203], v[236:239], v[0:3]
	s_setprio 0
	s_barrier
; #define PG8_STAGE(bufoff, gbase, voff) do { _Pragma("unroll") for (int _i = 0; _i < 2; ++_i) \
;         __builtin_amdgcn_global_load_lds((const unsigned*)((const char*)(gbase) + (voff)[_i]), (PG8_LAS unsigned*)(lds + (bufoff) + ldsw + _i * 8192), 16, 0, 0); } while (0)
; #define PG8_LDA(dst, b, h) do { _Pragma("unroll") for (int m = 0; m < 4; ++m) _Pragma("unroll") for (int k = 0; k < 2; ++k) dst[m][k] = *(const PG8_LAS bf16x8*)(lds + PG8_SA(b, h) + aoff + m * 2048 + k * 1024); } while (0)
; #define PG8_LDB(dst, b, h) do { _Pragma("unroll") for (int n = 0; n < 2; ++n) _Pragma("unroll") for (int k = 0; k < 2; ++k) dst[n][k] = *(const PG8_LAS bf16x8*)(lds + PG8_SB(b, h) + boff + n * 2048 + k * 1024); } while (0)
; #define PG8_MMA(ai, bj, At, Bt) do { __builtin_amdgcn_s_setprio(1); _Pragma("unroll") for (int m = 0; m < 4; ++m) _Pragma("unroll") for (int n = 0; n < 2; ++n) _Pragma("unroll") for (int k = 0; k < 2; ++k) \
;         acc[ai][bj][m][n] = mma16<F16>(Bt[n][k], At[m][k], acc[ai][bj][m][n]); __builtin_amdgcn_s_setprio(0); } while (0)
; #define PG8_WAIT_V(n) asm volatile("s_waitcnt vmcnt(" #n ")" ::: "memory")
; #define PG8_WAIT_L(n) asm volatile("s_waitcnt lgkmcnt(" #n ")" ::: "memory")
; #define PG8_BAR __builtin_amdgcn_s_barrier()
; #define PG8_SCHED __builtin_amdgcn_sched_barrier(0)
; template <class Epi, class Sched, bool ALIGN_EPI = false, bool SP2 = false, bool F16 = false, bool TOKPERM = false>
; __device__ __forceinline__ void gemm_phase(PG8_LAS unsigned char* lds, const Gemm g, const Sched& S, const Epi& E, int wv) {
;     ...
;         for (int t = 0; t < nt; t += 2) {
;     ...
;             PG8_LDB(B0, 1, 0); PG8_LDB(B1, 1, 1); PG8_SCHED; PG8_LDA(At, 1, 0); PG8_STAGE(PG8_SA(0, 1), a2 + hstep, voffA);
;             PG8_WAIT_V(8); PG8_WAIT_L(0); PG8_BAR; PG8_MMA(0, 0, At, B0); PG8_MMA(0, 1, At, B1); PG8_BAR; PG8_SCHED;
;             PG8_LDA(At, 1, 1); PG8_STAGE(PG8_SB(1, 0), b3, voffB); PG8_STAGE(PG8_SB(1, 1), b3 + hstep, voffB); PG8_STAGE(PG8_SA(1, 0), a3, voffA);
;             PG8_WAIT_V(8); PG8_WAIT_L(0); PG8_BAR; PG8_MMA(1, 0, At, B0); PG8_MMA(1, 1, At, B1); PG8_BAR; PG8_SCHED;
	ds_read_b128 v[172:175], v163
	ds_read_b128 v[176:179], v164
	ds_read_b128 v[180:183], v165
	ds_read_b128 v[184:187], v166
	ds_read_b128 v[188:191], v167
	ds_read_b128 v[192:195], v168
	ds_read_b128 v[196:199], v169
	ds_read_b128 v[200:203], v170
	s_add_u32 s56, s56, 0x40000
	s_addc_u32 s57, s57, 0
	s_mov_b32 m0, s61
	v_lshl_add_u64 v[244:245], s[56:57], 0, v[134:135]
	ds_read_b128 v[204:207], v153 offset:32768
	ds_read_b128 v[208:211], v153 offset:33792
	ds_read_b128 v[212:215], v153 offset:34816
	ds_read_b128 v[216:219], v153 offset:35840
	ds_read_b128 v[220:223], v153 offset:36864
	ds_read_b128 v[228:231], v153 offset:37888
	ds_read_b128 v[232:235], v153 offset:38912
	ds_read_b128 v[236:239], v153 offset:39936
	global_load_lds_dwordx4 v[244:245], off
	v_lshl_add_u64 v[244:245], s[56:57], 0, v[130:131]
	s_mov_b32 m0, s62
	s_nop 0
	global_load_lds_dwordx4 v[244:245], off
	s_waitcnt vmcnt(8)
	s_waitcnt lgkmcnt(0)
	s_barrier
	s_setprio 1
	v_mfma_f32_16x16x32_f16 v[124:127], v[172:175], v[204:207], v[124:127]
	v_mfma_f32_16x16x32_f16 v[116:119], v[180:183], v[204:207], v[116:119]
	v_mfma_f32_16x16x32_f16 v[108:111], v[172:175], v[212:215], v[108:111]
	v_mfma_f32_16x16x32_f16 v[104:107], v[180:183], v[212:215], v[104:107]
	v_mfma_f32_16x16x32_f16 v[92:95], v[172:175], v[220:223], v[92:95]
	v_mfma_f32_16x16x32_f16 v[88:91], v[180:183], v[220:223], v[88:91]
	v_mfma_f32_16x16x32_f16 v[76:79], v[172:175], v[232:235], v[76:79]
	v_mfma_f32_16x16x32_f16 v[72:75], v[180:183], v[232:235], v[72:75]
	v_mfma_f32_16x16x32_f16 v[124:127], v[176:179], v[208:211], v[124:127]
	v_mfma_f32_16x16x32_f16 v[116:119], v[184:187], v[208:211], v[116:119]
	v_mfma_f32_16x16x32_f16 v[108:111], v[176:179], v[216:219], v[108:111]
	v_mfma_f32_16x16x32_f16 v[104:107], v[184:187], v[216:219], v[104:107]
	v_mfma_f32_16x16x32_f16 v[92:95], v[176:179], v[228:231], v[92:95]
	v_mfma_f32_16x16x32_f16 v[88:91], v[184:187], v[228:231], v[88:91]
	v_mfma_f32_16x16x32_f16 v[76:79], v[176:179], v[236:239], v[76:79]
	v_mfma_f32_16x16x32_f16 v[72:75], v[184:187], v[236:239], v[72:75]
	s_setprio 0
	s_setprio 1
	v_mfma_f32_16x16x32_f16 v[120:123], v[188:191], v[204:207], v[120:123]
	v_mfma_f32_16x16x32_f16 v[112:115], v[196:199], v[204:207], v[112:115]
	v_mfma_f32_16x16x32_f16 v[100:103], v[188:191], v[212:215], v[100:103]
	v_mfma_f32_16x16x32_f16 v[96:99], v[196:199], v[212:215], v[96:99]
	v_mfma_f32_16x16x32_f16 v[84:87], v[188:191], v[220:223], v[84:87]
	v_mfma_f32_16x16x32_f16 v[80:83], v[196:199], v[220:223], v[80:83]
	v_mfma_f32_16x16x32_f16 v[68:71], v[188:191], v[232:235], v[68:71]
	v_mfma_f32_16x16x32_f16 v[64:67], v[196:199], v[232:235], v[64:67]
	v_mfma_f32_16x16x32_f16 v[120:123], v[192:195], v[208:211], v[120:123]
	v_mfma_f32_16x16x32_f16 v[112:115], v[200:203], v[208:211], v[112:115]
	v_mfma_f32_16x16x32_f16 v[100:103], v[192:195], v[216:219], v[100:103]
	v_mfma_f32_16x16x32_f16 v[96:99], v[200:203], v[216:219], v[96:99]
	v_mfma_f32_16x16x32_f16 v[84:87], v[192:195], v[228:231], v[84:87]
	v_mfma_f32_16x16x32_f16 v[80:83], v[200:203], v[228:231], v[80:83]
	v_mfma_f32_16x16x32_f16 v[68:71], v[192:195], v[236:239], v[68:71]
	v_mfma_f32_16x16x32_f16 v[64:67], v[200:203], v[236:239], v[64:67]
	s_setprio 0
	s_barrier
	s_mov_b32 m0, s64
	v_lshl_add_u64 v[148:149], v[148:149], 0, s[16:17]
	s_add_u32 s8, s8, 0x40080
	ds_read_b128 v[204:207], v153 offset:49152
	ds_read_b128 v[208:211], v153 offset:50176
	ds_read_b128 v[212:215], v153 offset:51200
	ds_read_b128 v[216:219], v153 offset:52224
	ds_read_b128 v[220:223], v153 offset:53248
	ds_read_b128 v[228:231], v153 offset:54272
	ds_read_b128 v[232:235], v153 offset:55296
	ds_read_b128 v[236:239], v153 offset:56320
	global_load_lds_dwordx4 v[148:149], off
	v_lshl_add_u64 v[148:149], v[224:225], 0, s[16:17]
	s_mov_b32 m0, s65
	s_addc_u32 s9, s9, 0
	global_load_lds_dwordx4 v[148:149], off
	v_lshl_add_u64 v[148:149], s[8:9], 0, v[132:133]
	s_mov_b32 m0, s69
	s_nop 0
	global_load_lds_dwordx4 v[148:149], off
	v_lshl_add_u64 v[148:149], s[8:9], 0, v[128:129]
	s_mov_b32 m0, s70
	s_nop 0
	global_load_lds_dwordx4 v[148:149], off
	v_lshl_add_u64 v[148:149], v[240:241], 0, s[16:17]
	s_mov_b32 m0, s66
	s_nop 0
	global_load_lds_dwordx4 v[148:149], off
	v_lshl_add_u64 v[148:149], v[242:243], 0, s[16:17]
	s_mov_b32 m0, s68
	s_nop 0
	global_load_lds_dwordx4 v[148:149], off
	s_waitcnt vmcnt(8)
	s_waitcnt lgkmcnt(0)
	s_barrier
	s_setprio 1
	v_mfma_f32_16x16x32_f16 v[60:63], v[172:175], v[204:207], v[60:63]
	v_mfma_f32_16x16x32_f16 v[56:59], v[180:183], v[204:207], v[56:59]
	v_mfma_f32_16x16x32_f16 v[44:47], v[172:175], v[212:215], v[44:47]
	v_mfma_f32_16x16x32_f16 v[40:43], v[180:183], v[212:215], v[40:43]
	v_mfma_f32_16x16x32_f16 v[28:31], v[172:175], v[220:223], v[28:31]
	v_mfma_f32_16x16x32_f16 v[24:27], v[180:183], v[220:223], v[24:27]
	v_mfma_f32_16x16x32_f16 v[12:15], v[172:175], v[232:235], v[12:15]
	v_mfma_f32_16x16x32_f16 v[8:11], v[180:183], v[232:235], v[8:11]
	v_mfma_f32_16x16x32_f16 v[60:63], v[176:179], v[208:211], v[60:63]
	v_mfma_f32_16x16x32_f16 v[56:59], v[184:187], v[208:211], v[56:59]
	v_mfma_f32_16x16x32_f16 v[44:47], v[176:179], v[216:219], v[44:47]
	v_mfma_f32_16x16x32_f16 v[40:43], v[184:187], v[216:219], v[40:43]
	v_mfma_f32_16x16x32_f16 v[28:31], v[176:179], v[228:231], v[28:31]
	v_mfma_f32_16x16x32_f16 v[24:27], v[184:187], v[228:231], v[24:27]
	v_mfma_f32_16x16x32_f16 v[12:15], v[176:179], v[236:239], v[12:15]
	v_mfma_f32_16x16x32_f16 v[8:11], v[184:187], v[236:239], v[8:11]
	s_setprio 0
	s_setprio 1
	v_mfma_f32_16x16x32_f16 v[52:55], v[188:191], v[204:207], v[52:55]
	v_mfma_f32_16x16x32_f16 v[48:51], v[196:199], v[204:207], v[48:51]
	v_mfma_f32_16x16x32_f16 v[36:39], v[188:191], v[212:215], v[36:39]
	v_mfma_f32_16x16x32_f16 v[32:35], v[196:199], v[212:215], v[32:35]
	v_mfma_f32_16x16x32_f16 v[20:23], v[188:191], v[220:223], v[20:23]
	v_mfma_f32_16x16x32_f16 v[16:19], v[196:199], v[220:223], v[16:19]
	v_mfma_f32_16x16x32_f16 v[4:7], v[188:191], v[232:235], v[4:7]
	v_mfma_f32_16x16x32_f16 v[0:3], v[196:199], v[232:235], v[0:3]
	v_mfma_f32_16x16x32_f16 v[52:55], v[192:195], v[208:211], v[52:55]
	v_mfma_f32_16x16x32_f16 v[48:51], v[200:203], v[208:211], v[48:51]
	v_mfma_f32_16x16x32_f16 v[36:39], v[192:195], v[216:219], v[36:39]
	v_mfma_f32_16x16x32_f16 v[32:35], v[200:203], v[216:219], v[32:35]
	v_mfma_f32_16x16x32_f16 v[20:23], v[192:195], v[228:231], v[20:23]
	v_mfma_f32_16x16x32_f16 v[16:19], v[200:203], v[228:231], v[16:19]
	v_mfma_f32_16x16x32_f16 v[4:7], v[192:195], v[236:239], v[4:7]
	v_mfma_f32_16x16x32_f16 v[0:3], v[200:203], v[236:239], v[0:3]
	s_setprio 0
	s_barrier
	s_add_i32 s81, s81, 2
	s_add_u32 s6, s6, 0x100
	s_addc_u32 s7, s7, 0
	s_add_u32 s79, s79, 0x100
	s_addc_u32 s80, s80, 0
	s_cmp_gt_u32 s81, 13
; #define PG8_STAGE(bufoff, gbase, voff) do { _Pragma("unroll") for (int _i = 0; _i < 2; ++_i) \
;         __builtin_amdgcn_global_load_lds((const unsigned*)((const char*)(gbase) + (voff)[_i]), (PG8_LAS unsigned*)(lds + (bufoff) + ldsw + _i * 8192), 16, 0, 0); } while (0)
; #define PG8_LDA(dst, b, h) do { _Pragma("unroll") for (int m = 0; m < 4; ++m) _Pragma("unroll") for (int k = 0; k < 2; ++k) dst[m][k] = *(const PG8_LAS bf16x8*)(lds + PG8_SA(b, h) + aoff + m * 2048 + k * 1024); } while (0)
; #define PG8_LDB(dst, b, h) do { _Pragma("unroll") for (int n = 0; n < 2; ++n) _Pragma("unroll") for (int k = 0; k < 2; ++k) dst[n][k] = *(const PG8_LAS bf16x8*)(lds + PG8_SB(b, h) + boff + n * 2048 + k * 1024); } while (0)
; #define PG8_MMA(ai, bj, At, Bt) do { __builtin_amdgcn_s_setprio(1); _Pragma("unroll") for (int m = 0; m < 4; ++m) _Pragma("unroll") for (int n = 0; n < 2; ++n) _Pragma("unroll") for (int k = 0; k < 2; ++k) \
;         acc[ai][bj][m][n] = mma16<F16>(Bt[n][k], At[m][k], acc[ai][bj][m][n]); __builtin_amdgcn_s_setprio(0); } while (0)
; #define PG8_WAIT_V(n) asm volatile("s_waitcnt vmcnt(" #n ")" ::: "memory")
; #define PG8_WAIT_L(n) asm volatile("s_waitcnt lgkmcnt(" #n ")" ::: "memory")
; #define PG8_BAR __builtin_amdgcn_s_barrier()
; #define PG8_SCHED __builtin_amdgcn_sched_barrier(0)
; template <class Epi, class Sched, bool ALIGN_EPI = false, bool SP2 = false, bool F16 = false, bool TOKPERM = false>
; __device__ __forceinline__ void gemm_phase(PG8_LAS unsigned char* lds, const Gemm g, const Sched& S, const Epi& E, int wv) {
;     ...
;             PG8_LDB(B0, 0, 0); PG8_LDB(B1, 0, 1); PG8_SCHED; PG8_LDA(At, 0, 0); PG8_STAGE(PG8_SA(1, 1), a1 + hstep, voffA);
;             PG8_WAIT_V(8); PG8_WAIT_L(0); PG8_BAR; PG8_MMA(0, 0, At, B0); PG8_MMA(0, 1, At, B1); PG8_BAR; PG8_SCHED;
;             PG8_LDA(At, 0, 1); PG8_STAGE(PG8_SB(0, 0), b2, voffB); PG8_STAGE(PG8_SB(0, 1), b2 + hstep, voffB); PG8_STAGE(PG8_SA(0, 0), a2, voffA);
;             PG8_WAIT_V(8); PG8_WAIT_L(0); PG8_BAR; PG8_MMA(1, 0, At, B0); PG8_MMA(1, 1, At, B1); PG8_BAR; PG8_SCHED;
.LBB0_181:
	ds_read_b128 v[172:175], v155
	ds_read_b128 v[176:179], v156
	ds_read_b128 v[180:183], v157
	ds_read_b128 v[184:187], v158
	ds_read_b128 v[188:191], v159
	ds_read_b128 v[192:195], v160
	ds_read_b128 v[196:199], v161
	ds_read_b128 v[200:203], v162
	s_add_u32 s8, s6, 0xfffc0080
	s_addc_u32 s9, s7, -1
	s_cmp_eq_u32 s81, 12
	s_cselect_b32 s57, s51, s9
	s_cselect_b32 s56, s77, s8
	s_cselect_b32 s9, s49, s80
	s_cselect_b32 s8, s78, s79
	s_mov_b32 m0, s73
	v_lshl_add_u64 v[148:149], s[6:7], 0, v[140:141]
	ds_read_b128 v[204:207], v153
	ds_read_b128 v[208:211], v153 offset:1024
	ds_read_b128 v[212:215], v153 offset:2048
	ds_read_b128 v[216:219], v153 offset:3072
	ds_read_b128 v[220:223], v153 offset:4096
	ds_read_b128 v[228:231], v153 offset:5120
	ds_read_b128 v[232:235], v153 offset:6144
	ds_read_b128 v[236:239], v153 offset:7168
	global_load_lds_dwordx4 v[148:149], off
	v_lshl_add_u64 v[148:149], s[6:7], 0, v[142:143]
	s_mov_b32 m0, s74
	s_nop 0
	global_load_lds_dwordx4 v[148:149], off
	s_waitcnt vmcnt(8)
	s_waitcnt lgkmcnt(0)
	s_barrier
	s_setprio 1
	v_mfma_f32_16x16x32_f16 v[124:127], v[172:175], v[204:207], v[124:127]
	v_mfma_f32_16x16x32_f16 v[116:119], v[180:183], v[204:207], v[116:119]
	v_mfma_f32_16x16x32_f16 v[108:111], v[172:175], v[212:215], v[108:111]
	v_mfma_f32_16x16x32_f16 v[104:107], v[180:183], v[212:215], v[104:107]
	v_mfma_f32_16x16x32_f16 v[92:95], v[172:175], v[220:223], v[92:95]
	v_mfma_f32_16x16x32_f16 v[88:91], v[180:183], v[220:223], v[88:91]
	v_mfma_f32_16x16x32_f16 v[76:79], v[172:175], v[232:235], v[76:79]
	v_mfma_f32_16x16x32_f16 v[72:75], v[180:183], v[232:235], v[72:75]
	v_mfma_f32_16x16x32_f16 v[124:127], v[176:179], v[208:211], v[124:127]
	v_mfma_f32_16x16x32_f16 v[116:119], v[184:187], v[208:211], v[116:119]
	v_mfma_f32_16x16x32_f16 v[108:111], v[176:179], v[216:219], v[108:111]
	v_mfma_f32_16x16x32_f16 v[104:107], v[184:187], v[216:219], v[104:107]
	v_mfma_f32_16x16x32_f16 v[92:95], v[176:179], v[228:231], v[92:95]
	v_mfma_f32_16x16x32_f16 v[88:91], v[184:187], v[228:231], v[88:91]
	v_mfma_f32_16x16x32_f16 v[76:79], v[176:179], v[236:239], v[76:79]
	v_mfma_f32_16x16x32_f16 v[72:75], v[184:187], v[236:239], v[72:75]
	s_setprio 0
	s_setprio 1
	v_mfma_f32_16x16x32_f16 v[120:123], v[188:191], v[204:207], v[120:123]
	v_mfma_f32_16x16x32_f16 v[112:115], v[196:199], v[204:207], v[112:115]
	v_mfma_f32_16x16x32_f16 v[100:103], v[188:191], v[212:215], v[100:103]
	v_mfma_f32_16x16x32_f16 v[96:99], v[196:199], v[212:215], v[96:99]
	v_mfma_f32_16x16x32_f16 v[84:87], v[188:191], v[220:223], v[84:87]
	v_mfma_f32_16x16x32_f16 v[80:83], v[196:199], v[220:223], v[80:83]
	v_mfma_f32_16x16x32_f16 v[68:71], v[188:191], v[232:235], v[68:71]
	v_mfma_f32_16x16x32_f16 v[64:67], v[196:199], v[232:235], v[64:67]
	v_mfma_f32_16x16x32_f16 v[120:123], v[192:195], v[208:211], v[120:123]
	v_mfma_f32_16x16x32_f16 v[112:115], v[200:203], v[208:211], v[112:115]
	v_mfma_f32_16x16x32_f16 v[100:103], v[192:195], v[216:219], v[100:103]
	v_mfma_f32_16x16x32_f16 v[96:99], v[200:203], v[216:219], v[96:99]
	v_mfma_f32_16x16x32_f16 v[84:87], v[192:195], v[228:231], v[84:87]
	v_mfma_f32_16x16x32_f16 v[80:83], v[200:203], v[228:231], v[80:83]
	v_mfma_f32_16x16x32_f16 v[68:71], v[192:195], v[236:239], v[68:71]
	v_mfma_f32_16x16x32_f16 v[64:67], v[200:203], v[236:239], v[64:67]
	s_setprio 0
	s_barrier
	s_mov_b32 m0, s37
	v_lshl_add_u64 v[148:149], s[8:9], 0, v[132:133]
	s_add_u32 s82, s8, 0x40000
	ds_read_b128 v[204:207], v153 offset:16384
	ds_read_b128 v[208:211], v153 offset:17408
	ds_read_b128 v[212:215], v153 offset:18432
	ds_read_b128 v[216:219], v153 offset:19456
	ds_read_b128 v[220:223], v153 offset:20480
	ds_read_b128 v[228:231], v153 offset:21504
	ds_read_b128 v[232:235], v153 offset:22528
	ds_read_b128 v[236:239], v153 offset:23552
	global_load_lds_dwordx4 v[148:149], off
	v_lshl_add_u64 v[224:225], s[8:9], 0, v[128:129]
	s_mov_b32 m0, s45
	s_addc_u32 s83, s9, 0
	global_load_lds_dwordx4 v[224:225], off
	v_lshl_add_u64 v[240:241], s[82:83], 0, v[132:133]
	s_mov_b32 m0, s58
	v_lshl_add_u64 v[242:243], s[56:57], 0, v[130:131]
	global_load_lds_dwordx4 v[240:241], off
	v_lshl_add_u64 v[240:241], s[82:83], 0, v[128:129]
	s_mov_b32 m0, s59
	s_nop 0
	global_load_lds_dwordx4 v[240:241], off
	v_lshl_add_u64 v[240:241], s[56:57], 0, v[134:135]
	s_mov_b32 m0, s20
	s_nop 0
	global_load_lds_dwordx4 v[240:241], off
	s_mov_b32 m0, s60
	s_nop 0
	global_load_lds_dwordx4 v[242:243], off
	s_waitcnt vmcnt(8)
	s_waitcnt lgkmcnt(0)
	s_barrier
	s_setprio 1
	v_mfma_f32_16x16x32_f16 v[60:63], v[172:175], v[204:207], v[60:63]
	v_mfma_f32_16x16x32_f16 v[56:59], v[180:183], v[204:207], v[56:59]
	v_mfma_f32_16x16x32_f16 v[44:47], v[172:175], v[212:215], v[44:47]
	v_mfma_f32_16x16x32_f16 v[40:43], v[180:183], v[212:215], v[40:43]
	v_mfma_f32_16x16x32_f16 v[28:31], v[172:175], v[220:223], v[28:31]
	v_mfma_f32_16x16x32_f16 v[24:27], v[180:183], v[220:223], v[24:27]
	v_mfma_f32_16x16x32_f16 v[12:15], v[172:175], v[232:235], v[12:15]
	v_mfma_f32_16x16x32_f16 v[8:11], v[180:183], v[232:235], v[8:11]
	v_mfma_f32_16x16x32_f16 v[60:63], v[176:179], v[208:211], v[60:63]
	v_mfma_f32_16x16x32_f16 v[56:59], v[184:187], v[208:211], v[56:59]
	v_mfma_f32_16x16x32_f16 v[44:47], v[176:179], v[216:219], v[44:47]
	v_mfma_f32_16x16x32_f16 v[40:43], v[184:187], v[216:219], v[40:43]
	v_mfma_f32_16x16x32_f16 v[28:31], v[176:179], v[228:231], v[28:31]
	v_mfma_f32_16x16x32_f16 v[24:27], v[184:187], v[228:231], v[24:27]
	v_mfma_f32_16x16x32_f16 v[12:15], v[176:179], v[236:239], v[12:15]
	v_mfma_f32_16x16x32_f16 v[8:11], v[184:187], v[236:239], v[8:11]
	s_setprio 0
	s_setprio 1
	v_mfma_f32_16x16x32_f16 v[52:55], v[188:191], v[204:207], v[52:55]
	v_mfma_f32_16x16x32_f16 v[48:51], v[196:199], v[204:207], v[48:51]
	v_mfma_f32_16x16x32_f16 v[36:39], v[188:191], v[212:215], v[36:39]
	v_mfma_f32_16x16x32_f16 v[32:35], v[196:199], v[212:215], v[32:35]
	v_mfma_f32_16x16x32_f16 v[20:23], v[188:191], v[220:223], v[20:23]
	v_mfma_f32_16x16x32_f16 v[16:19], v[196:199], v[220:223], v[16:19]
	v_mfma_f32_16x16x32_f16 v[4:7], v[188:191], v[232:235], v[4:7]
	v_mfma_f32_16x16x32_f16 v[0:3], v[196:199], v[232:235], v[0:3]
	v_mfma_f32_16x16x32_f16 v[52:55], v[192:195], v[208:211], v[52:55]
	v_mfma_f32_16x16x32_f16 v[48:51], v[200:203], v[208:211], v[48:51]
	v_mfma_f32_16x16x32_f16 v[36:39], v[192:195], v[216:219], v[36:39]
	v_mfma_f32_16x16x32_f16 v[32:35], v[200:203], v[216:219], v[32:35]
	v_mfma_f32_16x16x32_f16 v[20:23], v[192:195], v[228:231], v[20:23]
	v_mfma_f32_16x16x32_f16 v[16:19], v[200:203], v[228:231], v[16:19]
	v_mfma_f32_16x16x32_f16 v[4:7], v[192:195], v[236:239], v[4:7]
	v_mfma_f32_16x16x32_f16 v[0:3], v[200:203], v[236:239], v[0:3]
	s_setprio 0
	s_barrier
; #define PG8_STAGE(bufoff, gbase, voff) do { _Pragma("unroll") for (int _i = 0; _i < 2; ++_i) \
;         __builtin_amdgcn_global_load_lds((const unsigned*)((const char*)(gbase) + (voff)[_i]), (PG8_LAS unsigned*)(lds + (bufoff) + ldsw + _i * 8192), 16, 0, 0); } while (0)
; #define PG8_LDA(dst, b, h) do { _Pragma("unroll") for (int m = 0; m < 4; ++m) _Pragma("unroll") for (int k = 0; k < 2; ++k) dst[m][k] = *(const PG8_LAS bf16x8*)(lds + PG8_SA(b, h) + aoff + m * 2048 + k * 1024); } while (0)
; #define PG8_LDB(dst, b, h) do { _Pragma("unroll") for (int n = 0; n < 2; ++n) _Pragma("unroll") for (int k = 0; k < 2; ++k) dst[n][k] = *(const PG8_LAS bf16x8*)(lds + PG8_SB(b, h) + boff + n * 2048 + k * 1024); } while (0)
; #define PG8_MMA(ai, bj, At, Bt) do { __builtin_amdgcn_s_setprio(1); _Pragma("unroll") for (int m = 0; m < 4; ++m) _Pragma("unroll") for (int n = 0; n < 2; ++n) _Pragma("unroll") for (int k = 0; k < 2; ++k) \
;         acc[ai][bj][m][n] = mma16<F16>(Bt[n][k], At[m][k], acc[ai][bj][m][n]); __builtin_amdgcn_s_setprio(0); } while (0)
; #define PG8_WAIT_V(n) asm volatile("s_waitcnt vmcnt(" #n ")" ::: "memory")
; #define PG8_WAIT_L(n) asm volatile("s_waitcnt lgkmcnt(" #n ")" ::: "memory")
; #define PG8_BAR __builtin_amdgcn_s_barrier()
; #define PG8_SCHED __builtin_amdgcn_sched_barrier(0)
; template <class Epi, class Sched, bool ALIGN_EPI = false, bool SP2 = false, bool F16 = false, bool TOKPERM = false>
; __device__ __forceinline__ void gemm_phase(PG8_LAS unsigned char* lds, const Gemm g, const Sched& S, const Epi& E, int wv) {
;     ...
;         for (int t = 0; t < nt; t += 2) {
;     ...
;             PG8_LDB(B0, 1, 0); PG8_LDB(B1, 1, 1); PG8_SCHED; PG8_LDA(At, 1, 0); PG8_STAGE(PG8_SA(0, 1), a2 + hstep, voffA);
;             PG8_WAIT_V(8); PG8_WAIT_L(0); PG8_BAR; PG8_MMA(0, 0, At, B0); PG8_MMA(0, 1, At, B1); PG8_BAR; PG8_SCHED;
;             PG8_LDA(At, 1, 1); PG8_STAGE(PG8_SB(1, 0), b3, voffB); PG8_STAGE(PG8_SB(1, 1), b3 + hstep, voffB); PG8_STAGE(PG8_SA(1, 0), a3, voffA);
;             PG8_WAIT_V(8); PG8_WAIT_L(0); PG8_BAR; PG8_MMA(1, 0, At, B0); PG8_MMA(1, 1, At, B1); PG8_BAR; PG8_SCHED;
	ds_read_b128 v[172:175], v163
	ds_read_b128 v[176:179], v164
	ds_read_b128 v[180:183], v165
	ds_read_b128 v[184:187], v166
	ds_read_b128 v[188:191], v167
	ds_read_b128 v[192:195], v168
	ds_read_b128 v[196:199], v169
	ds_read_b128 v[200:203], v170
	s_add_u32 s56, s56, 0x40000
	s_addc_u32 s57, s57, 0
	s_mov_b32 m0, s61
	v_lshl_add_u64 v[244:245], s[56:57], 0, v[134:135]
	ds_read_b128 v[204:207], v153 offset:32768
	ds_read_b128 v[208:211], v153 offset:33792
	ds_read_b128 v[212:215], v153 offset:34816
	ds_read_b128 v[216:219], v153 offset:35840
	ds_read_b128 v[220:223], v153 offset:36864
	ds_read_b128 v[228:231], v153 offset:37888
	ds_read_b128 v[232:235], v153 offset:38912
	ds_read_b128 v[236:239], v153 offset:39936
	global_load_lds_dwordx4 v[244:245], off
	v_lshl_add_u64 v[244:245], s[56:57], 0, v[130:131]
	s_mov_b32 m0, s62
	s_nop 0
	global_load_lds_dwordx4 v[244:245], off
	s_waitcnt vmcnt(8)
	s_waitcnt lgkmcnt(0)
	s_barrier
	s_setprio 1
	v_mfma_f32_16x16x32_f16 v[124:127], v[172:175], v[204:207], v[124:127]
	v_mfma_f32_16x16x32_f16 v[116:119], v[180:183], v[204:207], v[116:119]
	v_mfma_f32_16x16x32_f16 v[108:111], v[172:175], v[212:215], v[108:111]
	v_mfma_f32_16x16x32_f16 v[104:107], v[180:183], v[212:215], v[104:107]
	v_mfma_f32_16x16x32_f16 v[92:95], v[172:175], v[220:223], v[92:95]
	v_mfma_f32_16x16x32_f16 v[88:91], v[180:183], v[220:223], v[88:91]
	v_mfma_f32_16x16x32_f16 v[76:79], v[172:175], v[232:235], v[76:79]
	v_mfma_f32_16x16x32_f16 v[72:75], v[180:183], v[232:235], v[72:75]
	v_mfma_f32_16x16x32_f16 v[124:127], v[176:179], v[208:211], v[124:127]
	v_mfma_f32_16x16x32_f16 v[116:119], v[184:187], v[208:211], v[116:119]
	v_mfma_f32_16x16x32_f16 v[108:111], v[176:179], v[216:219], v[108:111]
	v_mfma_f32_16x16x32_f16 v[104:107], v[184:187], v[216:219], v[104:107]
	v_mfma_f32_16x16x32_f16 v[92:95], v[176:179], v[228:231], v[92:95]
	v_mfma_f32_16x16x32_f16 v[88:91], v[184:187], v[228:231], v[88:91]
	v_mfma_f32_16x16x32_f16 v[76:79], v[176:179], v[236:239], v[76:79]
	v_mfma_f32_16x16x32_f16 v[72:75], v[184:187], v[236:239], v[72:75]
	s_setprio 0
	s_setprio 1
	v_mfma_f32_16x16x32_f16 v[120:123], v[188:191], v[204:207], v[120:123]
	v_mfma_f32_16x16x32_f16 v[112:115], v[196:199], v[204:207], v[112:115]
	v_mfma_f32_16x16x32_f16 v[100:103], v[188:191], v[212:215], v[100:103]
	v_mfma_f32_16x16x32_f16 v[96:99], v[196:199], v[212:215], v[96:99]
	v_mfma_f32_16x16x32_f16 v[84:87], v[188:191], v[220:223], v[84:87]
	v_mfma_f32_16x16x32_f16 v[80:83], v[196:199], v[220:223], v[80:83]
	v_mfma_f32_16x16x32_f16 v[68:71], v[188:191], v[232:235], v[68:71]
	v_mfma_f32_16x16x32_f16 v[64:67], v[196:199], v[232:235], v[64:67]
	v_mfma_f32_16x16x32_f16 v[120:123], v[192:195], v[208:211], v[120:123]
	v_mfma_f32_16x16x32_f16 v[112:115], v[200:203], v[208:211], v[112:115]
	v_mfma_f32_16x16x32_f16 v[100:103], v[192:195], v[216:219], v[100:103]
	v_mfma_f32_16x16x32_f16 v[96:99], v[200:203], v[216:219], v[96:99]
	v_mfma_f32_16x16x32_f16 v[84:87], v[192:195], v[228:231], v[84:87]
	v_mfma_f32_16x16x32_f16 v[80:83], v[200:203], v[228:231], v[80:83]
	v_mfma_f32_16x16x32_f16 v[68:71], v[192:195], v[236:239], v[68:71]
	v_mfma_f32_16x16x32_f16 v[64:67], v[200:203], v[236:239], v[64:67]
	s_setprio 0
	s_barrier
	s_mov_b32 m0, s64
	v_lshl_add_u64 v[148:149], v[148:149], 0, s[16:17]
	s_add_u32 s8, s8, 0x40080
	ds_read_b128 v[204:207], v153 offset:49152
	ds_read_b128 v[208:211], v153 offset:50176
	ds_read_b128 v[212:215], v153 offset:51200
	ds_read_b128 v[216:219], v153 offset:52224
	ds_read_b128 v[220:223], v153 offset:53248
	ds_read_b128 v[228:231], v153 offset:54272
	ds_read_b128 v[232:235], v153 offset:55296
	ds_read_b128 v[236:239], v153 offset:56320
	global_load_lds_dwordx4 v[148:149], off
	v_lshl_add_u64 v[148:149], v[224:225], 0, s[16:17]
	s_mov_b32 m0, s65
	s_addc_u32 s9, s9, 0
	global_load_lds_dwordx4 v[148:149], off
	v_lshl_add_u64 v[148:149], s[8:9], 0, v[132:133]
	s_mov_b32 m0, s69
	s_nop 0
	global_load_lds_dwordx4 v[148:149], off
	v_lshl_add_u64 v[148:149], s[8:9], 0, v[128:129]
	s_mov_b32 m0, s70
	s_nop 0
	global_load_lds_dwordx4 v[148:149], off
	v_lshl_add_u64 v[148:149], v[240:241], 0, s[16:17]
	s_mov_b32 m0, s66
	s_nop 0
	global_load_lds_dwordx4 v[148:149], off
	v_lshl_add_u64 v[148:149], v[242:243], 0, s[16:17]
	s_mov_b32 m0, s68
	s_nop 0
	global_load_lds_dwordx4 v[148:149], off
	s_waitcnt vmcnt(8)
	s_waitcnt lgkmcnt(0)
	s_barrier
	s_setprio 1
	v_mfma_f32_16x16x32_f16 v[60:63], v[172:175], v[204:207], v[60:63]
	v_mfma_f32_16x16x32_f16 v[56:59], v[180:183], v[204:207], v[56:59]
	v_mfma_f32_16x16x32_f16 v[44:47], v[172:175], v[212:215], v[44:47]
	v_mfma_f32_16x16x32_f16 v[40:43], v[180:183], v[212:215], v[40:43]
	v_mfma_f32_16x16x32_f16 v[28:31], v[172:175], v[220:223], v[28:31]
	v_mfma_f32_16x16x32_f16 v[24:27], v[180:183], v[220:223], v[24:27]
	v_mfma_f32_16x16x32_f16 v[12:15], v[172:175], v[232:235], v[12:15]
	v_mfma_f32_16x16x32_f16 v[8:11], v[180:183], v[232:235], v[8:11]
	v_mfma_f32_16x16x32_f16 v[60:63], v[176:179], v[208:211], v[60:63]
	v_mfma_f32_16x16x32_f16 v[56:59], v[184:187], v[208:211], v[56:59]
	v_mfma_f32_16x16x32_f16 v[44:47], v[176:179], v[216:219], v[44:47]
	v_mfma_f32_16x16x32_f16 v[40:43], v[184:187], v[216:219], v[40:43]
	v_mfma_f32_16x16x32_f16 v[28:31], v[176:179], v[228:231], v[28:31]
	v_mfma_f32_16x16x32_f16 v[24:27], v[184:187], v[228:231], v[24:27]
	v_mfma_f32_16x16x32_f16 v[12:15], v[176:179], v[236:239], v[12:15]
	v_mfma_f32_16x16x32_f16 v[8:11], v[184:187], v[236:239], v[8:11]
	s_setprio 0
	s_setprio 1
	v_mfma_f32_16x16x32_f16 v[52:55], v[188:191], v[204:207], v[52:55]
	v_mfma_f32_16x16x32_f16 v[48:51], v[196:199], v[204:207], v[48:51]
	v_mfma_f32_16x16x32_f16 v[36:39], v[188:191], v[212:215], v[36:39]
	v_mfma_f32_16x16x32_f16 v[32:35], v[196:199], v[212:215], v[32:35]
	v_mfma_f32_16x16x32_f16 v[20:23], v[188:191], v[220:223], v[20:23]
	v_mfma_f32_16x16x32_f16 v[16:19], v[196:199], v[220:223], v[16:19]
	v_mfma_f32_16x16x32_f16 v[4:7], v[188:191], v[232:235], v[4:7]
	v_mfma_f32_16x16x32_f16 v[0:3], v[196:199], v[232:235], v[0:3]
	v_mfma_f32_16x16x32_f16 v[52:55], v[192:195], v[208:211], v[52:55]
	v_mfma_f32_16x16x32_f16 v[48:51], v[200:203], v[208:211], v[48:51]
	v_mfma_f32_16x16x32_f16 v[36:39], v[192:195], v[216:219], v[36:39]
	v_mfma_f32_16x16x32_f16 v[32:35], v[200:203], v[216:219], v[32:35]
	v_mfma_f32_16x16x32_f16 v[20:23], v[192:195], v[228:231], v[20:23]
	v_mfma_f32_16x16x32_f16 v[16:19], v[200:203], v[228:231], v[16:19]
	v_mfma_f32_16x16x32_f16 v[4:7], v[192:195], v[236:239], v[4:7]
	v_mfma_f32_16x16x32_f16 v[0:3], v[200:203], v[236:239], v[0:3]
	s_setprio 0
	s_barrier
	s_add_i32 s81, s81, 2
	s_add_u32 s6, s6, 0x100
	s_addc_u32 s7, s7, 0
	s_add_u32 s79, s79, 0x100
	s_addc_u32 s80, s80, 0
	s_cmp_gt_u32 s81, 13
	s_cbranch_scc0 .LBB0_181
	s_and_b64 vcc, exec, s[18:19]
	s_cbranch_vccz .LBB0_184
	s_barrier

; #define PG8_STAGE(bufoff, gbase, voff) do { _Pragma("unroll") for (int _i = 0; _i < 2; ++_i) \
;         __builtin_amdgcn_global_load_lds((const unsigned*)((const char*)(gbase) + (voff)[_i]), (PG8_LAS unsigned*)(lds + (bufoff) + ldsw + _i * 8192), 16, 0, 0); } while (0)
; #define PG8_LDA(dst, b, h) do { _Pragma("unroll") for (int m = 0; m < 4; ++m) _Pragma("unroll") for (int k = 0; k < 2; ++k) dst[m][k] = *(const PG8_LAS bf16x8*)(lds + PG8_SA(b, h) + aoff + m * 2048 + k * 1024); } while (0)
; #define PG8_LDB(dst, b, h) do { _Pragma("unroll") for (int n = 0; n < 2; ++n) _Pragma("unroll") for (int k = 0; k < 2; ++k) dst[n][k] = *(const PG8_LAS bf16x8*)(lds + PG8_SB(b, h) + boff + n * 2048 + k * 1024); } while (0)
; #define PG8_MMA(ai, bj, At, Bt) do { __builtin_amdgcn_s_setprio(1); _Pragma("unroll") for (int m = 0; m < 4; ++m) _Pragma("unroll") for (int n = 0; n < 2; ++n) _Pragma("unroll") for (int k = 0; k < 2; ++k) \
;         acc[ai][bj][m][n] = mma16<F16>(Bt[n][k], At[m][k], acc[ai][bj][m][n]); __builtin_amdgcn_s_setprio(0); } while (0)
; #define PG8_WAIT_V(n) asm volatile("s_waitcnt vmcnt(" #n ")" ::: "memory")
; #define PG8_WAIT_L(n) asm volatile("s_waitcnt lgkmcnt(" #n ")" ::: "memory")
; #define PG8_BAR __builtin_amdgcn_s_barrier()
; #define PG8_SCHED __builtin_amdgcn_sched_barrier(0)
; template <class Epi, class Sched, bool ALIGN_EPI = false, bool SP2 = false, bool F16 = false, bool TOKPERM = false>
; __device__ __forceinline__ void gemm_phase(PG8_LAS unsigned char* lds, const Gemm g, const Sched& S, const Epi& E, int wv) {
;     ...
;             PG8_LDB(B0, 0, 0); PG8_LDB(B1, 0, 1); PG8_SCHED; PG8_LDA(At, 0, 0); PG8_STAGE(PG8_SA(1, 1), a1 + hstep, voffA);
;             PG8_WAIT_V(8); PG8_WAIT_L(0); PG8_BAR; PG8_MMA(0, 0, At, B0); PG8_MMA(0, 1, At, B1); PG8_BAR; PG8_SCHED;
;             PG8_LDA(At, 0, 1); PG8_STAGE(PG8_SB(0, 0), b2, voffB); PG8_STAGE(PG8_SB(0, 1), b2 + hstep, voffB); PG8_STAGE(PG8_SA(0, 0), a2, voffA);
;             PG8_WAIT_V(8); PG8_WAIT_L(0); PG8_BAR; PG8_MMA(1, 0, At, B0); PG8_MMA(1, 1, At, B1); PG8_BAR; PG8_SCHED;
.LBB0_297:
	ds_read_b128 v[166:169], v149
	ds_read_b128 v[170:173], v150
	ds_read_b128 v[174:177], v151
	ds_read_b128 v[178:181], v152
	ds_read_b128 v[182:185], v153
	ds_read_b128 v[186:189], v154
	ds_read_b128 v[190:193], v155
	ds_read_b128 v[194:197], v156
	s_add_u32 s18, s16, 0x100
	s_addc_u32 s19, s17, 0
	s_cmp_eq_u32 s70, 40
	s_cselect_b32 s51, s9, s19
	s_cselect_b32 s50, s8, s18
	s_cselect_b32 s49, s11, s69
	s_cselect_b32 s48, s10, s68
	s_mov_b32 m0, s61
	v_lshl_add_u64 v[232:233], s[16:17], 0, v[138:139]
	ds_read_b128 v[198:201], v147
	ds_read_b128 v[202:205], v147 offset:1024
	ds_read_b128 v[206:209], v147 offset:2048
	ds_read_b128 v[210:213], v147 offset:3072
	ds_read_b128 v[214:217], v147 offset:4096
	ds_read_b128 v[218:221], v147 offset:5120
	ds_read_b128 v[222:225], v147 offset:6144
	ds_read_b128 v[228:231], v147 offset:7168
	global_load_lds_dwordx4 v[232:233], off
	v_lshl_add_u64 v[232:233], s[16:17], 0, v[140:141]
	s_mov_b32 m0, s62
	s_nop 0
	global_load_lds_dwordx4 v[232:233], off
	s_waitcnt vmcnt(8)
	s_waitcnt lgkmcnt(0)
	s_barrier
	s_setprio 1
	v_mfma_f32_16x16x32_bf16 v[124:127], v[166:169], v[198:201], v[124:127]
	v_mfma_f32_16x16x32_bf16 v[120:123], v[174:177], v[198:201], v[120:123]
	v_mfma_f32_16x16x32_bf16 v[108:111], v[166:169], v[206:209], v[108:111]
	v_mfma_f32_16x16x32_bf16 v[104:107], v[174:177], v[206:209], v[104:107]
	v_mfma_f32_16x16x32_bf16 v[92:95], v[166:169], v[214:217], v[92:95]
	v_mfma_f32_16x16x32_bf16 v[88:91], v[174:177], v[214:217], v[88:91]
	v_mfma_f32_16x16x32_bf16 v[76:79], v[166:169], v[222:225], v[76:79]
	v_mfma_f32_16x16x32_bf16 v[72:75], v[174:177], v[222:225], v[72:75]
	v_mfma_f32_16x16x32_bf16 v[124:127], v[170:173], v[202:205], v[124:127]
	v_mfma_f32_16x16x32_bf16 v[120:123], v[178:181], v[202:205], v[120:123]
	v_mfma_f32_16x16x32_bf16 v[108:111], v[170:173], v[210:213], v[108:111]
	v_mfma_f32_16x16x32_bf16 v[104:107], v[178:181], v[210:213], v[104:107]
	v_mfma_f32_16x16x32_bf16 v[92:95], v[170:173], v[218:221], v[92:95]
	v_mfma_f32_16x16x32_bf16 v[88:91], v[178:181], v[218:221], v[88:91]
	v_mfma_f32_16x16x32_bf16 v[76:79], v[170:173], v[228:231], v[76:79]
	v_mfma_f32_16x16x32_bf16 v[72:75], v[178:181], v[228:231], v[72:75]
	s_setprio 0
	s_setprio 1
	v_mfma_f32_16x16x32_bf16 v[116:119], v[182:185], v[198:201], v[116:119]
	v_mfma_f32_16x16x32_bf16 v[112:115], v[190:193], v[198:201], v[112:115]
	v_mfma_f32_16x16x32_bf16 v[100:103], v[182:185], v[206:209], v[100:103]
	v_mfma_f32_16x16x32_bf16 v[96:99], v[190:193], v[206:209], v[96:99]
	v_mfma_f32_16x16x32_bf16 v[84:87], v[182:185], v[214:217], v[84:87]
	v_mfma_f32_16x16x32_bf16 v[80:83], v[190:193], v[214:217], v[80:83]
	v_mfma_f32_16x16x32_bf16 v[68:71], v[182:185], v[222:225], v[68:71]
	v_mfma_f32_16x16x32_bf16 v[64:67], v[190:193], v[222:225], v[64:67]
	v_mfma_f32_16x16x32_bf16 v[116:119], v[186:189], v[202:205], v[116:119]
	v_mfma_f32_16x16x32_bf16 v[112:115], v[194:197], v[202:205], v[112:115]
	v_mfma_f32_16x16x32_bf16 v[100:103], v[186:189], v[210:213], v[100:103]
	v_mfma_f32_16x16x32_bf16 v[96:99], v[194:197], v[210:213], v[96:99]
	v_mfma_f32_16x16x32_bf16 v[84:87], v[186:189], v[218:221], v[84:87]
	v_mfma_f32_16x16x32_bf16 v[80:83], v[194:197], v[218:221], v[80:83]
	v_mfma_f32_16x16x32_bf16 v[68:71], v[186:189], v[228:231], v[68:71]
	v_mfma_f32_16x16x32_bf16 v[64:67], v[194:197], v[228:231], v[64:67]
	s_setprio 0
	s_barrier
	s_mov_b32 m0, s3
	v_lshl_add_u64 v[232:233], s[48:49], 0, v[130:131]
	s_add_u32 s16, s48, 0xb0000
	ds_read_b128 v[198:201], v147 offset:16384
	ds_read_b128 v[202:205], v147 offset:17408
	ds_read_b128 v[206:209], v147 offset:18432
	ds_read_b128 v[210:213], v147 offset:19456
	ds_read_b128 v[214:217], v147 offset:20480
	ds_read_b128 v[218:221], v147 offset:21504
	ds_read_b128 v[222:225], v147 offset:22528
	ds_read_b128 v[228:231], v147 offset:23552
	global_load_lds_dwordx4 v[232:233], off
	v_lshl_add_u64 v[234:235], s[48:49], 0, v[134:135]
	s_mov_b32 m0, s21
	s_addc_u32 s17, s49, 0
	global_load_lds_dwordx4 v[234:235], off
	v_lshl_add_u64 v[236:237], s[16:17], 0, v[130:131]
	s_mov_b32 m0, s22
	v_lshl_add_u64 v[238:239], s[50:51], 0, v[132:133]
	global_load_lds_dwordx4 v[236:237], off
	v_lshl_add_u64 v[236:237], s[16:17], 0, v[134:135]
	s_mov_b32 m0, s23
	s_nop 0
	global_load_lds_dwordx4 v[236:237], off
	v_lshl_add_u64 v[236:237], s[50:51], 0, v[128:129]
	s_mov_b32 m0, s2
	s_nop 0
	global_load_lds_dwordx4 v[236:237], off
	s_mov_b32 m0, s33
	s_nop 0
	global_load_lds_dwordx4 v[238:239], off
	s_waitcnt vmcnt(8)
	s_waitcnt lgkmcnt(0)
	s_barrier
; #define PG8_STAGE(bufoff, gbase, voff) do { _Pragma("unroll") for (int _i = 0; _i < 2; ++_i) \
;         __builtin_amdgcn_global_load_lds((const unsigned*)((const char*)(gbase) + (voff)[_i]), (PG8_LAS unsigned*)(lds + (bufoff) + ldsw + _i * 8192), 16, 0, 0); } while (0)
; #define PG8_LDA(dst, b, h) do { _Pragma("unroll") for (int m = 0; m < 4; ++m) _Pragma("unroll") for (int k = 0; k < 2; ++k) dst[m][k] = *(const PG8_LAS bf16x8*)(lds + PG8_SA(b, h) + aoff + m * 2048 + k * 1024); } while (0)
; #define PG8_LDB(dst, b, h) do { _Pragma("unroll") for (int n = 0; n < 2; ++n) _Pragma("unroll") for (int k = 0; k < 2; ++k) dst[n][k] = *(const PG8_LAS bf16x8*)(lds + PG8_SB(b, h) + boff + n * 2048 + k * 1024); } while (0)
; #define PG8_MMA(ai, bj, At, Bt) do { __builtin_amdgcn_s_setprio(1); _Pragma("unroll") for (int m = 0; m < 4; ++m) _Pragma("unroll") for (int n = 0; n < 2; ++n) _Pragma("unroll") for (int k = 0; k < 2; ++k) \
;         acc[ai][bj][m][n] = mma16<F16>(Bt[n][k], At[m][k], acc[ai][bj][m][n]); __builtin_amdgcn_s_setprio(0); } while (0)
; #define PG8_WAIT_V(n) asm volatile("s_waitcnt vmcnt(" #n ")" ::: "memory")
; #define PG8_WAIT_L(n) asm volatile("s_waitcnt lgkmcnt(" #n ")" ::: "memory")
; #define PG8_BAR __builtin_amdgcn_s_barrier()
; #define PG8_SCHED __builtin_amdgcn_sched_barrier(0)
; template <class Epi, class Sched, bool ALIGN_EPI = false, bool SP2 = false, bool F16 = false, bool TOKPERM = false>
; __device__ __forceinline__ void gemm_phase(PG8_LAS unsigned char* lds, const Gemm g, const Sched& S, const Epi& E, int wv) {
;     ...
;             PG8_WAIT_V(8); PG8_WAIT_L(0); PG8_BAR; PG8_MMA(1, 0, At, B0); PG8_MMA(1, 1, At, B1); PG8_BAR; PG8_SCHED;
;             PG8_LDB(B0, 1, 0); PG8_LDB(B1, 1, 1); PG8_SCHED; PG8_LDA(At, 1, 0); PG8_STAGE(PG8_SA(0, 1), a2 + hstep, voffA);
;             PG8_WAIT_V(8); PG8_WAIT_L(0); PG8_BAR; PG8_MMA(0, 0, At, B0); PG8_MMA(0, 1, At, B1); PG8_BAR; PG8_SCHED;
	s_setprio 1
	v_mfma_f32_16x16x32_bf16 v[60:63], v[166:169], v[198:201], v[60:63]
	v_mfma_f32_16x16x32_bf16 v[56:59], v[174:177], v[198:201], v[56:59]
	v_mfma_f32_16x16x32_bf16 v[44:47], v[166:169], v[206:209], v[44:47]
	v_mfma_f32_16x16x32_bf16 v[40:43], v[174:177], v[206:209], v[40:43]
	v_mfma_f32_16x16x32_bf16 v[28:31], v[166:169], v[214:217], v[28:31]
	v_mfma_f32_16x16x32_bf16 v[24:27], v[174:177], v[214:217], v[24:27]
	v_mfma_f32_16x16x32_bf16 v[12:15], v[166:169], v[222:225], v[12:15]
	v_mfma_f32_16x16x32_bf16 v[8:11], v[174:177], v[222:225], v[8:11]
	v_mfma_f32_16x16x32_bf16 v[60:63], v[170:173], v[202:205], v[60:63]
	v_mfma_f32_16x16x32_bf16 v[56:59], v[178:181], v[202:205], v[56:59]
	v_mfma_f32_16x16x32_bf16 v[44:47], v[170:173], v[210:213], v[44:47]
	v_mfma_f32_16x16x32_bf16 v[40:43], v[178:181], v[210:213], v[40:43]
	v_mfma_f32_16x16x32_bf16 v[28:31], v[170:173], v[218:221], v[28:31]
	v_mfma_f32_16x16x32_bf16 v[24:27], v[178:181], v[218:221], v[24:27]
	v_mfma_f32_16x16x32_bf16 v[12:15], v[170:173], v[228:231], v[12:15]
	v_mfma_f32_16x16x32_bf16 v[8:11], v[178:181], v[228:231], v[8:11]
	s_setprio 0
	s_setprio 1
	v_mfma_f32_16x16x32_bf16 v[52:55], v[182:185], v[198:201], v[52:55]
	v_mfma_f32_16x16x32_bf16 v[48:51], v[190:193], v[198:201], v[48:51]
	v_mfma_f32_16x16x32_bf16 v[36:39], v[182:185], v[206:209], v[36:39]
	v_mfma_f32_16x16x32_bf16 v[32:35], v[190:193], v[206:209], v[32:35]
	v_mfma_f32_16x16x32_bf16 v[20:23], v[182:185], v[214:217], v[20:23]
	v_mfma_f32_16x16x32_bf16 v[16:19], v[190:193], v[214:217], v[16:19]
	v_mfma_f32_16x16x32_bf16 v[4:7], v[182:185], v[222:225], v[4:7]
	v_mfma_f32_16x16x32_bf16 v[0:3], v[190:193], v[222:225], v[0:3]
	v_mfma_f32_16x16x32_bf16 v[52:55], v[186:189], v[202:205], v[52:55]
	v_mfma_f32_16x16x32_bf16 v[48:51], v[194:197], v[202:205], v[48:51]
	v_mfma_f32_16x16x32_bf16 v[36:39], v[186:189], v[210:213], v[36:39]
	v_mfma_f32_16x16x32_bf16 v[32:35], v[194:197], v[210:213], v[32:35]
	v_mfma_f32_16x16x32_bf16 v[20:23], v[186:189], v[218:221], v[20:23]
	v_mfma_f32_16x16x32_bf16 v[16:19], v[194:197], v[218:221], v[16:19]
	v_mfma_f32_16x16x32_bf16 v[4:7], v[186:189], v[228:231], v[4:7]
	v_mfma_f32_16x16x32_bf16 v[0:3], v[194:197], v[228:231], v[0:3]
	s_setprio 0
	s_barrier
	ds_read_b128 v[166:169], v157
	ds_read_b128 v[170:173], v158
	ds_read_b128 v[174:177], v159
	ds_read_b128 v[178:181], v160
	ds_read_b128 v[182:185], v161
	ds_read_b128 v[186:189], v162
	ds_read_b128 v[190:193], v163
	ds_read_b128 v[194:197], v164
	s_add_u32 s16, s50, 0xb0000
	s_addc_u32 s17, s51, 0
	s_mov_b32 m0, s36
	v_lshl_add_u64 v[240:241], s[16:17], 0, v[128:129]
	ds_read_b128 v[198:201], v147 offset:32768
	ds_read_b128 v[202:205], v147 offset:33792
	ds_read_b128 v[206:209], v147 offset:34816
	ds_read_b128 v[210:213], v147 offset:35840
	ds_read_b128 v[214:217], v147 offset:36864
	ds_read_b128 v[218:221], v147 offset:37888
	ds_read_b128 v[222:225], v147 offset:38912
	ds_read_b128 v[228:231], v147 offset:39936
	global_load_lds_dwordx4 v[240:241], off
	v_lshl_add_u64 v[240:241], s[16:17], 0, v[132:133]
	s_mov_b32 m0, s37
	s_nop 0
	global_load_lds_dwordx4 v[240:241], off
	s_waitcnt vmcnt(8)
	s_waitcnt lgkmcnt(0)
	s_barrier
	s_setprio 1
	v_mfma_f32_16x16x32_bf16 v[124:127], v[166:169], v[198:201], v[124:127]
	v_mfma_f32_16x16x32_bf16 v[120:123], v[174:177], v[198:201], v[120:123]
	v_mfma_f32_16x16x32_bf16 v[108:111], v[166:169], v[206:209], v[108:111]
	v_mfma_f32_16x16x32_bf16 v[104:107], v[174:177], v[206:209], v[104:107]
	v_mfma_f32_16x16x32_bf16 v[92:95], v[166:169], v[214:217], v[92:95]
	v_mfma_f32_16x16x32_bf16 v[88:91], v[174:177], v[214:217], v[88:91]
	v_mfma_f32_16x16x32_bf16 v[76:79], v[166:169], v[222:225], v[76:79]
	v_mfma_f32_16x16x32_bf16 v[72:75], v[174:177], v[222:225], v[72:75]
	v_mfma_f32_16x16x32_bf16 v[124:127], v[170:173], v[202:205], v[124:127]
	v_mfma_f32_16x16x32_bf16 v[120:123], v[178:181], v[202:205], v[120:123]
	v_mfma_f32_16x16x32_bf16 v[108:111], v[170:173], v[210:213], v[108:111]
	v_mfma_f32_16x16x32_bf16 v[104:107], v[178:181], v[210:213], v[104:107]
	v_mfma_f32_16x16x32_bf16 v[92:95], v[170:173], v[218:221], v[92:95]
	v_mfma_f32_16x16x32_bf16 v[88:91], v[178:181], v[218:221], v[88:91]
	v_mfma_f32_16x16x32_bf16 v[76:79], v[170:173], v[228:231], v[76:79]
	v_mfma_f32_16x16x32_bf16 v[72:75], v[178:181], v[228:231], v[72:75]
	s_setprio 0
	s_setprio 1
	v_mfma_f32_16x16x32_bf16 v[116:119], v[182:185], v[198:201], v[116:119]
	v_mfma_f32_16x16x32_bf16 v[112:115], v[190:193], v[198:201], v[112:115]
	v_mfma_f32_16x16x32_bf16 v[100:103], v[182:185], v[206:209], v[100:103]
	v_mfma_f32_16x16x32_bf16 v[96:99], v[190:193], v[206:209], v[96:99]
	v_mfma_f32_16x16x32_bf16 v[84:87], v[182:185], v[214:217], v[84:87]
	v_mfma_f32_16x16x32_bf16 v[80:83], v[190:193], v[214:217], v[80:83]
	v_mfma_f32_16x16x32_bf16 v[68:71], v[182:185], v[222:225], v[68:71]
	v_mfma_f32_16x16x32_bf16 v[64:67], v[190:193], v[222:225], v[64:67]
	v_mfma_f32_16x16x32_bf16 v[116:119], v[186:189], v[202:205], v[116:119]
	v_mfma_f32_16x16x32_bf16 v[112:115], v[194:197], v[202:205], v[112:115]
	v_mfma_f32_16x16x32_bf16 v[100:103], v[186:189], v[210:213], v[100:103]
	v_mfma_f32_16x16x32_bf16 v[96:99], v[194:197], v[210:213], v[96:99]
	v_mfma_f32_16x16x32_bf16 v[84:87], v[186:189], v[218:221], v[84:87]
	v_mfma_f32_16x16x32_bf16 v[80:83], v[194:197], v[218:221], v[80:83]
	v_mfma_f32_16x16x32_bf16 v[68:71], v[186:189], v[228:231], v[68:71]
	v_mfma_f32_16x16x32_bf16 v[64:67], v[194:197], v[228:231], v[64:67]
	s_setprio 0
	s_barrier
; #define PG8_STAGE(bufoff, gbase, voff) do { _Pragma("unroll") for (int _i = 0; _i < 2; ++_i) \
;         __builtin_amdgcn_global_load_lds((const unsigned*)((const char*)(gbase) + (voff)[_i]), (PG8_LAS unsigned*)(lds + (bufoff) + ldsw + _i * 8192), 16, 0, 0); } while (0)
; #define PG8_LDA(dst, b, h) do { _Pragma("unroll") for (int m = 0; m < 4; ++m) _Pragma("unroll") for (int k = 0; k < 2; ++k) dst[m][k] = *(const PG8_LAS bf16x8*)(lds + PG8_SA(b, h) + aoff + m * 2048 + k * 1024); } while (0)
; #define PG8_MMA(ai, bj, At, Bt) do { __builtin_amdgcn_s_setprio(1); _Pragma("unroll") for (int m = 0; m < 4; ++m) _Pragma("unroll") for (int n = 0; n < 2; ++n) _Pragma("unroll") for (int k = 0; k < 2; ++k) \
;         acc[ai][bj][m][n] = mma16<F16>(Bt[n][k], At[m][k], acc[ai][bj][m][n]); __builtin_amdgcn_s_setprio(0); } while (0)
; #define PG8_WAIT_V(n) asm volatile("s_waitcnt vmcnt(" #n ")" ::: "memory")
; #define PG8_WAIT_L(n) asm volatile("s_waitcnt lgkmcnt(" #n ")" ::: "memory")
; #define PG8_BAR __builtin_amdgcn_s_barrier()
; #define PG8_SCHED __builtin_amdgcn_sched_barrier(0)
; template <class Epi, class Sched, bool ALIGN_EPI = false, bool SP2 = false, bool F16 = false, bool TOKPERM = false>
; __device__ __forceinline__ void gemm_phase(PG8_LAS unsigned char* lds, const Gemm g, const Sched& S, const Epi& E, int wv) {
;     ...
;         for (int t = 0; t < nt; t += 2) {
;     ...
;             PG8_LDA(At, 1, 1); PG8_STAGE(PG8_SB(1, 0), b3, voffB); PG8_STAGE(PG8_SB(1, 1), b3 + hstep, voffB); PG8_STAGE(PG8_SA(1, 0), a3, voffA);
;             PG8_WAIT_V(8); PG8_WAIT_L(0); PG8_BAR; PG8_MMA(1, 0, At, B0); PG8_MMA(1, 1, At, B1); PG8_BAR; PG8_SCHED;
	s_mov_b32 m0, s45
	v_lshl_add_u64 v[232:233], v[232:233], 0, s[12:13]
	s_add_u32 s16, s48, 0xb0080
	ds_read_b128 v[198:201], v147 offset:49152
	ds_read_b128 v[202:205], v147 offset:50176
	ds_read_b128 v[206:209], v147 offset:51200
	ds_read_b128 v[210:213], v147 offset:52224
	ds_read_b128 v[214:217], v147 offset:53248
	ds_read_b128 v[218:221], v147 offset:54272
	ds_read_b128 v[222:225], v147 offset:55296
	ds_read_b128 v[228:231], v147 offset:56320
	global_load_lds_dwordx4 v[232:233], off
	v_lshl_add_u64 v[232:233], v[234:235], 0, s[12:13]
	s_mov_b32 m0, s52
	s_addc_u32 s17, s49, 0
	global_load_lds_dwordx4 v[232:233], off
	v_lshl_add_u64 v[232:233], s[16:17], 0, v[130:131]
	s_mov_b32 m0, s55
	s_nop 0
	global_load_lds_dwordx4 v[232:233], off
	v_lshl_add_u64 v[232:233], s[16:17], 0, v[134:135]
	s_mov_b32 m0, s56
	s_nop 0
	global_load_lds_dwordx4 v[232:233], off
	v_lshl_add_u64 v[232:233], v[236:237], 0, s[12:13]
	s_mov_b32 m0, s53
	s_nop 0
	global_load_lds_dwordx4 v[232:233], off
	v_lshl_add_u64 v[232:233], v[238:239], 0, s[12:13]
	s_mov_b32 m0, s54
	s_nop 0
	global_load_lds_dwordx4 v[232:233], off
	s_waitcnt vmcnt(8)
	s_waitcnt lgkmcnt(0)
	s_barrier
	s_setprio 1
	v_mfma_f32_16x16x32_bf16 v[60:63], v[166:169], v[198:201], v[60:63]
	v_mfma_f32_16x16x32_bf16 v[56:59], v[174:177], v[198:201], v[56:59]
	v_mfma_f32_16x16x32_bf16 v[44:47], v[166:169], v[206:209], v[44:47]
	v_mfma_f32_16x16x32_bf16 v[40:43], v[174:177], v[206:209], v[40:43]
	v_mfma_f32_16x16x32_bf16 v[28:31], v[166:169], v[214:217], v[28:31]
	v_mfma_f32_16x16x32_bf16 v[24:27], v[174:177], v[214:217], v[24:27]
	v_mfma_f32_16x16x32_bf16 v[12:15], v[166:169], v[222:225], v[12:15]
	v_mfma_f32_16x16x32_bf16 v[8:11], v[174:177], v[222:225], v[8:11]
	v_mfma_f32_16x16x32_bf16 v[60:63], v[170:173], v[202:205], v[60:63]
	v_mfma_f32_16x16x32_bf16 v[56:59], v[178:181], v[202:205], v[56:59]
	v_mfma_f32_16x16x32_bf16 v[44:47], v[170:173], v[210:213], v[44:47]
	v_mfma_f32_16x16x32_bf16 v[40:43], v[178:181], v[210:213], v[40:43]
	v_mfma_f32_16x16x32_bf16 v[28:31], v[170:173], v[218:221], v[28:31]
	v_mfma_f32_16x16x32_bf16 v[24:27], v[178:181], v[218:221], v[24:27]
	v_mfma_f32_16x16x32_bf16 v[12:15], v[170:173], v[228:231], v[12:15]
	v_mfma_f32_16x16x32_bf16 v[8:11], v[178:181], v[228:231], v[8:11]
	s_setprio 0
	s_setprio 1
	v_mfma_f32_16x16x32_bf16 v[52:55], v[182:185], v[198:201], v[52:55]
	v_mfma_f32_16x16x32_bf16 v[48:51], v[190:193], v[198:201], v[48:51]
	v_mfma_f32_16x16x32_bf16 v[36:39], v[182:185], v[206:209], v[36:39]
	v_mfma_f32_16x16x32_bf16 v[32:35], v[190:193], v[206:209], v[32:35]
	v_mfma_f32_16x16x32_bf16 v[20:23], v[182:185], v[214:217], v[20:23]
	v_mfma_f32_16x16x32_bf16 v[16:19], v[190:193], v[214:217], v[16:19]
	v_mfma_f32_16x16x32_bf16 v[4:7], v[182:185], v[222:225], v[4:7]
	v_mfma_f32_16x16x32_bf16 v[0:3], v[190:193], v[222:225], v[0:3]
	v_mfma_f32_16x16x32_bf16 v[52:55], v[186:189], v[202:205], v[52:55]
	v_mfma_f32_16x16x32_bf16 v[48:51], v[194:197], v[202:205], v[48:51]
	v_mfma_f32_16x16x32_bf16 v[36:39], v[186:189], v[210:213], v[36:39]
	v_mfma_f32_16x16x32_bf16 v[32:35], v[194:197], v[210:213], v[32:35]
	v_mfma_f32_16x16x32_bf16 v[20:23], v[186:189], v[218:221], v[20:23]
	v_mfma_f32_16x16x32_bf16 v[16:19], v[194:197], v[218:221], v[16:19]
	v_mfma_f32_16x16x32_bf16 v[4:7], v[186:189], v[228:231], v[4:7]
	v_mfma_f32_16x16x32_bf16 v[0:3], v[194:197], v[228:231], v[0:3]
	s_setprio 0
	s_barrier
	s_add_i32 s70, s70, 2
	s_add_u32 s68, s68, 0x100
	s_addc_u32 s69, s69, 0
	s_cmp_gt_u32 s70, 41
	s_mov_b64 s[16:17], s[18:19]
	s_cbranch_scc0 .LBB0_297
;   __device__ __forceinline__ void operator()(const pg8::f32x4 (&acc)[2][2][4][2], const pg8::Unit& u, int wr, int wc, int fr, int fq) const {
;     int z; asm volatile("v_mov_b32 %0, 0" : "=v"(z));
;     const int row0 = u.pm * 256 + wr * 64 + fr + z, colb = u.pn * 256 + wc * 32 + 8 * fq + z;
; #pragma unroll
;     for (int ai = 0; ai < 2; ++ai)
; #pragma unroll
;       for (int m = 0; m < 4; ++m) {
;         const int tok = row0 + ai * 128 + m * 16; float ss = 0.f;
; #pragma unroll
;         for (int bj = 0; bj < 2; ++bj) {
;           const unsigned off = (unsigned)tok * DM + colb + 128 * bj;
;           f8_t n = __builtin_convertvector(*(const h8_t*)(x16 + off), f8_t);
; #pragma unroll
;           for (int c = 0; c < 4; ++c) { n[c] += sc * acc[ai][bj][m][0][c]; n[4 + c] += sc * acc[ai][bj][m][1][c]; }
;           if (aux) {
;             *(h8_t*)(x16 + off) = __builtin_convertvector(n, h8_t);
;             ss += ((n[0] * n[0] + n[1] * n[1]) + (n[2] * n[2] + n[3] * n[3])) + ((n[4] * n[4] + n[5] * n[5]) + (n[6] * n[6] + n[7] * n[7]));
;           } else {
;             *(f32x4*)(xout + off) = (f32x4){n[0], n[1], n[2], n[3]}; *(f32x4*)(xout + off + 4) = (f32x4){n[4], n[5], n[6], n[7]};
;           }
;         }
;         if (aux) { ss += __shfl_xor(ss, 16); ss += __shfl_xor(ss, 32); if (fq == 0) ssq[(unsigned)tok * 16 + u.pn * 4 + wc] = ss; }
;         if (m & 1) asm volatile("" ::: "memory");
;       }
	s_lshl_b32 s16, s66, 8
	v_lshl_or_b32 v166, s65, 8, v148
	v_mov_b32 v136, 0
	v_xor_b32_e32 v169, 32, v165
	v_add3_u32 v167, s16, v146, v136
	v_add_u32_e32 v168, v166, v136
	v_lshl_add_u32 v136, v167, 10, v168
	v_lshl_add_u64 v[178:179], v[136:137], 1, s[40:41]
	v_add_u32_e32 v136, 0x80, v136
	global_load_dwordx4 v[170:173], v[178:179], off
	v_lshl_add_u64 v[180:181], v[136:137], 1, s[40:41]
	global_load_dwordx4 v[174:177], v[180:181], off
	v_add_u32_e32 v136, 16, v167
	v_lshl_add_u32 v136, v136, 10, v168
	v_lshl_add_u64 v[224:225], v[136:137], 1, s[40:41]
	v_add_u32_e32 v136, 0x80, v136
	global_load_dwordx4 v[192:195], v[224:225], off
	v_lshl_add_u64 v[248:249], v[136:137], 1, s[40:41]
	global_load_dwordx4 v[196:199], v[248:249], off
	v_add_u32_e32 v136, 32, v167
	v_lshl_add_u32 v136, v136, 10, v168
	v_lshl_add_u64 v[224:225], v[136:137], 1, s[40:41]
	v_add_u32_e32 v136, 0x80, v136
	global_load_dwordx4 v[200:203], v[224:225], off
	v_lshl_add_u64 v[248:249], v[136:137], 1, s[40:41]
	global_load_dwordx4 v[204:207], v[248:249], off
	v_add_u32_e32 v136, 48, v167
	v_lshl_add_u32 v136, v136, 10, v168
	v_lshl_add_u64 v[224:225], v[136:137], 1, s[40:41]
	v_add_u32_e32 v136, 0x80, v136
	global_load_dwordx4 v[208:211], v[224:225], off
	v_lshl_add_u64 v[248:249], v[136:137], 1, s[40:41]
	global_load_dwordx4 v[212:215], v[248:249], off
	v_add_u32_e32 v136, 0x80, v167
	v_lshl_add_u32 v136, v136, 10, v168
	v_lshl_add_u64 v[224:225], v[136:137], 1, s[40:41]
	v_add_u32_e32 v136, 0x80, v136
	global_load_dwordx4 v[216:219], v[224:225], off
	v_lshl_add_u64 v[248:249], v[136:137], 1, s[40:41]
	global_load_dwordx4 v[220:223], v[248:249], off
	v_add_u32_e32 v136, 0x90, v167
	v_lshl_add_u32 v136, v136, 10, v168
	v_lshl_add_u64 v[224:225], v[136:137], 1, s[40:41]
	v_add_u32_e32 v136, 0x80, v136
	global_load_dwordx4 v[228:231], v[224:225], off
	v_lshl_add_u64 v[248:249], v[136:137], 1, s[40:41]
	global_load_dwordx4 v[244:247], v[248:249], off
	v_and_b32_e32 v166, 64, v165
	v_xor_b32_e32 v136, 16, v165
	v_add_u32_e32 v166, 64, v166
	v_cmp_lt_i32_e32 vcc, v136, v166
	s_lshl_b32 s16, s65, 2
	s_or_b32 s18, s16, s44
	v_cndmask_b32_e32 v136, v165, v136, vcc
	v_cmp_lt_i32_e32 vcc, v169, v166
	v_lshlrev_b32_e32 v166, 2, v136
	s_waitcnt vmcnt(10)
	v_cvt_f32_f16_e32 v182, v173
	v_cvt_f32_f16_sdwa v183, v173 dst_sel:DWORD dst_unused:UNUSED_PAD src0_sel:WORD_1
	v_cvt_f32_f16_e32 v184, v171
	v_cvt_f32_f16_sdwa v185, v171 dst_sel:DWORD dst_unused:UNUSED_PAD src0_sel:WORD_1
	v_cvt_f32_f16_e32 v186, v172
	v_cvt_f32_f16_sdwa v187, v172 dst_sel:DWORD dst_unused:UNUSED_PAD src0_sel:WORD_1
	v_cvt_f32_f16_e32 v172, v170
	v_cvt_f32_f16_sdwa v173, v170 dst_sel:DWORD dst_unused:UNUSED_PAD src0_sel:WORD_1
	v_cvt_f32_f16_e32 v170, v177
	v_cvt_f32_f16_sdwa v171, v177 dst_sel:DWORD dst_unused:UNUSED_PAD src0_sel:WORD_1
	v_cvt_f32_f16_e32 v188, v175
	v_cvt_f32_f16_sdwa v189, v175 dst_sel:DWORD dst_unused:UNUSED_PAD src0_sel:WORD_1
	v_cvt_f32_f16_e32 v190, v176
	v_cvt_f32_f16_sdwa v191, v176 dst_sel:DWORD dst_unused:UNUSED_PAD src0_sel:WORD_1
	v_cvt_f32_f16_e32 v176, v174
	v_cvt_f32_f16_sdwa v177, v174 dst_sel:DWORD dst_unused:UNUSED_PAD src0_sel:WORD_1
	v_pk_fma_f32 v[124:125], v[124:125], 0.5, v[172:173] op_sel_hi:[1,0,1]
	v_pk_fma_f32 v[172:173], v[120:121], 0.5, v[186:187] op_sel_hi:[1,0,1]
	v_pk_fma_f32 v[126:127], v[126:127], 0.5, v[184:185] op_sel_hi:[1,0,1]
	v_pk_fma_f32 v[122:123], v[122:123], 0.5, v[182:183] op_sel_hi:[1,0,1]
	v_cvt_pk_f16_f32 v120, v172, v173
	v_cvt_pk_f16_f32 v121, v122, v123
	v_pk_mul_f32 v[174:175], v[124:125], v[124:125]
	v_pk_mul_f32 v[182:183], v[126:127], v[126:127]
	v_pk_fma_f32 v[174:175], v[172:173], v[172:173], v[174:175]
	v_pk_fma_f32 v[182:183], v[122:123], v[122:123], v[182:183]
	v_pk_fma_f32 v[176:177], v[116:117], 0.5, v[176:177] op_sel_hi:[1,0,1]
	v_pk_fma_f32 v[116:117], v[112:113], 0.5, v[190:191] op_sel_hi:[1,0,1]
	v_pk_fma_f32 v[184:185], v[118:119], 0.5, v[188:189] op_sel_hi:[1,0,1]
	v_pk_fma_f32 v[112:113], v[114:115], 0.5, v[170:171] op_sel_hi:[1,0,1]
	v_pk_fma_f32 v[174:175], v[176:177], v[176:177], v[174:175]
	v_pk_fma_f32 v[182:183], v[184:185], v[184:185], v[182:183]
	v_pk_fma_f32 v[174:175], v[116:117], v[116:117], v[174:175]
	v_pk_fma_f32 v[182:183], v[112:113], v[112:113], v[182:183]
	v_pk_add_f32 v[174:175], v[174:175], v[182:183]
	v_add_f32_e32 v114, v174, v175
	v_mov_b32_e32 v115, v114
	s_nop 1
	v_permlane16_swap_b32_e32 v114, v115
	v_cndmask_b32_e32 v169, v165, v169, vcc
	v_cvt_pk_f16_f32 v119, v126, v127
	v_cvt_pk_f16_f32 v118, v124, v125
	global_store_dwordx4 v[178:179], v[118:121], off
	s_nop 1
	v_cvt_pk_f16_f32 v119, v112, v113
	s_waitcnt lgkmcnt(0)
	v_add_f32_e32 v113, v114, v115
	v_lshlrev_b32_e32 v112, 2, v169
	v_mov_b32_e32 v114, v113
	s_nop 1
	v_permlane32_swap_b32_e32 v113, v114
	v_cvt_pk_f16_f32 v118, v116, v117
	v_cvt_pk_f16_f32 v117, v184, v185
	v_cvt_pk_f16_f32 v116, v176, v177
	global_store_dwordx4 v[180:181], v[116:119], off
	s_and_saveexec_b64 s[16:17], s[4:5]
	s_cbranch_execz .LBB0_300
	v_lshl_add_u32 v136, v167, 4, s18
	s_waitcnt lgkmcnt(0)
	v_add_f32_e32 v113, v113, v114
	v_lshl_add_u64 v[114:115], v[136:137], 2, s[42:43]
	global_store_dword v[114:115], v113, off

; #define PG8_STAGE(bufoff, gbase, voff) do { _Pragma("unroll") for (int _i = 0; _i < 2; ++_i) \
;         __builtin_amdgcn_global_load_lds((const unsigned*)((const char*)(gbase) + (voff)[_i]), (PG8_LAS unsigned*)(lds + (bufoff) + ldsw + _i * 8192), 16, 0, 0); } while (0)
; #define PG8_LDA(dst, b, h) do { _Pragma("unroll") for (int m = 0; m < 4; ++m) _Pragma("unroll") for (int k = 0; k < 2; ++k) dst[m][k] = *(const PG8_LAS bf16x8*)(lds + PG8_SA(b, h) + aoff + m * 2048 + k * 1024); } while (0)
; #define PG8_LDB(dst, b, h) do { _Pragma("unroll") for (int n = 0; n < 2; ++n) _Pragma("unroll") for (int k = 0; k < 2; ++k) dst[n][k] = *(const PG8_LAS bf16x8*)(lds + PG8_SB(b, h) + boff + n * 2048 + k * 1024); } while (0)
; #define PG8_MMA(ai, bj, At, Bt) do { __builtin_amdgcn_s_setprio(1); _Pragma("unroll") for (int m = 0; m < 4; ++m) _Pragma("unroll") for (int n = 0; n < 2; ++n) _Pragma("unroll") for (int k = 0; k < 2; ++k) \
;         acc[ai][bj][m][n] = mma16<F16>(Bt[n][k], At[m][k], acc[ai][bj][m][n]); __builtin_amdgcn_s_setprio(0); } while (0)
; #define PG8_WAIT_V(n) asm volatile("s_waitcnt vmcnt(" #n ")" ::: "memory")
; #define PG8_WAIT_L(n) asm volatile("s_waitcnt lgkmcnt(" #n ")" ::: "memory")
; template <class Epi, class Sched, bool ALIGN_EPI = false, bool SP2 = false, bool F16 = false, bool TOKPERM = false>
; __device__ __forceinline__ void gemm_phase(PG8_LAS unsigned char* lds, const Gemm g, const Sched& S, const Epi& E, int wv) {
;     ...
;         const bool has_next = S.next(ui + 1, nxt);
;         const char* nA = has_next ? (const char*)g.A + (size_t)nxt.pm * tstep : cA; const char* nB = has_next ? (const char*)g.Bt + (size_t)nxt.pn * tstep : cB;
;         for (int t = 0; t < nt; t += 2) {
;             const bool last = (t == nt - 2);
;             const char* a1 = cA + (size_t)(t + 1) * kstep;
;             const char* a2 = last ? nA : cA + (size_t)(t + 2) * kstep; const char* b2 = last ? nB : cB + (size_t)(t + 2) * kstep;
;             const char* a3 = a2 + kstep; const char* b3 = b2 + kstep;
;             if (last && has_next) S.a_ready(nxt);
;             if constexpr (SP2) {
;             PG8_LDB(B0, 0, 0); PG8_LDB(B1, 0, 1); PG8_SCHED; PG8_LDA(At, 0, 0); PG8_STAGE(PG8_SA(1, 1), a1 + hstep, voffA);
;             PG8_WAIT_V(8); PG8_WAIT_L(0); PG8_BAR; PG8_MMA(0, 0, At, B0); PG8_MMA(0, 1, At, B1); PG8_BAR; PG8_SCHED;
.LBB0_381:
	s_ashr_i32 s71, s70, 31
	s_lshl_b64 s[10:11], s[70:71], 19
	s_add_u32 s72, s40, s10
	s_addc_u32 s73, s41, s11
	s_and_b64 s[10:11], s[4:5], exec
	s_cselect_b32 s12, s73, s7
	s_cselect_b32 s13, s72, s6
	s_ashr_i32 s69, s68, 31
	s_lshl_b64 s[10:11], s[68:69], 19
	s_add_u32 s74, s46, s10
	s_addc_u32 s75, s47, s11
	s_and_b64 s[10:11], s[4:5], exec
	s_cselect_b32 s59, s75, s9
	s_cselect_b32 s64, s74, s8
	s_add_u32 s6, s6, 0x40080
	s_addc_u32 s7, s7, 0
	s_add_u32 s69, s8, 0x100
	s_addc_u32 s71, s9, 0
	s_mov_b32 s76, -2
	s_waitcnt lgkmcnt(0)
	ds_read_b128 v[156:159], v181
	ds_read_b128 v[160:163], v182
	ds_read_b128 v[164:167], v183
	ds_read_b128 v[168:171], v184
	ds_read_b128 v[172:175], v185
	ds_read_b128 v[176:179], v186
	ds_read_b128 v[200:203], v187
	ds_read_b128 v[204:207], v188
	s_add_u32 s8, s6, 0xfffc0080
	s_addc_u32 s9, s7, -1
	s_cmp_eq_u32 s76, 12
	s_cselect_b32 s11, s12, s9
	s_cselect_b32 s10, s13, s8
	s_cselect_b32 s9, s59, s71
	s_cselect_b32 s8, s64, s69
	s_mov_b32 m0, s36
	v_lshl_add_u64 v[224:225], s[6:7], 0, v[146:147]
	ds_read_b128 v[208:211], v155
	ds_read_b128 v[212:215], v155 offset:1024
	ds_read_b128 v[216:219], v155 offset:2048
	ds_read_b128 v[220:223], v155 offset:3072
	ds_read_b128 v[228:231], v155 offset:4096
	ds_read_b128 v[232:235], v155 offset:5120
	ds_read_b128 v[236:239], v155 offset:6144
	ds_read_b128 v[240:243], v155 offset:7168
	global_load_lds_dwordx4 v[224:225], off
	v_lshl_add_u64 v[224:225], s[6:7], 0, v[148:149]
	s_mov_b32 m0, s2
	s_nop 0
	global_load_lds_dwordx4 v[224:225], off
	s_waitcnt vmcnt(8)
	s_waitcnt lgkmcnt(0)
	s_barrier
	s_setprio 1
	v_mfma_f32_16x16x32_f16 v[124:127], v[156:159], v[208:211], 0
	v_mfma_f32_16x16x32_f16 v[120:123], v[164:167], v[208:211], 0
	v_mfma_f32_16x16x32_f16 v[108:111], v[156:159], v[216:219], 0
	v_mfma_f32_16x16x32_f16 v[104:107], v[164:167], v[216:219], 0
	v_mfma_f32_16x16x32_f16 v[92:95], v[156:159], v[228:231], 0
	v_mfma_f32_16x16x32_f16 v[88:91], v[164:167], v[228:231], 0
	v_mfma_f32_16x16x32_f16 v[76:79], v[156:159], v[236:239], 0
	v_mfma_f32_16x16x32_f16 v[72:75], v[164:167], v[236:239], 0
	v_mfma_f32_16x16x32_f16 v[124:127], v[160:163], v[212:215], v[124:127]
	v_mfma_f32_16x16x32_f16 v[120:123], v[168:171], v[212:215], v[120:123]
	v_mfma_f32_16x16x32_f16 v[108:111], v[160:163], v[220:223], v[108:111]
	v_mfma_f32_16x16x32_f16 v[104:107], v[168:171], v[220:223], v[104:107]
	v_mfma_f32_16x16x32_f16 v[92:95], v[160:163], v[232:235], v[92:95]
	v_mfma_f32_16x16x32_f16 v[88:91], v[168:171], v[232:235], v[88:91]
	v_mfma_f32_16x16x32_f16 v[76:79], v[160:163], v[240:243], v[76:79]
	v_mfma_f32_16x16x32_f16 v[72:75], v[168:171], v[240:243], v[72:75]
	s_setprio 0
	s_setprio 1
	v_mfma_f32_16x16x32_f16 v[116:119], v[172:175], v[208:211], 0
	v_mfma_f32_16x16x32_f16 v[112:115], v[200:203], v[208:211], 0
	v_mfma_f32_16x16x32_f16 v[100:103], v[172:175], v[216:219], 0
	v_mfma_f32_16x16x32_f16 v[96:99], v[200:203], v[216:219], 0
	v_mfma_f32_16x16x32_f16 v[84:87], v[172:175], v[228:231], 0
	v_mfma_f32_16x16x32_f16 v[80:83], v[200:203], v[228:231], 0
	v_mfma_f32_16x16x32_f16 v[68:71], v[172:175], v[236:239], 0
	v_mfma_f32_16x16x32_f16 v[64:67], v[200:203], v[236:239], 0
	v_mfma_f32_16x16x32_f16 v[116:119], v[176:179], v[212:215], v[116:119]
	v_mfma_f32_16x16x32_f16 v[112:115], v[204:207], v[212:215], v[112:115]
	v_mfma_f32_16x16x32_f16 v[100:103], v[176:179], v[220:223], v[100:103]
	v_mfma_f32_16x16x32_f16 v[96:99], v[204:207], v[220:223], v[96:99]
	v_mfma_f32_16x16x32_f16 v[84:87], v[176:179], v[232:235], v[84:87]
	v_mfma_f32_16x16x32_f16 v[80:83], v[204:207], v[232:235], v[80:83]
	v_mfma_f32_16x16x32_f16 v[68:71], v[176:179], v[240:243], v[68:71]
	v_mfma_f32_16x16x32_f16 v[64:67], v[204:207], v[240:243], v[64:67]
	s_setprio 0
	s_barrier
	s_mov_b32 m0, s53
	v_lshl_add_u64 v[224:225], s[8:9], 0, v[130:131]
	s_add_u32 s78, s8, 0x40000
	ds_read_b128 v[208:211], v155 offset:16384
	ds_read_b128 v[212:215], v155 offset:17408
	ds_read_b128 v[216:219], v155 offset:18432
	ds_read_b128 v[220:223], v155 offset:19456
	ds_read_b128 v[228:231], v155 offset:20480
	ds_read_b128 v[232:235], v155 offset:21504
	ds_read_b128 v[236:239], v155 offset:22528
	ds_read_b128 v[240:243], v155 offset:23552
	global_load_lds_dwordx4 v[224:225], off
	v_lshl_add_u64 v[244:245], s[8:9], 0, v[134:135]
	s_mov_b32 m0, s55
	s_addc_u32 s79, s9, 0
	global_load_lds_dwordx4 v[244:245], off
	v_lshl_add_u64 v[246:247], s[78:79], 0, v[130:131]
	s_mov_b32 m0, s91
	v_lshl_add_u64 v[248:249], s[10:11], 0, v[132:133]
	global_load_lds_dwordx4 v[246:247], off
	v_lshl_add_u64 v[246:247], s[78:79], 0, v[134:135]
	s_mov_b32 m0, s92
	s_nop 0
	global_load_lds_dwordx4 v[246:247], off
	v_lshl_add_u64 v[246:247], s[10:11], 0, v[128:129]
	s_mov_b32 m0, s90
	s_nop 0
	global_load_lds_dwordx4 v[246:247], off
	s_mov_b32 m0, s93
	s_nop 0
	global_load_lds_dwordx4 v[248:249], off
	s_waitcnt vmcnt(8)
	s_waitcnt lgkmcnt(0)
	s_barrier
; #define PG8_STAGE(bufoff, gbase, voff) do { _Pragma("unroll") for (int _i = 0; _i < 2; ++_i) \
;         __builtin_amdgcn_global_load_lds((const unsigned*)((const char*)(gbase) + (voff)[_i]), (PG8_LAS unsigned*)(lds + (bufoff) + ldsw + _i * 8192), 16, 0, 0); } while (0)
; #define PG8_LDA(dst, b, h) do { _Pragma("unroll") for (int m = 0; m < 4; ++m) _Pragma("unroll") for (int k = 0; k < 2; ++k) dst[m][k] = *(const PG8_LAS bf16x8*)(lds + PG8_SA(b, h) + aoff + m * 2048 + k * 1024); } while (0)
; #define PG8_LDB(dst, b, h) do { _Pragma("unroll") for (int n = 0; n < 2; ++n) _Pragma("unroll") for (int k = 0; k < 2; ++k) dst[n][k] = *(const PG8_LAS bf16x8*)(lds + PG8_SB(b, h) + boff + n * 2048 + k * 1024); } while (0)
; #define PG8_MMA(ai, bj, At, Bt) do { __builtin_amdgcn_s_setprio(1); _Pragma("unroll") for (int m = 0; m < 4; ++m) _Pragma("unroll") for (int n = 0; n < 2; ++n) _Pragma("unroll") for (int k = 0; k < 2; ++k) \
;         acc[ai][bj][m][n] = mma16<F16>(Bt[n][k], At[m][k], acc[ai][bj][m][n]); __builtin_amdgcn_s_setprio(0); } while (0)
; #define PG8_BAR __builtin_amdgcn_s_barrier()
; template <class Epi, class Sched, bool ALIGN_EPI = false, bool SP2 = false, bool F16 = false, bool TOKPERM = false>
; __device__ __forceinline__ void gemm_phase(PG8_LAS unsigned char* lds, const Gemm g, const Sched& S, const Epi& E, int wv) {
;     ...
;             PG8_LDB(B0, 0, 0); PG8_LDB(B1, 0, 1); PG8_SCHED; PG8_LDA(At, 0, 0); PG8_STAGE(PG8_SA(1, 1), a1 + hstep, voffA);
;             PG8_WAIT_V(8); PG8_WAIT_L(0); PG8_BAR; PG8_MMA(0, 0, At, B0); PG8_MMA(0, 1, At, B1); PG8_BAR; PG8_SCHED;
;             PG8_LDA(At, 0, 1); PG8_STAGE(PG8_SB(0, 0), b2, voffB); PG8_STAGE(PG8_SB(0, 1), b2 + hstep, voffB); PG8_STAGE(PG8_SA(0, 0), a2, voffA);
;             PG8_WAIT_V(8); PG8_WAIT_L(0); PG8_BAR; PG8_MMA(1, 0, At, B0); PG8_MMA(1, 1, At, B1); PG8_BAR; PG8_SCHED;
;             PG8_LDB(B0, 1, 0); PG8_LDB(B1, 1, 1); PG8_SCHED; PG8_LDA(At, 1, 0); PG8_STAGE(PG8_SA(0, 1), a2 + hstep, voffA);
;             PG8_WAIT_V(8); PG8_WAIT_L(0); PG8_BAR; PG8_MMA(0, 0, At, B0); PG8_MMA(0, 1, At, B1); PG8_BAR; PG8_SCHED;
;             PG8_LDA(At, 1, 1); PG8_STAGE(PG8_SB(1, 0), b3, voffB); PG8_STAGE(PG8_SB(1, 1), b3 + hstep, voffB); PG8_STAGE(PG8_SA(1, 0), a3, voffA);
;             PG8_WAIT_V(8); PG8_WAIT_L(0); PG8_BAR; PG8_MMA(1, 0, At, B0); PG8_MMA(1, 1, At, B1); PG8_BAR; PG8_SCHED;
	s_setprio 1
	v_mfma_f32_16x16x32_f16 v[60:63], v[156:159], v[208:211], 0
	v_mfma_f32_16x16x32_f16 v[56:59], v[164:167], v[208:211], 0
	v_mfma_f32_16x16x32_f16 v[44:47], v[156:159], v[216:219], 0
	v_mfma_f32_16x16x32_f16 v[40:43], v[164:167], v[216:219], 0
	v_mfma_f32_16x16x32_f16 v[28:31], v[156:159], v[228:231], 0
	v_mfma_f32_16x16x32_f16 v[24:27], v[164:167], v[228:231], 0
	v_mfma_f32_16x16x32_f16 v[12:15], v[156:159], v[236:239], 0
	v_mfma_f32_16x16x32_f16 v[8:11], v[164:167], v[236:239], 0
	v_mfma_f32_16x16x32_f16 v[60:63], v[160:163], v[212:215], v[60:63]
	v_mfma_f32_16x16x32_f16 v[56:59], v[168:171], v[212:215], v[56:59]
	v_mfma_f32_16x16x32_f16 v[44:47], v[160:163], v[220:223], v[44:47]
	v_mfma_f32_16x16x32_f16 v[40:43], v[168:171], v[220:223], v[40:43]
	v_mfma_f32_16x16x32_f16 v[28:31], v[160:163], v[232:235], v[28:31]
	v_mfma_f32_16x16x32_f16 v[24:27], v[168:171], v[232:235], v[24:27]
	v_mfma_f32_16x16x32_f16 v[12:15], v[160:163], v[240:243], v[12:15]
	v_mfma_f32_16x16x32_f16 v[8:11], v[168:171], v[240:243], v[8:11]
	s_setprio 0
	s_setprio 1
	v_mfma_f32_16x16x32_f16 v[52:55], v[172:175], v[208:211], 0
	v_mfma_f32_16x16x32_f16 v[48:51], v[200:203], v[208:211], 0
	v_mfma_f32_16x16x32_f16 v[36:39], v[172:175], v[216:219], 0
	v_mfma_f32_16x16x32_f16 v[32:35], v[200:203], v[216:219], 0
	v_mfma_f32_16x16x32_f16 v[20:23], v[172:175], v[228:231], 0
	v_mfma_f32_16x16x32_f16 v[16:19], v[200:203], v[228:231], 0
	v_mfma_f32_16x16x32_f16 v[4:7], v[172:175], v[236:239], 0
	v_mfma_f32_16x16x32_f16 v[0:3], v[200:203], v[236:239], 0
	v_mfma_f32_16x16x32_f16 v[52:55], v[176:179], v[212:215], v[52:55]
	v_mfma_f32_16x16x32_f16 v[48:51], v[204:207], v[212:215], v[48:51]
	v_mfma_f32_16x16x32_f16 v[36:39], v[176:179], v[220:223], v[36:39]
	v_mfma_f32_16x16x32_f16 v[32:35], v[204:207], v[220:223], v[32:35]
	v_mfma_f32_16x16x32_f16 v[20:23], v[176:179], v[232:235], v[20:23]
	v_mfma_f32_16x16x32_f16 v[16:19], v[204:207], v[232:235], v[16:19]
	v_mfma_f32_16x16x32_f16 v[4:7], v[176:179], v[240:243], v[4:7]
	v_mfma_f32_16x16x32_f16 v[0:3], v[204:207], v[240:243], v[0:3]
	s_setprio 0
	s_barrier
	ds_read_b128 v[156:159], v189
	ds_read_b128 v[160:163], v190
	ds_read_b128 v[164:167], v191
	ds_read_b128 v[168:171], v192
	ds_read_b128 v[172:175], v193
	ds_read_b128 v[176:179], v194
	ds_read_b128 v[200:203], v195
	ds_read_b128 v[204:207], v196
	s_add_u32 s10, s10, 0x40000
	s_addc_u32 s11, s11, 0
	s_mov_b32 m0, s95
	v_lshl_add_u64 v[250:251], s[10:11], 0, v[128:129]
	ds_read_b128 v[208:211], v155 offset:32768
	ds_read_b128 v[212:215], v155 offset:33792
	ds_read_b128 v[216:219], v155 offset:34816
	ds_read_b128 v[220:223], v155 offset:35840
	ds_read_b128 v[228:231], v155 offset:36864
	ds_read_b128 v[232:235], v155 offset:37888
	ds_read_b128 v[236:239], v155 offset:38912
	ds_read_b128 v[240:243], v155 offset:39936
	global_load_lds_dwordx4 v[250:251], off
	v_lshl_add_u64 v[250:251], s[10:11], 0, v[132:133]
	s_mov_b32 m0, s96
	s_nop 0
	global_load_lds_dwordx4 v[250:251], off
	s_waitcnt vmcnt(8)
	s_waitcnt lgkmcnt(0)
	s_barrier
	s_setprio 1
	v_mfma_f32_16x16x32_f16 v[124:127], v[156:159], v[208:211], v[124:127]
	v_mfma_f32_16x16x32_f16 v[120:123], v[164:167], v[208:211], v[120:123]
	v_mfma_f32_16x16x32_f16 v[108:111], v[156:159], v[216:219], v[108:111]
	v_mfma_f32_16x16x32_f16 v[104:107], v[164:167], v[216:219], v[104:107]
	v_mfma_f32_16x16x32_f16 v[92:95], v[156:159], v[228:231], v[92:95]
	v_mfma_f32_16x16x32_f16 v[88:91], v[164:167], v[228:231], v[88:91]
	v_mfma_f32_16x16x32_f16 v[76:79], v[156:159], v[236:239], v[76:79]
	v_mfma_f32_16x16x32_f16 v[72:75], v[164:167], v[236:239], v[72:75]
	v_mfma_f32_16x16x32_f16 v[124:127], v[160:163], v[212:215], v[124:127]
	v_mfma_f32_16x16x32_f16 v[120:123], v[168:171], v[212:215], v[120:123]
	v_mfma_f32_16x16x32_f16 v[108:111], v[160:163], v[220:223], v[108:111]
	v_mfma_f32_16x16x32_f16 v[104:107], v[168:171], v[220:223], v[104:107]
	v_mfma_f32_16x16x32_f16 v[92:95], v[160:163], v[232:235], v[92:95]
	v_mfma_f32_16x16x32_f16 v[88:91], v[168:171], v[232:235], v[88:91]
	v_mfma_f32_16x16x32_f16 v[76:79], v[160:163], v[240:243], v[76:79]
	v_mfma_f32_16x16x32_f16 v[72:75], v[168:171], v[240:243], v[72:75]
	s_setprio 0
	s_setprio 1
	v_mfma_f32_16x16x32_f16 v[116:119], v[172:175], v[208:211], v[116:119]
	v_mfma_f32_16x16x32_f16 v[112:115], v[200:203], v[208:211], v[112:115]
	v_mfma_f32_16x16x32_f16 v[100:103], v[172:175], v[216:219], v[100:103]
	v_mfma_f32_16x16x32_f16 v[96:99], v[200:203], v[216:219], v[96:99]
	v_mfma_f32_16x16x32_f16 v[84:87], v[172:175], v[228:231], v[84:87]
	v_mfma_f32_16x16x32_f16 v[80:83], v[200:203], v[228:231], v[80:83]
	v_mfma_f32_16x16x32_f16 v[68:71], v[172:175], v[236:239], v[68:71]
	v_mfma_f32_16x16x32_f16 v[64:67], v[200:203], v[236:239], v[64:67]
	v_mfma_f32_16x16x32_f16 v[116:119], v[176:179], v[212:215], v[116:119]
	v_mfma_f32_16x16x32_f16 v[112:115], v[204:207], v[212:215], v[112:115]
	v_mfma_f32_16x16x32_f16 v[100:103], v[176:179], v[220:223], v[100:103]
	v_mfma_f32_16x16x32_f16 v[96:99], v[204:207], v[220:223], v[96:99]
	v_mfma_f32_16x16x32_f16 v[84:87], v[176:179], v[232:235], v[84:87]
	v_mfma_f32_16x16x32_f16 v[80:83], v[204:207], v[232:235], v[80:83]
	v_mfma_f32_16x16x32_f16 v[68:71], v[176:179], v[240:243], v[68:71]
	v_mfma_f32_16x16x32_f16 v[64:67], v[204:207], v[240:243], v[64:67]
	s_setprio 0
	s_barrier
; #define PG8_STAGE(bufoff, gbase, voff) do { _Pragma("unroll") for (int _i = 0; _i < 2; ++_i) \
;         __builtin_amdgcn_global_load_lds((const unsigned*)((const char*)(gbase) + (voff)[_i]), (PG8_LAS unsigned*)(lds + (bufoff) + ldsw + _i * 8192), 16, 0, 0); } while (0)
; #define PG8_LDA(dst, b, h) do { _Pragma("unroll") for (int m = 0; m < 4; ++m) _Pragma("unroll") for (int k = 0; k < 2; ++k) dst[m][k] = *(const PG8_LAS bf16x8*)(lds + PG8_SA(b, h) + aoff + m * 2048 + k * 1024); } while (0)
; #define PG8_LDB(dst, b, h) do { _Pragma("unroll") for (int n = 0; n < 2; ++n) _Pragma("unroll") for (int k = 0; k < 2; ++k) dst[n][k] = *(const PG8_LAS bf16x8*)(lds + PG8_SB(b, h) + boff + n * 2048 + k * 1024); } while (0)
; #define PG8_MMA(ai, bj, At, Bt) do { __builtin_amdgcn_s_setprio(1); _Pragma("unroll") for (int m = 0; m < 4; ++m) _Pragma("unroll") for (int n = 0; n < 2; ++n) _Pragma("unroll") for (int k = 0; k < 2; ++k) \
;         acc[ai][bj][m][n] = mma16<F16>(Bt[n][k], At[m][k], acc[ai][bj][m][n]); __builtin_amdgcn_s_setprio(0); } while (0)
; #define PG8_BAR __builtin_amdgcn_s_barrier()
; template <class Epi, class Sched, bool ALIGN_EPI = false, bool SP2 = false, bool F16 = false, bool TOKPERM = false>
; __device__ __forceinline__ void gemm_phase(PG8_LAS unsigned char* lds, const Gemm g, const Sched& S, const Epi& E, int wv) {
;     ...
;             PG8_LDB(B0, 0, 0); PG8_LDB(B1, 0, 1); PG8_SCHED; PG8_LDA(At, 0, 0); PG8_STAGE(PG8_SA(1, 1), a1 + hstep, voffA);
;             PG8_WAIT_V(8); PG8_WAIT_L(0); PG8_BAR; PG8_MMA(0, 0, At, B0); PG8_MMA(0, 1, At, B1); PG8_BAR; PG8_SCHED;
;             PG8_LDA(At, 0, 1); PG8_STAGE(PG8_SB(0, 0), b2, voffB); PG8_STAGE(PG8_SB(0, 1), b2 + hstep, voffB); PG8_STAGE(PG8_SA(0, 0), a2, voffA);
;             PG8_WAIT_V(8); PG8_WAIT_L(0); PG8_BAR; PG8_MMA(1, 0, At, B0); PG8_MMA(1, 1, At, B1); PG8_BAR; PG8_SCHED;
;             PG8_LDB(B0, 1, 0); PG8_LDB(B1, 1, 1); PG8_SCHED; PG8_LDA(At, 1, 0); PG8_STAGE(PG8_SA(0, 1), a2 + hstep, voffA);
;             PG8_WAIT_V(8); PG8_WAIT_L(0); PG8_BAR; PG8_MMA(0, 0, At, B0); PG8_MMA(0, 1, At, B1); PG8_BAR; PG8_SCHED;
;             PG8_LDA(At, 1, 1); PG8_STAGE(PG8_SB(1, 0), b3, voffB); PG8_STAGE(PG8_SB(1, 1), b3 + hstep, voffB); PG8_STAGE(PG8_SA(1, 0), a3, voffA);
;             PG8_WAIT_V(8); PG8_WAIT_L(0); PG8_BAR; PG8_MMA(1, 0, At, B0); PG8_MMA(1, 1, At, B1); PG8_BAR; PG8_SCHED;
	s_mov_b32 m0, s20
	v_lshl_add_u64 v[224:225], v[224:225], 0, s[60:61]
	s_add_u32 s8, s8, 0x40080
	ds_read_b128 v[208:211], v155 offset:49152
	ds_read_b128 v[212:215], v155 offset:50176
	ds_read_b128 v[216:219], v155 offset:51200
	ds_read_b128 v[220:223], v155 offset:52224
	ds_read_b128 v[228:231], v155 offset:53248
	ds_read_b128 v[232:235], v155 offset:54272
	ds_read_b128 v[236:239], v155 offset:55296
	ds_read_b128 v[240:243], v155 offset:56320
	global_load_lds_dwordx4 v[224:225], off
	v_lshl_add_u64 v[224:225], v[244:245], 0, s[60:61]
	s_mov_b32 m0, s21
	s_addc_u32 s9, s9, 0
	global_load_lds_dwordx4 v[224:225], off
	v_lshl_add_u64 v[224:225], s[8:9], 0, v[130:131]
	s_mov_b32 m0, s44
	s_nop 0
	global_load_lds_dwordx4 v[224:225], off
	v_lshl_add_u64 v[224:225], s[8:9], 0, v[134:135]
	s_mov_b32 m0, s45
	s_nop 0
	global_load_lds_dwordx4 v[224:225], off
	v_lshl_add_u64 v[224:225], v[246:247], 0, s[60:61]
	s_mov_b32 m0, s22
	s_nop 0
	global_load_lds_dwordx4 v[224:225], off
	v_lshl_add_u64 v[224:225], v[248:249], 0, s[60:61]
	s_mov_b32 m0, s23
	s_nop 0
	global_load_lds_dwordx4 v[224:225], off
	s_waitcnt vmcnt(8)
	s_waitcnt lgkmcnt(0)
	s_barrier
	s_setprio 1
	v_mfma_f32_16x16x32_f16 v[60:63], v[156:159], v[208:211], v[60:63]
	v_mfma_f32_16x16x32_f16 v[56:59], v[164:167], v[208:211], v[56:59]
	v_mfma_f32_16x16x32_f16 v[44:47], v[156:159], v[216:219], v[44:47]
	v_mfma_f32_16x16x32_f16 v[40:43], v[164:167], v[216:219], v[40:43]
	v_mfma_f32_16x16x32_f16 v[28:31], v[156:159], v[228:231], v[28:31]
	v_mfma_f32_16x16x32_f16 v[24:27], v[164:167], v[228:231], v[24:27]
	v_mfma_f32_16x16x32_f16 v[12:15], v[156:159], v[236:239], v[12:15]
	v_mfma_f32_16x16x32_f16 v[8:11], v[164:167], v[236:239], v[8:11]
	v_mfma_f32_16x16x32_f16 v[60:63], v[160:163], v[212:215], v[60:63]
	v_mfma_f32_16x16x32_f16 v[56:59], v[168:171], v[212:215], v[56:59]
	v_mfma_f32_16x16x32_f16 v[44:47], v[160:163], v[220:223], v[44:47]
	v_mfma_f32_16x16x32_f16 v[40:43], v[168:171], v[220:223], v[40:43]
	v_mfma_f32_16x16x32_f16 v[28:31], v[160:163], v[232:235], v[28:31]
	v_mfma_f32_16x16x32_f16 v[24:27], v[168:171], v[232:235], v[24:27]
	v_mfma_f32_16x16x32_f16 v[12:15], v[160:163], v[240:243], v[12:15]
	v_mfma_f32_16x16x32_f16 v[8:11], v[168:171], v[240:243], v[8:11]
	s_setprio 0
	s_setprio 1
	v_mfma_f32_16x16x32_f16 v[52:55], v[172:175], v[208:211], v[52:55]
	v_mfma_f32_16x16x32_f16 v[48:51], v[200:203], v[208:211], v[48:51]
	v_mfma_f32_16x16x32_f16 v[36:39], v[172:175], v[216:219], v[36:39]
	v_mfma_f32_16x16x32_f16 v[32:35], v[200:203], v[216:219], v[32:35]
	v_mfma_f32_16x16x32_f16 v[20:23], v[172:175], v[228:231], v[20:23]
	v_mfma_f32_16x16x32_f16 v[16:19], v[200:203], v[228:231], v[16:19]
	v_mfma_f32_16x16x32_f16 v[4:7], v[172:175], v[236:239], v[4:7]
	v_mfma_f32_16x16x32_f16 v[0:3], v[200:203], v[236:239], v[0:3]
	v_mfma_f32_16x16x32_f16 v[52:55], v[176:179], v[212:215], v[52:55]
	v_mfma_f32_16x16x32_f16 v[48:51], v[204:207], v[212:215], v[48:51]
	v_mfma_f32_16x16x32_f16 v[36:39], v[176:179], v[220:223], v[36:39]
	v_mfma_f32_16x16x32_f16 v[32:35], v[204:207], v[220:223], v[32:35]
	v_mfma_f32_16x16x32_f16 v[20:23], v[176:179], v[232:235], v[20:23]
	v_mfma_f32_16x16x32_f16 v[16:19], v[204:207], v[232:235], v[16:19]
	v_mfma_f32_16x16x32_f16 v[4:7], v[176:179], v[240:243], v[4:7]
	v_mfma_f32_16x16x32_f16 v[0:3], v[204:207], v[240:243], v[0:3]
	s_setprio 0
	s_barrier
	s_add_i32 s76, s76, 2
	s_add_u32 s6, s6, 0x100
	s_addc_u32 s7, s7, 0
	s_add_u32 s69, s69, 0x100
	s_addc_u32 s71, s71, 0
	s_cmp_gt_u32 s76, 13
.LBB0_382:
	ds_read_b128 v[156:159], v181
	ds_read_b128 v[160:163], v182
	ds_read_b128 v[164:167], v183
	ds_read_b128 v[168:171], v184
	ds_read_b128 v[172:175], v185
	ds_read_b128 v[176:179], v186
	ds_read_b128 v[200:203], v187
	ds_read_b128 v[204:207], v188
	s_add_u32 s8, s6, 0xfffc0080
	s_addc_u32 s9, s7, -1
	s_cmp_eq_u32 s76, 12
	s_cselect_b32 s11, s12, s9
	s_cselect_b32 s10, s13, s8
	s_cselect_b32 s9, s59, s71
	s_cselect_b32 s8, s64, s69
	s_mov_b32 m0, s36
	v_lshl_add_u64 v[224:225], s[6:7], 0, v[146:147]
	ds_read_b128 v[208:211], v155
	ds_read_b128 v[212:215], v155 offset:1024
	ds_read_b128 v[216:219], v155 offset:2048
	ds_read_b128 v[220:223], v155 offset:3072
	ds_read_b128 v[228:231], v155 offset:4096
	ds_read_b128 v[232:235], v155 offset:5120
	ds_read_b128 v[236:239], v155 offset:6144
	ds_read_b128 v[240:243], v155 offset:7168
	global_load_lds_dwordx4 v[224:225], off
	v_lshl_add_u64 v[224:225], s[6:7], 0, v[148:149]
	s_mov_b32 m0, s2
	s_nop 0
	global_load_lds_dwordx4 v[224:225], off
	s_waitcnt vmcnt(8)
	s_waitcnt lgkmcnt(0)
	s_barrier
; #define PG8_STAGE(bufoff, gbase, voff) do { _Pragma("unroll") for (int _i = 0; _i < 2; ++_i) \
;         __builtin_amdgcn_global_load_lds((const unsigned*)((const char*)(gbase) + (voff)[_i]), (PG8_LAS unsigned*)(lds + (bufoff) + ldsw + _i * 8192), 16, 0, 0); } while (0)
; #define PG8_LDA(dst, b, h) do { _Pragma("unroll") for (int m = 0; m < 4; ++m) _Pragma("unroll") for (int k = 0; k < 2; ++k) dst[m][k] = *(const PG8_LAS bf16x8*)(lds + PG8_SA(b, h) + aoff + m * 2048 + k * 1024); } while (0)
; #define PG8_LDB(dst, b, h) do { _Pragma("unroll") for (int n = 0; n < 2; ++n) _Pragma("unroll") for (int k = 0; k < 2; ++k) dst[n][k] = *(const PG8_LAS bf16x8*)(lds + PG8_SB(b, h) + boff + n * 2048 + k * 1024); } while (0)
; #define PG8_MMA(ai, bj, At, Bt) do { __builtin_amdgcn_s_setprio(1); _Pragma("unroll") for (int m = 0; m < 4; ++m) _Pragma("unroll") for (int n = 0; n < 2; ++n) _Pragma("unroll") for (int k = 0; k < 2; ++k) \
;         acc[ai][bj][m][n] = mma16<F16>(Bt[n][k], At[m][k], acc[ai][bj][m][n]); __builtin_amdgcn_s_setprio(0); } while (0)
; #define PG8_BAR __builtin_amdgcn_s_barrier()
; template <class Epi, class Sched, bool ALIGN_EPI = false, bool SP2 = false, bool F16 = false, bool TOKPERM = false>
; __device__ __forceinline__ void gemm_phase(PG8_LAS unsigned char* lds, const Gemm g, const Sched& S, const Epi& E, int wv) {
;     ...
;             PG8_LDB(B0, 0, 0); PG8_LDB(B1, 0, 1); PG8_SCHED; PG8_LDA(At, 0, 0); PG8_STAGE(PG8_SA(1, 1), a1 + hstep, voffA);
;             PG8_WAIT_V(8); PG8_WAIT_L(0); PG8_BAR; PG8_MMA(0, 0, At, B0); PG8_MMA(0, 1, At, B1); PG8_BAR; PG8_SCHED;
;             PG8_LDA(At, 0, 1); PG8_STAGE(PG8_SB(0, 0), b2, voffB); PG8_STAGE(PG8_SB(0, 1), b2 + hstep, voffB); PG8_STAGE(PG8_SA(0, 0), a2, voffA);
;             PG8_WAIT_V(8); PG8_WAIT_L(0); PG8_BAR; PG8_MMA(1, 0, At, B0); PG8_MMA(1, 1, At, B1); PG8_BAR; PG8_SCHED;
;             PG8_LDB(B0, 1, 0); PG8_LDB(B1, 1, 1); PG8_SCHED; PG8_LDA(At, 1, 0); PG8_STAGE(PG8_SA(0, 1), a2 + hstep, voffA);
;             PG8_WAIT_V(8); PG8_WAIT_L(0); PG8_BAR; PG8_MMA(0, 0, At, B0); PG8_MMA(0, 1, At, B1); PG8_BAR; PG8_SCHED;
;             PG8_LDA(At, 1, 1); PG8_STAGE(PG8_SB(1, 0), b3, voffB); PG8_STAGE(PG8_SB(1, 1), b3 + hstep, voffB); PG8_STAGE(PG8_SA(1, 0), a3, voffA);
;             PG8_WAIT_V(8); PG8_WAIT_L(0); PG8_BAR; PG8_MMA(1, 0, At, B0); PG8_MMA(1, 1, At, B1); PG8_BAR; PG8_SCHED;
	s_setprio 1
	v_mfma_f32_16x16x32_f16 v[124:127], v[156:159], v[208:211], v[124:127]
	v_mfma_f32_16x16x32_f16 v[120:123], v[164:167], v[208:211], v[120:123]
	v_mfma_f32_16x16x32_f16 v[108:111], v[156:159], v[216:219], v[108:111]
	v_mfma_f32_16x16x32_f16 v[104:107], v[164:167], v[216:219], v[104:107]
	v_mfma_f32_16x16x32_f16 v[92:95], v[156:159], v[228:231], v[92:95]
	v_mfma_f32_16x16x32_f16 v[88:91], v[164:167], v[228:231], v[88:91]
	v_mfma_f32_16x16x32_f16 v[76:79], v[156:159], v[236:239], v[76:79]
	v_mfma_f32_16x16x32_f16 v[72:75], v[164:167], v[236:239], v[72:75]
	v_mfma_f32_16x16x32_f16 v[124:127], v[160:163], v[212:215], v[124:127]
	v_mfma_f32_16x16x32_f16 v[120:123], v[168:171], v[212:215], v[120:123]
	v_mfma_f32_16x16x32_f16 v[108:111], v[160:163], v[220:223], v[108:111]
	v_mfma_f32_16x16x32_f16 v[104:107], v[168:171], v[220:223], v[104:107]
	v_mfma_f32_16x16x32_f16 v[92:95], v[160:163], v[232:235], v[92:95]
	v_mfma_f32_16x16x32_f16 v[88:91], v[168:171], v[232:235], v[88:91]
	v_mfma_f32_16x16x32_f16 v[76:79], v[160:163], v[240:243], v[76:79]
	v_mfma_f32_16x16x32_f16 v[72:75], v[168:171], v[240:243], v[72:75]
	s_setprio 0
	s_setprio 1
	v_mfma_f32_16x16x32_f16 v[116:119], v[172:175], v[208:211], v[116:119]
	v_mfma_f32_16x16x32_f16 v[112:115], v[200:203], v[208:211], v[112:115]
	v_mfma_f32_16x16x32_f16 v[100:103], v[172:175], v[216:219], v[100:103]
	v_mfma_f32_16x16x32_f16 v[96:99], v[200:203], v[216:219], v[96:99]
	v_mfma_f32_16x16x32_f16 v[84:87], v[172:175], v[228:231], v[84:87]
	v_mfma_f32_16x16x32_f16 v[80:83], v[200:203], v[228:231], v[80:83]
	v_mfma_f32_16x16x32_f16 v[68:71], v[172:175], v[236:239], v[68:71]
	v_mfma_f32_16x16x32_f16 v[64:67], v[200:203], v[236:239], v[64:67]
	v_mfma_f32_16x16x32_f16 v[116:119], v[176:179], v[212:215], v[116:119]
	v_mfma_f32_16x16x32_f16 v[112:115], v[204:207], v[212:215], v[112:115]
	v_mfma_f32_16x16x32_f16 v[100:103], v[176:179], v[220:223], v[100:103]
	v_mfma_f32_16x16x32_f16 v[96:99], v[204:207], v[220:223], v[96:99]
	v_mfma_f32_16x16x32_f16 v[84:87], v[176:179], v[232:235], v[84:87]
	v_mfma_f32_16x16x32_f16 v[80:83], v[204:207], v[232:235], v[80:83]
	v_mfma_f32_16x16x32_f16 v[68:71], v[176:179], v[240:243], v[68:71]
	v_mfma_f32_16x16x32_f16 v[64:67], v[204:207], v[240:243], v[64:67]
	s_setprio 0
	s_barrier
	s_mov_b32 m0, s53
	v_lshl_add_u64 v[224:225], s[8:9], 0, v[130:131]
	s_add_u32 s78, s8, 0x40000
	ds_read_b128 v[208:211], v155 offset:16384
	ds_read_b128 v[212:215], v155 offset:17408
	ds_read_b128 v[216:219], v155 offset:18432
	ds_read_b128 v[220:223], v155 offset:19456
	ds_read_b128 v[228:231], v155 offset:20480
	ds_read_b128 v[232:235], v155 offset:21504
	ds_read_b128 v[236:239], v155 offset:22528
	ds_read_b128 v[240:243], v155 offset:23552
	global_load_lds_dwordx4 v[224:225], off
	v_lshl_add_u64 v[244:245], s[8:9], 0, v[134:135]
	s_mov_b32 m0, s55
	s_addc_u32 s79, s9, 0
	global_load_lds_dwordx4 v[244:245], off
	v_lshl_add_u64 v[246:247], s[78:79], 0, v[130:131]
	s_mov_b32 m0, s91
	v_lshl_add_u64 v[248:249], s[10:11], 0, v[132:133]
	global_load_lds_dwordx4 v[246:247], off
	v_lshl_add_u64 v[246:247], s[78:79], 0, v[134:135]
	s_mov_b32 m0, s92
	s_nop 0
	global_load_lds_dwordx4 v[246:247], off
	v_lshl_add_u64 v[246:247], s[10:11], 0, v[128:129]
	s_mov_b32 m0, s90
	s_nop 0
	global_load_lds_dwordx4 v[246:247], off
	s_mov_b32 m0, s93
	s_nop 0
	global_load_lds_dwordx4 v[248:249], off
	s_waitcnt vmcnt(8)
	s_waitcnt lgkmcnt(0)
	s_barrier
	s_setprio 1
	v_mfma_f32_16x16x32_f16 v[60:63], v[156:159], v[208:211], v[60:63]
	v_mfma_f32_16x16x32_f16 v[56:59], v[164:167], v[208:211], v[56:59]
	v_mfma_f32_16x16x32_f16 v[44:47], v[156:159], v[216:219], v[44:47]
	v_mfma_f32_16x16x32_f16 v[40:43], v[164:167], v[216:219], v[40:43]
	v_mfma_f32_16x16x32_f16 v[28:31], v[156:159], v[228:231], v[28:31]
	v_mfma_f32_16x16x32_f16 v[24:27], v[164:167], v[228:231], v[24:27]
	v_mfma_f32_16x16x32_f16 v[12:15], v[156:159], v[236:239], v[12:15]
	v_mfma_f32_16x16x32_f16 v[8:11], v[164:167], v[236:239], v[8:11]
	v_mfma_f32_16x16x32_f16 v[60:63], v[160:163], v[212:215], v[60:63]
	v_mfma_f32_16x16x32_f16 v[56:59], v[168:171], v[212:215], v[56:59]
	v_mfma_f32_16x16x32_f16 v[44:47], v[160:163], v[220:223], v[44:47]
	v_mfma_f32_16x16x32_f16 v[40:43], v[168:171], v[220:223], v[40:43]
	v_mfma_f32_16x16x32_f16 v[28:31], v[160:163], v[232:235], v[28:31]
	v_mfma_f32_16x16x32_f16 v[24:27], v[168:171], v[232:235], v[24:27]
	v_mfma_f32_16x16x32_f16 v[12:15], v[160:163], v[240:243], v[12:15]
	v_mfma_f32_16x16x32_f16 v[8:11], v[168:171], v[240:243], v[8:11]
	s_setprio 0
	s_setprio 1
	v_mfma_f32_16x16x32_f16 v[52:55], v[172:175], v[208:211], v[52:55]
	v_mfma_f32_16x16x32_f16 v[48:51], v[200:203], v[208:211], v[48:51]
	v_mfma_f32_16x16x32_f16 v[36:39], v[172:175], v[216:219], v[36:39]
	v_mfma_f32_16x16x32_f16 v[32:35], v[200:203], v[216:219], v[32:35]
	v_mfma_f32_16x16x32_f16 v[20:23], v[172:175], v[228:231], v[20:23]
	v_mfma_f32_16x16x32_f16 v[16:19], v[200:203], v[228:231], v[16:19]
	v_mfma_f32_16x16x32_f16 v[4:7], v[172:175], v[236:239], v[4:7]
	v_mfma_f32_16x16x32_f16 v[0:3], v[200:203], v[236:239], v[0:3]
	v_mfma_f32_16x16x32_f16 v[52:55], v[176:179], v[212:215], v[52:55]
	v_mfma_f32_16x16x32_f16 v[48:51], v[204:207], v[212:215], v[48:51]
	v_mfma_f32_16x16x32_f16 v[36:39], v[176:179], v[220:223], v[36:39]
	v_mfma_f32_16x16x32_f16 v[32:35], v[204:207], v[220:223], v[32:35]
	v_mfma_f32_16x16x32_f16 v[20:23], v[176:179], v[232:235], v[20:23]
	v_mfma_f32_16x16x32_f16 v[16:19], v[204:207], v[232:235], v[16:19]
	v_mfma_f32_16x16x32_f16 v[4:7], v[176:179], v[240:243], v[4:7]
	v_mfma_f32_16x16x32_f16 v[0:3], v[204:207], v[240:243], v[0:3]
	s_setprio 0
	s_barrier
; #define PG8_STAGE(bufoff, gbase, voff) do { _Pragma("unroll") for (int _i = 0; _i < 2; ++_i) \
;         __builtin_amdgcn_global_load_lds((const unsigned*)((const char*)(gbase) + (voff)[_i]), (PG8_LAS unsigned*)(lds + (bufoff) + ldsw + _i * 8192), 16, 0, 0); } while (0)
; #define PG8_LDA(dst, b, h) do { _Pragma("unroll") for (int m = 0; m < 4; ++m) _Pragma("unroll") for (int k = 0; k < 2; ++k) dst[m][k] = *(const PG8_LAS bf16x8*)(lds + PG8_SA(b, h) + aoff + m * 2048 + k * 1024); } while (0)
; #define PG8_LDB(dst, b, h) do { _Pragma("unroll") for (int n = 0; n < 2; ++n) _Pragma("unroll") for (int k = 0; k < 2; ++k) dst[n][k] = *(const PG8_LAS bf16x8*)(lds + PG8_SB(b, h) + boff + n * 2048 + k * 1024); } while (0)
; #define PG8_MMA(ai, bj, At, Bt) do { __builtin_amdgcn_s_setprio(1); _Pragma("unroll") for (int m = 0; m < 4; ++m) _Pragma("unroll") for (int n = 0; n < 2; ++n) _Pragma("unroll") for (int k = 0; k < 2; ++k) \
;         acc[ai][bj][m][n] = mma16<F16>(Bt[n][k], At[m][k], acc[ai][bj][m][n]); __builtin_amdgcn_s_setprio(0); } while (0)
; #define PG8_BAR __builtin_amdgcn_s_barrier()
; template <class Epi, class Sched, bool ALIGN_EPI = false, bool SP2 = false, bool F16 = false, bool TOKPERM = false>
; __device__ __forceinline__ void gemm_phase(PG8_LAS unsigned char* lds, const Gemm g, const Sched& S, const Epi& E, int wv) {
;     ...
;             PG8_LDB(B0, 0, 0); PG8_LDB(B1, 0, 1); PG8_SCHED; PG8_LDA(At, 0, 0); PG8_STAGE(PG8_SA(1, 1), a1 + hstep, voffA);
;             PG8_WAIT_V(8); PG8_WAIT_L(0); PG8_BAR; PG8_MMA(0, 0, At, B0); PG8_MMA(0, 1, At, B1); PG8_BAR; PG8_SCHED;
;             PG8_LDA(At, 0, 1); PG8_STAGE(PG8_SB(0, 0), b2, voffB); PG8_STAGE(PG8_SB(0, 1), b2 + hstep, voffB); PG8_STAGE(PG8_SA(0, 0), a2, voffA);
;             PG8_WAIT_V(8); PG8_WAIT_L(0); PG8_BAR; PG8_MMA(1, 0, At, B0); PG8_MMA(1, 1, At, B1); PG8_BAR; PG8_SCHED;
;             PG8_LDB(B0, 1, 0); PG8_LDB(B1, 1, 1); PG8_SCHED; PG8_LDA(At, 1, 0); PG8_STAGE(PG8_SA(0, 1), a2 + hstep, voffA);
;             PG8_WAIT_V(8); PG8_WAIT_L(0); PG8_BAR; PG8_MMA(0, 0, At, B0); PG8_MMA(0, 1, At, B1); PG8_BAR; PG8_SCHED;
;             PG8_LDA(At, 1, 1); PG8_STAGE(PG8_SB(1, 0), b3, voffB); PG8_STAGE(PG8_SB(1, 1), b3 + hstep, voffB); PG8_STAGE(PG8_SA(1, 0), a3, voffA);
;             PG8_WAIT_V(8); PG8_WAIT_L(0); PG8_BAR; PG8_MMA(1, 0, At, B0); PG8_MMA(1, 1, At, B1); PG8_BAR; PG8_SCHED;
	ds_read_b128 v[156:159], v189
	ds_read_b128 v[160:163], v190
	ds_read_b128 v[164:167], v191
	ds_read_b128 v[168:171], v192
	ds_read_b128 v[172:175], v193
	ds_read_b128 v[176:179], v194
	ds_read_b128 v[200:203], v195
	ds_read_b128 v[204:207], v196
	s_add_u32 s10, s10, 0x40000
	s_addc_u32 s11, s11, 0
	s_mov_b32 m0, s95
	v_lshl_add_u64 v[250:251], s[10:11], 0, v[128:129]
	ds_read_b128 v[208:211], v155 offset:32768
	ds_read_b128 v[212:215], v155 offset:33792
	ds_read_b128 v[216:219], v155 offset:34816
	ds_read_b128 v[220:223], v155 offset:35840
	ds_read_b128 v[228:231], v155 offset:36864
	ds_read_b128 v[232:235], v155 offset:37888
	ds_read_b128 v[236:239], v155 offset:38912
	ds_read_b128 v[240:243], v155 offset:39936
	global_load_lds_dwordx4 v[250:251], off
	v_lshl_add_u64 v[250:251], s[10:11], 0, v[132:133]
	s_mov_b32 m0, s96
	s_nop 0
	global_load_lds_dwordx4 v[250:251], off
	s_waitcnt vmcnt(8)
	s_waitcnt lgkmcnt(0)
	s_barrier
	s_setprio 1
	v_mfma_f32_16x16x32_f16 v[124:127], v[156:159], v[208:211], v[124:127]
	v_mfma_f32_16x16x32_f16 v[120:123], v[164:167], v[208:211], v[120:123]
	v_mfma_f32_16x16x32_f16 v[108:111], v[156:159], v[216:219], v[108:111]
	v_mfma_f32_16x16x32_f16 v[104:107], v[164:167], v[216:219], v[104:107]
	v_mfma_f32_16x16x32_f16 v[92:95], v[156:159], v[228:231], v[92:95]
	v_mfma_f32_16x16x32_f16 v[88:91], v[164:167], v[228:231], v[88:91]
	v_mfma_f32_16x16x32_f16 v[76:79], v[156:159], v[236:239], v[76:79]
	v_mfma_f32_16x16x32_f16 v[72:75], v[164:167], v[236:239], v[72:75]
	v_mfma_f32_16x16x32_f16 v[124:127], v[160:163], v[212:215], v[124:127]
	v_mfma_f32_16x16x32_f16 v[120:123], v[168:171], v[212:215], v[120:123]
	v_mfma_f32_16x16x32_f16 v[108:111], v[160:163], v[220:223], v[108:111]
	v_mfma_f32_16x16x32_f16 v[104:107], v[168:171], v[220:223], v[104:107]
	v_mfma_f32_16x16x32_f16 v[92:95], v[160:163], v[232:235], v[92:95]
	v_mfma_f32_16x16x32_f16 v[88:91], v[168:171], v[232:235], v[88:91]
	v_mfma_f32_16x16x32_f16 v[76:79], v[160:163], v[240:243], v[76:79]
	v_mfma_f32_16x16x32_f16 v[72:75], v[168:171], v[240:243], v[72:75]
	s_setprio 0
	s_setprio 1
	v_mfma_f32_16x16x32_f16 v[116:119], v[172:175], v[208:211], v[116:119]
	v_mfma_f32_16x16x32_f16 v[112:115], v[200:203], v[208:211], v[112:115]
	v_mfma_f32_16x16x32_f16 v[100:103], v[172:175], v[216:219], v[100:103]
	v_mfma_f32_16x16x32_f16 v[96:99], v[200:203], v[216:219], v[96:99]
	v_mfma_f32_16x16x32_f16 v[84:87], v[172:175], v[228:231], v[84:87]
	v_mfma_f32_16x16x32_f16 v[80:83], v[200:203], v[228:231], v[80:83]
	v_mfma_f32_16x16x32_f16 v[68:71], v[172:175], v[236:239], v[68:71]
	v_mfma_f32_16x16x32_f16 v[64:67], v[200:203], v[236:239], v[64:67]
	v_mfma_f32_16x16x32_f16 v[116:119], v[176:179], v[212:215], v[116:119]
	v_mfma_f32_16x16x32_f16 v[112:115], v[204:207], v[212:215], v[112:115]
	v_mfma_f32_16x16x32_f16 v[100:103], v[176:179], v[220:223], v[100:103]
	v_mfma_f32_16x16x32_f16 v[96:99], v[204:207], v[220:223], v[96:99]
	v_mfma_f32_16x16x32_f16 v[84:87], v[176:179], v[232:235], v[84:87]
	v_mfma_f32_16x16x32_f16 v[80:83], v[204:207], v[232:235], v[80:83]
	v_mfma_f32_16x16x32_f16 v[68:71], v[176:179], v[240:243], v[68:71]
	v_mfma_f32_16x16x32_f16 v[64:67], v[204:207], v[240:243], v[64:67]
	s_setprio 0
	s_barrier
	s_mov_b32 m0, s20
	v_lshl_add_u64 v[224:225], v[224:225], 0, s[60:61]
	s_add_u32 s8, s8, 0x40080
	ds_read_b128 v[208:211], v155 offset:49152
	ds_read_b128 v[212:215], v155 offset:50176
	ds_read_b128 v[216:219], v155 offset:51200
	ds_read_b128 v[220:223], v155 offset:52224
	ds_read_b128 v[228:231], v155 offset:53248
	ds_read_b128 v[232:235], v155 offset:54272
	ds_read_b128 v[236:239], v155 offset:55296
	ds_read_b128 v[240:243], v155 offset:56320
	global_load_lds_dwordx4 v[224:225], off
	v_lshl_add_u64 v[224:225], v[244:245], 0, s[60:61]
	s_mov_b32 m0, s21
	s_addc_u32 s9, s9, 0
	global_load_lds_dwordx4 v[224:225], off
	v_lshl_add_u64 v[224:225], s[8:9], 0, v[130:131]
	s_mov_b32 m0, s44
	s_nop 0
	global_load_lds_dwordx4 v[224:225], off
	v_lshl_add_u64 v[224:225], s[8:9], 0, v[134:135]
	s_mov_b32 m0, s45
	s_nop 0
	global_load_lds_dwordx4 v[224:225], off
	v_lshl_add_u64 v[224:225], v[246:247], 0, s[60:61]
	s_mov_b32 m0, s22
	s_nop 0
	global_load_lds_dwordx4 v[224:225], off
	v_lshl_add_u64 v[224:225], v[248:249], 0, s[60:61]
	s_mov_b32 m0, s23
	s_nop 0
	global_load_lds_dwordx4 v[224:225], off
	s_waitcnt vmcnt(8)
	s_waitcnt lgkmcnt(0)
	s_barrier
	s_setprio 1
	v_mfma_f32_16x16x32_f16 v[60:63], v[156:159], v[208:211], v[60:63]
	v_mfma_f32_16x16x32_f16 v[56:59], v[164:167], v[208:211], v[56:59]
	v_mfma_f32_16x16x32_f16 v[44:47], v[156:159], v[216:219], v[44:47]
	v_mfma_f32_16x16x32_f16 v[40:43], v[164:167], v[216:219], v[40:43]
	v_mfma_f32_16x16x32_f16 v[28:31], v[156:159], v[228:231], v[28:31]
	v_mfma_f32_16x16x32_f16 v[24:27], v[164:167], v[228:231], v[24:27]
	v_mfma_f32_16x16x32_f16 v[12:15], v[156:159], v[236:239], v[12:15]
	v_mfma_f32_16x16x32_f16 v[8:11], v[164:167], v[236:239], v[8:11]
	v_mfma_f32_16x16x32_f16 v[60:63], v[160:163], v[212:215], v[60:63]
	v_mfma_f32_16x16x32_f16 v[56:59], v[168:171], v[212:215], v[56:59]
	v_mfma_f32_16x16x32_f16 v[44:47], v[160:163], v[220:223], v[44:47]
	v_mfma_f32_16x16x32_f16 v[40:43], v[168:171], v[220:223], v[40:43]
	v_mfma_f32_16x16x32_f16 v[28:31], v[160:163], v[232:235], v[28:31]
	v_mfma_f32_16x16x32_f16 v[24:27], v[168:171], v[232:235], v[24:27]
	v_mfma_f32_16x16x32_f16 v[12:15], v[160:163], v[240:243], v[12:15]
	v_mfma_f32_16x16x32_f16 v[8:11], v[168:171], v[240:243], v[8:11]
	s_setprio 0
	s_setprio 1
	v_mfma_f32_16x16x32_f16 v[52:55], v[172:175], v[208:211], v[52:55]
	v_mfma_f32_16x16x32_f16 v[48:51], v[200:203], v[208:211], v[48:51]
	v_mfma_f32_16x16x32_f16 v[36:39], v[172:175], v[216:219], v[36:39]
	v_mfma_f32_16x16x32_f16 v[32:35], v[200:203], v[216:219], v[32:35]
	v_mfma_f32_16x16x32_f16 v[20:23], v[172:175], v[228:231], v[20:23]
	v_mfma_f32_16x16x32_f16 v[16:19], v[200:203], v[228:231], v[16:19]
	v_mfma_f32_16x16x32_f16 v[4:7], v[172:175], v[236:239], v[4:7]
	v_mfma_f32_16x16x32_f16 v[0:3], v[200:203], v[236:239], v[0:3]
	v_mfma_f32_16x16x32_f16 v[52:55], v[176:179], v[212:215], v[52:55]
	v_mfma_f32_16x16x32_f16 v[48:51], v[204:207], v[212:215], v[48:51]
	v_mfma_f32_16x16x32_f16 v[36:39], v[176:179], v[220:223], v[36:39]
	v_mfma_f32_16x16x32_f16 v[32:35], v[204:207], v[220:223], v[32:35]
	v_mfma_f32_16x16x32_f16 v[20:23], v[176:179], v[232:235], v[20:23]
	v_mfma_f32_16x16x32_f16 v[16:19], v[204:207], v[232:235], v[16:19]
	v_mfma_f32_16x16x32_f16 v[4:7], v[176:179], v[240:243], v[4:7]
	v_mfma_f32_16x16x32_f16 v[0:3], v[204:207], v[240:243], v[0:3]
	s_setprio 0
	s_barrier
	s_add_i32 s76, s76, 2
	s_add_u32 s6, s6, 0x100
	s_addc_u32 s7, s7, 0
	s_add_u32 s69, s69, 0x100
	s_addc_u32 s71, s71, 0
	s_cmp_gt_u32 s76, 13
	s_cbranch_scc0 .LBB0_382
	s_and_b64 vcc, exec, s[62:63]
	s_cbranch_vccz .LBB0_385
	s_barrier

; #define PG8_STAGE(bufoff, gbase, voff) do { _Pragma("unroll") for (int _i = 0; _i < 2; ++_i) \
;         __builtin_amdgcn_global_load_lds((const unsigned*)((const char*)(gbase) + (voff)[_i]), (PG8_LAS unsigned*)(lds + (bufoff) + ldsw + _i * 8192), 16, 0, 0); } while (0)
; #define PG8_LDA(dst, b, h) do { _Pragma("unroll") for (int m = 0; m < 4; ++m) _Pragma("unroll") for (int k = 0; k < 2; ++k) dst[m][k] = *(const PG8_LAS bf16x8*)(lds + PG8_SA(b, h) + aoff + m * 2048 + k * 1024); } while (0)
; #define PG8_LDB(dst, b, h) do { _Pragma("unroll") for (int n = 0; n < 2; ++n) _Pragma("unroll") for (int k = 0; k < 2; ++k) dst[n][k] = *(const PG8_LAS bf16x8*)(lds + PG8_SB(b, h) + boff + n * 2048 + k * 1024); } while (0)
; #define PG8_MMA(ai, bj, At, Bt) do { __builtin_amdgcn_s_setprio(1); _Pragma("unroll") for (int m = 0; m < 4; ++m) _Pragma("unroll") for (int n = 0; n < 2; ++n) _Pragma("unroll") for (int k = 0; k < 2; ++k) \
;         acc[ai][bj][m][n] = mma16<F16>(Bt[n][k], At[m][k], acc[ai][bj][m][n]); __builtin_amdgcn_s_setprio(0); } while (0)
; #define PG8_BAR __builtin_amdgcn_s_barrier()
; template <class Epi, class Sched, bool ALIGN_EPI = false, bool SP2 = false, bool F16 = false, bool TOKPERM = false>
; __device__ __forceinline__ void gemm_phase(PG8_LAS unsigned char* lds, const Gemm g, const Sched& S, const Epi& E, int wv) {
;     ...
;             PG8_LDB(B0, 0, 0); PG8_LDB(B1, 0, 1); PG8_SCHED; PG8_LDA(At, 0, 0); PG8_STAGE(PG8_SA(1, 1), a1 + hstep, voffA);
;             PG8_WAIT_V(8); PG8_WAIT_L(0); PG8_BAR; PG8_MMA(0, 0, At, B0); PG8_MMA(0, 1, At, B1); PG8_BAR; PG8_SCHED;
;             PG8_LDA(At, 0, 1); PG8_STAGE(PG8_SB(0, 0), b2, voffB); PG8_STAGE(PG8_SB(0, 1), b2 + hstep, voffB); PG8_STAGE(PG8_SA(0, 0), a2, voffA);
;             PG8_WAIT_V(8); PG8_WAIT_L(0); PG8_BAR; PG8_MMA(1, 0, At, B0); PG8_MMA(1, 1, At, B1); PG8_BAR; PG8_SCHED;
;             PG8_LDB(B0, 1, 0); PG8_LDB(B1, 1, 1); PG8_SCHED; PG8_LDA(At, 1, 0); PG8_STAGE(PG8_SA(0, 1), a2 + hstep, voffA);
;             PG8_WAIT_V(8); PG8_WAIT_L(0); PG8_BAR; PG8_MMA(0, 0, At, B0); PG8_MMA(0, 1, At, B1); PG8_BAR; PG8_SCHED;
;             PG8_LDA(At, 1, 1); PG8_STAGE(PG8_SB(1, 0), b3, voffB); PG8_STAGE(PG8_SB(1, 1), b3 + hstep, voffB); PG8_STAGE(PG8_SA(1, 0), a3, voffA);
;             PG8_WAIT_V(8); PG8_WAIT_L(0); PG8_BAR; PG8_MMA(1, 0, At, B0); PG8_MMA(1, 1, At, B1); PG8_BAR; PG8_SCHED;
.LBB0_685:
	ds_read_b128 v[166:169], v149
	ds_read_b128 v[170:173], v150
	ds_read_b128 v[174:177], v151
	ds_read_b128 v[178:181], v152
	ds_read_b128 v[182:185], v153
	ds_read_b128 v[186:189], v154
	ds_read_b128 v[190:193], v155
	ds_read_b128 v[194:197], v156
	s_add_u32 s54, s52, 0xfffc0080
	s_addc_u32 s55, s53, -1
	s_cmp_eq_u32 s69, 12
	s_cselect_b32 s57, s13, s55
	s_cselect_b32 s56, s49, s54
	s_cselect_b32 s55, s11, s68
	s_cselect_b32 s54, s66, s67
	s_mov_b32 m0, s64
	v_lshl_add_u64 v[232:233], s[52:53], 0, v[138:139]
	ds_read_b128 v[198:201], v147
	ds_read_b128 v[202:205], v147 offset:1024
	ds_read_b128 v[206:209], v147 offset:2048
	ds_read_b128 v[210:213], v147 offset:3072
	ds_read_b128 v[214:217], v147 offset:4096
	ds_read_b128 v[218:221], v147 offset:5120
	ds_read_b128 v[222:225], v147 offset:6144
	ds_read_b128 v[228:231], v147 offset:7168
	global_load_lds_dwordx4 v[232:233], off
	v_lshl_add_u64 v[232:233], s[52:53], 0, v[140:141]
	s_mov_b32 m0, s65
	s_nop 0
	global_load_lds_dwordx4 v[232:233], off
	s_waitcnt vmcnt(8)
	s_waitcnt lgkmcnt(0)
	s_barrier
	s_setprio 1
	v_mfma_f32_16x16x32_bf16 v[124:127], v[166:169], v[198:201], v[124:127]
	v_mfma_f32_16x16x32_bf16 v[120:123], v[174:177], v[198:201], v[120:123]
	v_mfma_f32_16x16x32_bf16 v[108:111], v[166:169], v[206:209], v[108:111]
	v_mfma_f32_16x16x32_bf16 v[104:107], v[174:177], v[206:209], v[104:107]
	v_mfma_f32_16x16x32_bf16 v[92:95], v[166:169], v[214:217], v[92:95]
	v_mfma_f32_16x16x32_bf16 v[88:91], v[174:177], v[214:217], v[88:91]
	v_mfma_f32_16x16x32_bf16 v[76:79], v[166:169], v[222:225], v[76:79]
	v_mfma_f32_16x16x32_bf16 v[72:75], v[174:177], v[222:225], v[72:75]
	v_mfma_f32_16x16x32_bf16 v[124:127], v[170:173], v[202:205], v[124:127]
	v_mfma_f32_16x16x32_bf16 v[120:123], v[178:181], v[202:205], v[120:123]
	v_mfma_f32_16x16x32_bf16 v[108:111], v[170:173], v[210:213], v[108:111]
	v_mfma_f32_16x16x32_bf16 v[104:107], v[178:181], v[210:213], v[104:107]
	v_mfma_f32_16x16x32_bf16 v[92:95], v[170:173], v[218:221], v[92:95]
	v_mfma_f32_16x16x32_bf16 v[88:91], v[178:181], v[218:221], v[88:91]
	v_mfma_f32_16x16x32_bf16 v[76:79], v[170:173], v[228:231], v[76:79]
	v_mfma_f32_16x16x32_bf16 v[72:75], v[178:181], v[228:231], v[72:75]
	s_setprio 0
	s_setprio 1
	v_mfma_f32_16x16x32_bf16 v[116:119], v[182:185], v[198:201], v[116:119]
	v_mfma_f32_16x16x32_bf16 v[112:115], v[190:193], v[198:201], v[112:115]
	v_mfma_f32_16x16x32_bf16 v[100:103], v[182:185], v[206:209], v[100:103]
	v_mfma_f32_16x16x32_bf16 v[96:99], v[190:193], v[206:209], v[96:99]
	v_mfma_f32_16x16x32_bf16 v[84:87], v[182:185], v[214:217], v[84:87]
	v_mfma_f32_16x16x32_bf16 v[80:83], v[190:193], v[214:217], v[80:83]
	v_mfma_f32_16x16x32_bf16 v[68:71], v[182:185], v[222:225], v[68:71]
	v_mfma_f32_16x16x32_bf16 v[64:67], v[190:193], v[222:225], v[64:67]
	v_mfma_f32_16x16x32_bf16 v[116:119], v[186:189], v[202:205], v[116:119]
	v_mfma_f32_16x16x32_bf16 v[112:115], v[194:197], v[202:205], v[112:115]
	v_mfma_f32_16x16x32_bf16 v[100:103], v[186:189], v[210:213], v[100:103]
	v_mfma_f32_16x16x32_bf16 v[96:99], v[194:197], v[210:213], v[96:99]
	v_mfma_f32_16x16x32_bf16 v[84:87], v[186:189], v[218:221], v[84:87]
	v_mfma_f32_16x16x32_bf16 v[80:83], v[194:197], v[218:221], v[80:83]
	v_mfma_f32_16x16x32_bf16 v[68:71], v[186:189], v[228:231], v[68:71]
	v_mfma_f32_16x16x32_bf16 v[64:67], v[194:197], v[228:231], v[64:67]
	s_setprio 0
	s_barrier
	s_mov_b32 m0, s2
	v_lshl_add_u64 v[232:233], s[54:55], 0, v[130:131]
	s_add_u32 s70, s54, 0x40000
	ds_read_b128 v[198:201], v147 offset:16384
	ds_read_b128 v[202:205], v147 offset:17408
	ds_read_b128 v[206:209], v147 offset:18432
	ds_read_b128 v[210:213], v147 offset:19456
	ds_read_b128 v[214:217], v147 offset:20480
	ds_read_b128 v[218:221], v147 offset:21504
	ds_read_b128 v[222:225], v147 offset:22528
	ds_read_b128 v[228:231], v147 offset:23552
	global_load_lds_dwordx4 v[232:233], off
	v_lshl_add_u64 v[234:235], s[54:55], 0, v[134:135]
	s_mov_b32 m0, s3
	s_addc_u32 s71, s55, 0
	global_load_lds_dwordx4 v[234:235], off
	v_lshl_add_u64 v[236:237], s[70:71], 0, v[130:131]
	s_mov_b32 m0, s20
	v_lshl_add_u64 v[238:239], s[56:57], 0, v[132:133]
	global_load_lds_dwordx4 v[236:237], off
	v_lshl_add_u64 v[236:237], s[70:71], 0, v[134:135]
	s_mov_b32 m0, s21
	s_nop 0
	global_load_lds_dwordx4 v[236:237], off
	v_lshl_add_u64 v[236:237], s[56:57], 0, v[128:129]
	s_mov_b32 m0, s1
	s_nop 0
	global_load_lds_dwordx4 v[236:237], off
	s_mov_b32 m0, s22
	s_nop 0
	global_load_lds_dwordx4 v[238:239], off
	s_waitcnt vmcnt(8)
	s_waitcnt lgkmcnt(0)
	s_barrier
; #define PG8_STAGE(bufoff, gbase, voff) do { _Pragma("unroll") for (int _i = 0; _i < 2; ++_i) \
;         __builtin_amdgcn_global_load_lds((const unsigned*)((const char*)(gbase) + (voff)[_i]), (PG8_LAS unsigned*)(lds + (bufoff) + ldsw + _i * 8192), 16, 0, 0); } while (0)
; #define PG8_LDA(dst, b, h) do { _Pragma("unroll") for (int m = 0; m < 4; ++m) _Pragma("unroll") for (int k = 0; k < 2; ++k) dst[m][k] = *(const PG8_LAS bf16x8*)(lds + PG8_SA(b, h) + aoff + m * 2048 + k * 1024); } while (0)
; #define PG8_LDB(dst, b, h) do { _Pragma("unroll") for (int n = 0; n < 2; ++n) _Pragma("unroll") for (int k = 0; k < 2; ++k) dst[n][k] = *(const PG8_LAS bf16x8*)(lds + PG8_SB(b, h) + boff + n * 2048 + k * 1024); } while (0)
; #define PG8_MMA(ai, bj, At, Bt) do { __builtin_amdgcn_s_setprio(1); _Pragma("unroll") for (int m = 0; m < 4; ++m) _Pragma("unroll") for (int n = 0; n < 2; ++n) _Pragma("unroll") for (int k = 0; k < 2; ++k) \
;         acc[ai][bj][m][n] = mma16<F16>(Bt[n][k], At[m][k], acc[ai][bj][m][n]); __builtin_amdgcn_s_setprio(0); } while (0)
; #define PG8_BAR __builtin_amdgcn_s_barrier()
; template <class Epi, class Sched, bool ALIGN_EPI = false, bool SP2 = false, bool F16 = false, bool TOKPERM = false>
; __device__ __forceinline__ void gemm_phase(PG8_LAS unsigned char* lds, const Gemm g, const Sched& S, const Epi& E, int wv) {
;     ...
;             PG8_LDB(B0, 0, 0); PG8_LDB(B1, 0, 1); PG8_SCHED; PG8_LDA(At, 0, 0); PG8_STAGE(PG8_SA(1, 1), a1 + hstep, voffA);
;             PG8_WAIT_V(8); PG8_WAIT_L(0); PG8_BAR; PG8_MMA(0, 0, At, B0); PG8_MMA(0, 1, At, B1); PG8_BAR; PG8_SCHED;
;             PG8_LDA(At, 0, 1); PG8_STAGE(PG8_SB(0, 0), b2, voffB); PG8_STAGE(PG8_SB(0, 1), b2 + hstep, voffB); PG8_STAGE(PG8_SA(0, 0), a2, voffA);
;             PG8_WAIT_V(8); PG8_WAIT_L(0); PG8_BAR; PG8_MMA(1, 0, At, B0); PG8_MMA(1, 1, At, B1); PG8_BAR; PG8_SCHED;
;             PG8_LDB(B0, 1, 0); PG8_LDB(B1, 1, 1); PG8_SCHED; PG8_LDA(At, 1, 0); PG8_STAGE(PG8_SA(0, 1), a2 + hstep, voffA);
;             PG8_WAIT_V(8); PG8_WAIT_L(0); PG8_BAR; PG8_MMA(0, 0, At, B0); PG8_MMA(0, 1, At, B1); PG8_BAR; PG8_SCHED;
;             PG8_LDA(At, 1, 1); PG8_STAGE(PG8_SB(1, 0), b3, voffB); PG8_STAGE(PG8_SB(1, 1), b3 + hstep, voffB); PG8_STAGE(PG8_SA(1, 0), a3, voffA);
;             PG8_WAIT_V(8); PG8_WAIT_L(0); PG8_BAR; PG8_MMA(1, 0, At, B0); PG8_MMA(1, 1, At, B1); PG8_BAR; PG8_SCHED;
	s_setprio 1
	v_mfma_f32_16x16x32_bf16 v[60:63], v[166:169], v[198:201], v[60:63]
	v_mfma_f32_16x16x32_bf16 v[56:59], v[174:177], v[198:201], v[56:59]
	v_mfma_f32_16x16x32_bf16 v[44:47], v[166:169], v[206:209], v[44:47]
	v_mfma_f32_16x16x32_bf16 v[40:43], v[174:177], v[206:209], v[40:43]
	v_mfma_f32_16x16x32_bf16 v[28:31], v[166:169], v[214:217], v[28:31]
	v_mfma_f32_16x16x32_bf16 v[24:27], v[174:177], v[214:217], v[24:27]
	v_mfma_f32_16x16x32_bf16 v[12:15], v[166:169], v[222:225], v[12:15]
	v_mfma_f32_16x16x32_bf16 v[8:11], v[174:177], v[222:225], v[8:11]
	v_mfma_f32_16x16x32_bf16 v[60:63], v[170:173], v[202:205], v[60:63]
	v_mfma_f32_16x16x32_bf16 v[56:59], v[178:181], v[202:205], v[56:59]
	v_mfma_f32_16x16x32_bf16 v[44:47], v[170:173], v[210:213], v[44:47]
	v_mfma_f32_16x16x32_bf16 v[40:43], v[178:181], v[210:213], v[40:43]
	v_mfma_f32_16x16x32_bf16 v[28:31], v[170:173], v[218:221], v[28:31]
	v_mfma_f32_16x16x32_bf16 v[24:27], v[178:181], v[218:221], v[24:27]
	v_mfma_f32_16x16x32_bf16 v[12:15], v[170:173], v[228:231], v[12:15]
	v_mfma_f32_16x16x32_bf16 v[8:11], v[178:181], v[228:231], v[8:11]
	s_setprio 0
	s_setprio 1
	v_mfma_f32_16x16x32_bf16 v[52:55], v[182:185], v[198:201], v[52:55]
	v_mfma_f32_16x16x32_bf16 v[48:51], v[190:193], v[198:201], v[48:51]
	v_mfma_f32_16x16x32_bf16 v[36:39], v[182:185], v[206:209], v[36:39]
	v_mfma_f32_16x16x32_bf16 v[32:35], v[190:193], v[206:209], v[32:35]
	v_mfma_f32_16x16x32_bf16 v[20:23], v[182:185], v[214:217], v[20:23]
	v_mfma_f32_16x16x32_bf16 v[16:19], v[190:193], v[214:217], v[16:19]
	v_mfma_f32_16x16x32_bf16 v[4:7], v[182:185], v[222:225], v[4:7]
	v_mfma_f32_16x16x32_bf16 v[0:3], v[190:193], v[222:225], v[0:3]
	v_mfma_f32_16x16x32_bf16 v[52:55], v[186:189], v[202:205], v[52:55]
	v_mfma_f32_16x16x32_bf16 v[48:51], v[194:197], v[202:205], v[48:51]
	v_mfma_f32_16x16x32_bf16 v[36:39], v[186:189], v[210:213], v[36:39]
	v_mfma_f32_16x16x32_bf16 v[32:35], v[194:197], v[210:213], v[32:35]
	v_mfma_f32_16x16x32_bf16 v[20:23], v[186:189], v[218:221], v[20:23]
	v_mfma_f32_16x16x32_bf16 v[16:19], v[194:197], v[218:221], v[16:19]
	v_mfma_f32_16x16x32_bf16 v[4:7], v[186:189], v[228:231], v[4:7]
	v_mfma_f32_16x16x32_bf16 v[0:3], v[194:197], v[228:231], v[0:3]
	s_setprio 0
	s_barrier
	ds_read_b128 v[166:169], v157
	ds_read_b128 v[170:173], v158
	ds_read_b128 v[174:177], v159
	ds_read_b128 v[178:181], v160
	ds_read_b128 v[182:185], v161
	ds_read_b128 v[186:189], v162
	ds_read_b128 v[190:193], v163
	ds_read_b128 v[194:197], v164
	s_add_u32 s56, s56, 0x40000
	s_addc_u32 s57, s57, 0
	s_mov_b32 m0, s23
	v_lshl_add_u64 v[240:241], s[56:57], 0, v[128:129]
	ds_read_b128 v[198:201], v147 offset:32768
	ds_read_b128 v[202:205], v147 offset:33792
	ds_read_b128 v[206:209], v147 offset:34816
	ds_read_b128 v[210:213], v147 offset:35840
	ds_read_b128 v[214:217], v147 offset:36864
	ds_read_b128 v[218:221], v147 offset:37888
	ds_read_b128 v[222:225], v147 offset:38912
	ds_read_b128 v[228:231], v147 offset:39936
	global_load_lds_dwordx4 v[240:241], off
	v_lshl_add_u64 v[240:241], s[56:57], 0, v[132:133]
	s_mov_b32 m0, s33
	s_nop 0
	global_load_lds_dwordx4 v[240:241], off
	s_waitcnt vmcnt(8)
	s_waitcnt lgkmcnt(0)
	s_barrier
	s_setprio 1
	v_mfma_f32_16x16x32_bf16 v[124:127], v[166:169], v[198:201], v[124:127]
	v_mfma_f32_16x16x32_bf16 v[120:123], v[174:177], v[198:201], v[120:123]
	v_mfma_f32_16x16x32_bf16 v[108:111], v[166:169], v[206:209], v[108:111]
	v_mfma_f32_16x16x32_bf16 v[104:107], v[174:177], v[206:209], v[104:107]
	v_mfma_f32_16x16x32_bf16 v[92:95], v[166:169], v[214:217], v[92:95]
	v_mfma_f32_16x16x32_bf16 v[88:91], v[174:177], v[214:217], v[88:91]
	v_mfma_f32_16x16x32_bf16 v[76:79], v[166:169], v[222:225], v[76:79]
	v_mfma_f32_16x16x32_bf16 v[72:75], v[174:177], v[222:225], v[72:75]
	v_mfma_f32_16x16x32_bf16 v[124:127], v[170:173], v[202:205], v[124:127]
	v_mfma_f32_16x16x32_bf16 v[120:123], v[178:181], v[202:205], v[120:123]
	v_mfma_f32_16x16x32_bf16 v[108:111], v[170:173], v[210:213], v[108:111]
	v_mfma_f32_16x16x32_bf16 v[104:107], v[178:181], v[210:213], v[104:107]
	v_mfma_f32_16x16x32_bf16 v[92:95], v[170:173], v[218:221], v[92:95]
	v_mfma_f32_16x16x32_bf16 v[88:91], v[178:181], v[218:221], v[88:91]
	v_mfma_f32_16x16x32_bf16 v[76:79], v[170:173], v[228:231], v[76:79]
	v_mfma_f32_16x16x32_bf16 v[72:75], v[178:181], v[228:231], v[72:75]
	s_setprio 0
	s_setprio 1
	v_mfma_f32_16x16x32_bf16 v[116:119], v[182:185], v[198:201], v[116:119]
	v_mfma_f32_16x16x32_bf16 v[112:115], v[190:193], v[198:201], v[112:115]
	v_mfma_f32_16x16x32_bf16 v[100:103], v[182:185], v[206:209], v[100:103]
	v_mfma_f32_16x16x32_bf16 v[96:99], v[190:193], v[206:209], v[96:99]
	v_mfma_f32_16x16x32_bf16 v[84:87], v[182:185], v[214:217], v[84:87]
	v_mfma_f32_16x16x32_bf16 v[80:83], v[190:193], v[214:217], v[80:83]
	v_mfma_f32_16x16x32_bf16 v[68:71], v[182:185], v[222:225], v[68:71]
	v_mfma_f32_16x16x32_bf16 v[64:67], v[190:193], v[222:225], v[64:67]
	v_mfma_f32_16x16x32_bf16 v[116:119], v[186:189], v[202:205], v[116:119]
	v_mfma_f32_16x16x32_bf16 v[112:115], v[194:197], v[202:205], v[112:115]
	v_mfma_f32_16x16x32_bf16 v[100:103], v[186:189], v[210:213], v[100:103]
	v_mfma_f32_16x16x32_bf16 v[96:99], v[194:197], v[210:213], v[96:99]
	v_mfma_f32_16x16x32_bf16 v[84:87], v[186:189], v[218:221], v[84:87]
	v_mfma_f32_16x16x32_bf16 v[80:83], v[194:197], v[218:221], v[80:83]
	v_mfma_f32_16x16x32_bf16 v[68:71], v[186:189], v[228:231], v[68:71]
	v_mfma_f32_16x16x32_bf16 v[64:67], v[194:197], v[228:231], v[64:67]
	s_setprio 0
	s_barrier
; #define PG8_STAGE(bufoff, gbase, voff) do { _Pragma("unroll") for (int _i = 0; _i < 2; ++_i) \
;         __builtin_amdgcn_global_load_lds((const unsigned*)((const char*)(gbase) + (voff)[_i]), (PG8_LAS unsigned*)(lds + (bufoff) + ldsw + _i * 8192), 16, 0, 0); } while (0)
; #define PG8_LDA(dst, b, h) do { _Pragma("unroll") for (int m = 0; m < 4; ++m) _Pragma("unroll") for (int k = 0; k < 2; ++k) dst[m][k] = *(const PG8_LAS bf16x8*)(lds + PG8_SA(b, h) + aoff + m * 2048 + k * 1024); } while (0)
; #define PG8_LDB(dst, b, h) do { _Pragma("unroll") for (int n = 0; n < 2; ++n) _Pragma("unroll") for (int k = 0; k < 2; ++k) dst[n][k] = *(const PG8_LAS bf16x8*)(lds + PG8_SB(b, h) + boff + n * 2048 + k * 1024); } while (0)
; #define PG8_MMA(ai, bj, At, Bt) do { __builtin_amdgcn_s_setprio(1); _Pragma("unroll") for (int m = 0; m < 4; ++m) _Pragma("unroll") for (int n = 0; n < 2; ++n) _Pragma("unroll") for (int k = 0; k < 2; ++k) \
;         acc[ai][bj][m][n] = mma16<F16>(Bt[n][k], At[m][k], acc[ai][bj][m][n]); __builtin_amdgcn_s_setprio(0); } while (0)
; #define PG8_BAR __builtin_amdgcn_s_barrier()
; template <class Epi, class Sched, bool ALIGN_EPI = false, bool SP2 = false, bool F16 = false, bool TOKPERM = false>
; __device__ __forceinline__ void gemm_phase(PG8_LAS unsigned char* lds, const Gemm g, const Sched& S, const Epi& E, int wv) {
;     ...
;             PG8_LDB(B0, 0, 0); PG8_LDB(B1, 0, 1); PG8_SCHED; PG8_LDA(At, 0, 0); PG8_STAGE(PG8_SA(1, 1), a1 + hstep, voffA);
;             PG8_WAIT_V(8); PG8_WAIT_L(0); PG8_BAR; PG8_MMA(0, 0, At, B0); PG8_MMA(0, 1, At, B1); PG8_BAR; PG8_SCHED;
;             PG8_LDA(At, 0, 1); PG8_STAGE(PG8_SB(0, 0), b2, voffB); PG8_STAGE(PG8_SB(0, 1), b2 + hstep, voffB); PG8_STAGE(PG8_SA(0, 0), a2, voffA);
;             PG8_WAIT_V(8); PG8_WAIT_L(0); PG8_BAR; PG8_MMA(1, 0, At, B0); PG8_MMA(1, 1, At, B1); PG8_BAR; PG8_SCHED;
;             PG8_LDB(B0, 1, 0); PG8_LDB(B1, 1, 1); PG8_SCHED; PG8_LDA(At, 1, 0); PG8_STAGE(PG8_SA(0, 1), a2 + hstep, voffA);
;             PG8_WAIT_V(8); PG8_WAIT_L(0); PG8_BAR; PG8_MMA(0, 0, At, B0); PG8_MMA(0, 1, At, B1); PG8_BAR; PG8_SCHED;
;             PG8_LDA(At, 1, 1); PG8_STAGE(PG8_SB(1, 0), b3, voffB); PG8_STAGE(PG8_SB(1, 1), b3 + hstep, voffB); PG8_STAGE(PG8_SA(1, 0), a3, voffA);
;             PG8_WAIT_V(8); PG8_WAIT_L(0); PG8_BAR; PG8_MMA(1, 0, At, B0); PG8_MMA(1, 1, At, B1); PG8_BAR; PG8_SCHED;
	s_mov_b32 m0, s37
	v_lshl_add_u64 v[232:233], v[232:233], 0, s[8:9]
	s_add_u32 s54, s54, 0x40080
	ds_read_b128 v[198:201], v147 offset:49152
	ds_read_b128 v[202:205], v147 offset:50176
	ds_read_b128 v[206:209], v147 offset:51200
	ds_read_b128 v[210:213], v147 offset:52224
	ds_read_b128 v[214:217], v147 offset:53248
	ds_read_b128 v[218:221], v147 offset:54272
	ds_read_b128 v[222:225], v147 offset:55296
	ds_read_b128 v[228:231], v147 offset:56320
	global_load_lds_dwordx4 v[232:233], off
	v_lshl_add_u64 v[232:233], v[234:235], 0, s[8:9]
	s_mov_b32 m0, s44
	s_addc_u32 s55, s55, 0
	global_load_lds_dwordx4 v[232:233], off
	v_lshl_add_u64 v[232:233], s[54:55], 0, v[130:131]
	s_mov_b32 m0, s58
	s_nop 0
	global_load_lds_dwordx4 v[232:233], off
	v_lshl_add_u64 v[232:233], s[54:55], 0, v[134:135]
	s_mov_b32 m0, s59
	s_nop 0
	global_load_lds_dwordx4 v[232:233], off
	v_lshl_add_u64 v[232:233], v[236:237], 0, s[8:9]
	s_mov_b32 m0, s45
	s_nop 0
	global_load_lds_dwordx4 v[232:233], off
	v_lshl_add_u64 v[232:233], v[238:239], 0, s[8:9]
	s_mov_b32 m0, s51
	s_nop 0
	global_load_lds_dwordx4 v[232:233], off
	s_waitcnt vmcnt(8)
	s_waitcnt lgkmcnt(0)
	s_barrier
	s_setprio 1
	v_mfma_f32_16x16x32_bf16 v[60:63], v[166:169], v[198:201], v[60:63]
	v_mfma_f32_16x16x32_bf16 v[56:59], v[174:177], v[198:201], v[56:59]
	v_mfma_f32_16x16x32_bf16 v[44:47], v[166:169], v[206:209], v[44:47]
	v_mfma_f32_16x16x32_bf16 v[40:43], v[174:177], v[206:209], v[40:43]
	v_mfma_f32_16x16x32_bf16 v[28:31], v[166:169], v[214:217], v[28:31]
	v_mfma_f32_16x16x32_bf16 v[24:27], v[174:177], v[214:217], v[24:27]
	v_mfma_f32_16x16x32_bf16 v[12:15], v[166:169], v[222:225], v[12:15]
	v_mfma_f32_16x16x32_bf16 v[8:11], v[174:177], v[222:225], v[8:11]
	v_mfma_f32_16x16x32_bf16 v[60:63], v[170:173], v[202:205], v[60:63]
	v_mfma_f32_16x16x32_bf16 v[56:59], v[178:181], v[202:205], v[56:59]
	v_mfma_f32_16x16x32_bf16 v[44:47], v[170:173], v[210:213], v[44:47]
	v_mfma_f32_16x16x32_bf16 v[40:43], v[178:181], v[210:213], v[40:43]
	v_mfma_f32_16x16x32_bf16 v[28:31], v[170:173], v[218:221], v[28:31]
	v_mfma_f32_16x16x32_bf16 v[24:27], v[178:181], v[218:221], v[24:27]
	v_mfma_f32_16x16x32_bf16 v[12:15], v[170:173], v[228:231], v[12:15]
	v_mfma_f32_16x16x32_bf16 v[8:11], v[178:181], v[228:231], v[8:11]
	s_setprio 0
	s_setprio 1
	v_mfma_f32_16x16x32_bf16 v[52:55], v[182:185], v[198:201], v[52:55]
	v_mfma_f32_16x16x32_bf16 v[48:51], v[190:193], v[198:201], v[48:51]
	v_mfma_f32_16x16x32_bf16 v[36:39], v[182:185], v[206:209], v[36:39]
	v_mfma_f32_16x16x32_bf16 v[32:35], v[190:193], v[206:209], v[32:35]
	v_mfma_f32_16x16x32_bf16 v[20:23], v[182:185], v[214:217], v[20:23]
	v_mfma_f32_16x16x32_bf16 v[16:19], v[190:193], v[214:217], v[16:19]
	v_mfma_f32_16x16x32_bf16 v[4:7], v[182:185], v[222:225], v[4:7]
	v_mfma_f32_16x16x32_bf16 v[0:3], v[190:193], v[222:225], v[0:3]
	v_mfma_f32_16x16x32_bf16 v[52:55], v[186:189], v[202:205], v[52:55]
	v_mfma_f32_16x16x32_bf16 v[48:51], v[194:197], v[202:205], v[48:51]
	v_mfma_f32_16x16x32_bf16 v[36:39], v[186:189], v[210:213], v[36:39]
	v_mfma_f32_16x16x32_bf16 v[32:35], v[194:197], v[210:213], v[32:35]
	v_mfma_f32_16x16x32_bf16 v[20:23], v[186:189], v[218:221], v[20:23]
	v_mfma_f32_16x16x32_bf16 v[16:19], v[194:197], v[218:221], v[16:19]
	v_mfma_f32_16x16x32_bf16 v[4:7], v[186:189], v[228:231], v[4:7]
	v_mfma_f32_16x16x32_bf16 v[0:3], v[194:197], v[228:231], v[0:3]
	s_setprio 0
	s_barrier
	s_add_i32 s69, s69, 2
	s_add_u32 s52, s52, 0x100
	s_addc_u32 s53, s53, 0
	s_add_u32 s67, s67, 0x100
	s_addc_u32 s68, s68, 0
	s_cmp_gt_u32 s69, 13
	s_cbranch_scc0 .LBB0_685
;   __device__ __forceinline__ void operator()(const pg8::f32x4 (&acc)[2][2][4][2], const pg8::Unit& u, int wr, int wc, int fr, int fq) const {
;     int z; asm volatile("v_mov_b32 %0, 0" : "=v"(z));
;     const int row0 = u.pm * 256 + wr * 64 + fr + z, colb = u.pn * 256 + wc * 32 + 8 * fq + z;
; #pragma unroll
;     for (int ai = 0; ai < 2; ++ai)
; #pragma unroll
;       for (int m = 0; m < 4; ++m) {
;         const int tok = row0 + ai * 128 + m * 16; float ss = 0.f;
; #pragma unroll
;         for (int bj = 0; bj < 2; ++bj) {
;           const unsigned off = (unsigned)tok * DM + colb + 128 * bj;
;           f8_t n = __builtin_convertvector(*(const h8_t*)(x16 + off), f8_t);
; #pragma unroll
;           for (int c = 0; c < 4; ++c) { n[c] += sc * acc[ai][bj][m][0][c]; n[4 + c] += sc * acc[ai][bj][m][1][c]; }
;           if (aux) {
;             *(h8_t*)(x16 + off) = __builtin_convertvector(n, h8_t);
;             ss += ((n[0] * n[0] + n[1] * n[1]) + (n[2] * n[2] + n[3] * n[3])) + ((n[4] * n[4] + n[5] * n[5]) + (n[6] * n[6] + n[7] * n[7]));
;           } else {
;             *(f32x4*)(xout + off) = (f32x4){n[0], n[1], n[2], n[3]}; *(f32x4*)(xout + off + 4) = (f32x4){n[4], n[5], n[6], n[7]};
;           }
;         }
;         if (aux) { ss += __shfl_xor(ss, 16); ss += __shfl_xor(ss, 32); if (fq == 0) ssq[(unsigned)tok * 16 + u.pn * 4 + wc] = ss; }
;         if (m & 1) asm volatile("" ::: "memory");
;       }
;   }
	s_lshl_b32 s11, s50, 8
	v_lshl_or_b32 v166, s48, 8, v148
	v_mov_b32 v136, 0
	v_xor_b32_e32 v169, 32, v165
	v_add3_u32 v167, s11, v146, v136
	v_add_u32_e32 v168, v166, v136
	v_lshl_add_u32 v136, v167, 10, v168
	v_lshl_add_u64 v[178:179], v[136:137], 1, s[40:41]
	v_add_u32_e32 v136, 0x80, v136
	global_load_dwordx4 v[170:173], v[178:179], off
	v_lshl_add_u64 v[180:181], v[136:137], 1, s[40:41]
	global_load_dwordx4 v[174:177], v[180:181], off
	v_add_u32_e32 v136, 16, v167
	v_lshl_add_u32 v136, v136, 10, v168
	v_lshl_add_u64 v[224:225], v[136:137], 1, s[40:41]
	v_add_u32_e32 v136, 0x80, v136
	global_load_dwordx4 v[192:195], v[224:225], off
	v_lshl_add_u64 v[248:249], v[136:137], 1, s[40:41]
	global_load_dwordx4 v[196:199], v[248:249], off
	v_add_u32_e32 v136, 32, v167
	v_lshl_add_u32 v136, v136, 10, v168
	v_lshl_add_u64 v[224:225], v[136:137], 1, s[40:41]
	v_add_u32_e32 v136, 0x80, v136
	global_load_dwordx4 v[200:203], v[224:225], off
	v_lshl_add_u64 v[248:249], v[136:137], 1, s[40:41]
	global_load_dwordx4 v[204:207], v[248:249], off
	v_add_u32_e32 v136, 48, v167
	v_lshl_add_u32 v136, v136, 10, v168
	v_lshl_add_u64 v[224:225], v[136:137], 1, s[40:41]
	v_add_u32_e32 v136, 0x80, v136
	global_load_dwordx4 v[208:211], v[224:225], off
	v_lshl_add_u64 v[248:249], v[136:137], 1, s[40:41]
	global_load_dwordx4 v[212:215], v[248:249], off
	v_add_u32_e32 v136, 0x80, v167
	v_lshl_add_u32 v136, v136, 10, v168
	v_lshl_add_u64 v[224:225], v[136:137], 1, s[40:41]
	v_add_u32_e32 v136, 0x80, v136
	global_load_dwordx4 v[216:219], v[224:225], off
	v_lshl_add_u64 v[248:249], v[136:137], 1, s[40:41]
	global_load_dwordx4 v[220:223], v[248:249], off
	v_add_u32_e32 v136, 0x90, v167
	v_lshl_add_u32 v136, v136, 10, v168
	v_lshl_add_u64 v[224:225], v[136:137], 1, s[40:41]
	v_add_u32_e32 v136, 0x80, v136
	global_load_dwordx4 v[228:231], v[224:225], off
	v_lshl_add_u64 v[248:249], v[136:137], 1, s[40:41]
	global_load_dwordx4 v[244:247], v[248:249], off
	v_and_b32_e32 v166, 64, v165
	v_xor_b32_e32 v136, 16, v165
	v_add_u32_e32 v166, 64, v166
	v_cmp_lt_i32_e32 vcc, v136, v166
	s_lshl_b32 s11, s48, 2
	s_or_b32 s11, s11, s36
	v_cndmask_b32_e32 v136, v165, v136, vcc
	v_cmp_lt_i32_e32 vcc, v169, v166
	v_lshlrev_b32_e32 v166, 2, v136
	s_waitcnt vmcnt(10)
	v_cvt_f32_f16_e32 v182, v173
	v_cvt_f32_f16_sdwa v183, v173 dst_sel:DWORD dst_unused:UNUSED_PAD src0_sel:WORD_1
	v_cvt_f32_f16_e32 v184, v171
	v_cvt_f32_f16_sdwa v185, v171 dst_sel:DWORD dst_unused:UNUSED_PAD src0_sel:WORD_1
	v_cvt_f32_f16_e32 v186, v172
	v_cvt_f32_f16_sdwa v187, v172 dst_sel:DWORD dst_unused:UNUSED_PAD src0_sel:WORD_1
	v_cvt_f32_f16_e32 v172, v170
	v_cvt_f32_f16_sdwa v173, v170 dst_sel:DWORD dst_unused:UNUSED_PAD src0_sel:WORD_1
	v_cvt_f32_f16_e32 v170, v177
	v_cvt_f32_f16_sdwa v171, v177 dst_sel:DWORD dst_unused:UNUSED_PAD src0_sel:WORD_1
	v_cvt_f32_f16_e32 v188, v175
	v_cvt_f32_f16_sdwa v189, v175 dst_sel:DWORD dst_unused:UNUSED_PAD src0_sel:WORD_1
	v_cvt_f32_f16_e32 v190, v176
	v_cvt_f32_f16_sdwa v191, v176 dst_sel:DWORD dst_unused:UNUSED_PAD src0_sel:WORD_1
	v_cvt_f32_f16_e32 v176, v174
	v_cvt_f32_f16_sdwa v177, v174 dst_sel:DWORD dst_unused:UNUSED_PAD src0_sel:WORD_1
	v_pk_add_f32 v[124:125], v[124:125], v[172:173]
	v_pk_add_f32 v[172:173], v[120:121], v[186:187]
	v_pk_add_f32 v[126:127], v[126:127], v[184:185]
	v_pk_add_f32 v[122:123], v[122:123], v[182:183]
	v_cvt_pk_f16_f32 v120, v172, v173
	v_cvt_pk_f16_f32 v121, v122, v123
	v_pk_mul_f32 v[174:175], v[124:125], v[124:125]
	v_pk_mul_f32 v[182:183], v[126:127], v[126:127]
	v_pk_fma_f32 v[174:175], v[172:173], v[172:173], v[174:175]
	v_pk_fma_f32 v[182:183], v[122:123], v[122:123], v[182:183]
	v_pk_add_f32 v[176:177], v[116:117], v[176:177]
	v_pk_add_f32 v[116:117], v[112:113], v[190:191]
	v_pk_add_f32 v[184:185], v[118:119], v[188:189]
	v_pk_add_f32 v[112:113], v[114:115], v[170:171]
	v_pk_fma_f32 v[174:175], v[176:177], v[176:177], v[174:175]
	v_pk_fma_f32 v[182:183], v[184:185], v[184:185], v[182:183]
	v_pk_fma_f32 v[174:175], v[116:117], v[116:117], v[174:175]
	v_pk_fma_f32 v[182:183], v[112:113], v[112:113], v[182:183]
	v_pk_add_f32 v[174:175], v[174:175], v[182:183]
	v_add_f32_e32 v114, v174, v175
	v_mov_b32_e32 v115, v114
	s_nop 1
	v_permlane16_swap_b32_e32 v114, v115
	v_cndmask_b32_e32 v169, v165, v169, vcc
	v_cvt_pk_f16_f32 v119, v126, v127
	v_cvt_pk_f16_f32 v118, v124, v125
	global_store_dwordx4 v[178:179], v[118:121], off
	s_nop 1
	v_cvt_pk_f16_f32 v119, v112, v113
	s_waitcnt lgkmcnt(0)
	v_add_f32_e32 v113, v114, v115
	v_lshlrev_b32_e32 v112, 2, v169
	v_mov_b32_e32 v114, v113
	s_nop 1
	v_permlane32_swap_b32_e32 v113, v114
	v_cvt_pk_f16_f32 v118, v116, v117
	v_cvt_pk_f16_f32 v117, v184, v185
	v_cvt_pk_f16_f32 v116, v176, v177
	global_store_dwordx4 v[180:181], v[116:119], off
	s_and_saveexec_b64 s[48:49], s[4:5]
	s_cbranch_execz .LBB0_688
	v_lshl_add_u32 v136, v167, 4, s11
	s_waitcnt lgkmcnt(0)
	v_add_f32_e32 v113, v113, v114
	v_lshl_add_u64 v[114:115], v[136:137], 2, s[42:43]
	global_store_dword v[114:115], v113, off

; #define PG8_STAGE(bufoff, gbase, voff) do { _Pragma("unroll") for (int _i = 0; _i < 2; ++_i) \
;         __builtin_amdgcn_global_load_lds((const unsigned*)((const char*)(gbase) + (voff)[_i]), (PG8_LAS unsigned*)(lds + (bufoff) + ldsw + _i * 8192), 16, 0, 0); } while (0)
; #define PG8_LDA(dst, b, h) do { _Pragma("unroll") for (int m = 0; m < 4; ++m) _Pragma("unroll") for (int k = 0; k < 2; ++k) dst[m][k] = *(const PG8_LAS bf16x8*)(lds + PG8_SA(b, h) + aoff + m * 2048 + k * 1024); } while (0)
; #define PG8_LDB(dst, b, h) do { _Pragma("unroll") for (int n = 0; n < 2; ++n) _Pragma("unroll") for (int k = 0; k < 2; ++k) dst[n][k] = *(const PG8_LAS bf16x8*)(lds + PG8_SB(b, h) + boff + n * 2048 + k * 1024); } while (0)
; #define PG8_MMA(ai, bj, At, Bt) do { __builtin_amdgcn_s_setprio(1); _Pragma("unroll") for (int m = 0; m < 4; ++m) _Pragma("unroll") for (int n = 0; n < 2; ++n) _Pragma("unroll") for (int k = 0; k < 2; ++k) \
;         acc[ai][bj][m][n] = mma16<F16>(Bt[n][k], At[m][k], acc[ai][bj][m][n]); __builtin_amdgcn_s_setprio(0); } while (0)
; #define PG8_BAR __builtin_amdgcn_s_barrier()
; template <class Epi, class Sched, bool ALIGN_EPI = false, bool SP2 = false, bool F16 = false, bool TOKPERM = false>
; __device__ __forceinline__ void gemm_phase(PG8_LAS unsigned char* lds, const Gemm g, const Sched& S, const Epi& E, int wv) {
;     ...
;             PG8_LDB(B0, 0, 0); PG8_LDB(B1, 0, 1); PG8_SCHED; PG8_LDA(At, 0, 0); PG8_STAGE(PG8_SA(1, 1), a1 + hstep, voffA);
;             PG8_WAIT_V(8); PG8_WAIT_L(0); PG8_BAR; PG8_MMA(0, 0, At, B0); PG8_MMA(0, 1, At, B1); PG8_BAR; PG8_SCHED;
;             PG8_LDA(At, 0, 1); PG8_STAGE(PG8_SB(0, 0), b2, voffB); PG8_STAGE(PG8_SB(0, 1), b2 + hstep, voffB); PG8_STAGE(PG8_SA(0, 0), a2, voffA);
;             PG8_WAIT_V(8); PG8_WAIT_L(0); PG8_BAR; PG8_MMA(1, 0, At, B0); PG8_MMA(1, 1, At, B1); PG8_BAR; PG8_SCHED;
;             PG8_LDB(B0, 1, 0); PG8_LDB(B1, 1, 1); PG8_SCHED; PG8_LDA(At, 1, 0); PG8_STAGE(PG8_SA(0, 1), a2 + hstep, voffA);
;             PG8_WAIT_V(8); PG8_WAIT_L(0); PG8_BAR; PG8_MMA(0, 0, At, B0); PG8_MMA(0, 1, At, B1); PG8_BAR; PG8_SCHED;
;             PG8_LDA(At, 1, 1); PG8_STAGE(PG8_SB(1, 0), b3, voffB); PG8_STAGE(PG8_SB(1, 1), b3 + hstep, voffB); PG8_STAGE(PG8_SA(1, 0), a3, voffA);
;             PG8_WAIT_V(8); PG8_WAIT_L(0); PG8_BAR; PG8_MMA(1, 0, At, B0); PG8_MMA(1, 1, At, B1); PG8_BAR; PG8_SCHED;
.Lvmw_768_0:
	s_waitcnt lgkmcnt(0)
	s_barrier
	s_setprio 1
	v_mfma_f32_16x16x32_f16 v[124:127], v[172:175], v[204:207], 0
	v_mfma_f32_16x16x32_f16 v[116:119], v[180:183], v[204:207], 0
	v_mfma_f32_16x16x32_f16 v[108:111], v[172:175], v[212:215], 0
	v_mfma_f32_16x16x32_f16 v[104:107], v[180:183], v[212:215], 0
	v_mfma_f32_16x16x32_f16 v[92:95], v[172:175], v[220:223], 0
	v_mfma_f32_16x16x32_f16 v[88:91], v[180:183], v[220:223], 0
	v_mfma_f32_16x16x32_f16 v[76:79], v[172:175], v[232:235], 0
	v_mfma_f32_16x16x32_f16 v[72:75], v[180:183], v[232:235], 0
	v_mfma_f32_16x16x32_f16 v[124:127], v[176:179], v[208:211], v[124:127]
	v_mfma_f32_16x16x32_f16 v[116:119], v[184:187], v[208:211], v[116:119]
	v_mfma_f32_16x16x32_f16 v[108:111], v[176:179], v[216:219], v[108:111]
	v_mfma_f32_16x16x32_f16 v[104:107], v[184:187], v[216:219], v[104:107]
	v_mfma_f32_16x16x32_f16 v[92:95], v[176:179], v[228:231], v[92:95]
	v_mfma_f32_16x16x32_f16 v[88:91], v[184:187], v[228:231], v[88:91]
	v_mfma_f32_16x16x32_f16 v[76:79], v[176:179], v[236:239], v[76:79]
	v_mfma_f32_16x16x32_f16 v[72:75], v[184:187], v[236:239], v[72:75]
	s_setprio 0
	s_setprio 1
	v_mfma_f32_16x16x32_f16 v[120:123], v[188:191], v[204:207], 0
	v_mfma_f32_16x16x32_f16 v[112:115], v[196:199], v[204:207], 0
	v_mfma_f32_16x16x32_f16 v[100:103], v[188:191], v[212:215], 0
	v_mfma_f32_16x16x32_f16 v[96:99], v[196:199], v[212:215], 0
	v_mfma_f32_16x16x32_f16 v[84:87], v[188:191], v[220:223], 0
	v_mfma_f32_16x16x32_f16 v[80:83], v[196:199], v[220:223], 0
	v_mfma_f32_16x16x32_f16 v[68:71], v[188:191], v[232:235], 0
	v_mfma_f32_16x16x32_f16 v[64:67], v[196:199], v[232:235], 0
	v_mfma_f32_16x16x32_f16 v[120:123], v[192:195], v[208:211], v[120:123]
	v_mfma_f32_16x16x32_f16 v[112:115], v[200:203], v[208:211], v[112:115]
	v_mfma_f32_16x16x32_f16 v[100:103], v[192:195], v[216:219], v[100:103]
	v_mfma_f32_16x16x32_f16 v[96:99], v[200:203], v[216:219], v[96:99]
	v_mfma_f32_16x16x32_f16 v[84:87], v[192:195], v[228:231], v[84:87]
	v_mfma_f32_16x16x32_f16 v[80:83], v[200:203], v[228:231], v[80:83]
	v_mfma_f32_16x16x32_f16 v[68:71], v[192:195], v[236:239], v[68:71]
	v_mfma_f32_16x16x32_f16 v[64:67], v[200:203], v[236:239], v[64:67]
	s_setprio 0
	s_barrier
	s_mov_b32 m0, s5
	v_lshl_add_u64 v[148:149], s[12:13], 0, v[132:133]
	s_add_u32 s76, s12, 0x40000
	ds_read_b128 v[204:207], v153 offset:16384
	ds_read_b128 v[208:211], v153 offset:17408
	ds_read_b128 v[212:215], v153 offset:18432
	ds_read_b128 v[216:219], v153 offset:19456
	ds_read_b128 v[220:223], v153 offset:20480
	ds_read_b128 v[228:231], v153 offset:21504
	ds_read_b128 v[232:235], v153 offset:22528
	ds_read_b128 v[236:239], v153 offset:23552
	global_load_lds_dwordx4 v[148:149], off
	v_lshl_add_u64 v[224:225], s[12:13], 0, v[128:129]
	s_mov_b32 m0, s21
	s_addc_u32 s77, s13, 0
	global_load_lds_dwordx4 v[224:225], off
	v_lshl_add_u64 v[240:241], s[76:77], 0, v[132:133]
	s_mov_b32 m0, s22
	v_lshl_add_u64 v[242:243], s[58:59], 0, v[130:131]
	global_load_lds_dwordx4 v[240:241], off
	v_lshl_add_u64 v[240:241], s[76:77], 0, v[128:129]
	s_mov_b32 m0, s23
	s_nop 0
	global_load_lds_dwordx4 v[240:241], off
	v_lshl_add_u64 v[240:241], s[58:59], 0, v[134:135]
	s_mov_b32 m0, s2
	s_nop 0
	global_load_lds_dwordx4 v[240:241], off
	s_mov_b32 m0, s33
	s_nop 0
	global_load_lds_dwordx4 v[242:243], off
	s_waitcnt vmcnt(16)
	s_cmp_lg_u32 s99, -1
	s_cbranch_scc1 .Lvmw_768_1
	s_waitcnt vmcnt(8)
.Lvmw_768_1:
	s_waitcnt lgkmcnt(0)
	s_barrier
	s_setprio 1
	v_mfma_f32_16x16x32_f16 v[60:63], v[172:175], v[204:207], 0
	v_mfma_f32_16x16x32_f16 v[56:59], v[180:183], v[204:207], 0
	v_mfma_f32_16x16x32_f16 v[44:47], v[172:175], v[212:215], 0
	v_mfma_f32_16x16x32_f16 v[40:43], v[180:183], v[212:215], 0
	v_mfma_f32_16x16x32_f16 v[28:31], v[172:175], v[220:223], 0
	v_mfma_f32_16x16x32_f16 v[24:27], v[180:183], v[220:223], 0
	v_mfma_f32_16x16x32_f16 v[12:15], v[172:175], v[232:235], 0
	v_mfma_f32_16x16x32_f16 v[8:11], v[180:183], v[232:235], 0
	v_mfma_f32_16x16x32_f16 v[60:63], v[176:179], v[208:211], v[60:63]
	v_mfma_f32_16x16x32_f16 v[56:59], v[184:187], v[208:211], v[56:59]
	v_mfma_f32_16x16x32_f16 v[44:47], v[176:179], v[216:219], v[44:47]
	v_mfma_f32_16x16x32_f16 v[40:43], v[184:187], v[216:219], v[40:43]
	v_mfma_f32_16x16x32_f16 v[28:31], v[176:179], v[228:231], v[28:31]
	v_mfma_f32_16x16x32_f16 v[24:27], v[184:187], v[228:231], v[24:27]
	v_mfma_f32_16x16x32_f16 v[12:15], v[176:179], v[236:239], v[12:15]
	v_mfma_f32_16x16x32_f16 v[8:11], v[184:187], v[236:239], v[8:11]
	s_setprio 0
	s_setprio 1
	v_mfma_f32_16x16x32_f16 v[52:55], v[188:191], v[204:207], 0
	v_mfma_f32_16x16x32_f16 v[48:51], v[196:199], v[204:207], 0
	v_mfma_f32_16x16x32_f16 v[36:39], v[188:191], v[212:215], 0
	v_mfma_f32_16x16x32_f16 v[32:35], v[196:199], v[212:215], 0
	v_mfma_f32_16x16x32_f16 v[20:23], v[188:191], v[220:223], 0
	v_mfma_f32_16x16x32_f16 v[16:19], v[196:199], v[220:223], 0
	v_mfma_f32_16x16x32_f16 v[4:7], v[188:191], v[232:235], 0
	v_mfma_f32_16x16x32_f16 v[0:3], v[196:199], v[232:235], 0
	v_mfma_f32_16x16x32_f16 v[52:55], v[192:195], v[208:211], v[52:55]
	v_mfma_f32_16x16x32_f16 v[48:51], v[200:203], v[208:211], v[48:51]
	v_mfma_f32_16x16x32_f16 v[36:39], v[192:195], v[216:219], v[36:39]
	v_mfma_f32_16x16x32_f16 v[32:35], v[200:203], v[216:219], v[32:35]
	v_mfma_f32_16x16x32_f16 v[20:23], v[192:195], v[228:231], v[20:23]
	v_mfma_f32_16x16x32_f16 v[16:19], v[200:203], v[228:231], v[16:19]
	v_mfma_f32_16x16x32_f16 v[4:7], v[192:195], v[236:239], v[4:7]
	v_mfma_f32_16x16x32_f16 v[0:3], v[200:203], v[236:239], v[0:3]
	s_setprio 0
	s_barrier
; #define PG8_STAGE(bufoff, gbase, voff) do { _Pragma("unroll") for (int _i = 0; _i < 2; ++_i) \
;         __builtin_amdgcn_global_load_lds((const unsigned*)((const char*)(gbase) + (voff)[_i]), (PG8_LAS unsigned*)(lds + (bufoff) + ldsw + _i * 8192), 16, 0, 0); } while (0)
; #define PG8_LDA(dst, b, h) do { _Pragma("unroll") for (int m = 0; m < 4; ++m) _Pragma("unroll") for (int k = 0; k < 2; ++k) dst[m][k] = *(const PG8_LAS bf16x8*)(lds + PG8_SA(b, h) + aoff + m * 2048 + k * 1024); } while (0)
; #define PG8_LDB(dst, b, h) do { _Pragma("unroll") for (int n = 0; n < 2; ++n) _Pragma("unroll") for (int k = 0; k < 2; ++k) dst[n][k] = *(const PG8_LAS bf16x8*)(lds + PG8_SB(b, h) + boff + n * 2048 + k * 1024); } while (0)
; #define PG8_MMA(ai, bj, At, Bt) do { __builtin_amdgcn_s_setprio(1); _Pragma("unroll") for (int m = 0; m < 4; ++m) _Pragma("unroll") for (int n = 0; n < 2; ++n) _Pragma("unroll") for (int k = 0; k < 2; ++k) \
;         acc[ai][bj][m][n] = mma16<F16>(Bt[n][k], At[m][k], acc[ai][bj][m][n]); __builtin_amdgcn_s_setprio(0); } while (0)
; #define PG8_BAR __builtin_amdgcn_s_barrier()
; template <class Epi, class Sched, bool ALIGN_EPI = false, bool SP2 = false, bool F16 = false, bool TOKPERM = false>
; __device__ __forceinline__ void gemm_phase(PG8_LAS unsigned char* lds, const Gemm g, const Sched& S, const Epi& E, int wv) {
;     ...
;             PG8_LDB(B0, 0, 0); PG8_LDB(B1, 0, 1); PG8_SCHED; PG8_LDA(At, 0, 0); PG8_STAGE(PG8_SA(1, 1), a1 + hstep, voffA);
;             PG8_WAIT_V(8); PG8_WAIT_L(0); PG8_BAR; PG8_MMA(0, 0, At, B0); PG8_MMA(0, 1, At, B1); PG8_BAR; PG8_SCHED;
;             PG8_LDA(At, 0, 1); PG8_STAGE(PG8_SB(0, 0), b2, voffB); PG8_STAGE(PG8_SB(0, 1), b2 + hstep, voffB); PG8_STAGE(PG8_SA(0, 0), a2, voffA);
;             PG8_WAIT_V(8); PG8_WAIT_L(0); PG8_BAR; PG8_MMA(1, 0, At, B0); PG8_MMA(1, 1, At, B1); PG8_BAR; PG8_SCHED;
;             PG8_LDB(B0, 1, 0); PG8_LDB(B1, 1, 1); PG8_SCHED; PG8_LDA(At, 1, 0); PG8_STAGE(PG8_SA(0, 1), a2 + hstep, voffA);
;             PG8_WAIT_V(8); PG8_WAIT_L(0); PG8_BAR; PG8_MMA(0, 0, At, B0); PG8_MMA(0, 1, At, B1); PG8_BAR; PG8_SCHED;
;             PG8_LDA(At, 1, 1); PG8_STAGE(PG8_SB(1, 0), b3, voffB); PG8_STAGE(PG8_SB(1, 1), b3 + hstep, voffB); PG8_STAGE(PG8_SA(1, 0), a3, voffA);
;             PG8_WAIT_V(8); PG8_WAIT_L(0); PG8_BAR; PG8_MMA(1, 0, At, B0); PG8_MMA(1, 1, At, B1); PG8_BAR; PG8_SCHED;
	ds_read_b128 v[172:175], v163
	ds_read_b128 v[176:179], v164
	ds_read_b128 v[180:183], v165
	ds_read_b128 v[184:187], v166
	ds_read_b128 v[188:191], v167
	ds_read_b128 v[192:195], v168
	ds_read_b128 v[196:199], v169
	ds_read_b128 v[200:203], v170
	s_add_u32 s58, s58, 0x40000
	s_addc_u32 s59, s59, 0
	s_mov_b32 m0, s36
	v_lshl_add_u64 v[244:245], s[58:59], 0, v[134:135]
	ds_read_b128 v[204:207], v153 offset:32768
	ds_read_b128 v[208:211], v153 offset:33792
	ds_read_b128 v[212:215], v153 offset:34816
	ds_read_b128 v[216:219], v153 offset:35840
	ds_read_b128 v[220:223], v153 offset:36864
	ds_read_b128 v[228:231], v153 offset:37888
	ds_read_b128 v[232:235], v153 offset:38912
	ds_read_b128 v[236:239], v153 offset:39936
	global_load_lds_dwordx4 v[244:245], off
	v_lshl_add_u64 v[244:245], s[58:59], 0, v[130:131]
	s_mov_b32 m0, s37
	s_nop 0
	global_load_lds_dwordx4 v[244:245], off
	s_waitcnt vmcnt(8)
	s_waitcnt lgkmcnt(0)
	s_barrier
	s_setprio 1
	v_mfma_f32_16x16x32_f16 v[124:127], v[172:175], v[204:207], v[124:127]
	v_mfma_f32_16x16x32_f16 v[116:119], v[180:183], v[204:207], v[116:119]
	v_mfma_f32_16x16x32_f16 v[108:111], v[172:175], v[212:215], v[108:111]
	v_mfma_f32_16x16x32_f16 v[104:107], v[180:183], v[212:215], v[104:107]
	v_mfma_f32_16x16x32_f16 v[92:95], v[172:175], v[220:223], v[92:95]
	v_mfma_f32_16x16x32_f16 v[88:91], v[180:183], v[220:223], v[88:91]
	v_mfma_f32_16x16x32_f16 v[76:79], v[172:175], v[232:235], v[76:79]
	v_mfma_f32_16x16x32_f16 v[72:75], v[180:183], v[232:235], v[72:75]
	v_mfma_f32_16x16x32_f16 v[124:127], v[176:179], v[208:211], v[124:127]
	v_mfma_f32_16x16x32_f16 v[116:119], v[184:187], v[208:211], v[116:119]
	v_mfma_f32_16x16x32_f16 v[108:111], v[176:179], v[216:219], v[108:111]
	v_mfma_f32_16x16x32_f16 v[104:107], v[184:187], v[216:219], v[104:107]
	v_mfma_f32_16x16x32_f16 v[92:95], v[176:179], v[228:231], v[92:95]
	v_mfma_f32_16x16x32_f16 v[88:91], v[184:187], v[228:231], v[88:91]
	v_mfma_f32_16x16x32_f16 v[76:79], v[176:179], v[236:239], v[76:79]
	v_mfma_f32_16x16x32_f16 v[72:75], v[184:187], v[236:239], v[72:75]
	s_setprio 0
	s_setprio 1
	v_mfma_f32_16x16x32_f16 v[120:123], v[188:191], v[204:207], v[120:123]
	v_mfma_f32_16x16x32_f16 v[112:115], v[196:199], v[204:207], v[112:115]
	v_mfma_f32_16x16x32_f16 v[100:103], v[188:191], v[212:215], v[100:103]
	v_mfma_f32_16x16x32_f16 v[96:99], v[196:199], v[212:215], v[96:99]
	v_mfma_f32_16x16x32_f16 v[84:87], v[188:191], v[220:223], v[84:87]
	v_mfma_f32_16x16x32_f16 v[80:83], v[196:199], v[220:223], v[80:83]
	v_mfma_f32_16x16x32_f16 v[68:71], v[188:191], v[232:235], v[68:71]
	v_mfma_f32_16x16x32_f16 v[64:67], v[196:199], v[232:235], v[64:67]
	v_mfma_f32_16x16x32_f16 v[120:123], v[192:195], v[208:211], v[120:123]
	v_mfma_f32_16x16x32_f16 v[112:115], v[200:203], v[208:211], v[112:115]
	v_mfma_f32_16x16x32_f16 v[100:103], v[192:195], v[216:219], v[100:103]
	v_mfma_f32_16x16x32_f16 v[96:99], v[200:203], v[216:219], v[96:99]
	v_mfma_f32_16x16x32_f16 v[84:87], v[192:195], v[228:231], v[84:87]
	v_mfma_f32_16x16x32_f16 v[80:83], v[200:203], v[228:231], v[80:83]
	v_mfma_f32_16x16x32_f16 v[68:71], v[192:195], v[236:239], v[68:71]
	v_mfma_f32_16x16x32_f16 v[64:67], v[200:203], v[236:239], v[64:67]
	s_setprio 0
	s_barrier
	s_mov_b32 m0, s45
	v_lshl_add_u64 v[148:149], v[148:149], 0, s[16:17]
	s_add_u32 s12, s12, 0x40080
	ds_read_b128 v[204:207], v153 offset:49152
	ds_read_b128 v[208:211], v153 offset:50176
	ds_read_b128 v[212:215], v153 offset:51200
	ds_read_b128 v[216:219], v153 offset:52224
	ds_read_b128 v[220:223], v153 offset:53248
	ds_read_b128 v[228:231], v153 offset:54272
	ds_read_b128 v[232:235], v153 offset:55296
	ds_read_b128 v[236:239], v153 offset:56320
	global_load_lds_dwordx4 v[148:149], off
	v_lshl_add_u64 v[148:149], v[224:225], 0, s[16:17]
	s_mov_b32 m0, s49
	s_addc_u32 s13, s13, 0
	global_load_lds_dwordx4 v[148:149], off
	v_lshl_add_u64 v[148:149], s[12:13], 0, v[132:133]
	s_mov_b32 m0, s62
	s_nop 0
	global_load_lds_dwordx4 v[148:149], off
	v_lshl_add_u64 v[148:149], s[12:13], 0, v[128:129]
	s_mov_b32 m0, s63
	s_nop 0
	global_load_lds_dwordx4 v[148:149], off
	v_lshl_add_u64 v[148:149], v[240:241], 0, s[16:17]
	s_mov_b32 m0, s60
	s_nop 0
	global_load_lds_dwordx4 v[148:149], off
	v_lshl_add_u64 v[148:149], v[242:243], 0, s[16:17]
	s_mov_b32 m0, s61
	s_nop 0
	global_load_lds_dwordx4 v[148:149], off
	s_waitcnt vmcnt(8)
	s_waitcnt lgkmcnt(0)
	s_barrier
	s_setprio 1
	v_mfma_f32_16x16x32_f16 v[60:63], v[172:175], v[204:207], v[60:63]
	v_mfma_f32_16x16x32_f16 v[56:59], v[180:183], v[204:207], v[56:59]
	v_mfma_f32_16x16x32_f16 v[44:47], v[172:175], v[212:215], v[44:47]
	v_mfma_f32_16x16x32_f16 v[40:43], v[180:183], v[212:215], v[40:43]
	v_mfma_f32_16x16x32_f16 v[28:31], v[172:175], v[220:223], v[28:31]
	v_mfma_f32_16x16x32_f16 v[24:27], v[180:183], v[220:223], v[24:27]
	v_mfma_f32_16x16x32_f16 v[12:15], v[172:175], v[232:235], v[12:15]
	v_mfma_f32_16x16x32_f16 v[8:11], v[180:183], v[232:235], v[8:11]
	v_mfma_f32_16x16x32_f16 v[60:63], v[176:179], v[208:211], v[60:63]
	v_mfma_f32_16x16x32_f16 v[56:59], v[184:187], v[208:211], v[56:59]
	v_mfma_f32_16x16x32_f16 v[44:47], v[176:179], v[216:219], v[44:47]
	v_mfma_f32_16x16x32_f16 v[40:43], v[184:187], v[216:219], v[40:43]
	v_mfma_f32_16x16x32_f16 v[28:31], v[176:179], v[228:231], v[28:31]
	v_mfma_f32_16x16x32_f16 v[24:27], v[184:187], v[228:231], v[24:27]
	v_mfma_f32_16x16x32_f16 v[12:15], v[176:179], v[236:239], v[12:15]
	v_mfma_f32_16x16x32_f16 v[8:11], v[184:187], v[236:239], v[8:11]
	s_setprio 0
	s_setprio 1
	v_mfma_f32_16x16x32_f16 v[52:55], v[188:191], v[204:207], v[52:55]
	v_mfma_f32_16x16x32_f16 v[48:51], v[196:199], v[204:207], v[48:51]
	v_mfma_f32_16x16x32_f16 v[36:39], v[188:191], v[212:215], v[36:39]
	v_mfma_f32_16x16x32_f16 v[32:35], v[196:199], v[212:215], v[32:35]
	v_mfma_f32_16x16x32_f16 v[20:23], v[188:191], v[220:223], v[20:23]
	v_mfma_f32_16x16x32_f16 v[16:19], v[196:199], v[220:223], v[16:19]
	v_mfma_f32_16x16x32_f16 v[4:7], v[188:191], v[232:235], v[4:7]
	v_mfma_f32_16x16x32_f16 v[0:3], v[196:199], v[232:235], v[0:3]
	v_mfma_f32_16x16x32_f16 v[52:55], v[192:195], v[208:211], v[52:55]
	v_mfma_f32_16x16x32_f16 v[48:51], v[200:203], v[208:211], v[48:51]
	v_mfma_f32_16x16x32_f16 v[36:39], v[192:195], v[216:219], v[36:39]
	v_mfma_f32_16x16x32_f16 v[32:35], v[200:203], v[216:219], v[32:35]
	v_mfma_f32_16x16x32_f16 v[20:23], v[192:195], v[228:231], v[20:23]
	v_mfma_f32_16x16x32_f16 v[16:19], v[200:203], v[228:231], v[16:19]
	v_mfma_f32_16x16x32_f16 v[4:7], v[192:195], v[236:239], v[4:7]
	v_mfma_f32_16x16x32_f16 v[0:3], v[200:203], v[236:239], v[0:3]
	s_setprio 0
	s_barrier
	s_add_i32 s74, s74, 2
	s_add_u32 s10, s10, 0x100
	s_addc_u32 s11, s11, 0
	s_add_u32 s72, s72, 0x100
	s_addc_u32 s73, s73, 0
	s_cmp_gt_u32 s74, 13
; #define PG8_STAGE(bufoff, gbase, voff) do { _Pragma("unroll") for (int _i = 0; _i < 2; ++_i) \
;         __builtin_amdgcn_global_load_lds((const unsigned*)((const char*)(gbase) + (voff)[_i]), (PG8_LAS unsigned*)(lds + (bufoff) + ldsw + _i * 8192), 16, 0, 0); } while (0)
; #define PG8_WAIT_V(n) asm volatile("s_waitcnt vmcnt(" #n ")" ::: "memory")
; #define PG8_WAIT_L(n) asm volatile("s_waitcnt lgkmcnt(" #n ")" ::: "memory")
; template <class Epi, class Sched, bool ALIGN_EPI = false, bool SP2 = false, bool F16 = false, bool TOKPERM = false>
; __device__ __forceinline__ void gemm_phase(PG8_LAS unsigned char* lds, const Gemm g, const Sched& S, const Epi& E, int wv) {
;     ...
;         const bool has_next = S.next(ui + 1, nxt);
;         const char* nA = has_next ? (const char*)g.A + (size_t)nxt.pm * tstep : cA; const char* nB = has_next ? (const char*)g.Bt + (size_t)nxt.pn * tstep : cB;
;         for (int t = 0; t < nt; t += 2) {
;             const bool last = (t == nt - 2);
;             const char* a1 = cA + (size_t)(t + 1) * kstep;
;             const char* a2 = last ? nA : cA + (size_t)(t + 2) * kstep; const char* b2 = last ? nB : cB + (size_t)(t + 2) * kstep;
;             const char* a3 = a2 + kstep; const char* b3 = b2 + kstep;
;             if (last && has_next) S.a_ready(nxt);
;             if constexpr (SP2) {
;             PG8_LDB(B0, 0, 0); PG8_LDB(B1, 0, 1); PG8_SCHED; PG8_LDA(At, 0, 0); PG8_STAGE(PG8_SA(1, 1), a1 + hstep, voffA);
;             PG8_WAIT_V(8); PG8_WAIT_L(0); PG8_BAR; PG8_MMA(0, 0, At, B0); PG8_MMA(0, 1, At, B1); PG8_BAR; PG8_SCHED;
;             PG8_LDA(At, 0, 1); PG8_STAGE(PG8_SB(0, 0), b2, voffB); PG8_STAGE(PG8_SB(0, 1), b2 + hstep, voffB); PG8_STAGE(PG8_SA(0, 0), a2, voffA);
;             PG8_WAIT_V(8); PG8_WAIT_L(0); PG8_BAR; PG8_MMA(1, 0, At, B0); PG8_MMA(1, 1, At, B1); PG8_BAR; PG8_SCHED;
;             PG8_LDB(B0, 1, 0); PG8_LDB(B1, 1, 1); PG8_SCHED; PG8_LDA(At, 1, 0); PG8_STAGE(PG8_SA(0, 1), a2 + hstep, voffA);
;             PG8_WAIT_V(8); PG8_WAIT_L(0); PG8_BAR; PG8_MMA(0, 0, At, B0); PG8_MMA(0, 1, At, B1); PG8_BAR; PG8_SCHED;
;             PG8_LDA(At, 1, 1); PG8_STAGE(PG8_SB(1, 0), b3, voffB); PG8_STAGE(PG8_SB(1, 1), b3 + hstep, voffB); PG8_STAGE(PG8_SA(1, 0), a3, voffA);
;             PG8_WAIT_V(8); PG8_WAIT_L(0); PG8_BAR; PG8_MMA(1, 0, At, B0); PG8_MMA(1, 1, At, B1); PG8_BAR; PG8_SCHED;
.LBB0_768:
	ds_read_b128 v[172:175], v155
	ds_read_b128 v[176:179], v156
	ds_read_b128 v[180:183], v157
	ds_read_b128 v[184:187], v158
	ds_read_b128 v[188:191], v159
	ds_read_b128 v[192:195], v160
	ds_read_b128 v[196:199], v161
	ds_read_b128 v[200:203], v162
	s_add_u32 s12, s10, 0xfffc0080
	s_addc_u32 s13, s11, -1
	s_cmp_eq_u32 s74, 12
	s_cselect_b32 s59, s53, s13
	s_cselect_b32 s58, s70, s12
	s_cselect_b32 s13, s51, s73
	s_cselect_b32 s12, s71, s72
	s_mov_b32 m0, s66
	v_lshl_add_u64 v[148:149], s[10:11], 0, v[140:141]
	ds_read_b128 v[204:207], v153
	ds_read_b128 v[208:211], v153 offset:1024
	ds_read_b128 v[212:215], v153 offset:2048
	ds_read_b128 v[216:219], v153 offset:3072
	ds_read_b128 v[220:223], v153 offset:4096
	ds_read_b128 v[228:231], v153 offset:5120
	ds_read_b128 v[232:235], v153 offset:6144
	ds_read_b128 v[236:239], v153 offset:7168
	global_load_lds_dwordx4 v[148:149], off
	v_lshl_add_u64 v[148:149], s[10:11], 0, v[142:143]
	s_mov_b32 m0, s67
	s_nop 0
	global_load_lds_dwordx4 v[148:149], off
	s_waitcnt vmcnt(8)
	s_waitcnt lgkmcnt(0)
	s_barrier
	s_setprio 1
	v_mfma_f32_16x16x32_f16 v[124:127], v[172:175], v[204:207], v[124:127]
	v_mfma_f32_16x16x32_f16 v[116:119], v[180:183], v[204:207], v[116:119]
	v_mfma_f32_16x16x32_f16 v[108:111], v[172:175], v[212:215], v[108:111]
	v_mfma_f32_16x16x32_f16 v[104:107], v[180:183], v[212:215], v[104:107]
	v_mfma_f32_16x16x32_f16 v[92:95], v[172:175], v[220:223], v[92:95]
	v_mfma_f32_16x16x32_f16 v[88:91], v[180:183], v[220:223], v[88:91]
	v_mfma_f32_16x16x32_f16 v[76:79], v[172:175], v[232:235], v[76:79]
	v_mfma_f32_16x16x32_f16 v[72:75], v[180:183], v[232:235], v[72:75]
	v_mfma_f32_16x16x32_f16 v[124:127], v[176:179], v[208:211], v[124:127]
	v_mfma_f32_16x16x32_f16 v[116:119], v[184:187], v[208:211], v[116:119]
	v_mfma_f32_16x16x32_f16 v[108:111], v[176:179], v[216:219], v[108:111]
	v_mfma_f32_16x16x32_f16 v[104:107], v[184:187], v[216:219], v[104:107]
	v_mfma_f32_16x16x32_f16 v[92:95], v[176:179], v[228:231], v[92:95]
	v_mfma_f32_16x16x32_f16 v[88:91], v[184:187], v[228:231], v[88:91]
	v_mfma_f32_16x16x32_f16 v[76:79], v[176:179], v[236:239], v[76:79]
	v_mfma_f32_16x16x32_f16 v[72:75], v[184:187], v[236:239], v[72:75]
	s_setprio 0
	s_setprio 1
	v_mfma_f32_16x16x32_f16 v[120:123], v[188:191], v[204:207], v[120:123]
	v_mfma_f32_16x16x32_f16 v[112:115], v[196:199], v[204:207], v[112:115]
	v_mfma_f32_16x16x32_f16 v[100:103], v[188:191], v[212:215], v[100:103]
	v_mfma_f32_16x16x32_f16 v[96:99], v[196:199], v[212:215], v[96:99]
	v_mfma_f32_16x16x32_f16 v[84:87], v[188:191], v[220:223], v[84:87]
	v_mfma_f32_16x16x32_f16 v[80:83], v[196:199], v[220:223], v[80:83]
	v_mfma_f32_16x16x32_f16 v[68:71], v[188:191], v[232:235], v[68:71]
	v_mfma_f32_16x16x32_f16 v[64:67], v[196:199], v[232:235], v[64:67]
	v_mfma_f32_16x16x32_f16 v[120:123], v[192:195], v[208:211], v[120:123]
	v_mfma_f32_16x16x32_f16 v[112:115], v[200:203], v[208:211], v[112:115]
	v_mfma_f32_16x16x32_f16 v[100:103], v[192:195], v[216:219], v[100:103]
	v_mfma_f32_16x16x32_f16 v[96:99], v[200:203], v[216:219], v[96:99]
	v_mfma_f32_16x16x32_f16 v[84:87], v[192:195], v[228:231], v[84:87]
	v_mfma_f32_16x16x32_f16 v[80:83], v[200:203], v[228:231], v[80:83]
	v_mfma_f32_16x16x32_f16 v[68:71], v[192:195], v[236:239], v[68:71]
	v_mfma_f32_16x16x32_f16 v[64:67], v[200:203], v[236:239], v[64:67]
	s_setprio 0
	s_barrier
	s_mov_b32 m0, s5
	v_lshl_add_u64 v[148:149], s[12:13], 0, v[132:133]
	s_add_u32 s76, s12, 0x40000
	ds_read_b128 v[204:207], v153 offset:16384
	ds_read_b128 v[208:211], v153 offset:17408
	ds_read_b128 v[212:215], v153 offset:18432
	ds_read_b128 v[216:219], v153 offset:19456
	ds_read_b128 v[220:223], v153 offset:20480
	ds_read_b128 v[228:231], v153 offset:21504
	ds_read_b128 v[232:235], v153 offset:22528
	ds_read_b128 v[236:239], v153 offset:23552
	global_load_lds_dwordx4 v[148:149], off
	v_lshl_add_u64 v[224:225], s[12:13], 0, v[128:129]
	s_mov_b32 m0, s21
	s_addc_u32 s77, s13, 0
	global_load_lds_dwordx4 v[224:225], off
	v_lshl_add_u64 v[240:241], s[76:77], 0, v[132:133]
	s_mov_b32 m0, s22
	v_lshl_add_u64 v[242:243], s[58:59], 0, v[130:131]
	global_load_lds_dwordx4 v[240:241], off
	v_lshl_add_u64 v[240:241], s[76:77], 0, v[128:129]
	s_mov_b32 m0, s23
	s_nop 0
	global_load_lds_dwordx4 v[240:241], off
	v_lshl_add_u64 v[240:241], s[58:59], 0, v[134:135]
	s_mov_b32 m0, s2
	s_nop 0
	global_load_lds_dwordx4 v[240:241], off
	s_mov_b32 m0, s33
	s_nop 0
	global_load_lds_dwordx4 v[242:243], off
	s_waitcnt vmcnt(8)
	s_waitcnt lgkmcnt(0)
	s_barrier
	s_setprio 1
	v_mfma_f32_16x16x32_f16 v[60:63], v[172:175], v[204:207], v[60:63]
	v_mfma_f32_16x16x32_f16 v[56:59], v[180:183], v[204:207], v[56:59]
	v_mfma_f32_16x16x32_f16 v[44:47], v[172:175], v[212:215], v[44:47]
	v_mfma_f32_16x16x32_f16 v[40:43], v[180:183], v[212:215], v[40:43]
	v_mfma_f32_16x16x32_f16 v[28:31], v[172:175], v[220:223], v[28:31]
	v_mfma_f32_16x16x32_f16 v[24:27], v[180:183], v[220:223], v[24:27]
	v_mfma_f32_16x16x32_f16 v[12:15], v[172:175], v[232:235], v[12:15]
	v_mfma_f32_16x16x32_f16 v[8:11], v[180:183], v[232:235], v[8:11]
	v_mfma_f32_16x16x32_f16 v[60:63], v[176:179], v[208:211], v[60:63]
	v_mfma_f32_16x16x32_f16 v[56:59], v[184:187], v[208:211], v[56:59]
	v_mfma_f32_16x16x32_f16 v[44:47], v[176:179], v[216:219], v[44:47]
	v_mfma_f32_16x16x32_f16 v[40:43], v[184:187], v[216:219], v[40:43]
	v_mfma_f32_16x16x32_f16 v[28:31], v[176:179], v[228:231], v[28:31]
	v_mfma_f32_16x16x32_f16 v[24:27], v[184:187], v[228:231], v[24:27]
	v_mfma_f32_16x16x32_f16 v[12:15], v[176:179], v[236:239], v[12:15]
	v_mfma_f32_16x16x32_f16 v[8:11], v[184:187], v[236:239], v[8:11]
	s_setprio 0
	s_setprio 1
	v_mfma_f32_16x16x32_f16 v[52:55], v[188:191], v[204:207], v[52:55]
	v_mfma_f32_16x16x32_f16 v[48:51], v[196:199], v[204:207], v[48:51]
	v_mfma_f32_16x16x32_f16 v[36:39], v[188:191], v[212:215], v[36:39]
	v_mfma_f32_16x16x32_f16 v[32:35], v[196:199], v[212:215], v[32:35]
	v_mfma_f32_16x16x32_f16 v[20:23], v[188:191], v[220:223], v[20:23]
	v_mfma_f32_16x16x32_f16 v[16:19], v[196:199], v[220:223], v[16:19]
	v_mfma_f32_16x16x32_f16 v[4:7], v[188:191], v[232:235], v[4:7]
	v_mfma_f32_16x16x32_f16 v[0:3], v[196:199], v[232:235], v[0:3]
	v_mfma_f32_16x16x32_f16 v[52:55], v[192:195], v[208:211], v[52:55]
	v_mfma_f32_16x16x32_f16 v[48:51], v[200:203], v[208:211], v[48:51]
	v_mfma_f32_16x16x32_f16 v[36:39], v[192:195], v[216:219], v[36:39]
	v_mfma_f32_16x16x32_f16 v[32:35], v[200:203], v[216:219], v[32:35]
	v_mfma_f32_16x16x32_f16 v[20:23], v[192:195], v[228:231], v[20:23]
	v_mfma_f32_16x16x32_f16 v[16:19], v[200:203], v[228:231], v[16:19]
	v_mfma_f32_16x16x32_f16 v[4:7], v[192:195], v[236:239], v[4:7]
	v_mfma_f32_16x16x32_f16 v[0:3], v[200:203], v[236:239], v[0:3]
	s_setprio 0
	s_barrier
; #define PG8_STAGE(bufoff, gbase, voff) do { _Pragma("unroll") for (int _i = 0; _i < 2; ++_i) \
;         __builtin_amdgcn_global_load_lds((const unsigned*)((const char*)(gbase) + (voff)[_i]), (PG8_LAS unsigned*)(lds + (bufoff) + ldsw + _i * 8192), 16, 0, 0); } while (0)
; #define PG8_LDA(dst, b, h) do { _Pragma("unroll") for (int m = 0; m < 4; ++m) _Pragma("unroll") for (int k = 0; k < 2; ++k) dst[m][k] = *(const PG8_LAS bf16x8*)(lds + PG8_SA(b, h) + aoff + m * 2048 + k * 1024); } while (0)
; #define PG8_LDB(dst, b, h) do { _Pragma("unroll") for (int n = 0; n < 2; ++n) _Pragma("unroll") for (int k = 0; k < 2; ++k) dst[n][k] = *(const PG8_LAS bf16x8*)(lds + PG8_SB(b, h) + boff + n * 2048 + k * 1024); } while (0)
; #define PG8_MMA(ai, bj, At, Bt) do { __builtin_amdgcn_s_setprio(1); _Pragma("unroll") for (int m = 0; m < 4; ++m) _Pragma("unroll") for (int n = 0; n < 2; ++n) _Pragma("unroll") for (int k = 0; k < 2; ++k) \
;         acc[ai][bj][m][n] = mma16<F16>(Bt[n][k], At[m][k], acc[ai][bj][m][n]); __builtin_amdgcn_s_setprio(0); } while (0)
; #define PG8_BAR __builtin_amdgcn_s_barrier()
; template <class Epi, class Sched, bool ALIGN_EPI = false, bool SP2 = false, bool F16 = false, bool TOKPERM = false>
; __device__ __forceinline__ void gemm_phase(PG8_LAS unsigned char* lds, const Gemm g, const Sched& S, const Epi& E, int wv) {
;     ...
;             PG8_LDB(B0, 0, 0); PG8_LDB(B1, 0, 1); PG8_SCHED; PG8_LDA(At, 0, 0); PG8_STAGE(PG8_SA(1, 1), a1 + hstep, voffA);
;             PG8_WAIT_V(8); PG8_WAIT_L(0); PG8_BAR; PG8_MMA(0, 0, At, B0); PG8_MMA(0, 1, At, B1); PG8_BAR; PG8_SCHED;
;             PG8_LDA(At, 0, 1); PG8_STAGE(PG8_SB(0, 0), b2, voffB); PG8_STAGE(PG8_SB(0, 1), b2 + hstep, voffB); PG8_STAGE(PG8_SA(0, 0), a2, voffA);
;             PG8_WAIT_V(8); PG8_WAIT_L(0); PG8_BAR; PG8_MMA(1, 0, At, B0); PG8_MMA(1, 1, At, B1); PG8_BAR; PG8_SCHED;
;             PG8_LDB(B0, 1, 0); PG8_LDB(B1, 1, 1); PG8_SCHED; PG8_LDA(At, 1, 0); PG8_STAGE(PG8_SA(0, 1), a2 + hstep, voffA);
;             PG8_WAIT_V(8); PG8_WAIT_L(0); PG8_BAR; PG8_MMA(0, 0, At, B0); PG8_MMA(0, 1, At, B1); PG8_BAR; PG8_SCHED;
;             PG8_LDA(At, 1, 1); PG8_STAGE(PG8_SB(1, 0), b3, voffB); PG8_STAGE(PG8_SB(1, 1), b3 + hstep, voffB); PG8_STAGE(PG8_SA(1, 0), a3, voffA);
;             PG8_WAIT_V(8); PG8_WAIT_L(0); PG8_BAR; PG8_MMA(1, 0, At, B0); PG8_MMA(1, 1, At, B1); PG8_BAR; PG8_SCHED;
	ds_read_b128 v[172:175], v163
	ds_read_b128 v[176:179], v164
	ds_read_b128 v[180:183], v165
	ds_read_b128 v[184:187], v166
	ds_read_b128 v[188:191], v167
	ds_read_b128 v[192:195], v168
	ds_read_b128 v[196:199], v169
	ds_read_b128 v[200:203], v170
	s_add_u32 s58, s58, 0x40000
	s_addc_u32 s59, s59, 0
	s_mov_b32 m0, s36
	v_lshl_add_u64 v[244:245], s[58:59], 0, v[134:135]
	ds_read_b128 v[204:207], v153 offset:32768
	ds_read_b128 v[208:211], v153 offset:33792
	ds_read_b128 v[212:215], v153 offset:34816
	ds_read_b128 v[216:219], v153 offset:35840
	ds_read_b128 v[220:223], v153 offset:36864
	ds_read_b128 v[228:231], v153 offset:37888
	ds_read_b128 v[232:235], v153 offset:38912
	ds_read_b128 v[236:239], v153 offset:39936
	global_load_lds_dwordx4 v[244:245], off
	v_lshl_add_u64 v[244:245], s[58:59], 0, v[130:131]
	s_mov_b32 m0, s37
	s_nop 0
	global_load_lds_dwordx4 v[244:245], off
	s_waitcnt vmcnt(8)
	s_waitcnt lgkmcnt(0)
	s_barrier
	s_setprio 1
	v_mfma_f32_16x16x32_f16 v[124:127], v[172:175], v[204:207], v[124:127]
	v_mfma_f32_16x16x32_f16 v[116:119], v[180:183], v[204:207], v[116:119]
	v_mfma_f32_16x16x32_f16 v[108:111], v[172:175], v[212:215], v[108:111]
	v_mfma_f32_16x16x32_f16 v[104:107], v[180:183], v[212:215], v[104:107]
	v_mfma_f32_16x16x32_f16 v[92:95], v[172:175], v[220:223], v[92:95]
	v_mfma_f32_16x16x32_f16 v[88:91], v[180:183], v[220:223], v[88:91]
	v_mfma_f32_16x16x32_f16 v[76:79], v[172:175], v[232:235], v[76:79]
	v_mfma_f32_16x16x32_f16 v[72:75], v[180:183], v[232:235], v[72:75]
	v_mfma_f32_16x16x32_f16 v[124:127], v[176:179], v[208:211], v[124:127]
	v_mfma_f32_16x16x32_f16 v[116:119], v[184:187], v[208:211], v[116:119]
	v_mfma_f32_16x16x32_f16 v[108:111], v[176:179], v[216:219], v[108:111]
	v_mfma_f32_16x16x32_f16 v[104:107], v[184:187], v[216:219], v[104:107]
	v_mfma_f32_16x16x32_f16 v[92:95], v[176:179], v[228:231], v[92:95]
	v_mfma_f32_16x16x32_f16 v[88:91], v[184:187], v[228:231], v[88:91]
	v_mfma_f32_16x16x32_f16 v[76:79], v[176:179], v[236:239], v[76:79]
	v_mfma_f32_16x16x32_f16 v[72:75], v[184:187], v[236:239], v[72:75]
	s_setprio 0
	s_setprio 1
	v_mfma_f32_16x16x32_f16 v[120:123], v[188:191], v[204:207], v[120:123]
	v_mfma_f32_16x16x32_f16 v[112:115], v[196:199], v[204:207], v[112:115]
	v_mfma_f32_16x16x32_f16 v[100:103], v[188:191], v[212:215], v[100:103]
	v_mfma_f32_16x16x32_f16 v[96:99], v[196:199], v[212:215], v[96:99]
	v_mfma_f32_16x16x32_f16 v[84:87], v[188:191], v[220:223], v[84:87]
	v_mfma_f32_16x16x32_f16 v[80:83], v[196:199], v[220:223], v[80:83]
	v_mfma_f32_16x16x32_f16 v[68:71], v[188:191], v[232:235], v[68:71]
	v_mfma_f32_16x16x32_f16 v[64:67], v[196:199], v[232:235], v[64:67]
	v_mfma_f32_16x16x32_f16 v[120:123], v[192:195], v[208:211], v[120:123]
	v_mfma_f32_16x16x32_f16 v[112:115], v[200:203], v[208:211], v[112:115]
	v_mfma_f32_16x16x32_f16 v[100:103], v[192:195], v[216:219], v[100:103]
	v_mfma_f32_16x16x32_f16 v[96:99], v[200:203], v[216:219], v[96:99]
	v_mfma_f32_16x16x32_f16 v[84:87], v[192:195], v[228:231], v[84:87]
	v_mfma_f32_16x16x32_f16 v[80:83], v[200:203], v[228:231], v[80:83]
	v_mfma_f32_16x16x32_f16 v[68:71], v[192:195], v[236:239], v[68:71]
	v_mfma_f32_16x16x32_f16 v[64:67], v[200:203], v[236:239], v[64:67]
	s_setprio 0
	s_barrier
	s_mov_b32 m0, s45
	v_lshl_add_u64 v[148:149], v[148:149], 0, s[16:17]
	s_add_u32 s12, s12, 0x40080
	ds_read_b128 v[204:207], v153 offset:49152
	ds_read_b128 v[208:211], v153 offset:50176
	ds_read_b128 v[212:215], v153 offset:51200
	ds_read_b128 v[216:219], v153 offset:52224
	ds_read_b128 v[220:223], v153 offset:53248
	ds_read_b128 v[228:231], v153 offset:54272
	ds_read_b128 v[232:235], v153 offset:55296
	ds_read_b128 v[236:239], v153 offset:56320
	global_load_lds_dwordx4 v[148:149], off
	v_lshl_add_u64 v[148:149], v[224:225], 0, s[16:17]
	s_mov_b32 m0, s49
	s_addc_u32 s13, s13, 0
	global_load_lds_dwordx4 v[148:149], off
	v_lshl_add_u64 v[148:149], s[12:13], 0, v[132:133]
	s_mov_b32 m0, s62
	s_nop 0
	global_load_lds_dwordx4 v[148:149], off
	v_lshl_add_u64 v[148:149], s[12:13], 0, v[128:129]
	s_mov_b32 m0, s63
	s_nop 0
	global_load_lds_dwordx4 v[148:149], off
	v_lshl_add_u64 v[148:149], v[240:241], 0, s[16:17]
	s_mov_b32 m0, s60
	s_nop 0
	global_load_lds_dwordx4 v[148:149], off
	v_lshl_add_u64 v[148:149], v[242:243], 0, s[16:17]
	s_mov_b32 m0, s61
	s_nop 0
	global_load_lds_dwordx4 v[148:149], off
	s_waitcnt vmcnt(8)
	s_waitcnt lgkmcnt(0)
	s_barrier
	s_setprio 1
	v_mfma_f32_16x16x32_f16 v[60:63], v[172:175], v[204:207], v[60:63]
	v_mfma_f32_16x16x32_f16 v[56:59], v[180:183], v[204:207], v[56:59]
	v_mfma_f32_16x16x32_f16 v[44:47], v[172:175], v[212:215], v[44:47]
	v_mfma_f32_16x16x32_f16 v[40:43], v[180:183], v[212:215], v[40:43]
	v_mfma_f32_16x16x32_f16 v[28:31], v[172:175], v[220:223], v[28:31]
	v_mfma_f32_16x16x32_f16 v[24:27], v[180:183], v[220:223], v[24:27]
	v_mfma_f32_16x16x32_f16 v[12:15], v[172:175], v[232:235], v[12:15]
	v_mfma_f32_16x16x32_f16 v[8:11], v[180:183], v[232:235], v[8:11]
	v_mfma_f32_16x16x32_f16 v[60:63], v[176:179], v[208:211], v[60:63]
	v_mfma_f32_16x16x32_f16 v[56:59], v[184:187], v[208:211], v[56:59]
	v_mfma_f32_16x16x32_f16 v[44:47], v[176:179], v[216:219], v[44:47]
	v_mfma_f32_16x16x32_f16 v[40:43], v[184:187], v[216:219], v[40:43]
	v_mfma_f32_16x16x32_f16 v[28:31], v[176:179], v[228:231], v[28:31]
	v_mfma_f32_16x16x32_f16 v[24:27], v[184:187], v[228:231], v[24:27]
	v_mfma_f32_16x16x32_f16 v[12:15], v[176:179], v[236:239], v[12:15]
	v_mfma_f32_16x16x32_f16 v[8:11], v[184:187], v[236:239], v[8:11]
	s_setprio 0
	s_setprio 1
	v_mfma_f32_16x16x32_f16 v[52:55], v[188:191], v[204:207], v[52:55]
	v_mfma_f32_16x16x32_f16 v[48:51], v[196:199], v[204:207], v[48:51]
	v_mfma_f32_16x16x32_f16 v[36:39], v[188:191], v[212:215], v[36:39]
	v_mfma_f32_16x16x32_f16 v[32:35], v[196:199], v[212:215], v[32:35]
	v_mfma_f32_16x16x32_f16 v[20:23], v[188:191], v[220:223], v[20:23]
	v_mfma_f32_16x16x32_f16 v[16:19], v[196:199], v[220:223], v[16:19]
	v_mfma_f32_16x16x32_f16 v[4:7], v[188:191], v[232:235], v[4:7]
	v_mfma_f32_16x16x32_f16 v[0:3], v[196:199], v[232:235], v[0:3]
	v_mfma_f32_16x16x32_f16 v[52:55], v[192:195], v[208:211], v[52:55]
	v_mfma_f32_16x16x32_f16 v[48:51], v[200:203], v[208:211], v[48:51]
	v_mfma_f32_16x16x32_f16 v[36:39], v[192:195], v[216:219], v[36:39]
	v_mfma_f32_16x16x32_f16 v[32:35], v[200:203], v[216:219], v[32:35]
	v_mfma_f32_16x16x32_f16 v[20:23], v[192:195], v[228:231], v[20:23]
	v_mfma_f32_16x16x32_f16 v[16:19], v[200:203], v[228:231], v[16:19]
	v_mfma_f32_16x16x32_f16 v[4:7], v[192:195], v[236:239], v[4:7]
	v_mfma_f32_16x16x32_f16 v[0:3], v[200:203], v[236:239], v[0:3]
	s_setprio 0
	s_barrier
	s_add_i32 s74, s74, 2
	s_add_u32 s10, s10, 0x100
	s_addc_u32 s11, s11, 0
	s_add_u32 s72, s72, 0x100
	s_addc_u32 s73, s73, 0
	s_cmp_gt_u32 s74, 13
	s_cbranch_scc0 .LBB0_768
	s_and_b64 vcc, exec, s[18:19]
	s_cbranch_vccz .LBB0_771
	s_barrier

; #define PG8_STAGE(bufoff, gbase, voff) do { _Pragma("unroll") for (int _i = 0; _i < 2; ++_i) \
;         __builtin_amdgcn_global_load_lds((const unsigned*)((const char*)(gbase) + (voff)[_i]), (PG8_LAS unsigned*)(lds + (bufoff) + ldsw + _i * 8192), 16, 0, 0); } while (0)
; #define PG8_WAIT_V(n) asm volatile("s_waitcnt vmcnt(" #n ")" ::: "memory")
; #define PG8_WAIT_L(n) asm volatile("s_waitcnt lgkmcnt(" #n ")" ::: "memory")
; template <class Epi, class Sched, bool ALIGN_EPI = false, bool SP2 = false, bool F16 = false, bool TOKPERM = false>
; __device__ __forceinline__ void gemm_phase(PG8_LAS unsigned char* lds, const Gemm g, const Sched& S, const Epi& E, int wv) {
;     ...
;         const bool has_next = S.next(ui + 1, nxt);
;         const char* nA = has_next ? (const char*)g.A + (size_t)nxt.pm * tstep : cA; const char* nB = has_next ? (const char*)g.Bt + (size_t)nxt.pn * tstep : cB;
;         for (int t = 0; t < nt; t += 2) {
;             const bool last = (t == nt - 2);
;             const char* a1 = cA + (size_t)(t + 1) * kstep;
;             const char* a2 = last ? nA : cA + (size_t)(t + 2) * kstep; const char* b2 = last ? nB : cB + (size_t)(t + 2) * kstep;
;             const char* a3 = a2 + kstep; const char* b3 = b2 + kstep;
;             if (last && has_next) S.a_ready(nxt);
;             if constexpr (SP2) {
;             PG8_LDB(B0, 0, 0); PG8_LDB(B1, 0, 1); PG8_SCHED; PG8_LDA(At, 0, 0); PG8_STAGE(PG8_SA(1, 1), a1 + hstep, voffA);
;             PG8_WAIT_V(8); PG8_WAIT_L(0); PG8_BAR; PG8_MMA(0, 0, At, B0); PG8_MMA(0, 1, At, B1); PG8_BAR; PG8_SCHED;
;             PG8_LDA(At, 0, 1); PG8_STAGE(PG8_SB(0, 0), b2, voffB); PG8_STAGE(PG8_SB(0, 1), b2 + hstep, voffB); PG8_STAGE(PG8_SA(0, 0), a2, voffA);
;             PG8_WAIT_V(8); PG8_WAIT_L(0); PG8_BAR; PG8_MMA(1, 0, At, B0); PG8_MMA(1, 1, At, B1); PG8_BAR; PG8_SCHED;
;             PG8_LDB(B0, 1, 0); PG8_LDB(B1, 1, 1); PG8_SCHED; PG8_LDA(At, 1, 0); PG8_STAGE(PG8_SA(0, 1), a2 + hstep, voffA);
;             PG8_WAIT_V(8); PG8_WAIT_L(0); PG8_BAR; PG8_MMA(0, 0, At, B0); PG8_MMA(0, 1, At, B1); PG8_BAR; PG8_SCHED;
;             PG8_LDA(At, 1, 1); PG8_STAGE(PG8_SB(1, 0), b3, voffB); PG8_STAGE(PG8_SB(1, 1), b3 + hstep, voffB); PG8_STAGE(PG8_SA(1, 0), a3, voffA);
;             PG8_WAIT_V(8); PG8_WAIT_L(0); PG8_BAR; PG8_MMA(1, 0, At, B0); PG8_MMA(1, 1, At, B1); PG8_BAR; PG8_SCHED;
.LBB0_867:
	ds_read_b128 v[166:169], v149
	ds_read_b128 v[170:173], v150
	ds_read_b128 v[174:177], v151
	ds_read_b128 v[178:181], v152
	ds_read_b128 v[182:185], v153
	ds_read_b128 v[186:189], v154
	ds_read_b128 v[190:193], v155
	ds_read_b128 v[194:197], v156
	s_add_u32 s18, s16, 0x100
	s_addc_u32 s19, s17, 0
	s_cmp_eq_u32 s67, 40
	s_cselect_b32 s23, s11, s19
	s_cselect_b32 s22, s10, s18
	s_cselect_b32 s21, s13, s66
	s_cselect_b32 s20, s12, s65
	s_mov_b32 m0, s59
	v_lshl_add_u64 v[232:233], s[16:17], 0, v[138:139]
	ds_read_b128 v[198:201], v147
	ds_read_b128 v[202:205], v147 offset:1024
	ds_read_b128 v[206:209], v147 offset:2048
	ds_read_b128 v[210:213], v147 offset:3072
	ds_read_b128 v[214:217], v147 offset:4096
	ds_read_b128 v[218:221], v147 offset:5120
	ds_read_b128 v[222:225], v147 offset:6144
	ds_read_b128 v[228:231], v147 offset:7168
	global_load_lds_dwordx4 v[232:233], off
	v_lshl_add_u64 v[232:233], s[16:17], 0, v[140:141]
	s_mov_b32 m0, s60
	s_nop 0
	global_load_lds_dwordx4 v[232:233], off
	s_waitcnt vmcnt(8)
	s_waitcnt lgkmcnt(0)
	s_barrier
	s_setprio 1
	v_mfma_f32_16x16x32_bf16 v[124:127], v[166:169], v[198:201], v[124:127]
	v_mfma_f32_16x16x32_bf16 v[120:123], v[174:177], v[198:201], v[120:123]
	v_mfma_f32_16x16x32_bf16 v[108:111], v[166:169], v[206:209], v[108:111]
	v_mfma_f32_16x16x32_bf16 v[104:107], v[174:177], v[206:209], v[104:107]
	v_mfma_f32_16x16x32_bf16 v[92:95], v[166:169], v[214:217], v[92:95]
	v_mfma_f32_16x16x32_bf16 v[88:91], v[174:177], v[214:217], v[88:91]
	v_mfma_f32_16x16x32_bf16 v[76:79], v[166:169], v[222:225], v[76:79]
	v_mfma_f32_16x16x32_bf16 v[72:75], v[174:177], v[222:225], v[72:75]
	v_mfma_f32_16x16x32_bf16 v[124:127], v[170:173], v[202:205], v[124:127]
	v_mfma_f32_16x16x32_bf16 v[120:123], v[178:181], v[202:205], v[120:123]
	v_mfma_f32_16x16x32_bf16 v[108:111], v[170:173], v[210:213], v[108:111]
	v_mfma_f32_16x16x32_bf16 v[104:107], v[178:181], v[210:213], v[104:107]
	v_mfma_f32_16x16x32_bf16 v[92:95], v[170:173], v[218:221], v[92:95]
	v_mfma_f32_16x16x32_bf16 v[88:91], v[178:181], v[218:221], v[88:91]
	v_mfma_f32_16x16x32_bf16 v[76:79], v[170:173], v[228:231], v[76:79]
	v_mfma_f32_16x16x32_bf16 v[72:75], v[178:181], v[228:231], v[72:75]
	s_setprio 0
	s_setprio 1
	v_mfma_f32_16x16x32_bf16 v[116:119], v[182:185], v[198:201], v[116:119]
	v_mfma_f32_16x16x32_bf16 v[112:115], v[190:193], v[198:201], v[112:115]
	v_mfma_f32_16x16x32_bf16 v[100:103], v[182:185], v[206:209], v[100:103]
	v_mfma_f32_16x16x32_bf16 v[96:99], v[190:193], v[206:209], v[96:99]
	v_mfma_f32_16x16x32_bf16 v[84:87], v[182:185], v[214:217], v[84:87]
	v_mfma_f32_16x16x32_bf16 v[80:83], v[190:193], v[214:217], v[80:83]
	v_mfma_f32_16x16x32_bf16 v[68:71], v[182:185], v[222:225], v[68:71]
	v_mfma_f32_16x16x32_bf16 v[64:67], v[190:193], v[222:225], v[64:67]
	v_mfma_f32_16x16x32_bf16 v[116:119], v[186:189], v[202:205], v[116:119]
	v_mfma_f32_16x16x32_bf16 v[112:115], v[194:197], v[202:205], v[112:115]
	v_mfma_f32_16x16x32_bf16 v[100:103], v[186:189], v[210:213], v[100:103]
	v_mfma_f32_16x16x32_bf16 v[96:99], v[194:197], v[210:213], v[96:99]
	v_mfma_f32_16x16x32_bf16 v[84:87], v[186:189], v[218:221], v[84:87]
	v_mfma_f32_16x16x32_bf16 v[80:83], v[194:197], v[218:221], v[80:83]
	v_mfma_f32_16x16x32_bf16 v[68:71], v[186:189], v[228:231], v[68:71]
	v_mfma_f32_16x16x32_bf16 v[64:67], v[194:197], v[228:231], v[64:67]
	s_setprio 0
	s_barrier
	s_mov_b32 m0, s4
	v_lshl_add_u64 v[232:233], s[20:21], 0, v[130:131]
	s_add_u32 s16, s20, 0xb0000
	ds_read_b128 v[198:201], v147 offset:16384
	ds_read_b128 v[202:205], v147 offset:17408
	ds_read_b128 v[206:209], v147 offset:18432
	ds_read_b128 v[210:213], v147 offset:19456
	ds_read_b128 v[214:217], v147 offset:20480
	ds_read_b128 v[218:221], v147 offset:21504
	ds_read_b128 v[222:225], v147 offset:22528
	ds_read_b128 v[228:231], v147 offset:23552
	global_load_lds_dwordx4 v[232:233], off
	v_lshl_add_u64 v[234:235], s[20:21], 0, v[134:135]
	s_mov_b32 m0, s5
	s_addc_u32 s17, s21, 0
	global_load_lds_dwordx4 v[234:235], off
	v_lshl_add_u64 v[236:237], s[16:17], 0, v[130:131]
	s_mov_b32 m0, s33
	v_lshl_add_u64 v[238:239], s[22:23], 0, v[132:133]
	global_load_lds_dwordx4 v[236:237], off
	v_lshl_add_u64 v[236:237], s[16:17], 0, v[134:135]
	s_mov_b32 m0, s36
	s_nop 0
	global_load_lds_dwordx4 v[236:237], off
	v_lshl_add_u64 v[236:237], s[22:23], 0, v[128:129]
	s_mov_b32 m0, s3
	s_nop 0
	global_load_lds_dwordx4 v[236:237], off
	s_mov_b32 m0, s37
	s_nop 0
	global_load_lds_dwordx4 v[238:239], off
	s_waitcnt vmcnt(8)
	s_waitcnt lgkmcnt(0)
	s_barrier
; #define PG8_STAGE(bufoff, gbase, voff) do { _Pragma("unroll") for (int _i = 0; _i < 2; ++_i) \
;         __builtin_amdgcn_global_load_lds((const unsigned*)((const char*)(gbase) + (voff)[_i]), (PG8_LAS unsigned*)(lds + (bufoff) + ldsw + _i * 8192), 16, 0, 0); } while (0)
; #define PG8_LDA(dst, b, h) do { _Pragma("unroll") for (int m = 0; m < 4; ++m) _Pragma("unroll") for (int k = 0; k < 2; ++k) dst[m][k] = *(const PG8_LAS bf16x8*)(lds + PG8_SA(b, h) + aoff + m * 2048 + k * 1024); } while (0)
; #define PG8_LDB(dst, b, h) do { _Pragma("unroll") for (int n = 0; n < 2; ++n) _Pragma("unroll") for (int k = 0; k < 2; ++k) dst[n][k] = *(const PG8_LAS bf16x8*)(lds + PG8_SB(b, h) + boff + n * 2048 + k * 1024); } while (0)
; #define PG8_MMA(ai, bj, At, Bt) do { __builtin_amdgcn_s_setprio(1); _Pragma("unroll") for (int m = 0; m < 4; ++m) _Pragma("unroll") for (int n = 0; n < 2; ++n) _Pragma("unroll") for (int k = 0; k < 2; ++k) \
;         acc[ai][bj][m][n] = mma16<F16>(Bt[n][k], At[m][k], acc[ai][bj][m][n]); __builtin_amdgcn_s_setprio(0); } while (0)
; #define PG8_BAR __builtin_amdgcn_s_barrier()
; template <class Epi, class Sched, bool ALIGN_EPI = false, bool SP2 = false, bool F16 = false, bool TOKPERM = false>
; __device__ __forceinline__ void gemm_phase(PG8_LAS unsigned char* lds, const Gemm g, const Sched& S, const Epi& E, int wv) {
;     ...
;             PG8_LDB(B0, 0, 0); PG8_LDB(B1, 0, 1); PG8_SCHED; PG8_LDA(At, 0, 0); PG8_STAGE(PG8_SA(1, 1), a1 + hstep, voffA);
;             PG8_WAIT_V(8); PG8_WAIT_L(0); PG8_BAR; PG8_MMA(0, 0, At, B0); PG8_MMA(0, 1, At, B1); PG8_BAR; PG8_SCHED;
;             PG8_LDA(At, 0, 1); PG8_STAGE(PG8_SB(0, 0), b2, voffB); PG8_STAGE(PG8_SB(0, 1), b2 + hstep, voffB); PG8_STAGE(PG8_SA(0, 0), a2, voffA);
;             PG8_WAIT_V(8); PG8_WAIT_L(0); PG8_BAR; PG8_MMA(1, 0, At, B0); PG8_MMA(1, 1, At, B1); PG8_BAR; PG8_SCHED;
;             PG8_LDB(B0, 1, 0); PG8_LDB(B1, 1, 1); PG8_SCHED; PG8_LDA(At, 1, 0); PG8_STAGE(PG8_SA(0, 1), a2 + hstep, voffA);
;             PG8_WAIT_V(8); PG8_WAIT_L(0); PG8_BAR; PG8_MMA(0, 0, At, B0); PG8_MMA(0, 1, At, B1); PG8_BAR; PG8_SCHED;
;             PG8_LDA(At, 1, 1); PG8_STAGE(PG8_SB(1, 0), b3, voffB); PG8_STAGE(PG8_SB(1, 1), b3 + hstep, voffB); PG8_STAGE(PG8_SA(1, 0), a3, voffA);
;             PG8_WAIT_V(8); PG8_WAIT_L(0); PG8_BAR; PG8_MMA(1, 0, At, B0); PG8_MMA(1, 1, At, B1); PG8_BAR; PG8_SCHED;
	s_setprio 1
	v_mfma_f32_16x16x32_bf16 v[60:63], v[166:169], v[198:201], v[60:63]
	v_mfma_f32_16x16x32_bf16 v[56:59], v[174:177], v[198:201], v[56:59]
	v_mfma_f32_16x16x32_bf16 v[44:47], v[166:169], v[206:209], v[44:47]
	v_mfma_f32_16x16x32_bf16 v[40:43], v[174:177], v[206:209], v[40:43]
	v_mfma_f32_16x16x32_bf16 v[28:31], v[166:169], v[214:217], v[28:31]
	v_mfma_f32_16x16x32_bf16 v[24:27], v[174:177], v[214:217], v[24:27]
	v_mfma_f32_16x16x32_bf16 v[12:15], v[166:169], v[222:225], v[12:15]
	v_mfma_f32_16x16x32_bf16 v[8:11], v[174:177], v[222:225], v[8:11]
	v_mfma_f32_16x16x32_bf16 v[60:63], v[170:173], v[202:205], v[60:63]
	v_mfma_f32_16x16x32_bf16 v[56:59], v[178:181], v[202:205], v[56:59]
	v_mfma_f32_16x16x32_bf16 v[44:47], v[170:173], v[210:213], v[44:47]
	v_mfma_f32_16x16x32_bf16 v[40:43], v[178:181], v[210:213], v[40:43]
	v_mfma_f32_16x16x32_bf16 v[28:31], v[170:173], v[218:221], v[28:31]
	v_mfma_f32_16x16x32_bf16 v[24:27], v[178:181], v[218:221], v[24:27]
	v_mfma_f32_16x16x32_bf16 v[12:15], v[170:173], v[228:231], v[12:15]
	v_mfma_f32_16x16x32_bf16 v[8:11], v[178:181], v[228:231], v[8:11]
	s_setprio 0
	s_setprio 1
	v_mfma_f32_16x16x32_bf16 v[52:55], v[182:185], v[198:201], v[52:55]
	v_mfma_f32_16x16x32_bf16 v[48:51], v[190:193], v[198:201], v[48:51]
	v_mfma_f32_16x16x32_bf16 v[36:39], v[182:185], v[206:209], v[36:39]
	v_mfma_f32_16x16x32_bf16 v[32:35], v[190:193], v[206:209], v[32:35]
	v_mfma_f32_16x16x32_bf16 v[20:23], v[182:185], v[214:217], v[20:23]
	v_mfma_f32_16x16x32_bf16 v[16:19], v[190:193], v[214:217], v[16:19]
	v_mfma_f32_16x16x32_bf16 v[4:7], v[182:185], v[222:225], v[4:7]
	v_mfma_f32_16x16x32_bf16 v[0:3], v[190:193], v[222:225], v[0:3]
	v_mfma_f32_16x16x32_bf16 v[52:55], v[186:189], v[202:205], v[52:55]
	v_mfma_f32_16x16x32_bf16 v[48:51], v[194:197], v[202:205], v[48:51]
	v_mfma_f32_16x16x32_bf16 v[36:39], v[186:189], v[210:213], v[36:39]
	v_mfma_f32_16x16x32_bf16 v[32:35], v[194:197], v[210:213], v[32:35]
	v_mfma_f32_16x16x32_bf16 v[20:23], v[186:189], v[218:221], v[20:23]
	v_mfma_f32_16x16x32_bf16 v[16:19], v[194:197], v[218:221], v[16:19]
	v_mfma_f32_16x16x32_bf16 v[4:7], v[186:189], v[228:231], v[4:7]
	v_mfma_f32_16x16x32_bf16 v[0:3], v[194:197], v[228:231], v[0:3]
	s_setprio 0
	s_barrier
	ds_read_b128 v[166:169], v157
	ds_read_b128 v[170:173], v158
	ds_read_b128 v[174:177], v159
	ds_read_b128 v[178:181], v160
	ds_read_b128 v[182:185], v161
	ds_read_b128 v[186:189], v162
	ds_read_b128 v[190:193], v163
	ds_read_b128 v[194:197], v164
	s_add_u32 s16, s22, 0xb0000
	s_addc_u32 s17, s23, 0
	s_mov_b32 m0, s44
	v_lshl_add_u64 v[240:241], s[16:17], 0, v[128:129]
	ds_read_b128 v[198:201], v147 offset:32768
	ds_read_b128 v[202:205], v147 offset:33792
	ds_read_b128 v[206:209], v147 offset:34816
	ds_read_b128 v[210:213], v147 offset:35840
	ds_read_b128 v[214:217], v147 offset:36864
	ds_read_b128 v[218:221], v147 offset:37888
	ds_read_b128 v[222:225], v147 offset:38912
	ds_read_b128 v[228:231], v147 offset:39936
	global_load_lds_dwordx4 v[240:241], off
	v_lshl_add_u64 v[240:241], s[16:17], 0, v[132:133]
	s_mov_b32 m0, s45
	s_nop 0
	global_load_lds_dwordx4 v[240:241], off
	s_waitcnt vmcnt(8)
	s_waitcnt lgkmcnt(0)
	s_barrier
	s_setprio 1
	v_mfma_f32_16x16x32_bf16 v[124:127], v[166:169], v[198:201], v[124:127]
	v_mfma_f32_16x16x32_bf16 v[120:123], v[174:177], v[198:201], v[120:123]
	v_mfma_f32_16x16x32_bf16 v[108:111], v[166:169], v[206:209], v[108:111]
	v_mfma_f32_16x16x32_bf16 v[104:107], v[174:177], v[206:209], v[104:107]
	v_mfma_f32_16x16x32_bf16 v[92:95], v[166:169], v[214:217], v[92:95]
	v_mfma_f32_16x16x32_bf16 v[88:91], v[174:177], v[214:217], v[88:91]
	v_mfma_f32_16x16x32_bf16 v[76:79], v[166:169], v[222:225], v[76:79]
	v_mfma_f32_16x16x32_bf16 v[72:75], v[174:177], v[222:225], v[72:75]
	v_mfma_f32_16x16x32_bf16 v[124:127], v[170:173], v[202:205], v[124:127]
	v_mfma_f32_16x16x32_bf16 v[120:123], v[178:181], v[202:205], v[120:123]
	v_mfma_f32_16x16x32_bf16 v[108:111], v[170:173], v[210:213], v[108:111]
	v_mfma_f32_16x16x32_bf16 v[104:107], v[178:181], v[210:213], v[104:107]
	v_mfma_f32_16x16x32_bf16 v[92:95], v[170:173], v[218:221], v[92:95]
	v_mfma_f32_16x16x32_bf16 v[88:91], v[178:181], v[218:221], v[88:91]
	v_mfma_f32_16x16x32_bf16 v[76:79], v[170:173], v[228:231], v[76:79]
	v_mfma_f32_16x16x32_bf16 v[72:75], v[178:181], v[228:231], v[72:75]
	s_setprio 0
	s_setprio 1
	v_mfma_f32_16x16x32_bf16 v[116:119], v[182:185], v[198:201], v[116:119]
	v_mfma_f32_16x16x32_bf16 v[112:115], v[190:193], v[198:201], v[112:115]
	v_mfma_f32_16x16x32_bf16 v[100:103], v[182:185], v[206:209], v[100:103]
	v_mfma_f32_16x16x32_bf16 v[96:99], v[190:193], v[206:209], v[96:99]
	v_mfma_f32_16x16x32_bf16 v[84:87], v[182:185], v[214:217], v[84:87]
	v_mfma_f32_16x16x32_bf16 v[80:83], v[190:193], v[214:217], v[80:83]
	v_mfma_f32_16x16x32_bf16 v[68:71], v[182:185], v[222:225], v[68:71]
	v_mfma_f32_16x16x32_bf16 v[64:67], v[190:193], v[222:225], v[64:67]
	v_mfma_f32_16x16x32_bf16 v[116:119], v[186:189], v[202:205], v[116:119]
	v_mfma_f32_16x16x32_bf16 v[112:115], v[194:197], v[202:205], v[112:115]
	v_mfma_f32_16x16x32_bf16 v[100:103], v[186:189], v[210:213], v[100:103]
	v_mfma_f32_16x16x32_bf16 v[96:99], v[194:197], v[210:213], v[96:99]
	v_mfma_f32_16x16x32_bf16 v[84:87], v[186:189], v[218:221], v[84:87]
	v_mfma_f32_16x16x32_bf16 v[80:83], v[194:197], v[218:221], v[80:83]
	v_mfma_f32_16x16x32_bf16 v[68:71], v[186:189], v[228:231], v[68:71]
	v_mfma_f32_16x16x32_bf16 v[64:67], v[194:197], v[228:231], v[64:67]
	s_setprio 0
	s_barrier
; #define PG8_STAGE(bufoff, gbase, voff) do { _Pragma("unroll") for (int _i = 0; _i < 2; ++_i) \
;         __builtin_amdgcn_global_load_lds((const unsigned*)((const char*)(gbase) + (voff)[_i]), (PG8_LAS unsigned*)(lds + (bufoff) + ldsw + _i * 8192), 16, 0, 0); } while (0)
; #define PG8_LDA(dst, b, h) do { _Pragma("unroll") for (int m = 0; m < 4; ++m) _Pragma("unroll") for (int k = 0; k < 2; ++k) dst[m][k] = *(const PG8_LAS bf16x8*)(lds + PG8_SA(b, h) + aoff + m * 2048 + k * 1024); } while (0)
; #define PG8_LDB(dst, b, h) do { _Pragma("unroll") for (int n = 0; n < 2; ++n) _Pragma("unroll") for (int k = 0; k < 2; ++k) dst[n][k] = *(const PG8_LAS bf16x8*)(lds + PG8_SB(b, h) + boff + n * 2048 + k * 1024); } while (0)
; #define PG8_MMA(ai, bj, At, Bt) do { __builtin_amdgcn_s_setprio(1); _Pragma("unroll") for (int m = 0; m < 4; ++m) _Pragma("unroll") for (int n = 0; n < 2; ++n) _Pragma("unroll") for (int k = 0; k < 2; ++k) \
;         acc[ai][bj][m][n] = mma16<F16>(Bt[n][k], At[m][k], acc[ai][bj][m][n]); __builtin_amdgcn_s_setprio(0); } while (0)
; #define PG8_BAR __builtin_amdgcn_s_barrier()
; template <class Epi, class Sched, bool ALIGN_EPI = false, bool SP2 = false, bool F16 = false, bool TOKPERM = false>
; __device__ __forceinline__ void gemm_phase(PG8_LAS unsigned char* lds, const Gemm g, const Sched& S, const Epi& E, int wv) {
;     ...
;             PG8_LDB(B0, 0, 0); PG8_LDB(B1, 0, 1); PG8_SCHED; PG8_LDA(At, 0, 0); PG8_STAGE(PG8_SA(1, 1), a1 + hstep, voffA);
;             PG8_WAIT_V(8); PG8_WAIT_L(0); PG8_BAR; PG8_MMA(0, 0, At, B0); PG8_MMA(0, 1, At, B1); PG8_BAR; PG8_SCHED;
;             PG8_LDA(At, 0, 1); PG8_STAGE(PG8_SB(0, 0), b2, voffB); PG8_STAGE(PG8_SB(0, 1), b2 + hstep, voffB); PG8_STAGE(PG8_SA(0, 0), a2, voffA);
;             PG8_WAIT_V(8); PG8_WAIT_L(0); PG8_BAR; PG8_MMA(1, 0, At, B0); PG8_MMA(1, 1, At, B1); PG8_BAR; PG8_SCHED;
;             PG8_LDB(B0, 1, 0); PG8_LDB(B1, 1, 1); PG8_SCHED; PG8_LDA(At, 1, 0); PG8_STAGE(PG8_SA(0, 1), a2 + hstep, voffA);
;             PG8_WAIT_V(8); PG8_WAIT_L(0); PG8_BAR; PG8_MMA(0, 0, At, B0); PG8_MMA(0, 1, At, B1); PG8_BAR; PG8_SCHED;
;             PG8_LDA(At, 1, 1); PG8_STAGE(PG8_SB(1, 0), b3, voffB); PG8_STAGE(PG8_SB(1, 1), b3 + hstep, voffB); PG8_STAGE(PG8_SA(1, 0), a3, voffA);
;             PG8_WAIT_V(8); PG8_WAIT_L(0); PG8_BAR; PG8_MMA(1, 0, At, B0); PG8_MMA(1, 1, At, B1); PG8_BAR; PG8_SCHED;
	s_mov_b32 m0, s49
	v_lshl_add_u64 v[232:233], v[232:233], 0, s[14:15]
	s_add_u32 s16, s20, 0xb0080
	ds_read_b128 v[198:201], v147 offset:49152
	ds_read_b128 v[202:205], v147 offset:50176
	ds_read_b128 v[206:209], v147 offset:51200
	ds_read_b128 v[210:213], v147 offset:52224
	ds_read_b128 v[214:217], v147 offset:53248
	ds_read_b128 v[218:221], v147 offset:54272
	ds_read_b128 v[222:225], v147 offset:55296
	ds_read_b128 v[228:231], v147 offset:56320
	global_load_lds_dwordx4 v[232:233], off
	v_lshl_add_u64 v[232:233], v[234:235], 0, s[14:15]
	s_mov_b32 m0, s50
	s_addc_u32 s17, s21, 0
	global_load_lds_dwordx4 v[232:233], off
	v_lshl_add_u64 v[232:233], s[16:17], 0, v[130:131]
	s_mov_b32 m0, s53
	s_nop 0
	global_load_lds_dwordx4 v[232:233], off
	v_lshl_add_u64 v[232:233], s[16:17], 0, v[134:135]
	s_mov_b32 m0, s54
	s_nop 0
	global_load_lds_dwordx4 v[232:233], off
	v_lshl_add_u64 v[232:233], v[236:237], 0, s[14:15]
	s_mov_b32 m0, s51
	s_nop 0
	global_load_lds_dwordx4 v[232:233], off
	v_lshl_add_u64 v[232:233], v[238:239], 0, s[14:15]
	s_mov_b32 m0, s52
	s_nop 0
	global_load_lds_dwordx4 v[232:233], off
	s_waitcnt vmcnt(8)
	s_waitcnt lgkmcnt(0)
	s_barrier
	s_setprio 1
	v_mfma_f32_16x16x32_bf16 v[60:63], v[166:169], v[198:201], v[60:63]
	v_mfma_f32_16x16x32_bf16 v[56:59], v[174:177], v[198:201], v[56:59]
	v_mfma_f32_16x16x32_bf16 v[44:47], v[166:169], v[206:209], v[44:47]
	v_mfma_f32_16x16x32_bf16 v[40:43], v[174:177], v[206:209], v[40:43]
	v_mfma_f32_16x16x32_bf16 v[28:31], v[166:169], v[214:217], v[28:31]
	v_mfma_f32_16x16x32_bf16 v[24:27], v[174:177], v[214:217], v[24:27]
	v_mfma_f32_16x16x32_bf16 v[12:15], v[166:169], v[222:225], v[12:15]
	v_mfma_f32_16x16x32_bf16 v[8:11], v[174:177], v[222:225], v[8:11]
	v_mfma_f32_16x16x32_bf16 v[60:63], v[170:173], v[202:205], v[60:63]
	v_mfma_f32_16x16x32_bf16 v[56:59], v[178:181], v[202:205], v[56:59]
	v_mfma_f32_16x16x32_bf16 v[44:47], v[170:173], v[210:213], v[44:47]
	v_mfma_f32_16x16x32_bf16 v[40:43], v[178:181], v[210:213], v[40:43]
	v_mfma_f32_16x16x32_bf16 v[28:31], v[170:173], v[218:221], v[28:31]
	v_mfma_f32_16x16x32_bf16 v[24:27], v[178:181], v[218:221], v[24:27]
	v_mfma_f32_16x16x32_bf16 v[12:15], v[170:173], v[228:231], v[12:15]
	v_mfma_f32_16x16x32_bf16 v[8:11], v[178:181], v[228:231], v[8:11]
	s_setprio 0
	s_setprio 1
	v_mfma_f32_16x16x32_bf16 v[52:55], v[182:185], v[198:201], v[52:55]
	v_mfma_f32_16x16x32_bf16 v[48:51], v[190:193], v[198:201], v[48:51]
	v_mfma_f32_16x16x32_bf16 v[36:39], v[182:185], v[206:209], v[36:39]
	v_mfma_f32_16x16x32_bf16 v[32:35], v[190:193], v[206:209], v[32:35]
	v_mfma_f32_16x16x32_bf16 v[20:23], v[182:185], v[214:217], v[20:23]
	v_mfma_f32_16x16x32_bf16 v[16:19], v[190:193], v[214:217], v[16:19]
	v_mfma_f32_16x16x32_bf16 v[4:7], v[182:185], v[222:225], v[4:7]
	v_mfma_f32_16x16x32_bf16 v[0:3], v[190:193], v[222:225], v[0:3]
	v_mfma_f32_16x16x32_bf16 v[52:55], v[186:189], v[202:205], v[52:55]
	v_mfma_f32_16x16x32_bf16 v[48:51], v[194:197], v[202:205], v[48:51]
	v_mfma_f32_16x16x32_bf16 v[36:39], v[186:189], v[210:213], v[36:39]
	v_mfma_f32_16x16x32_bf16 v[32:35], v[194:197], v[210:213], v[32:35]
	v_mfma_f32_16x16x32_bf16 v[20:23], v[186:189], v[218:221], v[20:23]
	v_mfma_f32_16x16x32_bf16 v[16:19], v[194:197], v[218:221], v[16:19]
	v_mfma_f32_16x16x32_bf16 v[4:7], v[186:189], v[228:231], v[4:7]
	v_mfma_f32_16x16x32_bf16 v[0:3], v[194:197], v[228:231], v[0:3]
	s_setprio 0
	s_barrier
	s_add_i32 s67, s67, 2
	s_add_u32 s65, s65, 0x100
	s_addc_u32 s66, s66, 0
	s_cmp_gt_u32 s67, 41
	s_mov_b64 s[16:17], s[18:19]
	s_cbranch_scc0 .LBB0_867
;   __device__ __forceinline__ void operator()(const pg8::f32x4 (&acc)[2][2][4][2], const pg8::Unit& u, int wr, int wc, int fr, int fq) const {
;     int z; asm volatile("v_mov_b32 %0, 0" : "=v"(z));
;     const int row0 = u.pm * 256 + wr * 64 + fr + z, colb = u.pn * 256 + wc * 32 + 8 * fq + z;
; #pragma unroll
;     for (int ai = 0; ai < 2; ++ai)
; #pragma unroll
;       for (int m = 0; m < 4; ++m) {
;         const int tok = row0 + ai * 128 + m * 16; float ss = 0.f;
; #pragma unroll
;         for (int bj = 0; bj < 2; ++bj) {
;           const unsigned off = (unsigned)tok * DM + colb + 128 * bj;
;           f8_t n = __builtin_convertvector(*(const h8_t*)(x16 + off), f8_t);
; #pragma unroll
;           for (int c = 0; c < 4; ++c) { n[c] += sc * acc[ai][bj][m][0][c]; n[4 + c] += sc * acc[ai][bj][m][1][c]; }
;           if (aux) {
;             *(h8_t*)(x16 + off) = __builtin_convertvector(n, h8_t);
;             ss += ((n[0] * n[0] + n[1] * n[1]) + (n[2] * n[2] + n[3] * n[3])) + ((n[4] * n[4] + n[5] * n[5]) + (n[6] * n[6] + n[7] * n[7]));
;           } else {
;             *(f32x4*)(xout + off) = (f32x4){n[0], n[1], n[2], n[3]}; *(f32x4*)(xout + off + 4) = (f32x4){n[4], n[5], n[6], n[7]};
;           }
;         }
;         if (aux) { ss += __shfl_xor(ss, 16); ss += __shfl_xor(ss, 32); if (fq == 0) ssq[(unsigned)tok * 16 + u.pn * 4 + wc] = ss; }
;         if (m & 1) asm volatile("" ::: "memory");
;       }
;   }
	s_lshl_b32 s16, s64, 8
	v_lshl_or_b32 v166, s63, 8, v148
	v_mov_b32 v136, 0
	v_xor_b32_e32 v169, 32, v165
	v_add3_u32 v167, s16, v146, v136
	v_add_u32_e32 v168, v166, v136
	v_lshl_add_u32 v136, v167, 10, v168
	v_lshl_add_u64 v[178:179], v[136:137], 1, s[40:41]
	v_add_u32_e32 v136, 0x80, v136
	global_load_dwordx4 v[170:173], v[178:179], off
	v_lshl_add_u64 v[180:181], v[136:137], 1, s[40:41]
	global_load_dwordx4 v[174:177], v[180:181], off
	v_add_u32_e32 v136, 16, v167
	v_lshl_add_u32 v136, v136, 10, v168
	v_lshl_add_u64 v[224:225], v[136:137], 1, s[40:41]
	v_add_u32_e32 v136, 0x80, v136
	global_load_dwordx4 v[192:195], v[224:225], off
	v_lshl_add_u64 v[248:249], v[136:137], 1, s[40:41]
	global_load_dwordx4 v[196:199], v[248:249], off
	v_add_u32_e32 v136, 32, v167
	v_lshl_add_u32 v136, v136, 10, v168
	v_lshl_add_u64 v[224:225], v[136:137], 1, s[40:41]
	v_add_u32_e32 v136, 0x80, v136
	global_load_dwordx4 v[200:203], v[224:225], off
	v_lshl_add_u64 v[248:249], v[136:137], 1, s[40:41]
	global_load_dwordx4 v[204:207], v[248:249], off
	v_add_u32_e32 v136, 48, v167
	v_lshl_add_u32 v136, v136, 10, v168
	v_lshl_add_u64 v[224:225], v[136:137], 1, s[40:41]
	v_add_u32_e32 v136, 0x80, v136
	global_load_dwordx4 v[208:211], v[224:225], off
	v_lshl_add_u64 v[248:249], v[136:137], 1, s[40:41]
	global_load_dwordx4 v[212:215], v[248:249], off
	v_add_u32_e32 v136, 0x80, v167
	v_lshl_add_u32 v136, v136, 10, v168
	v_lshl_add_u64 v[224:225], v[136:137], 1, s[40:41]
	v_add_u32_e32 v136, 0x80, v136
	global_load_dwordx4 v[216:219], v[224:225], off
	v_lshl_add_u64 v[248:249], v[136:137], 1, s[40:41]
	global_load_dwordx4 v[220:223], v[248:249], off
	v_add_u32_e32 v136, 0x90, v167
	v_lshl_add_u32 v136, v136, 10, v168
	v_lshl_add_u64 v[224:225], v[136:137], 1, s[40:41]
	v_add_u32_e32 v136, 0x80, v136
	global_load_dwordx4 v[228:231], v[224:225], off
	v_lshl_add_u64 v[248:249], v[136:137], 1, s[40:41]
	global_load_dwordx4 v[244:247], v[248:249], off
	v_and_b32_e32 v166, 64, v165
	v_xor_b32_e32 v136, 16, v165
	v_add_u32_e32 v166, 64, v166
	v_cmp_lt_i32_e32 vcc, v136, v166
	s_lshl_b32 s16, s63, 2
	s_or_b32 s18, s16, s48
	v_cndmask_b32_e32 v136, v165, v136, vcc
	v_cmp_lt_i32_e32 vcc, v169, v166
	v_lshlrev_b32_e32 v166, 2, v136
	s_waitcnt vmcnt(10)
	v_cvt_f32_f16_e32 v182, v173
	v_cvt_f32_f16_sdwa v183, v173 dst_sel:DWORD dst_unused:UNUSED_PAD src0_sel:WORD_1
	v_cvt_f32_f16_e32 v184, v171
	v_cvt_f32_f16_sdwa v185, v171 dst_sel:DWORD dst_unused:UNUSED_PAD src0_sel:WORD_1
	v_cvt_f32_f16_e32 v186, v172
	v_cvt_f32_f16_sdwa v187, v172 dst_sel:DWORD dst_unused:UNUSED_PAD src0_sel:WORD_1
	v_cvt_f32_f16_e32 v172, v170
	v_cvt_f32_f16_sdwa v173, v170 dst_sel:DWORD dst_unused:UNUSED_PAD src0_sel:WORD_1
	v_cvt_f32_f16_e32 v170, v177
	v_cvt_f32_f16_sdwa v171, v177 dst_sel:DWORD dst_unused:UNUSED_PAD src0_sel:WORD_1
	v_cvt_f32_f16_e32 v188, v175
	v_cvt_f32_f16_sdwa v189, v175 dst_sel:DWORD dst_unused:UNUSED_PAD src0_sel:WORD_1
	v_cvt_f32_f16_e32 v190, v176
	v_cvt_f32_f16_sdwa v191, v176 dst_sel:DWORD dst_unused:UNUSED_PAD src0_sel:WORD_1
	v_cvt_f32_f16_e32 v176, v174
	v_cvt_f32_f16_sdwa v177, v174 dst_sel:DWORD dst_unused:UNUSED_PAD src0_sel:WORD_1
	v_pk_fma_f32 v[124:125], v[124:125], 0.5, v[172:173] op_sel_hi:[1,0,1]
	v_pk_fma_f32 v[172:173], v[120:121], 0.5, v[186:187] op_sel_hi:[1,0,1]
	v_pk_fma_f32 v[126:127], v[126:127], 0.5, v[184:185] op_sel_hi:[1,0,1]
	v_pk_fma_f32 v[122:123], v[122:123], 0.5, v[182:183] op_sel_hi:[1,0,1]
	v_cvt_pk_f16_f32 v120, v172, v173
	v_cvt_pk_f16_f32 v121, v122, v123
	v_pk_mul_f32 v[174:175], v[124:125], v[124:125]
	v_pk_mul_f32 v[182:183], v[126:127], v[126:127]
	v_pk_fma_f32 v[174:175], v[172:173], v[172:173], v[174:175]
	v_pk_fma_f32 v[182:183], v[122:123], v[122:123], v[182:183]
	v_pk_fma_f32 v[176:177], v[116:117], 0.5, v[176:177] op_sel_hi:[1,0,1]
	v_pk_fma_f32 v[116:117], v[112:113], 0.5, v[190:191] op_sel_hi:[1,0,1]
	v_pk_fma_f32 v[184:185], v[118:119], 0.5, v[188:189] op_sel_hi:[1,0,1]
	v_pk_fma_f32 v[112:113], v[114:115], 0.5, v[170:171] op_sel_hi:[1,0,1]
	v_pk_fma_f32 v[174:175], v[176:177], v[176:177], v[174:175]
	v_pk_fma_f32 v[182:183], v[184:185], v[184:185], v[182:183]
	v_pk_fma_f32 v[174:175], v[116:117], v[116:117], v[174:175]
	v_pk_fma_f32 v[182:183], v[112:113], v[112:113], v[182:183]
	v_pk_add_f32 v[174:175], v[174:175], v[182:183]
	v_add_f32_e32 v114, v174, v175
	v_mov_b32_e32 v115, v114
	s_nop 1
	v_permlane16_swap_b32_e32 v114, v115
	v_cndmask_b32_e32 v169, v165, v169, vcc
	v_cvt_pk_f16_f32 v119, v126, v127
	v_cvt_pk_f16_f32 v118, v124, v125
	global_store_dwordx4 v[178:179], v[118:121], off
	s_nop 1
	v_cvt_pk_f16_f32 v119, v112, v113
	s_waitcnt lgkmcnt(0)
	v_add_f32_e32 v113, v114, v115
	v_lshlrev_b32_e32 v112, 2, v169
	v_mov_b32_e32 v114, v113
	s_nop 1
	v_permlane32_swap_b32_e32 v113, v114
	v_cvt_pk_f16_f32 v118, v116, v117
	v_cvt_pk_f16_f32 v117, v184, v185
	v_cvt_pk_f16_f32 v116, v176, v177
	global_store_dwordx4 v[180:181], v[116:119], off
	s_and_saveexec_b64 s[16:17], s[6:7]
	s_cbranch_execz .LBB0_870
	v_lshl_add_u32 v136, v167, 4, s18
	s_waitcnt lgkmcnt(0)
	v_add_f32_e32 v113, v113, v114
	v_lshl_add_u64 v[114:115], v[136:137], 2, s[42:43]
	global_store_dword v[114:115], v113, off

; #define PG8_STAGE(bufoff, gbase, voff) do { _Pragma("unroll") for (int _i = 0; _i < 2; ++_i) \
;         __builtin_amdgcn_global_load_lds((const unsigned*)((const char*)(gbase) + (voff)[_i]), (PG8_LAS unsigned*)(lds + (bufoff) + ldsw + _i * 8192), 16, 0, 0); } while (0)
; #define PG8_LDA(dst, b, h) do { _Pragma("unroll") for (int m = 0; m < 4; ++m) _Pragma("unroll") for (int k = 0; k < 2; ++k) dst[m][k] = *(const PG8_LAS bf16x8*)(lds + PG8_SA(b, h) + aoff + m * 2048 + k * 1024); } while (0)
; #define PG8_LDB(dst, b, h) do { _Pragma("unroll") for (int n = 0; n < 2; ++n) _Pragma("unroll") for (int k = 0; k < 2; ++k) dst[n][k] = *(const PG8_LAS bf16x8*)(lds + PG8_SB(b, h) + boff + n * 2048 + k * 1024); } while (0)
; #define PG8_MMA(ai, bj, At, Bt) do { __builtin_amdgcn_s_setprio(1); _Pragma("unroll") for (int m = 0; m < 4; ++m) _Pragma("unroll") for (int n = 0; n < 2; ++n) _Pragma("unroll") for (int k = 0; k < 2; ++k) \
;         acc[ai][bj][m][n] = mma16<F16>(Bt[n][k], At[m][k], acc[ai][bj][m][n]); __builtin_amdgcn_s_setprio(0); } while (0)
; #define PG8_BAR __builtin_amdgcn_s_barrier()
; template <class Epi, class Sched, bool ALIGN_EPI = false, bool SP2 = false, bool F16 = false, bool TOKPERM = false>
; __device__ __forceinline__ void gemm_phase(PG8_LAS unsigned char* lds, const Gemm g, const Sched& S, const Epi& E, int wv) {
;     ...
;             PG8_LDB(B0, 0, 0); PG8_LDB(B1, 0, 1); PG8_SCHED; PG8_LDA(At, 0, 0); PG8_STAGE(PG8_SA(1, 1), a1 + hstep, voffA);
;             PG8_WAIT_V(8); PG8_WAIT_L(0); PG8_BAR; PG8_MMA(0, 0, At, B0); PG8_MMA(0, 1, At, B1); PG8_BAR; PG8_SCHED;
;             PG8_LDA(At, 0, 1); PG8_STAGE(PG8_SB(0, 0), b2, voffB); PG8_STAGE(PG8_SB(0, 1), b2 + hstep, voffB); PG8_STAGE(PG8_SA(0, 0), a2, voffA);
;             PG8_WAIT_V(8); PG8_WAIT_L(0); PG8_BAR; PG8_MMA(1, 0, At, B0); PG8_MMA(1, 1, At, B1); PG8_BAR; PG8_SCHED;
;             PG8_LDB(B0, 1, 0); PG8_LDB(B1, 1, 1); PG8_SCHED; PG8_LDA(At, 1, 0); PG8_STAGE(PG8_SA(0, 1), a2 + hstep, voffA);
;             PG8_WAIT_V(8); PG8_WAIT_L(0); PG8_BAR; PG8_MMA(0, 0, At, B0); PG8_MMA(0, 1, At, B1); PG8_BAR; PG8_SCHED;
;             PG8_LDA(At, 1, 1); PG8_STAGE(PG8_SB(1, 0), b3, voffB); PG8_STAGE(PG8_SB(1, 1), b3 + hstep, voffB); PG8_STAGE(PG8_SA(1, 0), a3, voffA);
;             PG8_WAIT_V(8); PG8_WAIT_L(0); PG8_BAR; PG8_MMA(1, 0, At, B0); PG8_MMA(1, 1, At, B1); PG8_BAR; PG8_SCHED;
.Lvmw_950_0:
	s_waitcnt lgkmcnt(0)
	s_barrier
	s_setprio 1
	v_mfma_f32_16x16x32_f16 v[124:127], v[172:175], v[204:207], 0
	v_mfma_f32_16x16x32_f16 v[116:119], v[180:183], v[204:207], 0
	v_mfma_f32_16x16x32_f16 v[108:111], v[172:175], v[212:215], 0
	v_mfma_f32_16x16x32_f16 v[104:107], v[180:183], v[212:215], 0
	v_mfma_f32_16x16x32_f16 v[92:95], v[172:175], v[220:223], 0
	v_mfma_f32_16x16x32_f16 v[88:91], v[180:183], v[220:223], 0
	v_mfma_f32_16x16x32_f16 v[76:79], v[172:175], v[232:235], 0
	v_mfma_f32_16x16x32_f16 v[72:75], v[180:183], v[232:235], 0
	v_mfma_f32_16x16x32_f16 v[124:127], v[176:179], v[208:211], v[124:127]
	v_mfma_f32_16x16x32_f16 v[116:119], v[184:187], v[208:211], v[116:119]
	v_mfma_f32_16x16x32_f16 v[108:111], v[176:179], v[216:219], v[108:111]
	v_mfma_f32_16x16x32_f16 v[104:107], v[184:187], v[216:219], v[104:107]
	v_mfma_f32_16x16x32_f16 v[92:95], v[176:179], v[228:231], v[92:95]
	v_mfma_f32_16x16x32_f16 v[88:91], v[184:187], v[228:231], v[88:91]
	v_mfma_f32_16x16x32_f16 v[76:79], v[176:179], v[236:239], v[76:79]
	v_mfma_f32_16x16x32_f16 v[72:75], v[184:187], v[236:239], v[72:75]
	s_setprio 0
	s_setprio 1
	v_mfma_f32_16x16x32_f16 v[120:123], v[188:191], v[204:207], 0
	v_mfma_f32_16x16x32_f16 v[112:115], v[196:199], v[204:207], 0
	v_mfma_f32_16x16x32_f16 v[100:103], v[188:191], v[212:215], 0
	v_mfma_f32_16x16x32_f16 v[96:99], v[196:199], v[212:215], 0
	v_mfma_f32_16x16x32_f16 v[84:87], v[188:191], v[220:223], 0
	v_mfma_f32_16x16x32_f16 v[80:83], v[196:199], v[220:223], 0
	v_mfma_f32_16x16x32_f16 v[68:71], v[188:191], v[232:235], 0
	v_mfma_f32_16x16x32_f16 v[64:67], v[196:199], v[232:235], 0
	v_mfma_f32_16x16x32_f16 v[120:123], v[192:195], v[208:211], v[120:123]
	v_mfma_f32_16x16x32_f16 v[112:115], v[200:203], v[208:211], v[112:115]
	v_mfma_f32_16x16x32_f16 v[100:103], v[192:195], v[216:219], v[100:103]
	v_mfma_f32_16x16x32_f16 v[96:99], v[200:203], v[216:219], v[96:99]
	v_mfma_f32_16x16x32_f16 v[84:87], v[192:195], v[228:231], v[84:87]
	v_mfma_f32_16x16x32_f16 v[80:83], v[200:203], v[228:231], v[80:83]
	v_mfma_f32_16x16x32_f16 v[68:71], v[192:195], v[236:239], v[68:71]
	v_mfma_f32_16x16x32_f16 v[64:67], v[200:203], v[236:239], v[64:67]
	s_setprio 0
	s_barrier
	s_mov_b32 m0, s5
	v_lshl_add_u64 v[148:149], s[12:13], 0, v[132:133]
	s_add_u32 s76, s12, 0x40000
	ds_read_b128 v[204:207], v153 offset:16384
	ds_read_b128 v[208:211], v153 offset:17408
	ds_read_b128 v[212:215], v153 offset:18432
	ds_read_b128 v[216:219], v153 offset:19456
	ds_read_b128 v[220:223], v153 offset:20480
	ds_read_b128 v[228:231], v153 offset:21504
	ds_read_b128 v[232:235], v153 offset:22528
	ds_read_b128 v[236:239], v153 offset:23552
	global_load_lds_dwordx4 v[148:149], off
	v_lshl_add_u64 v[224:225], s[12:13], 0, v[128:129]
	s_mov_b32 m0, s21
	s_addc_u32 s77, s13, 0
	global_load_lds_dwordx4 v[224:225], off
	v_lshl_add_u64 v[240:241], s[76:77], 0, v[132:133]
	s_mov_b32 m0, s23
	v_lshl_add_u64 v[242:243], s[56:57], 0, v[130:131]
	global_load_lds_dwordx4 v[240:241], off
	v_lshl_add_u64 v[240:241], s[76:77], 0, v[128:129]
	s_mov_b32 m0, s33
	s_nop 0
	global_load_lds_dwordx4 v[240:241], off
	v_lshl_add_u64 v[240:241], s[56:57], 0, v[134:135]
	s_mov_b32 m0, s2
	s_nop 0
	global_load_lds_dwordx4 v[240:241], off
	s_mov_b32 m0, s36
	s_nop 0
	global_load_lds_dwordx4 v[242:243], off
	s_waitcnt vmcnt(16)
	s_cmp_lg_u32 s99, -1
	s_cbranch_scc1 .Lvmw_950_1
	s_waitcnt vmcnt(8)
.Lvmw_950_1:
	s_waitcnt lgkmcnt(0)
	s_barrier
	s_setprio 1
	v_mfma_f32_16x16x32_f16 v[60:63], v[172:175], v[204:207], 0
	v_mfma_f32_16x16x32_f16 v[56:59], v[180:183], v[204:207], 0
	v_mfma_f32_16x16x32_f16 v[44:47], v[172:175], v[212:215], 0
	v_mfma_f32_16x16x32_f16 v[40:43], v[180:183], v[212:215], 0
	v_mfma_f32_16x16x32_f16 v[28:31], v[172:175], v[220:223], 0
	v_mfma_f32_16x16x32_f16 v[24:27], v[180:183], v[220:223], 0
	v_mfma_f32_16x16x32_f16 v[12:15], v[172:175], v[232:235], 0
	v_mfma_f32_16x16x32_f16 v[8:11], v[180:183], v[232:235], 0
	v_mfma_f32_16x16x32_f16 v[60:63], v[176:179], v[208:211], v[60:63]
	v_mfma_f32_16x16x32_f16 v[56:59], v[184:187], v[208:211], v[56:59]
	v_mfma_f32_16x16x32_f16 v[44:47], v[176:179], v[216:219], v[44:47]
	v_mfma_f32_16x16x32_f16 v[40:43], v[184:187], v[216:219], v[40:43]
	v_mfma_f32_16x16x32_f16 v[28:31], v[176:179], v[228:231], v[28:31]
	v_mfma_f32_16x16x32_f16 v[24:27], v[184:187], v[228:231], v[24:27]
	v_mfma_f32_16x16x32_f16 v[12:15], v[176:179], v[236:239], v[12:15]
	v_mfma_f32_16x16x32_f16 v[8:11], v[184:187], v[236:239], v[8:11]
	s_setprio 0
	s_setprio 1
	v_mfma_f32_16x16x32_f16 v[52:55], v[188:191], v[204:207], 0
	v_mfma_f32_16x16x32_f16 v[48:51], v[196:199], v[204:207], 0
	v_mfma_f32_16x16x32_f16 v[36:39], v[188:191], v[212:215], 0
	v_mfma_f32_16x16x32_f16 v[32:35], v[196:199], v[212:215], 0
	v_mfma_f32_16x16x32_f16 v[20:23], v[188:191], v[220:223], 0
	v_mfma_f32_16x16x32_f16 v[16:19], v[196:199], v[220:223], 0
	v_mfma_f32_16x16x32_f16 v[4:7], v[188:191], v[232:235], 0
	v_mfma_f32_16x16x32_f16 v[0:3], v[196:199], v[232:235], 0
	v_mfma_f32_16x16x32_f16 v[52:55], v[192:195], v[208:211], v[52:55]
	v_mfma_f32_16x16x32_f16 v[48:51], v[200:203], v[208:211], v[48:51]
	v_mfma_f32_16x16x32_f16 v[36:39], v[192:195], v[216:219], v[36:39]
	v_mfma_f32_16x16x32_f16 v[32:35], v[200:203], v[216:219], v[32:35]
	v_mfma_f32_16x16x32_f16 v[20:23], v[192:195], v[228:231], v[20:23]
	v_mfma_f32_16x16x32_f16 v[16:19], v[200:203], v[228:231], v[16:19]
	v_mfma_f32_16x16x32_f16 v[4:7], v[192:195], v[236:239], v[4:7]
	v_mfma_f32_16x16x32_f16 v[0:3], v[200:203], v[236:239], v[0:3]
	s_setprio 0
	s_barrier
; #define PG8_STAGE(bufoff, gbase, voff) do { _Pragma("unroll") for (int _i = 0; _i < 2; ++_i) \
;         __builtin_amdgcn_global_load_lds((const unsigned*)((const char*)(gbase) + (voff)[_i]), (PG8_LAS unsigned*)(lds + (bufoff) + ldsw + _i * 8192), 16, 0, 0); } while (0)
; #define PG8_LDA(dst, b, h) do { _Pragma("unroll") for (int m = 0; m < 4; ++m) _Pragma("unroll") for (int k = 0; k < 2; ++k) dst[m][k] = *(const PG8_LAS bf16x8*)(lds + PG8_SA(b, h) + aoff + m * 2048 + k * 1024); } while (0)
; #define PG8_LDB(dst, b, h) do { _Pragma("unroll") for (int n = 0; n < 2; ++n) _Pragma("unroll") for (int k = 0; k < 2; ++k) dst[n][k] = *(const PG8_LAS bf16x8*)(lds + PG8_SB(b, h) + boff + n * 2048 + k * 1024); } while (0)
; #define PG8_MMA(ai, bj, At, Bt) do { __builtin_amdgcn_s_setprio(1); _Pragma("unroll") for (int m = 0; m < 4; ++m) _Pragma("unroll") for (int n = 0; n < 2; ++n) _Pragma("unroll") for (int k = 0; k < 2; ++k) \
;         acc[ai][bj][m][n] = mma16<F16>(Bt[n][k], At[m][k], acc[ai][bj][m][n]); __builtin_amdgcn_s_setprio(0); } while (0)
; #define PG8_BAR __builtin_amdgcn_s_barrier()
; template <class Epi, class Sched, bool ALIGN_EPI = false, bool SP2 = false, bool F16 = false, bool TOKPERM = false>
; __device__ __forceinline__ void gemm_phase(PG8_LAS unsigned char* lds, const Gemm g, const Sched& S, const Epi& E, int wv) {
;     ...
;             PG8_LDB(B0, 0, 0); PG8_LDB(B1, 0, 1); PG8_SCHED; PG8_LDA(At, 0, 0); PG8_STAGE(PG8_SA(1, 1), a1 + hstep, voffA);
;             PG8_WAIT_V(8); PG8_WAIT_L(0); PG8_BAR; PG8_MMA(0, 0, At, B0); PG8_MMA(0, 1, At, B1); PG8_BAR; PG8_SCHED;
;             PG8_LDA(At, 0, 1); PG8_STAGE(PG8_SB(0, 0), b2, voffB); PG8_STAGE(PG8_SB(0, 1), b2 + hstep, voffB); PG8_STAGE(PG8_SA(0, 0), a2, voffA);
;             PG8_WAIT_V(8); PG8_WAIT_L(0); PG8_BAR; PG8_MMA(1, 0, At, B0); PG8_MMA(1, 1, At, B1); PG8_BAR; PG8_SCHED;
;             PG8_LDB(B0, 1, 0); PG8_LDB(B1, 1, 1); PG8_SCHED; PG8_LDA(At, 1, 0); PG8_STAGE(PG8_SA(0, 1), a2 + hstep, voffA);
;             PG8_WAIT_V(8); PG8_WAIT_L(0); PG8_BAR; PG8_MMA(0, 0, At, B0); PG8_MMA(0, 1, At, B1); PG8_BAR; PG8_SCHED;
;             PG8_LDA(At, 1, 1); PG8_STAGE(PG8_SB(1, 0), b3, voffB); PG8_STAGE(PG8_SB(1, 1), b3 + hstep, voffB); PG8_STAGE(PG8_SA(1, 0), a3, voffA);
;             PG8_WAIT_V(8); PG8_WAIT_L(0); PG8_BAR; PG8_MMA(1, 0, At, B0); PG8_MMA(1, 1, At, B1); PG8_BAR; PG8_SCHED;
	ds_read_b128 v[172:175], v163
	ds_read_b128 v[176:179], v164
	ds_read_b128 v[180:183], v165
	ds_read_b128 v[184:187], v166
	ds_read_b128 v[188:191], v167
	ds_read_b128 v[192:195], v168
	ds_read_b128 v[196:199], v169
	ds_read_b128 v[200:203], v170
	s_add_u32 s56, s56, 0x40000
	s_addc_u32 s57, s57, 0
	s_mov_b32 m0, s37
	v_lshl_add_u64 v[244:245], s[56:57], 0, v[134:135]
	ds_read_b128 v[204:207], v153 offset:32768
	ds_read_b128 v[208:211], v153 offset:33792
	ds_read_b128 v[212:215], v153 offset:34816
	ds_read_b128 v[216:219], v153 offset:35840
	ds_read_b128 v[220:223], v153 offset:36864
	ds_read_b128 v[228:231], v153 offset:37888
	ds_read_b128 v[232:235], v153 offset:38912
	ds_read_b128 v[236:239], v153 offset:39936
	global_load_lds_dwordx4 v[244:245], off
	v_lshl_add_u64 v[244:245], s[56:57], 0, v[130:131]
	s_mov_b32 m0, s44
	s_nop 0
	global_load_lds_dwordx4 v[244:245], off
	s_waitcnt vmcnt(8)
	s_waitcnt lgkmcnt(0)
	s_barrier
	s_setprio 1
	v_mfma_f32_16x16x32_f16 v[124:127], v[172:175], v[204:207], v[124:127]
	v_mfma_f32_16x16x32_f16 v[116:119], v[180:183], v[204:207], v[116:119]
	v_mfma_f32_16x16x32_f16 v[108:111], v[172:175], v[212:215], v[108:111]
	v_mfma_f32_16x16x32_f16 v[104:107], v[180:183], v[212:215], v[104:107]
	v_mfma_f32_16x16x32_f16 v[92:95], v[172:175], v[220:223], v[92:95]
	v_mfma_f32_16x16x32_f16 v[88:91], v[180:183], v[220:223], v[88:91]
	v_mfma_f32_16x16x32_f16 v[76:79], v[172:175], v[232:235], v[76:79]
	v_mfma_f32_16x16x32_f16 v[72:75], v[180:183], v[232:235], v[72:75]
	v_mfma_f32_16x16x32_f16 v[124:127], v[176:179], v[208:211], v[124:127]
	v_mfma_f32_16x16x32_f16 v[116:119], v[184:187], v[208:211], v[116:119]
	v_mfma_f32_16x16x32_f16 v[108:111], v[176:179], v[216:219], v[108:111]
	v_mfma_f32_16x16x32_f16 v[104:107], v[184:187], v[216:219], v[104:107]
	v_mfma_f32_16x16x32_f16 v[92:95], v[176:179], v[228:231], v[92:95]
	v_mfma_f32_16x16x32_f16 v[88:91], v[184:187], v[228:231], v[88:91]
	v_mfma_f32_16x16x32_f16 v[76:79], v[176:179], v[236:239], v[76:79]
	v_mfma_f32_16x16x32_f16 v[72:75], v[184:187], v[236:239], v[72:75]
	s_setprio 0
	s_setprio 1
	v_mfma_f32_16x16x32_f16 v[120:123], v[188:191], v[204:207], v[120:123]
	v_mfma_f32_16x16x32_f16 v[112:115], v[196:199], v[204:207], v[112:115]
	v_mfma_f32_16x16x32_f16 v[100:103], v[188:191], v[212:215], v[100:103]
	v_mfma_f32_16x16x32_f16 v[96:99], v[196:199], v[212:215], v[96:99]
	v_mfma_f32_16x16x32_f16 v[84:87], v[188:191], v[220:223], v[84:87]
	v_mfma_f32_16x16x32_f16 v[80:83], v[196:199], v[220:223], v[80:83]
	v_mfma_f32_16x16x32_f16 v[68:71], v[188:191], v[232:235], v[68:71]
	v_mfma_f32_16x16x32_f16 v[64:67], v[196:199], v[232:235], v[64:67]
	v_mfma_f32_16x16x32_f16 v[120:123], v[192:195], v[208:211], v[120:123]
	v_mfma_f32_16x16x32_f16 v[112:115], v[200:203], v[208:211], v[112:115]
	v_mfma_f32_16x16x32_f16 v[100:103], v[192:195], v[216:219], v[100:103]
	v_mfma_f32_16x16x32_f16 v[96:99], v[200:203], v[216:219], v[96:99]
	v_mfma_f32_16x16x32_f16 v[84:87], v[192:195], v[228:231], v[84:87]
	v_mfma_f32_16x16x32_f16 v[80:83], v[200:203], v[228:231], v[80:83]
	v_mfma_f32_16x16x32_f16 v[68:71], v[192:195], v[236:239], v[68:71]
	v_mfma_f32_16x16x32_f16 v[64:67], v[200:203], v[236:239], v[64:67]
	s_setprio 0
	s_barrier
	s_mov_b32 m0, s58
	v_lshl_add_u64 v[148:149], v[148:149], 0, s[16:17]
	s_add_u32 s12, s12, 0x40080
	ds_read_b128 v[204:207], v153 offset:49152
	ds_read_b128 v[208:211], v153 offset:50176
	ds_read_b128 v[212:215], v153 offset:51200
	ds_read_b128 v[216:219], v153 offset:52224
	ds_read_b128 v[220:223], v153 offset:53248
	ds_read_b128 v[228:231], v153 offset:54272
	ds_read_b128 v[232:235], v153 offset:55296
	ds_read_b128 v[236:239], v153 offset:56320
	global_load_lds_dwordx4 v[148:149], off
	v_lshl_add_u64 v[148:149], v[224:225], 0, s[16:17]
	s_mov_b32 m0, s59
	s_addc_u32 s13, s13, 0
	global_load_lds_dwordx4 v[148:149], off
	v_lshl_add_u64 v[148:149], s[12:13], 0, v[132:133]
	s_mov_b32 m0, s62
	s_nop 0
	global_load_lds_dwordx4 v[148:149], off
	v_lshl_add_u64 v[148:149], s[12:13], 0, v[128:129]
	s_mov_b32 m0, s63
	s_nop 0
	global_load_lds_dwordx4 v[148:149], off
	v_lshl_add_u64 v[148:149], v[240:241], 0, s[16:17]
	s_mov_b32 m0, s60
	s_nop 0
	global_load_lds_dwordx4 v[148:149], off
	v_lshl_add_u64 v[148:149], v[242:243], 0, s[16:17]
	s_mov_b32 m0, s61
	s_nop 0
	global_load_lds_dwordx4 v[148:149], off
	s_waitcnt vmcnt(8)
	s_waitcnt lgkmcnt(0)
	s_barrier
	s_setprio 1
	v_mfma_f32_16x16x32_f16 v[60:63], v[172:175], v[204:207], v[60:63]
	v_mfma_f32_16x16x32_f16 v[56:59], v[180:183], v[204:207], v[56:59]
	v_mfma_f32_16x16x32_f16 v[44:47], v[172:175], v[212:215], v[44:47]
	v_mfma_f32_16x16x32_f16 v[40:43], v[180:183], v[212:215], v[40:43]
	v_mfma_f32_16x16x32_f16 v[28:31], v[172:175], v[220:223], v[28:31]
	v_mfma_f32_16x16x32_f16 v[24:27], v[180:183], v[220:223], v[24:27]
	v_mfma_f32_16x16x32_f16 v[12:15], v[172:175], v[232:235], v[12:15]
	v_mfma_f32_16x16x32_f16 v[8:11], v[180:183], v[232:235], v[8:11]
	v_mfma_f32_16x16x32_f16 v[60:63], v[176:179], v[208:211], v[60:63]
	v_mfma_f32_16x16x32_f16 v[56:59], v[184:187], v[208:211], v[56:59]
	v_mfma_f32_16x16x32_f16 v[44:47], v[176:179], v[216:219], v[44:47]
	v_mfma_f32_16x16x32_f16 v[40:43], v[184:187], v[216:219], v[40:43]
	v_mfma_f32_16x16x32_f16 v[28:31], v[176:179], v[228:231], v[28:31]
	v_mfma_f32_16x16x32_f16 v[24:27], v[184:187], v[228:231], v[24:27]
	v_mfma_f32_16x16x32_f16 v[12:15], v[176:179], v[236:239], v[12:15]
	v_mfma_f32_16x16x32_f16 v[8:11], v[184:187], v[236:239], v[8:11]
	s_setprio 0
	s_setprio 1
	v_mfma_f32_16x16x32_f16 v[52:55], v[188:191], v[204:207], v[52:55]
	v_mfma_f32_16x16x32_f16 v[48:51], v[196:199], v[204:207], v[48:51]
	v_mfma_f32_16x16x32_f16 v[36:39], v[188:191], v[212:215], v[36:39]
	v_mfma_f32_16x16x32_f16 v[32:35], v[196:199], v[212:215], v[32:35]
	v_mfma_f32_16x16x32_f16 v[20:23], v[188:191], v[220:223], v[20:23]
	v_mfma_f32_16x16x32_f16 v[16:19], v[196:199], v[220:223], v[16:19]
	v_mfma_f32_16x16x32_f16 v[4:7], v[188:191], v[232:235], v[4:7]
	v_mfma_f32_16x16x32_f16 v[0:3], v[196:199], v[232:235], v[0:3]
	v_mfma_f32_16x16x32_f16 v[52:55], v[192:195], v[208:211], v[52:55]
	v_mfma_f32_16x16x32_f16 v[48:51], v[200:203], v[208:211], v[48:51]
	v_mfma_f32_16x16x32_f16 v[36:39], v[192:195], v[216:219], v[36:39]
	v_mfma_f32_16x16x32_f16 v[32:35], v[200:203], v[216:219], v[32:35]
	v_mfma_f32_16x16x32_f16 v[20:23], v[192:195], v[228:231], v[20:23]
	v_mfma_f32_16x16x32_f16 v[16:19], v[200:203], v[228:231], v[16:19]
	v_mfma_f32_16x16x32_f16 v[4:7], v[192:195], v[236:239], v[4:7]
	v_mfma_f32_16x16x32_f16 v[0:3], v[200:203], v[236:239], v[0:3]
	s_setprio 0
	s_barrier
	s_add_i32 s74, s74, 2
	s_add_u32 s10, s10, 0x100
	s_addc_u32 s11, s11, 0
	s_add_u32 s72, s72, 0x100
	s_addc_u32 s73, s73, 0
	s_cmp_gt_u32 s74, 13
; #define PG8_STAGE(bufoff, gbase, voff) do { _Pragma("unroll") for (int _i = 0; _i < 2; ++_i) \
;         __builtin_amdgcn_global_load_lds((const unsigned*)((const char*)(gbase) + (voff)[_i]), (PG8_LAS unsigned*)(lds + (bufoff) + ldsw + _i * 8192), 16, 0, 0); } while (0)
; #define PG8_WAIT_V(n) asm volatile("s_waitcnt vmcnt(" #n ")" ::: "memory")
; #define PG8_WAIT_L(n) asm volatile("s_waitcnt lgkmcnt(" #n ")" ::: "memory")
; template <class Epi, class Sched, bool ALIGN_EPI = false, bool SP2 = false, bool F16 = false, bool TOKPERM = false>
; __device__ __forceinline__ void gemm_phase(PG8_LAS unsigned char* lds, const Gemm g, const Sched& S, const Epi& E, int wv) {
;     ...
;         const bool has_next = S.next(ui + 1, nxt);
;         const char* nA = has_next ? (const char*)g.A + (size_t)nxt.pm * tstep : cA; const char* nB = has_next ? (const char*)g.Bt + (size_t)nxt.pn * tstep : cB;
;         for (int t = 0; t < nt; t += 2) {
;             const bool last = (t == nt - 2);
;             const char* a1 = cA + (size_t)(t + 1) * kstep;
;             const char* a2 = last ? nA : cA + (size_t)(t + 2) * kstep; const char* b2 = last ? nB : cB + (size_t)(t + 2) * kstep;
;             const char* a3 = a2 + kstep; const char* b3 = b2 + kstep;
;             if (last && has_next) S.a_ready(nxt);
;             if constexpr (SP2) {
;             PG8_LDB(B0, 0, 0); PG8_LDB(B1, 0, 1); PG8_SCHED; PG8_LDA(At, 0, 0); PG8_STAGE(PG8_SA(1, 1), a1 + hstep, voffA);
;             PG8_WAIT_V(8); PG8_WAIT_L(0); PG8_BAR; PG8_MMA(0, 0, At, B0); PG8_MMA(0, 1, At, B1); PG8_BAR; PG8_SCHED;
;             PG8_LDA(At, 0, 1); PG8_STAGE(PG8_SB(0, 0), b2, voffB); PG8_STAGE(PG8_SB(0, 1), b2 + hstep, voffB); PG8_STAGE(PG8_SA(0, 0), a2, voffA);
;             PG8_WAIT_V(8); PG8_WAIT_L(0); PG8_BAR; PG8_MMA(1, 0, At, B0); PG8_MMA(1, 1, At, B1); PG8_BAR; PG8_SCHED;
;             PG8_LDB(B0, 1, 0); PG8_LDB(B1, 1, 1); PG8_SCHED; PG8_LDA(At, 1, 0); PG8_STAGE(PG8_SA(0, 1), a2 + hstep, voffA);
;             PG8_WAIT_V(8); PG8_WAIT_L(0); PG8_BAR; PG8_MMA(0, 0, At, B0); PG8_MMA(0, 1, At, B1); PG8_BAR; PG8_SCHED;
;             PG8_LDA(At, 1, 1); PG8_STAGE(PG8_SB(1, 0), b3, voffB); PG8_STAGE(PG8_SB(1, 1), b3 + hstep, voffB); PG8_STAGE(PG8_SA(1, 0), a3, voffA);
;             PG8_WAIT_V(8); PG8_WAIT_L(0); PG8_BAR; PG8_MMA(1, 0, At, B0); PG8_MMA(1, 1, At, B1); PG8_BAR; PG8_SCHED;
.LBB0_950:
	ds_read_b128 v[172:175], v155
	ds_read_b128 v[176:179], v156
	ds_read_b128 v[180:183], v157
	ds_read_b128 v[184:187], v158
	ds_read_b128 v[188:191], v159
	ds_read_b128 v[192:195], v160
	ds_read_b128 v[196:199], v161
	ds_read_b128 v[200:203], v162
	s_add_u32 s12, s10, 0xfffc0080
	s_addc_u32 s13, s11, -1
	s_cmp_eq_u32 s74, 12
	s_cselect_b32 s57, s51, s13
	s_cselect_b32 s56, s70, s12
	s_cselect_b32 s13, s49, s73
	s_cselect_b32 s12, s71, s72
	s_mov_b32 m0, s66
	v_lshl_add_u64 v[148:149], s[10:11], 0, v[140:141]
	ds_read_b128 v[204:207], v153
	ds_read_b128 v[208:211], v153 offset:1024
	ds_read_b128 v[212:215], v153 offset:2048
	ds_read_b128 v[216:219], v153 offset:3072
	ds_read_b128 v[220:223], v153 offset:4096
	ds_read_b128 v[228:231], v153 offset:5120
	ds_read_b128 v[232:235], v153 offset:6144
	ds_read_b128 v[236:239], v153 offset:7168
	global_load_lds_dwordx4 v[148:149], off
	v_lshl_add_u64 v[148:149], s[10:11], 0, v[142:143]
	s_mov_b32 m0, s67
	s_nop 0
	global_load_lds_dwordx4 v[148:149], off
	s_waitcnt vmcnt(8)
	s_waitcnt lgkmcnt(0)
	s_barrier
	s_setprio 1
	v_mfma_f32_16x16x32_f16 v[124:127], v[172:175], v[204:207], v[124:127]
	v_mfma_f32_16x16x32_f16 v[116:119], v[180:183], v[204:207], v[116:119]
	v_mfma_f32_16x16x32_f16 v[108:111], v[172:175], v[212:215], v[108:111]
	v_mfma_f32_16x16x32_f16 v[104:107], v[180:183], v[212:215], v[104:107]
	v_mfma_f32_16x16x32_f16 v[92:95], v[172:175], v[220:223], v[92:95]
	v_mfma_f32_16x16x32_f16 v[88:91], v[180:183], v[220:223], v[88:91]
	v_mfma_f32_16x16x32_f16 v[76:79], v[172:175], v[232:235], v[76:79]
	v_mfma_f32_16x16x32_f16 v[72:75], v[180:183], v[232:235], v[72:75]
	v_mfma_f32_16x16x32_f16 v[124:127], v[176:179], v[208:211], v[124:127]
	v_mfma_f32_16x16x32_f16 v[116:119], v[184:187], v[208:211], v[116:119]
	v_mfma_f32_16x16x32_f16 v[108:111], v[176:179], v[216:219], v[108:111]
	v_mfma_f32_16x16x32_f16 v[104:107], v[184:187], v[216:219], v[104:107]
	v_mfma_f32_16x16x32_f16 v[92:95], v[176:179], v[228:231], v[92:95]
	v_mfma_f32_16x16x32_f16 v[88:91], v[184:187], v[228:231], v[88:91]
	v_mfma_f32_16x16x32_f16 v[76:79], v[176:179], v[236:239], v[76:79]
	v_mfma_f32_16x16x32_f16 v[72:75], v[184:187], v[236:239], v[72:75]
	s_setprio 0
	s_setprio 1
	v_mfma_f32_16x16x32_f16 v[120:123], v[188:191], v[204:207], v[120:123]
	v_mfma_f32_16x16x32_f16 v[112:115], v[196:199], v[204:207], v[112:115]
	v_mfma_f32_16x16x32_f16 v[100:103], v[188:191], v[212:215], v[100:103]
	v_mfma_f32_16x16x32_f16 v[96:99], v[196:199], v[212:215], v[96:99]
	v_mfma_f32_16x16x32_f16 v[84:87], v[188:191], v[220:223], v[84:87]
	v_mfma_f32_16x16x32_f16 v[80:83], v[196:199], v[220:223], v[80:83]
	v_mfma_f32_16x16x32_f16 v[68:71], v[188:191], v[232:235], v[68:71]
	v_mfma_f32_16x16x32_f16 v[64:67], v[196:199], v[232:235], v[64:67]
	v_mfma_f32_16x16x32_f16 v[120:123], v[192:195], v[208:211], v[120:123]
	v_mfma_f32_16x16x32_f16 v[112:115], v[200:203], v[208:211], v[112:115]
	v_mfma_f32_16x16x32_f16 v[100:103], v[192:195], v[216:219], v[100:103]
	v_mfma_f32_16x16x32_f16 v[96:99], v[200:203], v[216:219], v[96:99]
	v_mfma_f32_16x16x32_f16 v[84:87], v[192:195], v[228:231], v[84:87]
	v_mfma_f32_16x16x32_f16 v[80:83], v[200:203], v[228:231], v[80:83]
	v_mfma_f32_16x16x32_f16 v[68:71], v[192:195], v[236:239], v[68:71]
	v_mfma_f32_16x16x32_f16 v[64:67], v[200:203], v[236:239], v[64:67]
	s_setprio 0
	s_barrier
	s_mov_b32 m0, s5
	v_lshl_add_u64 v[148:149], s[12:13], 0, v[132:133]
	s_add_u32 s76, s12, 0x40000
	ds_read_b128 v[204:207], v153 offset:16384
	ds_read_b128 v[208:211], v153 offset:17408
	ds_read_b128 v[212:215], v153 offset:18432
	ds_read_b128 v[216:219], v153 offset:19456
	ds_read_b128 v[220:223], v153 offset:20480
	ds_read_b128 v[228:231], v153 offset:21504
	ds_read_b128 v[232:235], v153 offset:22528
	ds_read_b128 v[236:239], v153 offset:23552
	global_load_lds_dwordx4 v[148:149], off
	v_lshl_add_u64 v[224:225], s[12:13], 0, v[128:129]
	s_mov_b32 m0, s21
	s_addc_u32 s77, s13, 0
	global_load_lds_dwordx4 v[224:225], off
	v_lshl_add_u64 v[240:241], s[76:77], 0, v[132:133]
	s_mov_b32 m0, s23
	v_lshl_add_u64 v[242:243], s[56:57], 0, v[130:131]
	global_load_lds_dwordx4 v[240:241], off
	v_lshl_add_u64 v[240:241], s[76:77], 0, v[128:129]
	s_mov_b32 m0, s33
	s_nop 0
	global_load_lds_dwordx4 v[240:241], off
	v_lshl_add_u64 v[240:241], s[56:57], 0, v[134:135]
	s_mov_b32 m0, s2
	s_nop 0
	global_load_lds_dwordx4 v[240:241], off
	s_mov_b32 m0, s36
	s_nop 0
	global_load_lds_dwordx4 v[242:243], off
	s_waitcnt vmcnt(8)
	s_waitcnt lgkmcnt(0)
	s_barrier
	s_setprio 1
	v_mfma_f32_16x16x32_f16 v[60:63], v[172:175], v[204:207], v[60:63]
	v_mfma_f32_16x16x32_f16 v[56:59], v[180:183], v[204:207], v[56:59]
	v_mfma_f32_16x16x32_f16 v[44:47], v[172:175], v[212:215], v[44:47]
	v_mfma_f32_16x16x32_f16 v[40:43], v[180:183], v[212:215], v[40:43]
	v_mfma_f32_16x16x32_f16 v[28:31], v[172:175], v[220:223], v[28:31]
	v_mfma_f32_16x16x32_f16 v[24:27], v[180:183], v[220:223], v[24:27]
	v_mfma_f32_16x16x32_f16 v[12:15], v[172:175], v[232:235], v[12:15]
	v_mfma_f32_16x16x32_f16 v[8:11], v[180:183], v[232:235], v[8:11]
	v_mfma_f32_16x16x32_f16 v[60:63], v[176:179], v[208:211], v[60:63]
	v_mfma_f32_16x16x32_f16 v[56:59], v[184:187], v[208:211], v[56:59]
	v_mfma_f32_16x16x32_f16 v[44:47], v[176:179], v[216:219], v[44:47]
	v_mfma_f32_16x16x32_f16 v[40:43], v[184:187], v[216:219], v[40:43]
	v_mfma_f32_16x16x32_f16 v[28:31], v[176:179], v[228:231], v[28:31]
	v_mfma_f32_16x16x32_f16 v[24:27], v[184:187], v[228:231], v[24:27]
	v_mfma_f32_16x16x32_f16 v[12:15], v[176:179], v[236:239], v[12:15]
	v_mfma_f32_16x16x32_f16 v[8:11], v[184:187], v[236:239], v[8:11]
	s_setprio 0
	s_setprio 1
	v_mfma_f32_16x16x32_f16 v[52:55], v[188:191], v[204:207], v[52:55]
	v_mfma_f32_16x16x32_f16 v[48:51], v[196:199], v[204:207], v[48:51]
	v_mfma_f32_16x16x32_f16 v[36:39], v[188:191], v[212:215], v[36:39]
	v_mfma_f32_16x16x32_f16 v[32:35], v[196:199], v[212:215], v[32:35]
	v_mfma_f32_16x16x32_f16 v[20:23], v[188:191], v[220:223], v[20:23]
	v_mfma_f32_16x16x32_f16 v[16:19], v[196:199], v[220:223], v[16:19]
	v_mfma_f32_16x16x32_f16 v[4:7], v[188:191], v[232:235], v[4:7]
	v_mfma_f32_16x16x32_f16 v[0:3], v[196:199], v[232:235], v[0:3]
	v_mfma_f32_16x16x32_f16 v[52:55], v[192:195], v[208:211], v[52:55]
	v_mfma_f32_16x16x32_f16 v[48:51], v[200:203], v[208:211], v[48:51]
	v_mfma_f32_16x16x32_f16 v[36:39], v[192:195], v[216:219], v[36:39]
	v_mfma_f32_16x16x32_f16 v[32:35], v[200:203], v[216:219], v[32:35]
	v_mfma_f32_16x16x32_f16 v[20:23], v[192:195], v[228:231], v[20:23]
	v_mfma_f32_16x16x32_f16 v[16:19], v[200:203], v[228:231], v[16:19]
	v_mfma_f32_16x16x32_f16 v[4:7], v[192:195], v[236:239], v[4:7]
	v_mfma_f32_16x16x32_f16 v[0:3], v[200:203], v[236:239], v[0:3]
	s_setprio 0
	s_barrier
; #define PG8_STAGE(bufoff, gbase, voff) do { _Pragma("unroll") for (int _i = 0; _i < 2; ++_i) \
;         __builtin_amdgcn_global_load_lds((const unsigned*)((const char*)(gbase) + (voff)[_i]), (PG8_LAS unsigned*)(lds + (bufoff) + ldsw + _i * 8192), 16, 0, 0); } while (0)
; #define PG8_LDA(dst, b, h) do { _Pragma("unroll") for (int m = 0; m < 4; ++m) _Pragma("unroll") for (int k = 0; k < 2; ++k) dst[m][k] = *(const PG8_LAS bf16x8*)(lds + PG8_SA(b, h) + aoff + m * 2048 + k * 1024); } while (0)
; #define PG8_LDB(dst, b, h) do { _Pragma("unroll") for (int n = 0; n < 2; ++n) _Pragma("unroll") for (int k = 0; k < 2; ++k) dst[n][k] = *(const PG8_LAS bf16x8*)(lds + PG8_SB(b, h) + boff + n * 2048 + k * 1024); } while (0)
; #define PG8_MMA(ai, bj, At, Bt) do { __builtin_amdgcn_s_setprio(1); _Pragma("unroll") for (int m = 0; m < 4; ++m) _Pragma("unroll") for (int n = 0; n < 2; ++n) _Pragma("unroll") for (int k = 0; k < 2; ++k) \
;         acc[ai][bj][m][n] = mma16<F16>(Bt[n][k], At[m][k], acc[ai][bj][m][n]); __builtin_amdgcn_s_setprio(0); } while (0)
; #define PG8_BAR __builtin_amdgcn_s_barrier()
; template <class Epi, class Sched, bool ALIGN_EPI = false, bool SP2 = false, bool F16 = false, bool TOKPERM = false>
; __device__ __forceinline__ void gemm_phase(PG8_LAS unsigned char* lds, const Gemm g, const Sched& S, const Epi& E, int wv) {
;     ...
;             PG8_LDB(B0, 0, 0); PG8_LDB(B1, 0, 1); PG8_SCHED; PG8_LDA(At, 0, 0); PG8_STAGE(PG8_SA(1, 1), a1 + hstep, voffA);
;             PG8_WAIT_V(8); PG8_WAIT_L(0); PG8_BAR; PG8_MMA(0, 0, At, B0); PG8_MMA(0, 1, At, B1); PG8_BAR; PG8_SCHED;
;             PG8_LDA(At, 0, 1); PG8_STAGE(PG8_SB(0, 0), b2, voffB); PG8_STAGE(PG8_SB(0, 1), b2 + hstep, voffB); PG8_STAGE(PG8_SA(0, 0), a2, voffA);
;             PG8_WAIT_V(8); PG8_WAIT_L(0); PG8_BAR; PG8_MMA(1, 0, At, B0); PG8_MMA(1, 1, At, B1); PG8_BAR; PG8_SCHED;
;             PG8_LDB(B0, 1, 0); PG8_LDB(B1, 1, 1); PG8_SCHED; PG8_LDA(At, 1, 0); PG8_STAGE(PG8_SA(0, 1), a2 + hstep, voffA);
;             PG8_WAIT_V(8); PG8_WAIT_L(0); PG8_BAR; PG8_MMA(0, 0, At, B0); PG8_MMA(0, 1, At, B1); PG8_BAR; PG8_SCHED;
;             PG8_LDA(At, 1, 1); PG8_STAGE(PG8_SB(1, 0), b3, voffB); PG8_STAGE(PG8_SB(1, 1), b3 + hstep, voffB); PG8_STAGE(PG8_SA(1, 0), a3, voffA);
;             PG8_WAIT_V(8); PG8_WAIT_L(0); PG8_BAR; PG8_MMA(1, 0, At, B0); PG8_MMA(1, 1, At, B1); PG8_BAR; PG8_SCHED;
	ds_read_b128 v[172:175], v163
	ds_read_b128 v[176:179], v164
	ds_read_b128 v[180:183], v165
	ds_read_b128 v[184:187], v166
	ds_read_b128 v[188:191], v167
	ds_read_b128 v[192:195], v168
	ds_read_b128 v[196:199], v169
	ds_read_b128 v[200:203], v170
	s_add_u32 s56, s56, 0x40000
	s_addc_u32 s57, s57, 0
	s_mov_b32 m0, s37
	v_lshl_add_u64 v[244:245], s[56:57], 0, v[134:135]
	ds_read_b128 v[204:207], v153 offset:32768
	ds_read_b128 v[208:211], v153 offset:33792
	ds_read_b128 v[212:215], v153 offset:34816
	ds_read_b128 v[216:219], v153 offset:35840
	ds_read_b128 v[220:223], v153 offset:36864
	ds_read_b128 v[228:231], v153 offset:37888
	ds_read_b128 v[232:235], v153 offset:38912
	ds_read_b128 v[236:239], v153 offset:39936
	global_load_lds_dwordx4 v[244:245], off
	v_lshl_add_u64 v[244:245], s[56:57], 0, v[130:131]
	s_mov_b32 m0, s44
	s_nop 0
	global_load_lds_dwordx4 v[244:245], off
	s_waitcnt vmcnt(8)
	s_waitcnt lgkmcnt(0)
	s_barrier
	s_setprio 1
	v_mfma_f32_16x16x32_f16 v[124:127], v[172:175], v[204:207], v[124:127]
	v_mfma_f32_16x16x32_f16 v[116:119], v[180:183], v[204:207], v[116:119]
	v_mfma_f32_16x16x32_f16 v[108:111], v[172:175], v[212:215], v[108:111]
	v_mfma_f32_16x16x32_f16 v[104:107], v[180:183], v[212:215], v[104:107]
	v_mfma_f32_16x16x32_f16 v[92:95], v[172:175], v[220:223], v[92:95]
	v_mfma_f32_16x16x32_f16 v[88:91], v[180:183], v[220:223], v[88:91]
	v_mfma_f32_16x16x32_f16 v[76:79], v[172:175], v[232:235], v[76:79]
	v_mfma_f32_16x16x32_f16 v[72:75], v[180:183], v[232:235], v[72:75]
	v_mfma_f32_16x16x32_f16 v[124:127], v[176:179], v[208:211], v[124:127]
	v_mfma_f32_16x16x32_f16 v[116:119], v[184:187], v[208:211], v[116:119]
	v_mfma_f32_16x16x32_f16 v[108:111], v[176:179], v[216:219], v[108:111]
	v_mfma_f32_16x16x32_f16 v[104:107], v[184:187], v[216:219], v[104:107]
	v_mfma_f32_16x16x32_f16 v[92:95], v[176:179], v[228:231], v[92:95]
	v_mfma_f32_16x16x32_f16 v[88:91], v[184:187], v[228:231], v[88:91]
	v_mfma_f32_16x16x32_f16 v[76:79], v[176:179], v[236:239], v[76:79]
	v_mfma_f32_16x16x32_f16 v[72:75], v[184:187], v[236:239], v[72:75]
	s_setprio 0
	s_setprio 1
	v_mfma_f32_16x16x32_f16 v[120:123], v[188:191], v[204:207], v[120:123]
	v_mfma_f32_16x16x32_f16 v[112:115], v[196:199], v[204:207], v[112:115]
	v_mfma_f32_16x16x32_f16 v[100:103], v[188:191], v[212:215], v[100:103]
	v_mfma_f32_16x16x32_f16 v[96:99], v[196:199], v[212:215], v[96:99]
	v_mfma_f32_16x16x32_f16 v[84:87], v[188:191], v[220:223], v[84:87]
	v_mfma_f32_16x16x32_f16 v[80:83], v[196:199], v[220:223], v[80:83]
	v_mfma_f32_16x16x32_f16 v[68:71], v[188:191], v[232:235], v[68:71]
	v_mfma_f32_16x16x32_f16 v[64:67], v[196:199], v[232:235], v[64:67]
	v_mfma_f32_16x16x32_f16 v[120:123], v[192:195], v[208:211], v[120:123]
	v_mfma_f32_16x16x32_f16 v[112:115], v[200:203], v[208:211], v[112:115]
	v_mfma_f32_16x16x32_f16 v[100:103], v[192:195], v[216:219], v[100:103]
	v_mfma_f32_16x16x32_f16 v[96:99], v[200:203], v[216:219], v[96:99]
	v_mfma_f32_16x16x32_f16 v[84:87], v[192:195], v[228:231], v[84:87]
	v_mfma_f32_16x16x32_f16 v[80:83], v[200:203], v[228:231], v[80:83]
	v_mfma_f32_16x16x32_f16 v[68:71], v[192:195], v[236:239], v[68:71]
	v_mfma_f32_16x16x32_f16 v[64:67], v[200:203], v[236:239], v[64:67]
	s_setprio 0
	s_barrier
	s_mov_b32 m0, s58
	v_lshl_add_u64 v[148:149], v[148:149], 0, s[16:17]
	s_add_u32 s12, s12, 0x40080
	ds_read_b128 v[204:207], v153 offset:49152
	ds_read_b128 v[208:211], v153 offset:50176
	ds_read_b128 v[212:215], v153 offset:51200
	ds_read_b128 v[216:219], v153 offset:52224
	ds_read_b128 v[220:223], v153 offset:53248
	ds_read_b128 v[228:231], v153 offset:54272
	ds_read_b128 v[232:235], v153 offset:55296
	ds_read_b128 v[236:239], v153 offset:56320
	global_load_lds_dwordx4 v[148:149], off
	v_lshl_add_u64 v[148:149], v[224:225], 0, s[16:17]
	s_mov_b32 m0, s59
	s_addc_u32 s13, s13, 0
	global_load_lds_dwordx4 v[148:149], off
	v_lshl_add_u64 v[148:149], s[12:13], 0, v[132:133]
	s_mov_b32 m0, s62
	s_nop 0
	global_load_lds_dwordx4 v[148:149], off
	v_lshl_add_u64 v[148:149], s[12:13], 0, v[128:129]
	s_mov_b32 m0, s63
	s_nop 0
	global_load_lds_dwordx4 v[148:149], off
	v_lshl_add_u64 v[148:149], v[240:241], 0, s[16:17]
	s_mov_b32 m0, s60
	s_nop 0
	global_load_lds_dwordx4 v[148:149], off
	v_lshl_add_u64 v[148:149], v[242:243], 0, s[16:17]
	s_mov_b32 m0, s61
	s_nop 0
	global_load_lds_dwordx4 v[148:149], off
	s_waitcnt vmcnt(8)
	s_waitcnt lgkmcnt(0)
	s_barrier
	s_setprio 1
	v_mfma_f32_16x16x32_f16 v[60:63], v[172:175], v[204:207], v[60:63]
	v_mfma_f32_16x16x32_f16 v[56:59], v[180:183], v[204:207], v[56:59]
	v_mfma_f32_16x16x32_f16 v[44:47], v[172:175], v[212:215], v[44:47]
	v_mfma_f32_16x16x32_f16 v[40:43], v[180:183], v[212:215], v[40:43]
	v_mfma_f32_16x16x32_f16 v[28:31], v[172:175], v[220:223], v[28:31]
	v_mfma_f32_16x16x32_f16 v[24:27], v[180:183], v[220:223], v[24:27]
	v_mfma_f32_16x16x32_f16 v[12:15], v[172:175], v[232:235], v[12:15]
	v_mfma_f32_16x16x32_f16 v[8:11], v[180:183], v[232:235], v[8:11]
	v_mfma_f32_16x16x32_f16 v[60:63], v[176:179], v[208:211], v[60:63]
	v_mfma_f32_16x16x32_f16 v[56:59], v[184:187], v[208:211], v[56:59]
	v_mfma_f32_16x16x32_f16 v[44:47], v[176:179], v[216:219], v[44:47]
	v_mfma_f32_16x16x32_f16 v[40:43], v[184:187], v[216:219], v[40:43]
	v_mfma_f32_16x16x32_f16 v[28:31], v[176:179], v[228:231], v[28:31]
	v_mfma_f32_16x16x32_f16 v[24:27], v[184:187], v[228:231], v[24:27]
	v_mfma_f32_16x16x32_f16 v[12:15], v[176:179], v[236:239], v[12:15]
	v_mfma_f32_16x16x32_f16 v[8:11], v[184:187], v[236:239], v[8:11]
	s_setprio 0
	s_setprio 1
	v_mfma_f32_16x16x32_f16 v[52:55], v[188:191], v[204:207], v[52:55]
	v_mfma_f32_16x16x32_f16 v[48:51], v[196:199], v[204:207], v[48:51]
	v_mfma_f32_16x16x32_f16 v[36:39], v[188:191], v[212:215], v[36:39]
	v_mfma_f32_16x16x32_f16 v[32:35], v[196:199], v[212:215], v[32:35]
	v_mfma_f32_16x16x32_f16 v[20:23], v[188:191], v[220:223], v[20:23]
	v_mfma_f32_16x16x32_f16 v[16:19], v[196:199], v[220:223], v[16:19]
	v_mfma_f32_16x16x32_f16 v[4:7], v[188:191], v[232:235], v[4:7]
	v_mfma_f32_16x16x32_f16 v[0:3], v[196:199], v[232:235], v[0:3]
	v_mfma_f32_16x16x32_f16 v[52:55], v[192:195], v[208:211], v[52:55]
	v_mfma_f32_16x16x32_f16 v[48:51], v[200:203], v[208:211], v[48:51]
	v_mfma_f32_16x16x32_f16 v[36:39], v[192:195], v[216:219], v[36:39]
	v_mfma_f32_16x16x32_f16 v[32:35], v[200:203], v[216:219], v[32:35]
	v_mfma_f32_16x16x32_f16 v[20:23], v[192:195], v[228:231], v[20:23]
	v_mfma_f32_16x16x32_f16 v[16:19], v[200:203], v[228:231], v[16:19]
	v_mfma_f32_16x16x32_f16 v[4:7], v[192:195], v[236:239], v[4:7]
	v_mfma_f32_16x16x32_f16 v[0:3], v[200:203], v[236:239], v[0:3]
	s_setprio 0
	s_barrier
	s_add_i32 s74, s74, 2
	s_add_u32 s10, s10, 0x100
	s_addc_u32 s11, s11, 0
	s_add_u32 s72, s72, 0x100
	s_addc_u32 s73, s73, 0
	s_cmp_gt_u32 s74, 13
	s_cbranch_scc0 .LBB0_950
	s_and_b64 vcc, exec, s[18:19]
	s_cbranch_vccz .LBB0_953
	s_barrier

; #define PG8_STAGE(bufoff, gbase, voff) do { _Pragma("unroll") for (int _i = 0; _i < 2; ++_i) \
;         __builtin_amdgcn_global_load_lds((const unsigned*)((const char*)(gbase) + (voff)[_i]), (PG8_LAS unsigned*)(lds + (bufoff) + ldsw + _i * 8192), 16, 0, 0); } while (0)
; #define PG8_WAIT_V(n) asm volatile("s_waitcnt vmcnt(" #n ")" ::: "memory")
; #define PG8_WAIT_L(n) asm volatile("s_waitcnt lgkmcnt(" #n ")" ::: "memory")
; template <class Epi, class Sched, bool ALIGN_EPI = false, bool SP2 = false, bool F16 = false, bool TOKPERM = false>
; __device__ __forceinline__ void gemm_phase(PG8_LAS unsigned char* lds, const Gemm g, const Sched& S, const Epi& E, int wv) {
;     ...
;         const bool has_next = S.next(ui + 1, nxt);
;         const char* nA = has_next ? (const char*)g.A + (size_t)nxt.pm * tstep : cA; const char* nB = has_next ? (const char*)g.Bt + (size_t)nxt.pn * tstep : cB;
;         for (int t = 0; t < nt; t += 2) {
;             const bool last = (t == nt - 2);
;             const char* a1 = cA + (size_t)(t + 1) * kstep;
;             const char* a2 = last ? nA : cA + (size_t)(t + 2) * kstep; const char* b2 = last ? nB : cB + (size_t)(t + 2) * kstep;
;             const char* a3 = a2 + kstep; const char* b3 = b2 + kstep;
;             if (last && has_next) S.a_ready(nxt);
;             if constexpr (SP2) {
;             PG8_LDB(B0, 0, 0); PG8_LDB(B1, 0, 1); PG8_SCHED; PG8_LDA(At, 0, 0); PG8_STAGE(PG8_SA(1, 1), a1 + hstep, voffA);
;             PG8_WAIT_V(8); PG8_WAIT_L(0); PG8_BAR; PG8_MMA(0, 0, At, B0); PG8_MMA(0, 1, At, B1); PG8_BAR; PG8_SCHED;
;             PG8_LDA(At, 0, 1); PG8_STAGE(PG8_SB(0, 0), b2, voffB); PG8_STAGE(PG8_SB(0, 1), b2 + hstep, voffB); PG8_STAGE(PG8_SA(0, 0), a2, voffA);
;             PG8_WAIT_V(8); PG8_WAIT_L(0); PG8_BAR; PG8_MMA(1, 0, At, B0); PG8_MMA(1, 1, At, B1); PG8_BAR; PG8_SCHED;
;             PG8_LDB(B0, 1, 0); PG8_LDB(B1, 1, 1); PG8_SCHED; PG8_LDA(At, 1, 0); PG8_STAGE(PG8_SA(0, 1), a2 + hstep, voffA);
;             PG8_WAIT_V(8); PG8_WAIT_L(0); PG8_BAR; PG8_MMA(0, 0, At, B0); PG8_MMA(0, 1, At, B1); PG8_BAR; PG8_SCHED;
;             PG8_LDA(At, 1, 1); PG8_STAGE(PG8_SB(1, 0), b3, voffB); PG8_STAGE(PG8_SB(1, 1), b3 + hstep, voffB); PG8_STAGE(PG8_SA(1, 0), a3, voffA);
;             PG8_WAIT_V(8); PG8_WAIT_L(0); PG8_BAR; PG8_MMA(1, 0, At, B0); PG8_MMA(1, 1, At, B1); PG8_BAR; PG8_SCHED;
.LBB0_1117:
	s_ashr_i32 s79, s78, 31
	s_lshl_b64 s[14:15], s[78:79], 19
	s_add_u32 s80, s40, s14
	s_addc_u32 s81, s41, s15
	s_and_b64 s[14:15], s[6:7], exec
	s_cselect_b32 s9, s81, s11
	s_cselect_b32 s18, s80, s10
	s_ashr_i32 s77, s76, 31
	s_lshl_b64 s[14:15], s[76:77], 19
	s_add_u32 s82, s0, s14
	s_addc_u32 s83, s1, s15
	s_and_b64 s[14:15], s[6:7], exec
	s_cselect_b32 s19, s83, s13
	s_cselect_b32 s58, s82, s12
	s_add_u32 s59, s12, 0x100
	s_addc_u32 s62, s13, 0
	s_mov_b32 s63, -2
	s_waitcnt lgkmcnt(0)
	ds_read_b128 v[128:131], v190
	ds_read_b128 v[132:135], v191
	ds_read_b128 v[154:157], v192
	ds_read_b128 v[158:161], v193
	ds_read_b128 v[162:165], v194
	ds_read_b128 v[166:169], v195
	ds_read_b128 v[170:173], v196
	ds_read_b128 v[174:177], v197
	s_add_u32 s12, s10, 0x100
	s_addc_u32 s13, s11, 0
	s_cmp_eq_u32 s63, 12
	s_cselect_b32 s17, s9, s13
	s_cselect_b32 s16, s18, s12
	s_cselect_b32 s15, s19, s62
	s_cselect_b32 s14, s58, s59
	s_mov_b32 m0, s22
	v_lshl_add_u64 v[236:237], s[10:11], 0, v[146:147]
	ds_read_b128 v[178:181], v187
	ds_read_b128 v[182:185], v187 offset:1024
	ds_read_b128 v[210:213], v187 offset:2048
	ds_read_b128 v[214:217], v187 offset:3072
	ds_read_b128 v[218:221], v187 offset:4096
	ds_read_b128 v[222:225], v187 offset:5120
	ds_read_b128 v[228:231], v187 offset:6144
	ds_read_b128 v[232:235], v187 offset:7168
	global_load_lds_dwordx4 v[236:237], off
	v_lshl_add_u64 v[236:237], s[10:11], 0, v[148:149]
	s_mov_b32 m0, s23
	s_nop 0
	global_load_lds_dwordx4 v[236:237], off
	s_waitcnt vmcnt(8)
	s_waitcnt lgkmcnt(0)
	s_barrier
	s_setprio 1
	v_mfma_f32_16x16x32_f16 v[124:127], v[128:131], v[178:181], 0
	v_mfma_f32_16x16x32_f16 v[108:111], v[154:157], v[178:181], 0
	v_mfma_f32_16x16x32_f16 v[120:123], v[128:131], v[210:213], 0
	v_mfma_f32_16x16x32_f16 v[104:107], v[154:157], v[210:213], 0
	v_mfma_f32_16x16x32_f16 v[116:119], v[128:131], v[218:221], 0
	v_mfma_f32_16x16x32_f16 v[100:103], v[154:157], v[218:221], 0
	v_mfma_f32_16x16x32_f16 v[112:115], v[128:131], v[228:231], 0
	v_mfma_f32_16x16x32_f16 v[96:99], v[154:157], v[228:231], 0
	v_mfma_f32_16x16x32_f16 v[124:127], v[132:135], v[182:185], v[124:127]
	v_mfma_f32_16x16x32_f16 v[108:111], v[158:161], v[182:185], v[108:111]
	v_mfma_f32_16x16x32_f16 v[120:123], v[132:135], v[214:217], v[120:123]
	v_mfma_f32_16x16x32_f16 v[104:107], v[158:161], v[214:217], v[104:107]
	v_mfma_f32_16x16x32_f16 v[116:119], v[132:135], v[222:225], v[116:119]
	v_mfma_f32_16x16x32_f16 v[100:103], v[158:161], v[222:225], v[100:103]
	v_mfma_f32_16x16x32_f16 v[112:115], v[132:135], v[232:235], v[112:115]
	v_mfma_f32_16x16x32_f16 v[96:99], v[158:161], v[232:235], v[96:99]
	s_setprio 0
	s_setprio 1
	v_mfma_f32_16x16x32_f16 v[92:95], v[162:165], v[178:181], 0
	v_mfma_f32_16x16x32_f16 v[76:79], v[170:173], v[178:181], 0
	v_mfma_f32_16x16x32_f16 v[88:91], v[162:165], v[210:213], 0
	v_mfma_f32_16x16x32_f16 v[72:75], v[170:173], v[210:213], 0
	v_mfma_f32_16x16x32_f16 v[84:87], v[162:165], v[218:221], 0
	v_mfma_f32_16x16x32_f16 v[68:71], v[170:173], v[218:221], 0
	v_mfma_f32_16x16x32_f16 v[80:83], v[162:165], v[228:231], 0
	v_mfma_f32_16x16x32_f16 v[64:67], v[170:173], v[228:231], 0
	v_mfma_f32_16x16x32_f16 v[92:95], v[166:169], v[182:185], v[92:95]
	v_mfma_f32_16x16x32_f16 v[76:79], v[174:177], v[182:185], v[76:79]
	v_mfma_f32_16x16x32_f16 v[88:91], v[166:169], v[214:217], v[88:91]
	v_mfma_f32_16x16x32_f16 v[72:75], v[174:177], v[214:217], v[72:75]
	v_mfma_f32_16x16x32_f16 v[84:87], v[166:169], v[222:225], v[84:87]
	v_mfma_f32_16x16x32_f16 v[68:71], v[174:177], v[222:225], v[68:71]
	v_mfma_f32_16x16x32_f16 v[80:83], v[166:169], v[232:235], v[80:83]
	v_mfma_f32_16x16x32_f16 v[64:67], v[174:177], v[232:235], v[64:67]
	s_setprio 0
	s_barrier
	s_mov_b32 m0, s3
	v_lshl_add_u64 v[236:237], s[14:15], 0, v[138:139]
	s_add_u32 s10, s14, 0x40000
	ds_read_b128 v[178:181], v187 offset:16384
	ds_read_b128 v[182:185], v187 offset:17408
	ds_read_b128 v[210:213], v187 offset:18432
	ds_read_b128 v[214:217], v187 offset:19456
	ds_read_b128 v[218:221], v187 offset:20480
	ds_read_b128 v[222:225], v187 offset:21504
	ds_read_b128 v[228:231], v187 offset:22528
	ds_read_b128 v[232:235], v187 offset:23552
	global_load_lds_dwordx4 v[236:237], off
	v_lshl_add_u64 v[238:239], s[14:15], 0, v[142:143]
	s_mov_b32 m0, s33
	s_addc_u32 s11, s15, 0
	global_load_lds_dwordx4 v[238:239], off
	v_lshl_add_u64 v[240:241], s[10:11], 0, v[138:139]
	s_mov_b32 m0, s36
	v_lshl_add_u64 v[242:243], s[16:17], 0, v[140:141]
	global_load_lds_dwordx4 v[240:241], off
	v_lshl_add_u64 v[240:241], s[10:11], 0, v[142:143]
	s_mov_b32 m0, s37
	s_nop 0
	global_load_lds_dwordx4 v[240:241], off
	v_lshl_add_u64 v[240:241], s[16:17], 0, v[136:137]
	s_mov_b32 m0, s2
	s_nop 0
	global_load_lds_dwordx4 v[240:241], off
	s_mov_b32 m0, s44
	s_nop 0
	global_load_lds_dwordx4 v[242:243], off
	s_waitcnt vmcnt(8)
	s_waitcnt lgkmcnt(0)
	s_barrier
; #define PG8_STAGE(bufoff, gbase, voff) do { _Pragma("unroll") for (int _i = 0; _i < 2; ++_i) \
;         __builtin_amdgcn_global_load_lds((const unsigned*)((const char*)(gbase) + (voff)[_i]), (PG8_LAS unsigned*)(lds + (bufoff) + ldsw + _i * 8192), 16, 0, 0); } while (0)
; #define PG8_LDA(dst, b, h) do { _Pragma("unroll") for (int m = 0; m < 4; ++m) _Pragma("unroll") for (int k = 0; k < 2; ++k) dst[m][k] = *(const PG8_LAS bf16x8*)(lds + PG8_SA(b, h) + aoff + m * 2048 + k * 1024); } while (0)
; #define PG8_LDB(dst, b, h) do { _Pragma("unroll") for (int n = 0; n < 2; ++n) _Pragma("unroll") for (int k = 0; k < 2; ++k) dst[n][k] = *(const PG8_LAS bf16x8*)(lds + PG8_SB(b, h) + boff + n * 2048 + k * 1024); } while (0)
; #define PG8_MMA(ai, bj, At, Bt) do { __builtin_amdgcn_s_setprio(1); _Pragma("unroll") for (int m = 0; m < 4; ++m) _Pragma("unroll") for (int n = 0; n < 2; ++n) _Pragma("unroll") for (int k = 0; k < 2; ++k) \
;         acc[ai][bj][m][n] = mma16<F16>(Bt[n][k], At[m][k], acc[ai][bj][m][n]); __builtin_amdgcn_s_setprio(0); } while (0)
; #define PG8_BAR __builtin_amdgcn_s_barrier()
; template <class Epi, class Sched, bool ALIGN_EPI = false, bool SP2 = false, bool F16 = false, bool TOKPERM = false>
; __device__ __forceinline__ void gemm_phase(PG8_LAS unsigned char* lds, const Gemm g, const Sched& S, const Epi& E, int wv) {
;     ...
;             PG8_LDB(B0, 0, 0); PG8_LDB(B1, 0, 1); PG8_SCHED; PG8_LDA(At, 0, 0); PG8_STAGE(PG8_SA(1, 1), a1 + hstep, voffA);
;             PG8_WAIT_V(8); PG8_WAIT_L(0); PG8_BAR; PG8_MMA(0, 0, At, B0); PG8_MMA(0, 1, At, B1); PG8_BAR; PG8_SCHED;
;             PG8_LDA(At, 0, 1); PG8_STAGE(PG8_SB(0, 0), b2, voffB); PG8_STAGE(PG8_SB(0, 1), b2 + hstep, voffB); PG8_STAGE(PG8_SA(0, 0), a2, voffA);
;             PG8_WAIT_V(8); PG8_WAIT_L(0); PG8_BAR; PG8_MMA(1, 0, At, B0); PG8_MMA(1, 1, At, B1); PG8_BAR; PG8_SCHED;
;             PG8_LDB(B0, 1, 0); PG8_LDB(B1, 1, 1); PG8_SCHED; PG8_LDA(At, 1, 0); PG8_STAGE(PG8_SA(0, 1), a2 + hstep, voffA);
;             PG8_WAIT_V(8); PG8_WAIT_L(0); PG8_BAR; PG8_MMA(0, 0, At, B0); PG8_MMA(0, 1, At, B1); PG8_BAR; PG8_SCHED;
;             PG8_LDA(At, 1, 1); PG8_STAGE(PG8_SB(1, 0), b3, voffB); PG8_STAGE(PG8_SB(1, 1), b3 + hstep, voffB); PG8_STAGE(PG8_SA(1, 0), a3, voffA);
;             PG8_WAIT_V(8); PG8_WAIT_L(0); PG8_BAR; PG8_MMA(1, 0, At, B0); PG8_MMA(1, 1, At, B1); PG8_BAR; PG8_SCHED;
	s_setprio 1
	v_mfma_f32_16x16x32_f16 v[60:63], v[128:131], v[178:181], 0
	v_mfma_f32_16x16x32_f16 v[44:47], v[154:157], v[178:181], 0
	v_mfma_f32_16x16x32_f16 v[56:59], v[128:131], v[210:213], 0
	v_mfma_f32_16x16x32_f16 v[40:43], v[154:157], v[210:213], 0
	v_mfma_f32_16x16x32_f16 v[52:55], v[128:131], v[218:221], 0
	v_mfma_f32_16x16x32_f16 v[36:39], v[154:157], v[218:221], 0
	v_mfma_f32_16x16x32_f16 v[48:51], v[128:131], v[228:231], 0
	v_mfma_f32_16x16x32_f16 v[32:35], v[154:157], v[228:231], 0
	v_mfma_f32_16x16x32_f16 v[60:63], v[132:135], v[182:185], v[60:63]
	v_mfma_f32_16x16x32_f16 v[44:47], v[158:161], v[182:185], v[44:47]
	v_mfma_f32_16x16x32_f16 v[56:59], v[132:135], v[214:217], v[56:59]
	v_mfma_f32_16x16x32_f16 v[40:43], v[158:161], v[214:217], v[40:43]
	v_mfma_f32_16x16x32_f16 v[52:55], v[132:135], v[222:225], v[52:55]
	v_mfma_f32_16x16x32_f16 v[36:39], v[158:161], v[222:225], v[36:39]
	v_mfma_f32_16x16x32_f16 v[48:51], v[132:135], v[232:235], v[48:51]
	v_mfma_f32_16x16x32_f16 v[32:35], v[158:161], v[232:235], v[32:35]
	s_setprio 0
	s_setprio 1
	v_mfma_f32_16x16x32_f16 v[28:31], v[162:165], v[178:181], 0
	v_mfma_f32_16x16x32_f16 v[12:15], v[170:173], v[178:181], 0
	v_mfma_f32_16x16x32_f16 v[24:27], v[162:165], v[210:213], 0
	v_mfma_f32_16x16x32_f16 v[8:11], v[170:173], v[210:213], 0
	v_mfma_f32_16x16x32_f16 v[20:23], v[162:165], v[218:221], 0
	v_mfma_f32_16x16x32_f16 v[4:7], v[170:173], v[218:221], 0
	v_mfma_f32_16x16x32_f16 v[16:19], v[162:165], v[228:231], 0
	v_mfma_f32_16x16x32_f16 v[0:3], v[170:173], v[228:231], 0
	v_mfma_f32_16x16x32_f16 v[28:31], v[166:169], v[182:185], v[28:31]
	v_mfma_f32_16x16x32_f16 v[12:15], v[174:177], v[182:185], v[12:15]
	v_mfma_f32_16x16x32_f16 v[24:27], v[166:169], v[214:217], v[24:27]
	v_mfma_f32_16x16x32_f16 v[8:11], v[174:177], v[214:217], v[8:11]
	v_mfma_f32_16x16x32_f16 v[20:23], v[166:169], v[222:225], v[20:23]
	v_mfma_f32_16x16x32_f16 v[4:7], v[174:177], v[222:225], v[4:7]
	v_mfma_f32_16x16x32_f16 v[16:19], v[166:169], v[232:235], v[16:19]
	v_mfma_f32_16x16x32_f16 v[0:3], v[174:177], v[232:235], v[0:3]
	s_setprio 0
	s_barrier
	ds_read_b128 v[128:131], v198
	ds_read_b128 v[132:135], v199
	ds_read_b128 v[154:157], v200
	ds_read_b128 v[158:161], v201
	ds_read_b128 v[162:165], v202
	ds_read_b128 v[166:169], v203
	ds_read_b128 v[170:173], v204
	ds_read_b128 v[174:177], v205
	s_add_u32 s10, s16, 0x40000
	s_addc_u32 s11, s17, 0
	s_mov_b32 m0, s45
	v_lshl_add_u64 v[244:245], s[10:11], 0, v[136:137]
	ds_read_b128 v[178:181], v187 offset:32768
	ds_read_b128 v[182:185], v187 offset:33792
	ds_read_b128 v[210:213], v187 offset:34816
	ds_read_b128 v[214:217], v187 offset:35840
	ds_read_b128 v[218:221], v187 offset:36864
	ds_read_b128 v[222:225], v187 offset:37888
	ds_read_b128 v[228:231], v187 offset:38912
	ds_read_b128 v[232:235], v187 offset:39936
	global_load_lds_dwordx4 v[244:245], off
	v_lshl_add_u64 v[244:245], s[10:11], 0, v[140:141]
	s_mov_b32 m0, s61
	s_nop 0
	global_load_lds_dwordx4 v[244:245], off
	s_waitcnt vmcnt(8)
	s_waitcnt lgkmcnt(0)
	s_barrier
	s_setprio 1
	v_mfma_f32_16x16x32_f16 v[124:127], v[128:131], v[178:181], v[124:127]
	v_mfma_f32_16x16x32_f16 v[108:111], v[154:157], v[178:181], v[108:111]
	v_mfma_f32_16x16x32_f16 v[120:123], v[128:131], v[210:213], v[120:123]
	v_mfma_f32_16x16x32_f16 v[104:107], v[154:157], v[210:213], v[104:107]
	v_mfma_f32_16x16x32_f16 v[116:119], v[128:131], v[218:221], v[116:119]
	v_mfma_f32_16x16x32_f16 v[100:103], v[154:157], v[218:221], v[100:103]
	v_mfma_f32_16x16x32_f16 v[112:115], v[128:131], v[228:231], v[112:115]
	v_mfma_f32_16x16x32_f16 v[96:99], v[154:157], v[228:231], v[96:99]
	v_mfma_f32_16x16x32_f16 v[124:127], v[132:135], v[182:185], v[124:127]
	v_mfma_f32_16x16x32_f16 v[108:111], v[158:161], v[182:185], v[108:111]
	v_mfma_f32_16x16x32_f16 v[120:123], v[132:135], v[214:217], v[120:123]
	v_mfma_f32_16x16x32_f16 v[104:107], v[158:161], v[214:217], v[104:107]
	v_mfma_f32_16x16x32_f16 v[116:119], v[132:135], v[222:225], v[116:119]
	v_mfma_f32_16x16x32_f16 v[100:103], v[158:161], v[222:225], v[100:103]
	v_mfma_f32_16x16x32_f16 v[112:115], v[132:135], v[232:235], v[112:115]
	v_mfma_f32_16x16x32_f16 v[96:99], v[158:161], v[232:235], v[96:99]
	s_setprio 0
	s_setprio 1
	v_mfma_f32_16x16x32_f16 v[92:95], v[162:165], v[178:181], v[92:95]
	v_mfma_f32_16x16x32_f16 v[76:79], v[170:173], v[178:181], v[76:79]
	v_mfma_f32_16x16x32_f16 v[88:91], v[162:165], v[210:213], v[88:91]
	v_mfma_f32_16x16x32_f16 v[72:75], v[170:173], v[210:213], v[72:75]
	v_mfma_f32_16x16x32_f16 v[84:87], v[162:165], v[218:221], v[84:87]
	v_mfma_f32_16x16x32_f16 v[68:71], v[170:173], v[218:221], v[68:71]
	v_mfma_f32_16x16x32_f16 v[80:83], v[162:165], v[228:231], v[80:83]
	v_mfma_f32_16x16x32_f16 v[64:67], v[170:173], v[228:231], v[64:67]
	v_mfma_f32_16x16x32_f16 v[92:95], v[166:169], v[182:185], v[92:95]
	v_mfma_f32_16x16x32_f16 v[76:79], v[174:177], v[182:185], v[76:79]
	v_mfma_f32_16x16x32_f16 v[88:91], v[166:169], v[214:217], v[88:91]
	v_mfma_f32_16x16x32_f16 v[72:75], v[174:177], v[214:217], v[72:75]
	v_mfma_f32_16x16x32_f16 v[84:87], v[166:169], v[222:225], v[84:87]
	v_mfma_f32_16x16x32_f16 v[68:71], v[174:177], v[222:225], v[68:71]
	v_mfma_f32_16x16x32_f16 v[80:83], v[166:169], v[232:235], v[80:83]
	v_mfma_f32_16x16x32_f16 v[64:67], v[174:177], v[232:235], v[64:67]
	s_setprio 0
	s_barrier
; #define PG8_STAGE(bufoff, gbase, voff) do { _Pragma("unroll") for (int _i = 0; _i < 2; ++_i) \
;         __builtin_amdgcn_global_load_lds((const unsigned*)((const char*)(gbase) + (voff)[_i]), (PG8_LAS unsigned*)(lds + (bufoff) + ldsw + _i * 8192), 16, 0, 0); } while (0)
; #define PG8_LDA(dst, b, h) do { _Pragma("unroll") for (int m = 0; m < 4; ++m) _Pragma("unroll") for (int k = 0; k < 2; ++k) dst[m][k] = *(const PG8_LAS bf16x8*)(lds + PG8_SA(b, h) + aoff + m * 2048 + k * 1024); } while (0)
; #define PG8_WAIT_V(n) asm volatile("s_waitcnt vmcnt(" #n ")" ::: "memory")
; #define PG8_WAIT_L(n) asm volatile("s_waitcnt lgkmcnt(" #n ")" ::: "memory")
; template <class Epi, class Sched, bool ALIGN_EPI = false, bool SP2 = false, bool F16 = false, bool TOKPERM = false>
; __device__ __forceinline__ void gemm_phase(PG8_LAS unsigned char* lds, const Gemm g, const Sched& S, const Epi& E, int wv) {
;     ...
;         for (int t = 0; t < nt; t += 2) {
;             const bool last = (t == nt - 2);
;             const char* a1 = cA + (size_t)(t + 1) * kstep;
;             const char* a2 = last ? nA : cA + (size_t)(t + 2) * kstep; const char* b2 = last ? nB : cB + (size_t)(t + 2) * kstep;
;             const char* a3 = a2 + kstep; const char* b3 = b2 + kstep;
;             if (last && has_next) S.a_ready(nxt);
;             if constexpr (SP2) {
;             PG8_LDB(B0, 0, 0); PG8_LDB(B1, 0, 1); PG8_SCHED; PG8_LDA(At, 0, 0); PG8_STAGE(PG8_SA(1, 1), a1 + hstep, voffA);
;             PG8_WAIT_V(8); PG8_WAIT_L(0); PG8_BAR; PG8_MMA(0, 0, At, B0); PG8_MMA(0, 1, At, B1); PG8_BAR; PG8_SCHED;
;             PG8_LDA(At, 0, 1); PG8_STAGE(PG8_SB(0, 0), b2, voffB); PG8_STAGE(PG8_SB(0, 1), b2 + hstep, voffB); PG8_STAGE(PG8_SA(0, 0), a2, voffA);
;             PG8_WAIT_V(8); PG8_WAIT_L(0); PG8_BAR; PG8_MMA(1, 0, At, B0); PG8_MMA(1, 1, At, B1); PG8_BAR; PG8_SCHED;
;             PG8_LDB(B0, 1, 0); PG8_LDB(B1, 1, 1); PG8_SCHED; PG8_LDA(At, 1, 0); PG8_STAGE(PG8_SA(0, 1), a2 + hstep, voffA);
;             PG8_WAIT_V(8); PG8_WAIT_L(0); PG8_BAR; PG8_MMA(0, 0, At, B0); PG8_MMA(0, 1, At, B1); PG8_BAR; PG8_SCHED;
;             PG8_LDA(At, 1, 1); PG8_STAGE(PG8_SB(1, 0), b3, voffB); PG8_STAGE(PG8_SB(1, 1), b3 + hstep, voffB); PG8_STAGE(PG8_SA(1, 0), a3, voffA);
;             PG8_WAIT_V(8); PG8_WAIT_L(0); PG8_BAR; PG8_MMA(1, 0, At, B0); PG8_MMA(1, 1, At, B1); PG8_BAR; PG8_SCHED;
	s_mov_b32 m0, s94
	v_lshl_add_u64 v[236:237], v[236:237], 0, s[64:65]
	s_add_u32 s10, s14, 0x40080
	ds_read_b128 v[178:181], v187 offset:49152
	ds_read_b128 v[182:185], v187 offset:50176
	ds_read_b128 v[210:213], v187 offset:51200
	ds_read_b128 v[214:217], v187 offset:52224
	ds_read_b128 v[218:221], v187 offset:53248
	ds_read_b128 v[222:225], v187 offset:54272
	ds_read_b128 v[228:231], v187 offset:55296
	ds_read_b128 v[232:235], v187 offset:56320
	global_load_lds_dwordx4 v[236:237], off
	v_lshl_add_u64 v[236:237], v[238:239], 0, s[64:65]
	s_mov_b32 m0, s97
	s_addc_u32 s11, s15, 0
	global_load_lds_dwordx4 v[236:237], off
	v_lshl_add_u64 v[236:237], s[10:11], 0, v[138:139]
	s_mov_b32 m0, s73
	s_nop 0
	global_load_lds_dwordx4 v[236:237], off
	v_lshl_add_u64 v[236:237], s[10:11], 0, v[142:143]
	s_mov_b32 m0, s75
	s_nop 0
	global_load_lds_dwordx4 v[236:237], off
	v_lshl_add_u64 v[236:237], v[240:241], 0, s[64:65]
	s_mov_b32 m0, s4
	s_nop 0
	global_load_lds_dwordx4 v[236:237], off
	v_lshl_add_u64 v[236:237], v[242:243], 0, s[64:65]
	s_mov_b32 m0, s71
	s_nop 0
	global_load_lds_dwordx4 v[236:237], off
	s_waitcnt vmcnt(8)
	s_waitcnt lgkmcnt(0)
	s_barrier
	s_setprio 1
	v_mfma_f32_16x16x32_f16 v[60:63], v[128:131], v[178:181], v[60:63]
	v_mfma_f32_16x16x32_f16 v[44:47], v[154:157], v[178:181], v[44:47]
	v_mfma_f32_16x16x32_f16 v[56:59], v[128:131], v[210:213], v[56:59]
	v_mfma_f32_16x16x32_f16 v[40:43], v[154:157], v[210:213], v[40:43]
	v_mfma_f32_16x16x32_f16 v[52:55], v[128:131], v[218:221], v[52:55]
	v_mfma_f32_16x16x32_f16 v[36:39], v[154:157], v[218:221], v[36:39]
	v_mfma_f32_16x16x32_f16 v[48:51], v[128:131], v[228:231], v[48:51]
	v_mfma_f32_16x16x32_f16 v[32:35], v[154:157], v[228:231], v[32:35]
	v_mfma_f32_16x16x32_f16 v[60:63], v[132:135], v[182:185], v[60:63]
	v_mfma_f32_16x16x32_f16 v[44:47], v[158:161], v[182:185], v[44:47]
	v_mfma_f32_16x16x32_f16 v[56:59], v[132:135], v[214:217], v[56:59]
	v_mfma_f32_16x16x32_f16 v[40:43], v[158:161], v[214:217], v[40:43]
	v_mfma_f32_16x16x32_f16 v[52:55], v[132:135], v[222:225], v[52:55]
	v_mfma_f32_16x16x32_f16 v[36:39], v[158:161], v[222:225], v[36:39]
	v_mfma_f32_16x16x32_f16 v[48:51], v[132:135], v[232:235], v[48:51]
	v_mfma_f32_16x16x32_f16 v[32:35], v[158:161], v[232:235], v[32:35]
	s_setprio 0
	s_setprio 1
	v_mfma_f32_16x16x32_f16 v[28:31], v[162:165], v[178:181], v[28:31]
	v_mfma_f32_16x16x32_f16 v[12:15], v[170:173], v[178:181], v[12:15]
	v_mfma_f32_16x16x32_f16 v[24:27], v[162:165], v[210:213], v[24:27]
	v_mfma_f32_16x16x32_f16 v[8:11], v[170:173], v[210:213], v[8:11]
	v_mfma_f32_16x16x32_f16 v[20:23], v[162:165], v[218:221], v[20:23]
	v_mfma_f32_16x16x32_f16 v[4:7], v[170:173], v[218:221], v[4:7]
	v_mfma_f32_16x16x32_f16 v[16:19], v[162:165], v[228:231], v[16:19]
	v_mfma_f32_16x16x32_f16 v[0:3], v[170:173], v[228:231], v[0:3]
	v_mfma_f32_16x16x32_f16 v[28:31], v[166:169], v[182:185], v[28:31]
	v_mfma_f32_16x16x32_f16 v[12:15], v[174:177], v[182:185], v[12:15]
	v_mfma_f32_16x16x32_f16 v[24:27], v[166:169], v[214:217], v[24:27]
	v_mfma_f32_16x16x32_f16 v[8:11], v[174:177], v[214:217], v[8:11]
	v_mfma_f32_16x16x32_f16 v[20:23], v[166:169], v[222:225], v[20:23]
	v_mfma_f32_16x16x32_f16 v[4:7], v[174:177], v[222:225], v[4:7]
	v_mfma_f32_16x16x32_f16 v[16:19], v[166:169], v[232:235], v[16:19]
	v_mfma_f32_16x16x32_f16 v[0:3], v[174:177], v[232:235], v[0:3]
	s_setprio 0
	s_barrier
	s_add_i32 s63, s63, 2
	s_add_u32 s59, s59, 0x100
	s_addc_u32 s62, s62, 0
	s_cmp_gt_u32 s63, 13
	s_mov_b64 s[10:11], s[12:13]
.LBB0_1118:
	ds_read_b128 v[128:131], v190
	ds_read_b128 v[132:135], v191
	ds_read_b128 v[154:157], v192
	ds_read_b128 v[158:161], v193
	ds_read_b128 v[162:165], v194
	ds_read_b128 v[166:169], v195
	ds_read_b128 v[170:173], v196
	ds_read_b128 v[174:177], v197
	s_add_u32 s12, s10, 0x100
	s_addc_u32 s13, s11, 0
	s_cmp_eq_u32 s63, 12
	s_cselect_b32 s17, s9, s13
	s_cselect_b32 s16, s18, s12
	s_cselect_b32 s15, s19, s62
	s_cselect_b32 s14, s58, s59
	s_mov_b32 m0, s22
	v_lshl_add_u64 v[236:237], s[10:11], 0, v[146:147]
	ds_read_b128 v[178:181], v187
	ds_read_b128 v[182:185], v187 offset:1024
	ds_read_b128 v[210:213], v187 offset:2048
	ds_read_b128 v[214:217], v187 offset:3072
	ds_read_b128 v[218:221], v187 offset:4096
	ds_read_b128 v[222:225], v187 offset:5120
	ds_read_b128 v[228:231], v187 offset:6144
	ds_read_b128 v[232:235], v187 offset:7168
	global_load_lds_dwordx4 v[236:237], off
	v_lshl_add_u64 v[236:237], s[10:11], 0, v[148:149]
	s_mov_b32 m0, s23
	s_nop 0
	global_load_lds_dwordx4 v[236:237], off
	s_waitcnt vmcnt(8)
	s_waitcnt lgkmcnt(0)
	s_barrier
; #define PG8_STAGE(bufoff, gbase, voff) do { _Pragma("unroll") for (int _i = 0; _i < 2; ++_i) \
;         __builtin_amdgcn_global_load_lds((const unsigned*)((const char*)(gbase) + (voff)[_i]), (PG8_LAS unsigned*)(lds + (bufoff) + ldsw + _i * 8192), 16, 0, 0); } while (0)
; #define PG8_LDA(dst, b, h) do { _Pragma("unroll") for (int m = 0; m < 4; ++m) _Pragma("unroll") for (int k = 0; k < 2; ++k) dst[m][k] = *(const PG8_LAS bf16x8*)(lds + PG8_SA(b, h) + aoff + m * 2048 + k * 1024); } while (0)
; #define PG8_LDB(dst, b, h) do { _Pragma("unroll") for (int n = 0; n < 2; ++n) _Pragma("unroll") for (int k = 0; k < 2; ++k) dst[n][k] = *(const PG8_LAS bf16x8*)(lds + PG8_SB(b, h) + boff + n * 2048 + k * 1024); } while (0)
; #define PG8_MMA(ai, bj, At, Bt) do { __builtin_amdgcn_s_setprio(1); _Pragma("unroll") for (int m = 0; m < 4; ++m) _Pragma("unroll") for (int n = 0; n < 2; ++n) _Pragma("unroll") for (int k = 0; k < 2; ++k) \
;         acc[ai][bj][m][n] = mma16<F16>(Bt[n][k], At[m][k], acc[ai][bj][m][n]); __builtin_amdgcn_s_setprio(0); } while (0)
; #define PG8_WAIT_V(n) asm volatile("s_waitcnt vmcnt(" #n ")" ::: "memory")
; #define PG8_WAIT_L(n) asm volatile("s_waitcnt lgkmcnt(" #n ")" ::: "memory")
; #define PG8_BAR __builtin_amdgcn_s_barrier()
; #define PG8_SCHED __builtin_amdgcn_sched_barrier(0)
; template <class Epi, class Sched, bool ALIGN_EPI = false, bool SP2 = false, bool F16 = false, bool TOKPERM = false>
; __device__ __forceinline__ void gemm_phase(PG8_LAS unsigned char* lds, const Gemm g, const Sched& S, const Epi& E, int wv) {
;     ...
;             PG8_LDB(B0, 0, 0); PG8_LDB(B1, 0, 1); PG8_SCHED; PG8_LDA(At, 0, 0); PG8_STAGE(PG8_SA(1, 1), a1 + hstep, voffA);
;             PG8_WAIT_V(8); PG8_WAIT_L(0); PG8_BAR; PG8_MMA(0, 0, At, B0); PG8_MMA(0, 1, At, B1); PG8_BAR; PG8_SCHED;
;             PG8_LDA(At, 0, 1); PG8_STAGE(PG8_SB(0, 0), b2, voffB); PG8_STAGE(PG8_SB(0, 1), b2 + hstep, voffB); PG8_STAGE(PG8_SA(0, 0), a2, voffA);
;             PG8_WAIT_V(8); PG8_WAIT_L(0); PG8_BAR; PG8_MMA(1, 0, At, B0); PG8_MMA(1, 1, At, B1); PG8_BAR; PG8_SCHED;
	s_setprio 1
	v_mfma_f32_16x16x32_f16 v[124:127], v[128:131], v[178:181], v[124:127]
	v_mfma_f32_16x16x32_f16 v[108:111], v[154:157], v[178:181], v[108:111]
	v_mfma_f32_16x16x32_f16 v[120:123], v[128:131], v[210:213], v[120:123]
	v_mfma_f32_16x16x32_f16 v[104:107], v[154:157], v[210:213], v[104:107]
	v_mfma_f32_16x16x32_f16 v[116:119], v[128:131], v[218:221], v[116:119]
	v_mfma_f32_16x16x32_f16 v[100:103], v[154:157], v[218:221], v[100:103]
	v_mfma_f32_16x16x32_f16 v[112:115], v[128:131], v[228:231], v[112:115]
	v_mfma_f32_16x16x32_f16 v[96:99], v[154:157], v[228:231], v[96:99]
	v_mfma_f32_16x16x32_f16 v[124:127], v[132:135], v[182:185], v[124:127]
	v_mfma_f32_16x16x32_f16 v[108:111], v[158:161], v[182:185], v[108:111]
	v_mfma_f32_16x16x32_f16 v[120:123], v[132:135], v[214:217], v[120:123]
	v_mfma_f32_16x16x32_f16 v[104:107], v[158:161], v[214:217], v[104:107]
	v_mfma_f32_16x16x32_f16 v[116:119], v[132:135], v[222:225], v[116:119]
	v_mfma_f32_16x16x32_f16 v[100:103], v[158:161], v[222:225], v[100:103]
	v_mfma_f32_16x16x32_f16 v[112:115], v[132:135], v[232:235], v[112:115]
	v_mfma_f32_16x16x32_f16 v[96:99], v[158:161], v[232:235], v[96:99]
	s_setprio 0
	s_setprio 1
	v_mfma_f32_16x16x32_f16 v[92:95], v[162:165], v[178:181], v[92:95]
	v_mfma_f32_16x16x32_f16 v[76:79], v[170:173], v[178:181], v[76:79]
	v_mfma_f32_16x16x32_f16 v[88:91], v[162:165], v[210:213], v[88:91]
	v_mfma_f32_16x16x32_f16 v[72:75], v[170:173], v[210:213], v[72:75]
	v_mfma_f32_16x16x32_f16 v[84:87], v[162:165], v[218:221], v[84:87]
	v_mfma_f32_16x16x32_f16 v[68:71], v[170:173], v[218:221], v[68:71]
	v_mfma_f32_16x16x32_f16 v[80:83], v[162:165], v[228:231], v[80:83]
	v_mfma_f32_16x16x32_f16 v[64:67], v[170:173], v[228:231], v[64:67]
	v_mfma_f32_16x16x32_f16 v[92:95], v[166:169], v[182:185], v[92:95]
	v_mfma_f32_16x16x32_f16 v[76:79], v[174:177], v[182:185], v[76:79]
	v_mfma_f32_16x16x32_f16 v[88:91], v[166:169], v[214:217], v[88:91]
	v_mfma_f32_16x16x32_f16 v[72:75], v[174:177], v[214:217], v[72:75]
	v_mfma_f32_16x16x32_f16 v[84:87], v[166:169], v[222:225], v[84:87]
	v_mfma_f32_16x16x32_f16 v[68:71], v[174:177], v[222:225], v[68:71]
	v_mfma_f32_16x16x32_f16 v[80:83], v[166:169], v[232:235], v[80:83]
	v_mfma_f32_16x16x32_f16 v[64:67], v[174:177], v[232:235], v[64:67]
	s_setprio 0
	s_barrier
	s_mov_b32 m0, s3
	v_lshl_add_u64 v[236:237], s[14:15], 0, v[138:139]
	s_add_u32 s10, s14, 0x40000
	ds_read_b128 v[178:181], v187 offset:16384
	ds_read_b128 v[182:185], v187 offset:17408
	ds_read_b128 v[210:213], v187 offset:18432
	ds_read_b128 v[214:217], v187 offset:19456
	ds_read_b128 v[218:221], v187 offset:20480
	ds_read_b128 v[222:225], v187 offset:21504
	ds_read_b128 v[228:231], v187 offset:22528
	ds_read_b128 v[232:235], v187 offset:23552
	global_load_lds_dwordx4 v[236:237], off
	v_lshl_add_u64 v[238:239], s[14:15], 0, v[142:143]
	s_mov_b32 m0, s33
	s_addc_u32 s11, s15, 0
	global_load_lds_dwordx4 v[238:239], off
	v_lshl_add_u64 v[240:241], s[10:11], 0, v[138:139]
	s_mov_b32 m0, s36
	v_lshl_add_u64 v[242:243], s[16:17], 0, v[140:141]
	global_load_lds_dwordx4 v[240:241], off
	v_lshl_add_u64 v[240:241], s[10:11], 0, v[142:143]
	s_mov_b32 m0, s37
	s_nop 0
	global_load_lds_dwordx4 v[240:241], off
	v_lshl_add_u64 v[240:241], s[16:17], 0, v[136:137]
	s_mov_b32 m0, s2
	s_nop 0
	global_load_lds_dwordx4 v[240:241], off
	s_mov_b32 m0, s44
	s_nop 0
	global_load_lds_dwordx4 v[242:243], off
	s_waitcnt vmcnt(8)
	s_waitcnt lgkmcnt(0)
	s_barrier
	s_setprio 1
	v_mfma_f32_16x16x32_f16 v[60:63], v[128:131], v[178:181], v[60:63]
	v_mfma_f32_16x16x32_f16 v[44:47], v[154:157], v[178:181], v[44:47]
	v_mfma_f32_16x16x32_f16 v[56:59], v[128:131], v[210:213], v[56:59]
	v_mfma_f32_16x16x32_f16 v[40:43], v[154:157], v[210:213], v[40:43]
	v_mfma_f32_16x16x32_f16 v[52:55], v[128:131], v[218:221], v[52:55]
	v_mfma_f32_16x16x32_f16 v[36:39], v[154:157], v[218:221], v[36:39]
	v_mfma_f32_16x16x32_f16 v[48:51], v[128:131], v[228:231], v[48:51]
	v_mfma_f32_16x16x32_f16 v[32:35], v[154:157], v[228:231], v[32:35]
	v_mfma_f32_16x16x32_f16 v[60:63], v[132:135], v[182:185], v[60:63]
	v_mfma_f32_16x16x32_f16 v[44:47], v[158:161], v[182:185], v[44:47]
	v_mfma_f32_16x16x32_f16 v[56:59], v[132:135], v[214:217], v[56:59]
	v_mfma_f32_16x16x32_f16 v[40:43], v[158:161], v[214:217], v[40:43]
	v_mfma_f32_16x16x32_f16 v[52:55], v[132:135], v[222:225], v[52:55]
	v_mfma_f32_16x16x32_f16 v[36:39], v[158:161], v[222:225], v[36:39]
	v_mfma_f32_16x16x32_f16 v[48:51], v[132:135], v[232:235], v[48:51]
	v_mfma_f32_16x16x32_f16 v[32:35], v[158:161], v[232:235], v[32:35]
	s_setprio 0
	s_setprio 1
	v_mfma_f32_16x16x32_f16 v[28:31], v[162:165], v[178:181], v[28:31]
	v_mfma_f32_16x16x32_f16 v[12:15], v[170:173], v[178:181], v[12:15]
	v_mfma_f32_16x16x32_f16 v[24:27], v[162:165], v[210:213], v[24:27]
	v_mfma_f32_16x16x32_f16 v[8:11], v[170:173], v[210:213], v[8:11]
	v_mfma_f32_16x16x32_f16 v[20:23], v[162:165], v[218:221], v[20:23]
	v_mfma_f32_16x16x32_f16 v[4:7], v[170:173], v[218:221], v[4:7]
	v_mfma_f32_16x16x32_f16 v[16:19], v[162:165], v[228:231], v[16:19]
	v_mfma_f32_16x16x32_f16 v[0:3], v[170:173], v[228:231], v[0:3]
	v_mfma_f32_16x16x32_f16 v[28:31], v[166:169], v[182:185], v[28:31]
	v_mfma_f32_16x16x32_f16 v[12:15], v[174:177], v[182:185], v[12:15]
	v_mfma_f32_16x16x32_f16 v[24:27], v[166:169], v[214:217], v[24:27]
	v_mfma_f32_16x16x32_f16 v[8:11], v[174:177], v[214:217], v[8:11]
	v_mfma_f32_16x16x32_f16 v[20:23], v[166:169], v[222:225], v[20:23]
	v_mfma_f32_16x16x32_f16 v[4:7], v[174:177], v[222:225], v[4:7]
	v_mfma_f32_16x16x32_f16 v[16:19], v[166:169], v[232:235], v[16:19]
	v_mfma_f32_16x16x32_f16 v[0:3], v[174:177], v[232:235], v[0:3]
	s_setprio 0
	s_barrier
; #define PG8_STAGE(bufoff, gbase, voff) do { _Pragma("unroll") for (int _i = 0; _i < 2; ++_i) \
;         __builtin_amdgcn_global_load_lds((const unsigned*)((const char*)(gbase) + (voff)[_i]), (PG8_LAS unsigned*)(lds + (bufoff) + ldsw + _i * 8192), 16, 0, 0); } while (0)
; #define PG8_LDA(dst, b, h) do { _Pragma("unroll") for (int m = 0; m < 4; ++m) _Pragma("unroll") for (int k = 0; k < 2; ++k) dst[m][k] = *(const PG8_LAS bf16x8*)(lds + PG8_SA(b, h) + aoff + m * 2048 + k * 1024); } while (0)
; #define PG8_LDB(dst, b, h) do { _Pragma("unroll") for (int n = 0; n < 2; ++n) _Pragma("unroll") for (int k = 0; k < 2; ++k) dst[n][k] = *(const PG8_LAS bf16x8*)(lds + PG8_SB(b, h) + boff + n * 2048 + k * 1024); } while (0)
; #define PG8_MMA(ai, bj, At, Bt) do { __builtin_amdgcn_s_setprio(1); _Pragma("unroll") for (int m = 0; m < 4; ++m) _Pragma("unroll") for (int n = 0; n < 2; ++n) _Pragma("unroll") for (int k = 0; k < 2; ++k) \
;         acc[ai][bj][m][n] = mma16<F16>(Bt[n][k], At[m][k], acc[ai][bj][m][n]); __builtin_amdgcn_s_setprio(0); } while (0)
; #define PG8_WAIT_V(n) asm volatile("s_waitcnt vmcnt(" #n ")" ::: "memory")
; #define PG8_WAIT_L(n) asm volatile("s_waitcnt lgkmcnt(" #n ")" ::: "memory")
; #define PG8_BAR __builtin_amdgcn_s_barrier()
; #define PG8_SCHED __builtin_amdgcn_sched_barrier(0)
; template <class Epi, class Sched, bool ALIGN_EPI = false, bool SP2 = false, bool F16 = false, bool TOKPERM = false>
; __device__ __forceinline__ void gemm_phase(PG8_LAS unsigned char* lds, const Gemm g, const Sched& S, const Epi& E, int wv) {
;     ...
;             PG8_LDB(B0, 1, 0); PG8_LDB(B1, 1, 1); PG8_SCHED; PG8_LDA(At, 1, 0); PG8_STAGE(PG8_SA(0, 1), a2 + hstep, voffA);
;             PG8_WAIT_V(8); PG8_WAIT_L(0); PG8_BAR; PG8_MMA(0, 0, At, B0); PG8_MMA(0, 1, At, B1); PG8_BAR; PG8_SCHED;
;             PG8_LDA(At, 1, 1); PG8_STAGE(PG8_SB(1, 0), b3, voffB); PG8_STAGE(PG8_SB(1, 1), b3 + hstep, voffB); PG8_STAGE(PG8_SA(1, 0), a3, voffA);
;             PG8_WAIT_V(8); PG8_WAIT_L(0); PG8_BAR; PG8_MMA(1, 0, At, B0); PG8_MMA(1, 1, At, B1); PG8_BAR; PG8_SCHED;
;     ...
;         if constexpr (ALIGN_EPI) { if (wr == 0) PG8_BAR; }
	ds_read_b128 v[128:131], v198
	ds_read_b128 v[132:135], v199
	ds_read_b128 v[154:157], v200
	ds_read_b128 v[158:161], v201
	ds_read_b128 v[162:165], v202
	ds_read_b128 v[166:169], v203
	ds_read_b128 v[170:173], v204
	ds_read_b128 v[174:177], v205
	s_add_u32 s10, s16, 0x40000
	s_addc_u32 s11, s17, 0
	s_mov_b32 m0, s45
	v_lshl_add_u64 v[244:245], s[10:11], 0, v[136:137]
	ds_read_b128 v[178:181], v187 offset:32768
	ds_read_b128 v[182:185], v187 offset:33792
	ds_read_b128 v[210:213], v187 offset:34816
	ds_read_b128 v[214:217], v187 offset:35840
	ds_read_b128 v[218:221], v187 offset:36864
	ds_read_b128 v[222:225], v187 offset:37888
	ds_read_b128 v[228:231], v187 offset:38912
	ds_read_b128 v[232:235], v187 offset:39936
	global_load_lds_dwordx4 v[244:245], off
	v_lshl_add_u64 v[244:245], s[10:11], 0, v[140:141]
	s_mov_b32 m0, s61
	s_nop 0
	global_load_lds_dwordx4 v[244:245], off
	s_waitcnt vmcnt(8)
	s_waitcnt lgkmcnt(0)
	s_barrier
	s_setprio 1
	v_mfma_f32_16x16x32_f16 v[124:127], v[128:131], v[178:181], v[124:127]
	v_mfma_f32_16x16x32_f16 v[108:111], v[154:157], v[178:181], v[108:111]
	v_mfma_f32_16x16x32_f16 v[120:123], v[128:131], v[210:213], v[120:123]
	v_mfma_f32_16x16x32_f16 v[104:107], v[154:157], v[210:213], v[104:107]
	v_mfma_f32_16x16x32_f16 v[116:119], v[128:131], v[218:221], v[116:119]
	v_mfma_f32_16x16x32_f16 v[100:103], v[154:157], v[218:221], v[100:103]
	v_mfma_f32_16x16x32_f16 v[112:115], v[128:131], v[228:231], v[112:115]
	v_mfma_f32_16x16x32_f16 v[96:99], v[154:157], v[228:231], v[96:99]
	v_mfma_f32_16x16x32_f16 v[124:127], v[132:135], v[182:185], v[124:127]
	v_mfma_f32_16x16x32_f16 v[108:111], v[158:161], v[182:185], v[108:111]
	v_mfma_f32_16x16x32_f16 v[120:123], v[132:135], v[214:217], v[120:123]
	v_mfma_f32_16x16x32_f16 v[104:107], v[158:161], v[214:217], v[104:107]
	v_mfma_f32_16x16x32_f16 v[116:119], v[132:135], v[222:225], v[116:119]
	v_mfma_f32_16x16x32_f16 v[100:103], v[158:161], v[222:225], v[100:103]
	v_mfma_f32_16x16x32_f16 v[112:115], v[132:135], v[232:235], v[112:115]
	v_mfma_f32_16x16x32_f16 v[96:99], v[158:161], v[232:235], v[96:99]
	s_setprio 0
	s_setprio 1
	v_mfma_f32_16x16x32_f16 v[92:95], v[162:165], v[178:181], v[92:95]
	v_mfma_f32_16x16x32_f16 v[76:79], v[170:173], v[178:181], v[76:79]
	v_mfma_f32_16x16x32_f16 v[88:91], v[162:165], v[210:213], v[88:91]
	v_mfma_f32_16x16x32_f16 v[72:75], v[170:173], v[210:213], v[72:75]
	v_mfma_f32_16x16x32_f16 v[84:87], v[162:165], v[218:221], v[84:87]
	v_mfma_f32_16x16x32_f16 v[68:71], v[170:173], v[218:221], v[68:71]
	v_mfma_f32_16x16x32_f16 v[80:83], v[162:165], v[228:231], v[80:83]
	v_mfma_f32_16x16x32_f16 v[64:67], v[170:173], v[228:231], v[64:67]
	v_mfma_f32_16x16x32_f16 v[92:95], v[166:169], v[182:185], v[92:95]
	v_mfma_f32_16x16x32_f16 v[76:79], v[174:177], v[182:185], v[76:79]
	v_mfma_f32_16x16x32_f16 v[88:91], v[166:169], v[214:217], v[88:91]
	v_mfma_f32_16x16x32_f16 v[72:75], v[174:177], v[214:217], v[72:75]
	v_mfma_f32_16x16x32_f16 v[84:87], v[166:169], v[222:225], v[84:87]
	v_mfma_f32_16x16x32_f16 v[68:71], v[174:177], v[222:225], v[68:71]
	v_mfma_f32_16x16x32_f16 v[80:83], v[166:169], v[232:235], v[80:83]
	v_mfma_f32_16x16x32_f16 v[64:67], v[174:177], v[232:235], v[64:67]
	s_setprio 0
	s_barrier
	s_mov_b32 m0, s94
	v_lshl_add_u64 v[236:237], v[236:237], 0, s[64:65]
	s_add_u32 s10, s14, 0x40080
	ds_read_b128 v[178:181], v187 offset:49152
	ds_read_b128 v[182:185], v187 offset:50176
	ds_read_b128 v[210:213], v187 offset:51200
	ds_read_b128 v[214:217], v187 offset:52224
	ds_read_b128 v[218:221], v187 offset:53248
	ds_read_b128 v[222:225], v187 offset:54272
	ds_read_b128 v[228:231], v187 offset:55296
	ds_read_b128 v[232:235], v187 offset:56320
	global_load_lds_dwordx4 v[236:237], off
	v_lshl_add_u64 v[236:237], v[238:239], 0, s[64:65]
	s_mov_b32 m0, s97
	s_addc_u32 s11, s15, 0
	global_load_lds_dwordx4 v[236:237], off
	v_lshl_add_u64 v[236:237], s[10:11], 0, v[138:139]
	s_mov_b32 m0, s73
	s_nop 0
	global_load_lds_dwordx4 v[236:237], off
	v_lshl_add_u64 v[236:237], s[10:11], 0, v[142:143]
	s_mov_b32 m0, s75
	s_nop 0
	global_load_lds_dwordx4 v[236:237], off
	v_lshl_add_u64 v[236:237], v[240:241], 0, s[64:65]
	s_mov_b32 m0, s4
	s_nop 0
	global_load_lds_dwordx4 v[236:237], off
	v_lshl_add_u64 v[236:237], v[242:243], 0, s[64:65]
	s_mov_b32 m0, s71
	s_nop 0
	global_load_lds_dwordx4 v[236:237], off
	s_waitcnt vmcnt(8)
	s_waitcnt lgkmcnt(0)
	s_barrier
	s_setprio 1
	v_mfma_f32_16x16x32_f16 v[60:63], v[128:131], v[178:181], v[60:63]
	v_mfma_f32_16x16x32_f16 v[44:47], v[154:157], v[178:181], v[44:47]
	v_mfma_f32_16x16x32_f16 v[56:59], v[128:131], v[210:213], v[56:59]
	v_mfma_f32_16x16x32_f16 v[40:43], v[154:157], v[210:213], v[40:43]
	v_mfma_f32_16x16x32_f16 v[52:55], v[128:131], v[218:221], v[52:55]
	v_mfma_f32_16x16x32_f16 v[36:39], v[154:157], v[218:221], v[36:39]
	v_mfma_f32_16x16x32_f16 v[48:51], v[128:131], v[228:231], v[48:51]
	v_mfma_f32_16x16x32_f16 v[32:35], v[154:157], v[228:231], v[32:35]
	v_mfma_f32_16x16x32_f16 v[60:63], v[132:135], v[182:185], v[60:63]
	v_mfma_f32_16x16x32_f16 v[44:47], v[158:161], v[182:185], v[44:47]
	v_mfma_f32_16x16x32_f16 v[56:59], v[132:135], v[214:217], v[56:59]
	v_mfma_f32_16x16x32_f16 v[40:43], v[158:161], v[214:217], v[40:43]
	v_mfma_f32_16x16x32_f16 v[52:55], v[132:135], v[222:225], v[52:55]
	v_mfma_f32_16x16x32_f16 v[36:39], v[158:161], v[222:225], v[36:39]
	v_mfma_f32_16x16x32_f16 v[48:51], v[132:135], v[232:235], v[48:51]
	v_mfma_f32_16x16x32_f16 v[32:35], v[158:161], v[232:235], v[32:35]
	s_setprio 0
	s_setprio 1
	v_mfma_f32_16x16x32_f16 v[28:31], v[162:165], v[178:181], v[28:31]
	v_mfma_f32_16x16x32_f16 v[12:15], v[170:173], v[178:181], v[12:15]
	v_mfma_f32_16x16x32_f16 v[24:27], v[162:165], v[210:213], v[24:27]
	v_mfma_f32_16x16x32_f16 v[8:11], v[170:173], v[210:213], v[8:11]
	v_mfma_f32_16x16x32_f16 v[20:23], v[162:165], v[218:221], v[20:23]
	v_mfma_f32_16x16x32_f16 v[4:7], v[170:173], v[218:221], v[4:7]
	v_mfma_f32_16x16x32_f16 v[16:19], v[162:165], v[228:231], v[16:19]
	v_mfma_f32_16x16x32_f16 v[0:3], v[170:173], v[228:231], v[0:3]
	v_mfma_f32_16x16x32_f16 v[28:31], v[166:169], v[182:185], v[28:31]
	v_mfma_f32_16x16x32_f16 v[12:15], v[174:177], v[182:185], v[12:15]
	v_mfma_f32_16x16x32_f16 v[24:27], v[166:169], v[214:217], v[24:27]
	v_mfma_f32_16x16x32_f16 v[8:11], v[174:177], v[214:217], v[8:11]
	v_mfma_f32_16x16x32_f16 v[20:23], v[166:169], v[222:225], v[20:23]
	v_mfma_f32_16x16x32_f16 v[4:7], v[174:177], v[222:225], v[4:7]
	v_mfma_f32_16x16x32_f16 v[16:19], v[166:169], v[232:235], v[16:19]
	v_mfma_f32_16x16x32_f16 v[0:3], v[174:177], v[232:235], v[0:3]
	s_setprio 0
	s_barrier
	s_add_i32 s63, s63, 2
	s_add_u32 s59, s59, 0x100
	s_addc_u32 s62, s62, 0
	s_cmp_gt_u32 s63, 13
	s_mov_b64 s[10:11], s[12:13]
	s_cbranch_scc0 .LBB0_1118
	s_and_b64 vcc, exec, s[66:67]
	s_cbranch_vccz .LBB0_1121
	s_barrier

; #define PG8_STAGE(bufoff, gbase, voff) do { _Pragma("unroll") for (int _i = 0; _i < 2; ++_i) \
;         __builtin_amdgcn_global_load_lds((const unsigned*)((const char*)(gbase) + (voff)[_i]), (PG8_LAS unsigned*)(lds + (bufoff) + ldsw + _i * 8192), 16, 0, 0); } while (0)
; #define PG8_LDA(dst, b, h) do { _Pragma("unroll") for (int m = 0; m < 4; ++m) _Pragma("unroll") for (int k = 0; k < 2; ++k) dst[m][k] = *(const PG8_LAS bf16x8*)(lds + PG8_SA(b, h) + aoff + m * 2048 + k * 1024); } while (0)
; #define PG8_LDB(dst, b, h) do { _Pragma("unroll") for (int n = 0; n < 2; ++n) _Pragma("unroll") for (int k = 0; k < 2; ++k) dst[n][k] = *(const PG8_LAS bf16x8*)(lds + PG8_SB(b, h) + boff + n * 2048 + k * 1024); } while (0)
; #define PG8_MMA(ai, bj, At, Bt) do { __builtin_amdgcn_s_setprio(1); _Pragma("unroll") for (int m = 0; m < 4; ++m) _Pragma("unroll") for (int n = 0; n < 2; ++n) _Pragma("unroll") for (int k = 0; k < 2; ++k) \
;         acc[ai][bj][m][n] = mma16<F16>(Bt[n][k], At[m][k], acc[ai][bj][m][n]); __builtin_amdgcn_s_setprio(0); } while (0)
; #define PG8_WAIT_V(n) asm volatile("s_waitcnt vmcnt(" #n ")" ::: "memory")
; #define PG8_WAIT_L(n) asm volatile("s_waitcnt lgkmcnt(" #n ")" ::: "memory")
; #define PG8_BAR __builtin_amdgcn_s_barrier()
; #define PG8_SCHED __builtin_amdgcn_sched_barrier(0)
; template <class Epi, class Sched, bool ALIGN_EPI = false, bool SP2 = false, bool F16 = false, bool TOKPERM = false>
; __device__ __forceinline__ void gemm_phase(PG8_LAS unsigned char* lds, const Gemm g, const Sched& S, const Epi& E, int wv) {
;     ...
;             PG8_LDB(B0, 0, 0); PG8_LDB(B1, 0, 1); PG8_SCHED; PG8_LDA(At, 0, 0); PG8_STAGE(PG8_SA(1, 1), a1 + hstep, voffA);
;             PG8_WAIT_V(8); PG8_WAIT_L(0); PG8_BAR; PG8_MMA(0, 0, At, B0); PG8_MMA(0, 1, At, B1); PG8_BAR; PG8_SCHED;
;             PG8_LDA(At, 0, 1); PG8_STAGE(PG8_SB(0, 0), b2, voffB); PG8_STAGE(PG8_SB(0, 1), b2 + hstep, voffB); PG8_STAGE(PG8_SA(0, 0), a2, voffA);
.LBB0_1524:
	ds_read_b128 v[166:169], v149
	ds_read_b128 v[170:173], v150
	ds_read_b128 v[174:177], v151
	ds_read_b128 v[178:181], v152
	ds_read_b128 v[182:185], v153
	ds_read_b128 v[186:189], v154
	ds_read_b128 v[190:193], v155
	ds_read_b128 v[194:197], v156
	s_add_u32 s44, s24, 0xfffc0080
	s_addc_u32 s45, s25, -1
	s_cmp_eq_u32 s65, 12
	s_cselect_b32 s47, s15, s45
	s_cselect_b32 s46, s21, s44
	s_cselect_b32 s45, s13, s64
	s_cselect_b32 s44, s62, s63
	s_mov_b32 m0, s60
	v_lshl_add_u64 v[232:233], s[24:25], 0, v[138:139]
	ds_read_b128 v[198:201], v147
	ds_read_b128 v[202:205], v147 offset:1024
	ds_read_b128 v[206:209], v147 offset:2048
	ds_read_b128 v[210:213], v147 offset:3072
	ds_read_b128 v[214:217], v147 offset:4096
	ds_read_b128 v[218:221], v147 offset:5120
	ds_read_b128 v[222:225], v147 offset:6144
	ds_read_b128 v[228:231], v147 offset:7168
	global_load_lds_dwordx4 v[232:233], off
	v_lshl_add_u64 v[232:233], s[24:25], 0, v[140:141]
	s_mov_b32 m0, s61
	s_nop 0
	global_load_lds_dwordx4 v[232:233], off
	s_waitcnt vmcnt(8)
	s_waitcnt lgkmcnt(0)
	s_barrier
	s_setprio 1
	v_mfma_f32_16x16x32_bf16 v[124:127], v[166:169], v[198:201], v[124:127]
	v_mfma_f32_16x16x32_bf16 v[120:123], v[174:177], v[198:201], v[120:123]
	v_mfma_f32_16x16x32_bf16 v[108:111], v[166:169], v[206:209], v[108:111]
	v_mfma_f32_16x16x32_bf16 v[104:107], v[174:177], v[206:209], v[104:107]
	v_mfma_f32_16x16x32_bf16 v[92:95], v[166:169], v[214:217], v[92:95]
	v_mfma_f32_16x16x32_bf16 v[88:91], v[174:177], v[214:217], v[88:91]
	v_mfma_f32_16x16x32_bf16 v[76:79], v[166:169], v[222:225], v[76:79]
	v_mfma_f32_16x16x32_bf16 v[72:75], v[174:177], v[222:225], v[72:75]
	v_mfma_f32_16x16x32_bf16 v[124:127], v[170:173], v[202:205], v[124:127]
	v_mfma_f32_16x16x32_bf16 v[120:123], v[178:181], v[202:205], v[120:123]
	v_mfma_f32_16x16x32_bf16 v[108:111], v[170:173], v[210:213], v[108:111]
	v_mfma_f32_16x16x32_bf16 v[104:107], v[178:181], v[210:213], v[104:107]
	v_mfma_f32_16x16x32_bf16 v[92:95], v[170:173], v[218:221], v[92:95]
	v_mfma_f32_16x16x32_bf16 v[88:91], v[178:181], v[218:221], v[88:91]
	v_mfma_f32_16x16x32_bf16 v[76:79], v[170:173], v[228:231], v[76:79]
	v_mfma_f32_16x16x32_bf16 v[72:75], v[178:181], v[228:231], v[72:75]
	s_setprio 0
	s_setprio 1
	v_mfma_f32_16x16x32_bf16 v[116:119], v[182:185], v[198:201], v[116:119]
	v_mfma_f32_16x16x32_bf16 v[112:115], v[190:193], v[198:201], v[112:115]
	v_mfma_f32_16x16x32_bf16 v[100:103], v[182:185], v[206:209], v[100:103]
	v_mfma_f32_16x16x32_bf16 v[96:99], v[190:193], v[206:209], v[96:99]
	v_mfma_f32_16x16x32_bf16 v[84:87], v[182:185], v[214:217], v[84:87]
	v_mfma_f32_16x16x32_bf16 v[80:83], v[190:193], v[214:217], v[80:83]
	v_mfma_f32_16x16x32_bf16 v[68:71], v[182:185], v[222:225], v[68:71]
	v_mfma_f32_16x16x32_bf16 v[64:67], v[190:193], v[222:225], v[64:67]
	v_mfma_f32_16x16x32_bf16 v[116:119], v[186:189], v[202:205], v[116:119]
	v_mfma_f32_16x16x32_bf16 v[112:115], v[194:197], v[202:205], v[112:115]
	v_mfma_f32_16x16x32_bf16 v[100:103], v[186:189], v[210:213], v[100:103]
	v_mfma_f32_16x16x32_bf16 v[96:99], v[194:197], v[210:213], v[96:99]
	v_mfma_f32_16x16x32_bf16 v[84:87], v[186:189], v[218:221], v[84:87]
	v_mfma_f32_16x16x32_bf16 v[80:83], v[194:197], v[218:221], v[80:83]
	v_mfma_f32_16x16x32_bf16 v[68:71], v[186:189], v[228:231], v[68:71]
	v_mfma_f32_16x16x32_bf16 v[64:67], v[194:197], v[228:231], v[64:67]
	s_setprio 0
	s_barrier
	s_mov_b32 m0, s4
	v_lshl_add_u64 v[232:233], s[44:45], 0, v[130:131]
	s_add_u32 s66, s44, 0x40000
	ds_read_b128 v[198:201], v147 offset:16384
	ds_read_b128 v[202:205], v147 offset:17408
	ds_read_b128 v[206:209], v147 offset:18432
	ds_read_b128 v[210:213], v147 offset:19456
	ds_read_b128 v[214:217], v147 offset:20480
	ds_read_b128 v[218:221], v147 offset:21504
	ds_read_b128 v[222:225], v147 offset:22528
	ds_read_b128 v[228:231], v147 offset:23552
	global_load_lds_dwordx4 v[232:233], off
	v_lshl_add_u64 v[234:235], s[44:45], 0, v[134:135]
	s_mov_b32 m0, s5
	s_addc_u32 s67, s45, 0
	global_load_lds_dwordx4 v[234:235], off
	v_lshl_add_u64 v[236:237], s[66:67], 0, v[130:131]
	s_mov_b32 m0, s23
	v_lshl_add_u64 v[238:239], s[46:47], 0, v[132:133]
	global_load_lds_dwordx4 v[236:237], off
	v_lshl_add_u64 v[236:237], s[66:67], 0, v[134:135]
	s_mov_b32 m0, s33
	s_nop 0
	global_load_lds_dwordx4 v[236:237], off
	v_lshl_add_u64 v[236:237], s[46:47], 0, v[128:129]
	s_mov_b32 m0, s3
	s_nop 0
	global_load_lds_dwordx4 v[236:237], off
	s_mov_b32 m0, s36
	s_nop 0
	global_load_lds_dwordx4 v[238:239], off
	s_waitcnt vmcnt(8)
	s_waitcnt lgkmcnt(0)
	s_barrier
; #define PG8_STAGE(bufoff, gbase, voff) do { _Pragma("unroll") for (int _i = 0; _i < 2; ++_i) \
;         __builtin_amdgcn_global_load_lds((const unsigned*)((const char*)(gbase) + (voff)[_i]), (PG8_LAS unsigned*)(lds + (bufoff) + ldsw + _i * 8192), 16, 0, 0); } while (0)
; #define PG8_LDA(dst, b, h) do { _Pragma("unroll") for (int m = 0; m < 4; ++m) _Pragma("unroll") for (int k = 0; k < 2; ++k) dst[m][k] = *(const PG8_LAS bf16x8*)(lds + PG8_SA(b, h) + aoff + m * 2048 + k * 1024); } while (0)
; #define PG8_LDB(dst, b, h) do { _Pragma("unroll") for (int n = 0; n < 2; ++n) _Pragma("unroll") for (int k = 0; k < 2; ++k) dst[n][k] = *(const PG8_LAS bf16x8*)(lds + PG8_SB(b, h) + boff + n * 2048 + k * 1024); } while (0)
; #define PG8_MMA(ai, bj, At, Bt) do { __builtin_amdgcn_s_setprio(1); _Pragma("unroll") for (int m = 0; m < 4; ++m) _Pragma("unroll") for (int n = 0; n < 2; ++n) _Pragma("unroll") for (int k = 0; k < 2; ++k) \
;         acc[ai][bj][m][n] = mma16<F16>(Bt[n][k], At[m][k], acc[ai][bj][m][n]); __builtin_amdgcn_s_setprio(0); } while (0)
; #define PG8_WAIT_V(n) asm volatile("s_waitcnt vmcnt(" #n ")" ::: "memory")
; #define PG8_WAIT_L(n) asm volatile("s_waitcnt lgkmcnt(" #n ")" ::: "memory")
; #define PG8_BAR __builtin_amdgcn_s_barrier()
; #define PG8_SCHED __builtin_amdgcn_sched_barrier(0)
; template <class Epi, class Sched, bool ALIGN_EPI = false, bool SP2 = false, bool F16 = false, bool TOKPERM = false>
; __device__ __forceinline__ void gemm_phase(PG8_LAS unsigned char* lds, const Gemm g, const Sched& S, const Epi& E, int wv) {
;     ...
;             PG8_WAIT_V(8); PG8_WAIT_L(0); PG8_BAR; PG8_MMA(1, 0, At, B0); PG8_MMA(1, 1, At, B1); PG8_BAR; PG8_SCHED;
;             PG8_LDB(B0, 1, 0); PG8_LDB(B1, 1, 1); PG8_SCHED; PG8_LDA(At, 1, 0); PG8_STAGE(PG8_SA(0, 1), a2 + hstep, voffA);
;             PG8_WAIT_V(8); PG8_WAIT_L(0); PG8_BAR; PG8_MMA(0, 0, At, B0); PG8_MMA(0, 1, At, B1); PG8_BAR; PG8_SCHED;
	s_setprio 1
	v_mfma_f32_16x16x32_bf16 v[60:63], v[166:169], v[198:201], v[60:63]
	v_mfma_f32_16x16x32_bf16 v[56:59], v[174:177], v[198:201], v[56:59]
	v_mfma_f32_16x16x32_bf16 v[44:47], v[166:169], v[206:209], v[44:47]
	v_mfma_f32_16x16x32_bf16 v[40:43], v[174:177], v[206:209], v[40:43]
	v_mfma_f32_16x16x32_bf16 v[28:31], v[166:169], v[214:217], v[28:31]
	v_mfma_f32_16x16x32_bf16 v[24:27], v[174:177], v[214:217], v[24:27]
	v_mfma_f32_16x16x32_bf16 v[12:15], v[166:169], v[222:225], v[12:15]
	v_mfma_f32_16x16x32_bf16 v[8:11], v[174:177], v[222:225], v[8:11]
	v_mfma_f32_16x16x32_bf16 v[60:63], v[170:173], v[202:205], v[60:63]
	v_mfma_f32_16x16x32_bf16 v[56:59], v[178:181], v[202:205], v[56:59]
	v_mfma_f32_16x16x32_bf16 v[44:47], v[170:173], v[210:213], v[44:47]
	v_mfma_f32_16x16x32_bf16 v[40:43], v[178:181], v[210:213], v[40:43]
	v_mfma_f32_16x16x32_bf16 v[28:31], v[170:173], v[218:221], v[28:31]
	v_mfma_f32_16x16x32_bf16 v[24:27], v[178:181], v[218:221], v[24:27]
	v_mfma_f32_16x16x32_bf16 v[12:15], v[170:173], v[228:231], v[12:15]
	v_mfma_f32_16x16x32_bf16 v[8:11], v[178:181], v[228:231], v[8:11]
	s_setprio 0
	s_setprio 1
	v_mfma_f32_16x16x32_bf16 v[52:55], v[182:185], v[198:201], v[52:55]
	v_mfma_f32_16x16x32_bf16 v[48:51], v[190:193], v[198:201], v[48:51]
	v_mfma_f32_16x16x32_bf16 v[36:39], v[182:185], v[206:209], v[36:39]
	v_mfma_f32_16x16x32_bf16 v[32:35], v[190:193], v[206:209], v[32:35]
	v_mfma_f32_16x16x32_bf16 v[20:23], v[182:185], v[214:217], v[20:23]
	v_mfma_f32_16x16x32_bf16 v[16:19], v[190:193], v[214:217], v[16:19]
	v_mfma_f32_16x16x32_bf16 v[4:7], v[182:185], v[222:225], v[4:7]
	v_mfma_f32_16x16x32_bf16 v[0:3], v[190:193], v[222:225], v[0:3]
	v_mfma_f32_16x16x32_bf16 v[52:55], v[186:189], v[202:205], v[52:55]
	v_mfma_f32_16x16x32_bf16 v[48:51], v[194:197], v[202:205], v[48:51]
	v_mfma_f32_16x16x32_bf16 v[36:39], v[186:189], v[210:213], v[36:39]
	v_mfma_f32_16x16x32_bf16 v[32:35], v[194:197], v[210:213], v[32:35]
	v_mfma_f32_16x16x32_bf16 v[20:23], v[186:189], v[218:221], v[20:23]
	v_mfma_f32_16x16x32_bf16 v[16:19], v[194:197], v[218:221], v[16:19]
	v_mfma_f32_16x16x32_bf16 v[4:7], v[186:189], v[228:231], v[4:7]
	v_mfma_f32_16x16x32_bf16 v[0:3], v[194:197], v[228:231], v[0:3]
	s_setprio 0
	s_barrier
	ds_read_b128 v[166:169], v157
	ds_read_b128 v[170:173], v158
	ds_read_b128 v[174:177], v159
	ds_read_b128 v[178:181], v160
	ds_read_b128 v[182:185], v161
	ds_read_b128 v[186:189], v162
	ds_read_b128 v[190:193], v163
	ds_read_b128 v[194:197], v164
	s_add_u32 s46, s46, 0x40000
	s_addc_u32 s47, s47, 0
	s_mov_b32 m0, s37
	v_lshl_add_u64 v[240:241], s[46:47], 0, v[128:129]
	ds_read_b128 v[198:201], v147 offset:32768
	ds_read_b128 v[202:205], v147 offset:33792
	ds_read_b128 v[206:209], v147 offset:34816
	ds_read_b128 v[210:213], v147 offset:35840
	ds_read_b128 v[214:217], v147 offset:36864
	ds_read_b128 v[218:221], v147 offset:37888
	ds_read_b128 v[222:225], v147 offset:38912
	ds_read_b128 v[228:231], v147 offset:39936
	global_load_lds_dwordx4 v[240:241], off
	v_lshl_add_u64 v[240:241], s[46:47], 0, v[132:133]
	s_mov_b32 m0, s48
	s_nop 0
	global_load_lds_dwordx4 v[240:241], off
	s_waitcnt vmcnt(8)
	s_waitcnt lgkmcnt(0)
	s_barrier
	s_setprio 1
	v_mfma_f32_16x16x32_bf16 v[124:127], v[166:169], v[198:201], v[124:127]
	v_mfma_f32_16x16x32_bf16 v[120:123], v[174:177], v[198:201], v[120:123]
	v_mfma_f32_16x16x32_bf16 v[108:111], v[166:169], v[206:209], v[108:111]
	v_mfma_f32_16x16x32_bf16 v[104:107], v[174:177], v[206:209], v[104:107]
	v_mfma_f32_16x16x32_bf16 v[92:95], v[166:169], v[214:217], v[92:95]
	v_mfma_f32_16x16x32_bf16 v[88:91], v[174:177], v[214:217], v[88:91]
	v_mfma_f32_16x16x32_bf16 v[76:79], v[166:169], v[222:225], v[76:79]
	v_mfma_f32_16x16x32_bf16 v[72:75], v[174:177], v[222:225], v[72:75]
	v_mfma_f32_16x16x32_bf16 v[124:127], v[170:173], v[202:205], v[124:127]
	v_mfma_f32_16x16x32_bf16 v[120:123], v[178:181], v[202:205], v[120:123]
	v_mfma_f32_16x16x32_bf16 v[108:111], v[170:173], v[210:213], v[108:111]
	v_mfma_f32_16x16x32_bf16 v[104:107], v[178:181], v[210:213], v[104:107]
	v_mfma_f32_16x16x32_bf16 v[92:95], v[170:173], v[218:221], v[92:95]
	v_mfma_f32_16x16x32_bf16 v[88:91], v[178:181], v[218:221], v[88:91]
	v_mfma_f32_16x16x32_bf16 v[76:79], v[170:173], v[228:231], v[76:79]
	v_mfma_f32_16x16x32_bf16 v[72:75], v[178:181], v[228:231], v[72:75]
	s_setprio 0
	s_setprio 1
	v_mfma_f32_16x16x32_bf16 v[116:119], v[182:185], v[198:201], v[116:119]
	v_mfma_f32_16x16x32_bf16 v[112:115], v[190:193], v[198:201], v[112:115]
	v_mfma_f32_16x16x32_bf16 v[100:103], v[182:185], v[206:209], v[100:103]
	v_mfma_f32_16x16x32_bf16 v[96:99], v[190:193], v[206:209], v[96:99]
	v_mfma_f32_16x16x32_bf16 v[84:87], v[182:185], v[214:217], v[84:87]
	v_mfma_f32_16x16x32_bf16 v[80:83], v[190:193], v[214:217], v[80:83]
	v_mfma_f32_16x16x32_bf16 v[68:71], v[182:185], v[222:225], v[68:71]
	v_mfma_f32_16x16x32_bf16 v[64:67], v[190:193], v[222:225], v[64:67]
	v_mfma_f32_16x16x32_bf16 v[116:119], v[186:189], v[202:205], v[116:119]
	v_mfma_f32_16x16x32_bf16 v[112:115], v[194:197], v[202:205], v[112:115]
	v_mfma_f32_16x16x32_bf16 v[100:103], v[186:189], v[210:213], v[100:103]
	v_mfma_f32_16x16x32_bf16 v[96:99], v[194:197], v[210:213], v[96:99]
	v_mfma_f32_16x16x32_bf16 v[84:87], v[186:189], v[218:221], v[84:87]
	v_mfma_f32_16x16x32_bf16 v[80:83], v[194:197], v[218:221], v[80:83]
	v_mfma_f32_16x16x32_bf16 v[68:71], v[186:189], v[228:231], v[68:71]
	v_mfma_f32_16x16x32_bf16 v[64:67], v[194:197], v[228:231], v[64:67]
	s_setprio 0
	s_barrier
; #define PG8_STAGE(bufoff, gbase, voff) do { _Pragma("unroll") for (int _i = 0; _i < 2; ++_i) \
;         __builtin_amdgcn_global_load_lds((const unsigned*)((const char*)(gbase) + (voff)[_i]), (PG8_LAS unsigned*)(lds + (bufoff) + ldsw + _i * 8192), 16, 0, 0); } while (0)
; #define PG8_LDA(dst, b, h) do { _Pragma("unroll") for (int m = 0; m < 4; ++m) _Pragma("unroll") for (int k = 0; k < 2; ++k) dst[m][k] = *(const PG8_LAS bf16x8*)(lds + PG8_SA(b, h) + aoff + m * 2048 + k * 1024); } while (0)
; #define PG8_MMA(ai, bj, At, Bt) do { __builtin_amdgcn_s_setprio(1); _Pragma("unroll") for (int m = 0; m < 4; ++m) _Pragma("unroll") for (int n = 0; n < 2; ++n) _Pragma("unroll") for (int k = 0; k < 2; ++k) \
;         acc[ai][bj][m][n] = mma16<F16>(Bt[n][k], At[m][k], acc[ai][bj][m][n]); __builtin_amdgcn_s_setprio(0); } while (0)
; #define PG8_WAIT_V(n) asm volatile("s_waitcnt vmcnt(" #n ")" ::: "memory")
; #define PG8_WAIT_L(n) asm volatile("s_waitcnt lgkmcnt(" #n ")" ::: "memory")
; #define PG8_BAR __builtin_amdgcn_s_barrier()
; #define PG8_SCHED __builtin_amdgcn_sched_barrier(0)
; template <class Epi, class Sched, bool ALIGN_EPI = false, bool SP2 = false, bool F16 = false, bool TOKPERM = false>
; __device__ __forceinline__ void gemm_phase(PG8_LAS unsigned char* lds, const Gemm g, const Sched& S, const Epi& E, int wv) {
;     ...
;             PG8_LDA(At, 1, 1); PG8_STAGE(PG8_SB(1, 0), b3, voffB); PG8_STAGE(PG8_SB(1, 1), b3 + hstep, voffB); PG8_STAGE(PG8_SA(1, 0), a3, voffA);
;             PG8_WAIT_V(8); PG8_WAIT_L(0); PG8_BAR; PG8_MMA(1, 0, At, B0); PG8_MMA(1, 1, At, B1); PG8_BAR; PG8_SCHED;
	s_mov_b32 m0, s50
	v_lshl_add_u64 v[232:233], v[232:233], 0, s[10:11]
	s_add_u32 s44, s44, 0x40080
	ds_read_b128 v[198:201], v147 offset:49152
	ds_read_b128 v[202:205], v147 offset:50176
	ds_read_b128 v[206:209], v147 offset:51200
	ds_read_b128 v[210:213], v147 offset:52224
	ds_read_b128 v[214:217], v147 offset:53248
	ds_read_b128 v[218:221], v147 offset:54272
	ds_read_b128 v[222:225], v147 offset:55296
	ds_read_b128 v[228:231], v147 offset:56320
	global_load_lds_dwordx4 v[232:233], off
	v_lshl_add_u64 v[232:233], v[234:235], 0, s[10:11]
	s_mov_b32 m0, s51
	s_addc_u32 s45, s45, 0
	global_load_lds_dwordx4 v[232:233], off
	v_lshl_add_u64 v[232:233], s[44:45], 0, v[130:131]
	s_mov_b32 m0, s54
	s_nop 0
	global_load_lds_dwordx4 v[232:233], off
	v_lshl_add_u64 v[232:233], s[44:45], 0, v[134:135]
	s_mov_b32 m0, s55
	s_nop 0
	global_load_lds_dwordx4 v[232:233], off
	v_lshl_add_u64 v[232:233], v[236:237], 0, s[10:11]
	s_mov_b32 m0, s52
	s_nop 0
	global_load_lds_dwordx4 v[232:233], off
	v_lshl_add_u64 v[232:233], v[238:239], 0, s[10:11]
	s_mov_b32 m0, s53
	s_nop 0
	global_load_lds_dwordx4 v[232:233], off
	s_waitcnt vmcnt(8)
	s_waitcnt lgkmcnt(0)
	s_barrier
	s_setprio 1
	v_mfma_f32_16x16x32_bf16 v[60:63], v[166:169], v[198:201], v[60:63]
	v_mfma_f32_16x16x32_bf16 v[56:59], v[174:177], v[198:201], v[56:59]
	v_mfma_f32_16x16x32_bf16 v[44:47], v[166:169], v[206:209], v[44:47]
	v_mfma_f32_16x16x32_bf16 v[40:43], v[174:177], v[206:209], v[40:43]
	v_mfma_f32_16x16x32_bf16 v[28:31], v[166:169], v[214:217], v[28:31]
	v_mfma_f32_16x16x32_bf16 v[24:27], v[174:177], v[214:217], v[24:27]
	v_mfma_f32_16x16x32_bf16 v[12:15], v[166:169], v[222:225], v[12:15]
	v_mfma_f32_16x16x32_bf16 v[8:11], v[174:177], v[222:225], v[8:11]
	v_mfma_f32_16x16x32_bf16 v[60:63], v[170:173], v[202:205], v[60:63]
	v_mfma_f32_16x16x32_bf16 v[56:59], v[178:181], v[202:205], v[56:59]
	v_mfma_f32_16x16x32_bf16 v[44:47], v[170:173], v[210:213], v[44:47]
	v_mfma_f32_16x16x32_bf16 v[40:43], v[178:181], v[210:213], v[40:43]
	v_mfma_f32_16x16x32_bf16 v[28:31], v[170:173], v[218:221], v[28:31]
	v_mfma_f32_16x16x32_bf16 v[24:27], v[178:181], v[218:221], v[24:27]
	v_mfma_f32_16x16x32_bf16 v[12:15], v[170:173], v[228:231], v[12:15]
	v_mfma_f32_16x16x32_bf16 v[8:11], v[178:181], v[228:231], v[8:11]
	s_setprio 0
	s_setprio 1
	v_mfma_f32_16x16x32_bf16 v[52:55], v[182:185], v[198:201], v[52:55]
	v_mfma_f32_16x16x32_bf16 v[48:51], v[190:193], v[198:201], v[48:51]
	v_mfma_f32_16x16x32_bf16 v[36:39], v[182:185], v[206:209], v[36:39]
	v_mfma_f32_16x16x32_bf16 v[32:35], v[190:193], v[206:209], v[32:35]
	v_mfma_f32_16x16x32_bf16 v[20:23], v[182:185], v[214:217], v[20:23]
	v_mfma_f32_16x16x32_bf16 v[16:19], v[190:193], v[214:217], v[16:19]
	v_mfma_f32_16x16x32_bf16 v[4:7], v[182:185], v[222:225], v[4:7]
	v_mfma_f32_16x16x32_bf16 v[0:3], v[190:193], v[222:225], v[0:3]
	v_mfma_f32_16x16x32_bf16 v[52:55], v[186:189], v[202:205], v[52:55]
	v_mfma_f32_16x16x32_bf16 v[48:51], v[194:197], v[202:205], v[48:51]
	v_mfma_f32_16x16x32_bf16 v[36:39], v[186:189], v[210:213], v[36:39]
	v_mfma_f32_16x16x32_bf16 v[32:35], v[194:197], v[210:213], v[32:35]
	v_mfma_f32_16x16x32_bf16 v[20:23], v[186:189], v[218:221], v[20:23]
	v_mfma_f32_16x16x32_bf16 v[16:19], v[194:197], v[218:221], v[16:19]
	v_mfma_f32_16x16x32_bf16 v[4:7], v[186:189], v[228:231], v[4:7]
	v_mfma_f32_16x16x32_bf16 v[0:3], v[194:197], v[228:231], v[0:3]
	s_setprio 0
	s_barrier
	s_add_i32 s65, s65, 2
	s_add_u32 s24, s24, 0x100
	s_addc_u32 s25, s25, 0
	s_add_u32 s63, s63, 0x100
	s_addc_u32 s64, s64, 0
	s_cmp_gt_u32 s65, 13
	s_cbranch_scc0 .LBB0_1524
;   __device__ __forceinline__ void operator()(const pg8::f32x4 (&acc)[2][2][4][2], const pg8::Unit& u, int wr, int wc, int fr, int fq) const {
;     int z; asm volatile("v_mov_b32 %0, 0" : "=v"(z));
;     const int row0 = u.pm * 256 + wr * 64 + fr + z, colb = u.pn * 256 + wc * 32 + 8 * fq + z;
; #pragma unroll
;     for (int ai = 0; ai < 2; ++ai)
; #pragma unroll
;       for (int m = 0; m < 4; ++m) {
;         const int tok = row0 + ai * 128 + m * 16; float ss = 0.f;
; #pragma unroll
;         for (int bj = 0; bj < 2; ++bj) {
;           const unsigned off = (unsigned)tok * DM + colb + 128 * bj;
;           f8_t n = __builtin_convertvector(*(const h8_t*)(x16 + off), f8_t);
; #pragma unroll
;           for (int c = 0; c < 4; ++c) { n[c] += sc * acc[ai][bj][m][0][c]; n[4 + c] += sc * acc[ai][bj][m][1][c]; }
;           if (aux) {
;             *(h8_t*)(x16 + off) = __builtin_convertvector(n, h8_t);
;             ss += ((n[0] * n[0] + n[1] * n[1]) + (n[2] * n[2] + n[3] * n[3])) + ((n[4] * n[4] + n[5] * n[5]) + (n[6] * n[6] + n[7] * n[7]));
;           } else {
;             *(f32x4*)(xout + off) = (f32x4){n[0], n[1], n[2], n[3]}; *(f32x4*)(xout + off + 4) = (f32x4){n[4], n[5], n[6], n[7]};
;           }
;         }
;         if (aux) { ss += __shfl_xor(ss, 16); ss += __shfl_xor(ss, 32); if (fq == 0) ssq[(unsigned)tok * 16 + u.pn * 4 + wc] = ss; }
;         if (m & 1) asm volatile("" ::: "memory");
;       }
	s_lshl_b32 s13, s22, 8
	v_lshl_or_b32 v166, s20, 8, v148
	v_mov_b32 v136, 0
	v_xor_b32_e32 v169, 32, v165
	v_add3_u32 v167, s13, v146, v136
	v_add_u32_e32 v168, v166, v136
	v_lshl_add_u32 v136, v167, 10, v168
	v_lshl_add_u64 v[178:179], v[136:137], 1, s[40:41]
	v_add_u32_e32 v136, 0x80, v136
	global_load_dwordx4 v[170:173], v[178:179], off
	v_lshl_add_u64 v[180:181], v[136:137], 1, s[40:41]
	global_load_dwordx4 v[174:177], v[180:181], off
	v_add_u32_e32 v136, 16, v167
	v_lshl_add_u32 v136, v136, 10, v168
	v_lshl_add_u64 v[224:225], v[136:137], 1, s[40:41]
	v_add_u32_e32 v136, 0x80, v136
	global_load_dwordx4 v[192:195], v[224:225], off
	v_lshl_add_u64 v[248:249], v[136:137], 1, s[40:41]
	global_load_dwordx4 v[196:199], v[248:249], off
	v_add_u32_e32 v136, 32, v167
	v_lshl_add_u32 v136, v136, 10, v168
	v_lshl_add_u64 v[224:225], v[136:137], 1, s[40:41]
	v_add_u32_e32 v136, 0x80, v136
	global_load_dwordx4 v[200:203], v[224:225], off
	v_lshl_add_u64 v[248:249], v[136:137], 1, s[40:41]
	global_load_dwordx4 v[204:207], v[248:249], off
	v_add_u32_e32 v136, 48, v167
	v_lshl_add_u32 v136, v136, 10, v168
	v_lshl_add_u64 v[224:225], v[136:137], 1, s[40:41]
	v_add_u32_e32 v136, 0x80, v136
	global_load_dwordx4 v[208:211], v[224:225], off
	v_lshl_add_u64 v[248:249], v[136:137], 1, s[40:41]
	global_load_dwordx4 v[212:215], v[248:249], off
	v_add_u32_e32 v136, 0x80, v167
	v_lshl_add_u32 v136, v136, 10, v168
	v_lshl_add_u64 v[224:225], v[136:137], 1, s[40:41]
	v_add_u32_e32 v136, 0x80, v136
	global_load_dwordx4 v[216:219], v[224:225], off
	v_lshl_add_u64 v[248:249], v[136:137], 1, s[40:41]
	global_load_dwordx4 v[220:223], v[248:249], off
	v_add_u32_e32 v136, 0x90, v167
	v_lshl_add_u32 v136, v136, 10, v168
	v_lshl_add_u64 v[224:225], v[136:137], 1, s[40:41]
	v_add_u32_e32 v136, 0x80, v136
	global_load_dwordx4 v[228:231], v[224:225], off
	v_lshl_add_u64 v[248:249], v[136:137], 1, s[40:41]
	global_load_dwordx4 v[244:247], v[248:249], off
	v_and_b32_e32 v166, 64, v165
	v_xor_b32_e32 v136, 16, v165
	v_add_u32_e32 v166, 64, v166
	v_cmp_lt_i32_e32 vcc, v136, v166
	s_lshl_b32 s13, s20, 2
	s_or_b32 s13, s13, s49
	v_cndmask_b32_e32 v136, v165, v136, vcc
	v_cmp_lt_i32_e32 vcc, v169, v166
	v_lshlrev_b32_e32 v166, 2, v136
	s_waitcnt vmcnt(10)
	v_cvt_f32_f16_e32 v182, v173
	v_cvt_f32_f16_sdwa v183, v173 dst_sel:DWORD dst_unused:UNUSED_PAD src0_sel:WORD_1
	v_cvt_f32_f16_e32 v184, v171
	v_cvt_f32_f16_sdwa v185, v171 dst_sel:DWORD dst_unused:UNUSED_PAD src0_sel:WORD_1
	v_cvt_f32_f16_e32 v186, v172
	v_cvt_f32_f16_sdwa v187, v172 dst_sel:DWORD dst_unused:UNUSED_PAD src0_sel:WORD_1
	v_cvt_f32_f16_e32 v172, v170
	v_cvt_f32_f16_sdwa v173, v170 dst_sel:DWORD dst_unused:UNUSED_PAD src0_sel:WORD_1
	v_cvt_f32_f16_e32 v170, v177
	v_cvt_f32_f16_sdwa v171, v177 dst_sel:DWORD dst_unused:UNUSED_PAD src0_sel:WORD_1
	v_cvt_f32_f16_e32 v188, v175
	v_cvt_f32_f16_sdwa v189, v175 dst_sel:DWORD dst_unused:UNUSED_PAD src0_sel:WORD_1
	v_cvt_f32_f16_e32 v190, v176
	v_cvt_f32_f16_sdwa v191, v176 dst_sel:DWORD dst_unused:UNUSED_PAD src0_sel:WORD_1
	v_cvt_f32_f16_e32 v176, v174
	v_cvt_f32_f16_sdwa v177, v174 dst_sel:DWORD dst_unused:UNUSED_PAD src0_sel:WORD_1
	v_pk_add_f32 v[124:125], v[124:125], v[172:173]
	v_pk_add_f32 v[172:173], v[120:121], v[186:187]
	v_pk_add_f32 v[126:127], v[126:127], v[184:185]
	v_pk_add_f32 v[122:123], v[122:123], v[182:183]
	v_cvt_pk_f16_f32 v120, v172, v173
	v_cvt_pk_f16_f32 v121, v122, v123
	v_pk_mul_f32 v[174:175], v[124:125], v[124:125]
	v_pk_mul_f32 v[182:183], v[126:127], v[126:127]
	v_pk_fma_f32 v[174:175], v[172:173], v[172:173], v[174:175]
	v_pk_fma_f32 v[182:183], v[122:123], v[122:123], v[182:183]
	v_pk_add_f32 v[176:177], v[116:117], v[176:177]
	v_pk_add_f32 v[116:117], v[112:113], v[190:191]
	v_pk_add_f32 v[184:185], v[118:119], v[188:189]
	v_pk_add_f32 v[112:113], v[114:115], v[170:171]
	v_pk_fma_f32 v[174:175], v[176:177], v[176:177], v[174:175]
	v_pk_fma_f32 v[182:183], v[184:185], v[184:185], v[182:183]
	v_pk_fma_f32 v[174:175], v[116:117], v[116:117], v[174:175]
	v_pk_fma_f32 v[182:183], v[112:113], v[112:113], v[182:183]
	v_pk_add_f32 v[174:175], v[174:175], v[182:183]
	v_add_f32_e32 v114, v174, v175
	v_mov_b32_e32 v115, v114
	s_nop 1
	v_permlane16_swap_b32_e32 v114, v115
	v_cndmask_b32_e32 v169, v165, v169, vcc
	v_cvt_pk_f16_f32 v119, v126, v127
	v_cvt_pk_f16_f32 v118, v124, v125
	global_store_dwordx4 v[178:179], v[118:121], off
	s_nop 1
	v_cvt_pk_f16_f32 v119, v112, v113
	s_waitcnt lgkmcnt(0)
	v_add_f32_e32 v113, v114, v115
	v_lshlrev_b32_e32 v112, 2, v169
	v_mov_b32_e32 v114, v113
	s_nop 1
	v_permlane32_swap_b32_e32 v113, v114
	v_cvt_pk_f16_f32 v118, v116, v117
	v_cvt_pk_f16_f32 v117, v184, v185
	v_cvt_pk_f16_f32 v116, v176, v177
	global_store_dwordx4 v[180:181], v[116:119], off
	s_and_saveexec_b64 s[20:21], s[6:7]
	s_cbranch_execz .LBB0_1527
	v_lshl_add_u32 v136, v167, 4, s13
	s_waitcnt lgkmcnt(0)
	v_add_f32_e32 v113, v113, v114
	v_lshl_add_u64 v[114:115], v[136:137], 2, s[42:43]
	global_store_dword v[114:115], v113, off

; #define PG8_STAGE(bufoff, gbase, voff) do { _Pragma("unroll") for (int _i = 0; _i < 2; ++_i) \
;         __builtin_amdgcn_global_load_lds((const unsigned*)((const char*)(gbase) + (voff)[_i]), (PG8_LAS unsigned*)(lds + (bufoff) + ldsw + _i * 8192), 16, 0, 0); } while (0)
; #define PG8_LDA(dst, b, h) do { _Pragma("unroll") for (int m = 0; m < 4; ++m) _Pragma("unroll") for (int k = 0; k < 2; ++k) dst[m][k] = *(const PG8_LAS bf16x8*)(lds + PG8_SA(b, h) + aoff + m * 2048 + k * 1024); } while (0)
; #define PG8_LDB(dst, b, h) do { _Pragma("unroll") for (int n = 0; n < 2; ++n) _Pragma("unroll") for (int k = 0; k < 2; ++k) dst[n][k] = *(const PG8_LAS bf16x8*)(lds + PG8_SB(b, h) + boff + n * 2048 + k * 1024); } while (0)
; #define PG8_MMA(ai, bj, At, Bt) do { __builtin_amdgcn_s_setprio(1); _Pragma("unroll") for (int m = 0; m < 4; ++m) _Pragma("unroll") for (int n = 0; n < 2; ++n) _Pragma("unroll") for (int k = 0; k < 2; ++k) \
;         acc[ai][bj][m][n] = mma16<F16>(Bt[n][k], At[m][k], acc[ai][bj][m][n]); __builtin_amdgcn_s_setprio(0); } while (0)
; #define PG8_BAR __builtin_amdgcn_s_barrier()
; template <class Epi, class Sched, bool ALIGN_EPI = false, bool SP2 = false, bool F16 = false, bool TOKPERM = false>
; __device__ __forceinline__ void gemm_phase(PG8_LAS unsigned char* lds, const Gemm g, const Sched& S, const Epi& E, int wv) {
;     ...
;             PG8_LDB(B0, 0, 0); PG8_LDB(B1, 0, 1); PG8_SCHED; PG8_LDA(At, 0, 0); PG8_STAGE(PG8_SA(1, 1), a1 + hstep, voffA);
;             PG8_WAIT_V(8); PG8_WAIT_L(0); PG8_BAR; PG8_MMA(0, 0, At, B0); PG8_MMA(0, 1, At, B1); PG8_BAR; PG8_SCHED;
;             PG8_LDA(At, 0, 1); PG8_STAGE(PG8_SB(0, 0), b2, voffB); PG8_STAGE(PG8_SB(0, 1), b2 + hstep, voffB); PG8_STAGE(PG8_SA(0, 0), a2, voffA);
;             PG8_WAIT_V(8); PG8_WAIT_L(0); PG8_BAR; PG8_MMA(1, 0, At, B0); PG8_MMA(1, 1, At, B1); PG8_BAR; PG8_SCHED;
;             PG8_LDB(B0, 1, 0); PG8_LDB(B1, 1, 1); PG8_SCHED; PG8_LDA(At, 1, 0); PG8_STAGE(PG8_SA(0, 1), a2 + hstep, voffA);
;             PG8_WAIT_V(8); PG8_WAIT_L(0); PG8_BAR; PG8_MMA(0, 0, At, B0); PG8_MMA(0, 1, At, B1); PG8_BAR; PG8_SCHED;
;             PG8_LDA(At, 1, 1); PG8_STAGE(PG8_SB(1, 0), b3, voffB); PG8_STAGE(PG8_SB(1, 1), b3 + hstep, voffB); PG8_STAGE(PG8_SA(1, 0), a3, voffA);
;             PG8_WAIT_V(8); PG8_WAIT_L(0); PG8_BAR; PG8_MMA(1, 0, At, B0); PG8_MMA(1, 1, At, B1); PG8_BAR; PG8_SCHED;
.Lvmw_1607_0:
	s_waitcnt lgkmcnt(0)
	s_barrier
	s_setprio 1
	v_mfma_f32_16x16x32_f16 v[124:127], v[172:175], v[204:207], 0
	v_mfma_f32_16x16x32_f16 v[116:119], v[180:183], v[204:207], 0
	v_mfma_f32_16x16x32_f16 v[108:111], v[172:175], v[212:215], 0
	v_mfma_f32_16x16x32_f16 v[104:107], v[180:183], v[212:215], 0
	v_mfma_f32_16x16x32_f16 v[92:95], v[172:175], v[220:223], 0
	v_mfma_f32_16x16x32_f16 v[88:91], v[180:183], v[220:223], 0
	v_mfma_f32_16x16x32_f16 v[76:79], v[172:175], v[228:231], 0
	v_mfma_f32_16x16x32_f16 v[72:75], v[180:183], v[228:231], 0
	v_mfma_f32_16x16x32_f16 v[124:127], v[176:179], v[208:211], v[124:127]
	v_mfma_f32_16x16x32_f16 v[116:119], v[184:187], v[208:211], v[116:119]
	v_mfma_f32_16x16x32_f16 v[108:111], v[176:179], v[216:219], v[108:111]
	v_mfma_f32_16x16x32_f16 v[104:107], v[184:187], v[216:219], v[104:107]
	v_mfma_f32_16x16x32_f16 v[92:95], v[176:179], v[224:227], v[92:95]
	v_mfma_f32_16x16x32_f16 v[88:91], v[184:187], v[224:227], v[88:91]
	v_mfma_f32_16x16x32_f16 v[76:79], v[176:179], v[232:235], v[76:79]
	v_mfma_f32_16x16x32_f16 v[72:75], v[184:187], v[232:235], v[72:75]
	s_setprio 0
	s_setprio 1
	v_mfma_f32_16x16x32_f16 v[120:123], v[188:191], v[204:207], 0
	v_mfma_f32_16x16x32_f16 v[112:115], v[196:199], v[204:207], 0
	v_mfma_f32_16x16x32_f16 v[100:103], v[188:191], v[212:215], 0
	v_mfma_f32_16x16x32_f16 v[96:99], v[196:199], v[212:215], 0
	v_mfma_f32_16x16x32_f16 v[84:87], v[188:191], v[220:223], 0
	v_mfma_f32_16x16x32_f16 v[80:83], v[196:199], v[220:223], 0
	v_mfma_f32_16x16x32_f16 v[68:71], v[188:191], v[228:231], 0
	v_mfma_f32_16x16x32_f16 v[64:67], v[196:199], v[228:231], 0
	v_mfma_f32_16x16x32_f16 v[120:123], v[192:195], v[208:211], v[120:123]
	v_mfma_f32_16x16x32_f16 v[112:115], v[200:203], v[208:211], v[112:115]
	v_mfma_f32_16x16x32_f16 v[100:103], v[192:195], v[216:219], v[100:103]
	v_mfma_f32_16x16x32_f16 v[96:99], v[200:203], v[216:219], v[96:99]
	v_mfma_f32_16x16x32_f16 v[84:87], v[192:195], v[224:227], v[84:87]
	v_mfma_f32_16x16x32_f16 v[80:83], v[200:203], v[224:227], v[80:83]
	v_mfma_f32_16x16x32_f16 v[68:71], v[192:195], v[232:235], v[68:71]
	v_mfma_f32_16x16x32_f16 v[64:67], v[200:203], v[232:235], v[64:67]
	s_setprio 0
	s_barrier
	s_mov_b32 m0, s21
	v_lshl_add_u64 v[148:149], s[10:11], 0, v[132:133]
	s_add_u32 s70, s10, 0x40000
	ds_read_b128 v[204:207], v153 offset:16384
	ds_read_b128 v[208:211], v153 offset:17408
	ds_read_b128 v[212:215], v153 offset:18432
	ds_read_b128 v[216:219], v153 offset:19456
	ds_read_b128 v[220:223], v153 offset:20480
	ds_read_b128 v[224:227], v153 offset:21504
	ds_read_b128 v[228:231], v153 offset:22528
	ds_read_b128 v[232:235], v153 offset:23552
	global_load_lds_dwordx4 v[148:149], off
	v_lshl_add_u64 v[236:237], s[10:11], 0, v[128:129]
	s_mov_b32 m0, s33
	s_addc_u32 s71, s11, 0
	global_load_lds_dwordx4 v[236:237], off
	v_lshl_add_u64 v[238:239], s[70:71], 0, v[132:133]
	s_mov_b32 m0, s46
	v_lshl_add_u64 v[240:241], s[44:45], 0, v[130:131]
	global_load_lds_dwordx4 v[238:239], off
	v_lshl_add_u64 v[238:239], s[70:71], 0, v[128:129]
	s_mov_b32 m0, s47
	s_nop 0
	global_load_lds_dwordx4 v[238:239], off
	v_lshl_add_u64 v[238:239], s[44:45], 0, v[134:135]
	s_mov_b32 m0, s2
	s_nop 0
	global_load_lds_dwordx4 v[238:239], off
	s_mov_b32 m0, s48
	s_nop 0
	global_load_lds_dwordx4 v[240:241], off
	s_waitcnt vmcnt(16)
	s_cmp_lg_u32 s99, -1
	s_cbranch_scc1 .Lvmw_1607_1
	s_waitcnt vmcnt(8)
.Lvmw_1607_1:
	s_waitcnt lgkmcnt(0)
	s_barrier
	s_setprio 1
	v_mfma_f32_16x16x32_f16 v[60:63], v[172:175], v[204:207], 0
	v_mfma_f32_16x16x32_f16 v[56:59], v[180:183], v[204:207], 0
	v_mfma_f32_16x16x32_f16 v[44:47], v[172:175], v[212:215], 0
	v_mfma_f32_16x16x32_f16 v[40:43], v[180:183], v[212:215], 0
	v_mfma_f32_16x16x32_f16 v[28:31], v[172:175], v[220:223], 0
	v_mfma_f32_16x16x32_f16 v[24:27], v[180:183], v[220:223], 0
	v_mfma_f32_16x16x32_f16 v[12:15], v[172:175], v[228:231], 0
	v_mfma_f32_16x16x32_f16 v[8:11], v[180:183], v[228:231], 0
	v_mfma_f32_16x16x32_f16 v[60:63], v[176:179], v[208:211], v[60:63]
	v_mfma_f32_16x16x32_f16 v[56:59], v[184:187], v[208:211], v[56:59]
	v_mfma_f32_16x16x32_f16 v[44:47], v[176:179], v[216:219], v[44:47]
	v_mfma_f32_16x16x32_f16 v[40:43], v[184:187], v[216:219], v[40:43]
	v_mfma_f32_16x16x32_f16 v[28:31], v[176:179], v[224:227], v[28:31]
	v_mfma_f32_16x16x32_f16 v[24:27], v[184:187], v[224:227], v[24:27]
	v_mfma_f32_16x16x32_f16 v[12:15], v[176:179], v[232:235], v[12:15]
	v_mfma_f32_16x16x32_f16 v[8:11], v[184:187], v[232:235], v[8:11]
	s_setprio 0
	s_setprio 1
	v_mfma_f32_16x16x32_f16 v[52:55], v[188:191], v[204:207], 0
	v_mfma_f32_16x16x32_f16 v[48:51], v[196:199], v[204:207], 0
	v_mfma_f32_16x16x32_f16 v[36:39], v[188:191], v[212:215], 0
	v_mfma_f32_16x16x32_f16 v[32:35], v[196:199], v[212:215], 0
	v_mfma_f32_16x16x32_f16 v[20:23], v[188:191], v[220:223], 0
	v_mfma_f32_16x16x32_f16 v[16:19], v[196:199], v[220:223], 0
	v_mfma_f32_16x16x32_f16 v[4:7], v[188:191], v[228:231], 0
	v_mfma_f32_16x16x32_f16 v[0:3], v[196:199], v[228:231], 0
	v_mfma_f32_16x16x32_f16 v[52:55], v[192:195], v[208:211], v[52:55]
	v_mfma_f32_16x16x32_f16 v[48:51], v[200:203], v[208:211], v[48:51]
	v_mfma_f32_16x16x32_f16 v[36:39], v[192:195], v[216:219], v[36:39]
	v_mfma_f32_16x16x32_f16 v[32:35], v[200:203], v[216:219], v[32:35]
	v_mfma_f32_16x16x32_f16 v[20:23], v[192:195], v[224:227], v[20:23]
	v_mfma_f32_16x16x32_f16 v[16:19], v[200:203], v[224:227], v[16:19]
	v_mfma_f32_16x16x32_f16 v[4:7], v[192:195], v[232:235], v[4:7]
	v_mfma_f32_16x16x32_f16 v[0:3], v[200:203], v[232:235], v[0:3]
	s_setprio 0
	s_barrier
; #define PG8_STAGE(bufoff, gbase, voff) do { _Pragma("unroll") for (int _i = 0; _i < 2; ++_i) \
;         __builtin_amdgcn_global_load_lds((const unsigned*)((const char*)(gbase) + (voff)[_i]), (PG8_LAS unsigned*)(lds + (bufoff) + ldsw + _i * 8192), 16, 0, 0); } while (0)
; #define PG8_LDA(dst, b, h) do { _Pragma("unroll") for (int m = 0; m < 4; ++m) _Pragma("unroll") for (int k = 0; k < 2; ++k) dst[m][k] = *(const PG8_LAS bf16x8*)(lds + PG8_SA(b, h) + aoff + m * 2048 + k * 1024); } while (0)
; #define PG8_LDB(dst, b, h) do { _Pragma("unroll") for (int n = 0; n < 2; ++n) _Pragma("unroll") for (int k = 0; k < 2; ++k) dst[n][k] = *(const PG8_LAS bf16x8*)(lds + PG8_SB(b, h) + boff + n * 2048 + k * 1024); } while (0)
; #define PG8_MMA(ai, bj, At, Bt) do { __builtin_amdgcn_s_setprio(1); _Pragma("unroll") for (int m = 0; m < 4; ++m) _Pragma("unroll") for (int n = 0; n < 2; ++n) _Pragma("unroll") for (int k = 0; k < 2; ++k) \
;         acc[ai][bj][m][n] = mma16<F16>(Bt[n][k], At[m][k], acc[ai][bj][m][n]); __builtin_amdgcn_s_setprio(0); } while (0)
; #define PG8_WAIT_V(n) asm volatile("s_waitcnt vmcnt(" #n ")" ::: "memory")
; #define PG8_WAIT_L(n) asm volatile("s_waitcnt lgkmcnt(" #n ")" ::: "memory")
; #define PG8_BAR __builtin_amdgcn_s_barrier()
; #define PG8_SCHED __builtin_amdgcn_sched_barrier(0)
; template <class Epi, class Sched, bool ALIGN_EPI = false, bool SP2 = false, bool F16 = false, bool TOKPERM = false>
; __device__ __forceinline__ void gemm_phase(PG8_LAS unsigned char* lds, const Gemm g, const Sched& S, const Epi& E, int wv) {
;     ...
;             PG8_LDB(B0, 1, 0); PG8_LDB(B1, 1, 1); PG8_SCHED; PG8_LDA(At, 1, 0); PG8_STAGE(PG8_SA(0, 1), a2 + hstep, voffA);
;             PG8_WAIT_V(8); PG8_WAIT_L(0); PG8_BAR; PG8_MMA(0, 0, At, B0); PG8_MMA(0, 1, At, B1); PG8_BAR; PG8_SCHED;
;             PG8_LDA(At, 1, 1); PG8_STAGE(PG8_SB(1, 0), b3, voffB); PG8_STAGE(PG8_SB(1, 1), b3 + hstep, voffB); PG8_STAGE(PG8_SA(1, 0), a3, voffA);
;             PG8_WAIT_V(8); PG8_WAIT_L(0); PG8_BAR; PG8_MMA(1, 0, At, B0); PG8_MMA(1, 1, At, B1); PG8_BAR; PG8_SCHED;
	ds_read_b128 v[172:175], v163
	ds_read_b128 v[176:179], v164
	ds_read_b128 v[180:183], v165
	ds_read_b128 v[184:187], v166
	ds_read_b128 v[188:191], v167
	ds_read_b128 v[192:195], v168
	ds_read_b128 v[196:199], v169
	ds_read_b128 v[200:203], v170
	s_add_u32 s44, s44, 0x40000
	s_addc_u32 s45, s45, 0
	s_mov_b32 m0, s49
	v_lshl_add_u64 v[242:243], s[44:45], 0, v[134:135]
	ds_read_b128 v[204:207], v153 offset:32768
	ds_read_b128 v[208:211], v153 offset:33792
	ds_read_b128 v[212:215], v153 offset:34816
	ds_read_b128 v[216:219], v153 offset:35840
	ds_read_b128 v[220:223], v153 offset:36864
	ds_read_b128 v[224:227], v153 offset:37888
	ds_read_b128 v[228:231], v153 offset:38912
	ds_read_b128 v[232:235], v153 offset:39936
	global_load_lds_dwordx4 v[242:243], off
	v_lshl_add_u64 v[242:243], s[44:45], 0, v[130:131]
	s_mov_b32 m0, s50
	s_nop 0
	global_load_lds_dwordx4 v[242:243], off
	s_waitcnt vmcnt(8)
	s_waitcnt lgkmcnt(0)
	s_barrier
	s_setprio 1
	v_mfma_f32_16x16x32_f16 v[124:127], v[172:175], v[204:207], v[124:127]
	v_mfma_f32_16x16x32_f16 v[116:119], v[180:183], v[204:207], v[116:119]
	v_mfma_f32_16x16x32_f16 v[108:111], v[172:175], v[212:215], v[108:111]
	v_mfma_f32_16x16x32_f16 v[104:107], v[180:183], v[212:215], v[104:107]
	v_mfma_f32_16x16x32_f16 v[92:95], v[172:175], v[220:223], v[92:95]
	v_mfma_f32_16x16x32_f16 v[88:91], v[180:183], v[220:223], v[88:91]
	v_mfma_f32_16x16x32_f16 v[76:79], v[172:175], v[228:231], v[76:79]
	v_mfma_f32_16x16x32_f16 v[72:75], v[180:183], v[228:231], v[72:75]
	v_mfma_f32_16x16x32_f16 v[124:127], v[176:179], v[208:211], v[124:127]
	v_mfma_f32_16x16x32_f16 v[116:119], v[184:187], v[208:211], v[116:119]
	v_mfma_f32_16x16x32_f16 v[108:111], v[176:179], v[216:219], v[108:111]
	v_mfma_f32_16x16x32_f16 v[104:107], v[184:187], v[216:219], v[104:107]
	v_mfma_f32_16x16x32_f16 v[92:95], v[176:179], v[224:227], v[92:95]
	v_mfma_f32_16x16x32_f16 v[88:91], v[184:187], v[224:227], v[88:91]
	v_mfma_f32_16x16x32_f16 v[76:79], v[176:179], v[232:235], v[76:79]
	v_mfma_f32_16x16x32_f16 v[72:75], v[184:187], v[232:235], v[72:75]
	s_setprio 0
	s_setprio 1
	v_mfma_f32_16x16x32_f16 v[120:123], v[188:191], v[204:207], v[120:123]
	v_mfma_f32_16x16x32_f16 v[112:115], v[196:199], v[204:207], v[112:115]
	v_mfma_f32_16x16x32_f16 v[100:103], v[188:191], v[212:215], v[100:103]
	v_mfma_f32_16x16x32_f16 v[96:99], v[196:199], v[212:215], v[96:99]
	v_mfma_f32_16x16x32_f16 v[84:87], v[188:191], v[220:223], v[84:87]
	v_mfma_f32_16x16x32_f16 v[80:83], v[196:199], v[220:223], v[80:83]
	v_mfma_f32_16x16x32_f16 v[68:71], v[188:191], v[228:231], v[68:71]
	v_mfma_f32_16x16x32_f16 v[64:67], v[196:199], v[228:231], v[64:67]
	v_mfma_f32_16x16x32_f16 v[120:123], v[192:195], v[208:211], v[120:123]
	v_mfma_f32_16x16x32_f16 v[112:115], v[200:203], v[208:211], v[112:115]
	v_mfma_f32_16x16x32_f16 v[100:103], v[192:195], v[216:219], v[100:103]
	v_mfma_f32_16x16x32_f16 v[96:99], v[200:203], v[216:219], v[96:99]
	v_mfma_f32_16x16x32_f16 v[84:87], v[192:195], v[224:227], v[84:87]
	v_mfma_f32_16x16x32_f16 v[80:83], v[200:203], v[224:227], v[80:83]
	v_mfma_f32_16x16x32_f16 v[68:71], v[192:195], v[232:235], v[68:71]
	v_mfma_f32_16x16x32_f16 v[64:67], v[200:203], v[232:235], v[64:67]
	s_setprio 0
	s_barrier
	s_mov_b32 m0, s52
	v_lshl_add_u64 v[148:149], v[148:149], 0, s[14:15]
	s_add_u32 s10, s10, 0x40080
	ds_read_b128 v[204:207], v153 offset:49152
	ds_read_b128 v[208:211], v153 offset:50176
	ds_read_b128 v[212:215], v153 offset:51200
	ds_read_b128 v[216:219], v153 offset:52224
	ds_read_b128 v[220:223], v153 offset:53248
	ds_read_b128 v[224:227], v153 offset:54272
	ds_read_b128 v[228:231], v153 offset:55296
	ds_read_b128 v[232:235], v153 offset:56320
	global_load_lds_dwordx4 v[148:149], off
	v_lshl_add_u64 v[148:149], v[236:237], 0, s[14:15]
	s_mov_b32 m0, s53
	s_addc_u32 s11, s11, 0
	global_load_lds_dwordx4 v[148:149], off
	v_lshl_add_u64 v[148:149], s[10:11], 0, v[132:133]
	s_mov_b32 m0, s56
	s_nop 0
	global_load_lds_dwordx4 v[148:149], off
	v_lshl_add_u64 v[148:149], s[10:11], 0, v[128:129]
	s_mov_b32 m0, s57
	s_nop 0
	global_load_lds_dwordx4 v[148:149], off
	v_lshl_add_u64 v[148:149], v[238:239], 0, s[14:15]
	s_mov_b32 m0, s54
	s_nop 0
	global_load_lds_dwordx4 v[148:149], off
	v_lshl_add_u64 v[148:149], v[240:241], 0, s[14:15]
	s_mov_b32 m0, s55
	s_nop 0
	global_load_lds_dwordx4 v[148:149], off
	s_waitcnt vmcnt(8)
	s_waitcnt lgkmcnt(0)
	s_barrier
	s_setprio 1
	v_mfma_f32_16x16x32_f16 v[60:63], v[172:175], v[204:207], v[60:63]
	v_mfma_f32_16x16x32_f16 v[56:59], v[180:183], v[204:207], v[56:59]
	v_mfma_f32_16x16x32_f16 v[44:47], v[172:175], v[212:215], v[44:47]
	v_mfma_f32_16x16x32_f16 v[40:43], v[180:183], v[212:215], v[40:43]
	v_mfma_f32_16x16x32_f16 v[28:31], v[172:175], v[220:223], v[28:31]
	v_mfma_f32_16x16x32_f16 v[24:27], v[180:183], v[220:223], v[24:27]
	v_mfma_f32_16x16x32_f16 v[12:15], v[172:175], v[228:231], v[12:15]
	v_mfma_f32_16x16x32_f16 v[8:11], v[180:183], v[228:231], v[8:11]
	v_mfma_f32_16x16x32_f16 v[60:63], v[176:179], v[208:211], v[60:63]
	v_mfma_f32_16x16x32_f16 v[56:59], v[184:187], v[208:211], v[56:59]
	v_mfma_f32_16x16x32_f16 v[44:47], v[176:179], v[216:219], v[44:47]
	v_mfma_f32_16x16x32_f16 v[40:43], v[184:187], v[216:219], v[40:43]
	v_mfma_f32_16x16x32_f16 v[28:31], v[176:179], v[224:227], v[28:31]
	v_mfma_f32_16x16x32_f16 v[24:27], v[184:187], v[224:227], v[24:27]
	v_mfma_f32_16x16x32_f16 v[12:15], v[176:179], v[232:235], v[12:15]
	v_mfma_f32_16x16x32_f16 v[8:11], v[184:187], v[232:235], v[8:11]
	s_setprio 0
	s_setprio 1
	v_mfma_f32_16x16x32_f16 v[52:55], v[188:191], v[204:207], v[52:55]
	v_mfma_f32_16x16x32_f16 v[48:51], v[196:199], v[204:207], v[48:51]
	v_mfma_f32_16x16x32_f16 v[36:39], v[188:191], v[212:215], v[36:39]
	v_mfma_f32_16x16x32_f16 v[32:35], v[196:199], v[212:215], v[32:35]
	v_mfma_f32_16x16x32_f16 v[20:23], v[188:191], v[220:223], v[20:23]
	v_mfma_f32_16x16x32_f16 v[16:19], v[196:199], v[220:223], v[16:19]
	v_mfma_f32_16x16x32_f16 v[4:7], v[188:191], v[228:231], v[4:7]
	v_mfma_f32_16x16x32_f16 v[0:3], v[196:199], v[228:231], v[0:3]
	v_mfma_f32_16x16x32_f16 v[52:55], v[192:195], v[208:211], v[52:55]
	v_mfma_f32_16x16x32_f16 v[48:51], v[200:203], v[208:211], v[48:51]
	v_mfma_f32_16x16x32_f16 v[36:39], v[192:195], v[216:219], v[36:39]
	v_mfma_f32_16x16x32_f16 v[32:35], v[200:203], v[216:219], v[32:35]
	v_mfma_f32_16x16x32_f16 v[20:23], v[192:195], v[224:227], v[20:23]
	v_mfma_f32_16x16x32_f16 v[16:19], v[200:203], v[224:227], v[16:19]
	v_mfma_f32_16x16x32_f16 v[4:7], v[192:195], v[232:235], v[4:7]
	v_mfma_f32_16x16x32_f16 v[0:3], v[200:203], v[232:235], v[0:3]
	s_setprio 0
	s_barrier
	s_add_i32 s68, s68, 2
	s_add_u32 s8, s8, 0x100
	s_addc_u32 s9, s9, 0
	s_add_u32 s66, s66, 0x100
	s_addc_u32 s67, s67, 0
	s_cmp_gt_u32 s68, 13
; #define PG8_STAGE(bufoff, gbase, voff) do { _Pragma("unroll") for (int _i = 0; _i < 2; ++_i) \
;         __builtin_amdgcn_global_load_lds((const unsigned*)((const char*)(gbase) + (voff)[_i]), (PG8_LAS unsigned*)(lds + (bufoff) + ldsw + _i * 8192), 16, 0, 0); } while (0)
; #define PG8_LDA(dst, b, h) do { _Pragma("unroll") for (int m = 0; m < 4; ++m) _Pragma("unroll") for (int k = 0; k < 2; ++k) dst[m][k] = *(const PG8_LAS bf16x8*)(lds + PG8_SA(b, h) + aoff + m * 2048 + k * 1024); } while (0)
; #define PG8_LDB(dst, b, h) do { _Pragma("unroll") for (int n = 0; n < 2; ++n) _Pragma("unroll") for (int k = 0; k < 2; ++k) dst[n][k] = *(const PG8_LAS bf16x8*)(lds + PG8_SB(b, h) + boff + n * 2048 + k * 1024); } while (0)
; #define PG8_MMA(ai, bj, At, Bt) do { __builtin_amdgcn_s_setprio(1); _Pragma("unroll") for (int m = 0; m < 4; ++m) _Pragma("unroll") for (int n = 0; n < 2; ++n) _Pragma("unroll") for (int k = 0; k < 2; ++k) \
;         acc[ai][bj][m][n] = mma16<F16>(Bt[n][k], At[m][k], acc[ai][bj][m][n]); __builtin_amdgcn_s_setprio(0); } while (0)
; #define PG8_WAIT_V(n) asm volatile("s_waitcnt vmcnt(" #n ")" ::: "memory")
; #define PG8_WAIT_L(n) asm volatile("s_waitcnt lgkmcnt(" #n ")" ::: "memory")
; #define PG8_BAR __builtin_amdgcn_s_barrier()
; #define PG8_SCHED __builtin_amdgcn_sched_barrier(0)
; template <class Epi, class Sched, bool ALIGN_EPI = false, bool SP2 = false, bool F16 = false, bool TOKPERM = false>
; __device__ __forceinline__ void gemm_phase(PG8_LAS unsigned char* lds, const Gemm g, const Sched& S, const Epi& E, int wv) {
;     ...
;             PG8_LDB(B0, 0, 0); PG8_LDB(B1, 0, 1); PG8_SCHED; PG8_LDA(At, 0, 0); PG8_STAGE(PG8_SA(1, 1), a1 + hstep, voffA);
;             PG8_WAIT_V(8); PG8_WAIT_L(0); PG8_BAR; PG8_MMA(0, 0, At, B0); PG8_MMA(0, 1, At, B1); PG8_BAR; PG8_SCHED;
;             PG8_LDA(At, 0, 1); PG8_STAGE(PG8_SB(0, 0), b2, voffB); PG8_STAGE(PG8_SB(0, 1), b2 + hstep, voffB); PG8_STAGE(PG8_SA(0, 0), a2, voffA);
;             PG8_WAIT_V(8); PG8_WAIT_L(0); PG8_BAR; PG8_MMA(1, 0, At, B0); PG8_MMA(1, 1, At, B1); PG8_BAR; PG8_SCHED;
.LBB0_1607:
	ds_read_b128 v[172:175], v155
	ds_read_b128 v[176:179], v156
	ds_read_b128 v[180:183], v157
	ds_read_b128 v[184:187], v158
	ds_read_b128 v[188:191], v159
	ds_read_b128 v[192:195], v160
	ds_read_b128 v[196:199], v161
	ds_read_b128 v[200:203], v162
	s_add_u32 s10, s8, 0xfffc0080
	s_addc_u32 s11, s9, -1
	s_cmp_eq_u32 s68, 12
	s_cselect_b32 s45, s25, s11
	s_cselect_b32 s44, s64, s10
	s_cselect_b32 s11, s23, s67
	s_cselect_b32 s10, s65, s66
	s_mov_b32 m0, s60
	v_lshl_add_u64 v[148:149], s[8:9], 0, v[140:141]
	ds_read_b128 v[204:207], v153
	ds_read_b128 v[208:211], v153 offset:1024
	ds_read_b128 v[212:215], v153 offset:2048
	ds_read_b128 v[216:219], v153 offset:3072
	ds_read_b128 v[220:223], v153 offset:4096
	ds_read_b128 v[224:227], v153 offset:5120
	ds_read_b128 v[228:231], v153 offset:6144
	ds_read_b128 v[232:235], v153 offset:7168
	global_load_lds_dwordx4 v[148:149], off
	v_lshl_add_u64 v[148:149], s[8:9], 0, v[142:143]
	s_mov_b32 m0, s61
	s_nop 0
	global_load_lds_dwordx4 v[148:149], off
	s_waitcnt vmcnt(8)
	s_waitcnt lgkmcnt(0)
	s_barrier
	s_setprio 1
	v_mfma_f32_16x16x32_f16 v[124:127], v[172:175], v[204:207], v[124:127]
	v_mfma_f32_16x16x32_f16 v[116:119], v[180:183], v[204:207], v[116:119]
	v_mfma_f32_16x16x32_f16 v[108:111], v[172:175], v[212:215], v[108:111]
	v_mfma_f32_16x16x32_f16 v[104:107], v[180:183], v[212:215], v[104:107]
	v_mfma_f32_16x16x32_f16 v[92:95], v[172:175], v[220:223], v[92:95]
	v_mfma_f32_16x16x32_f16 v[88:91], v[180:183], v[220:223], v[88:91]
	v_mfma_f32_16x16x32_f16 v[76:79], v[172:175], v[228:231], v[76:79]
	v_mfma_f32_16x16x32_f16 v[72:75], v[180:183], v[228:231], v[72:75]
	v_mfma_f32_16x16x32_f16 v[124:127], v[176:179], v[208:211], v[124:127]
	v_mfma_f32_16x16x32_f16 v[116:119], v[184:187], v[208:211], v[116:119]
	v_mfma_f32_16x16x32_f16 v[108:111], v[176:179], v[216:219], v[108:111]
	v_mfma_f32_16x16x32_f16 v[104:107], v[184:187], v[216:219], v[104:107]
	v_mfma_f32_16x16x32_f16 v[92:95], v[176:179], v[224:227], v[92:95]
	v_mfma_f32_16x16x32_f16 v[88:91], v[184:187], v[224:227], v[88:91]
	v_mfma_f32_16x16x32_f16 v[76:79], v[176:179], v[232:235], v[76:79]
	v_mfma_f32_16x16x32_f16 v[72:75], v[184:187], v[232:235], v[72:75]
	s_setprio 0
	s_setprio 1
	v_mfma_f32_16x16x32_f16 v[120:123], v[188:191], v[204:207], v[120:123]
	v_mfma_f32_16x16x32_f16 v[112:115], v[196:199], v[204:207], v[112:115]
	v_mfma_f32_16x16x32_f16 v[100:103], v[188:191], v[212:215], v[100:103]
	v_mfma_f32_16x16x32_f16 v[96:99], v[196:199], v[212:215], v[96:99]
	v_mfma_f32_16x16x32_f16 v[84:87], v[188:191], v[220:223], v[84:87]
	v_mfma_f32_16x16x32_f16 v[80:83], v[196:199], v[220:223], v[80:83]
	v_mfma_f32_16x16x32_f16 v[68:71], v[188:191], v[228:231], v[68:71]
	v_mfma_f32_16x16x32_f16 v[64:67], v[196:199], v[228:231], v[64:67]
	v_mfma_f32_16x16x32_f16 v[120:123], v[192:195], v[208:211], v[120:123]
	v_mfma_f32_16x16x32_f16 v[112:115], v[200:203], v[208:211], v[112:115]
	v_mfma_f32_16x16x32_f16 v[100:103], v[192:195], v[216:219], v[100:103]
	v_mfma_f32_16x16x32_f16 v[96:99], v[200:203], v[216:219], v[96:99]
	v_mfma_f32_16x16x32_f16 v[84:87], v[192:195], v[224:227], v[84:87]
	v_mfma_f32_16x16x32_f16 v[80:83], v[200:203], v[224:227], v[80:83]
	v_mfma_f32_16x16x32_f16 v[68:71], v[192:195], v[232:235], v[68:71]
	v_mfma_f32_16x16x32_f16 v[64:67], v[200:203], v[232:235], v[64:67]
	s_setprio 0
	s_barrier
	s_mov_b32 m0, s21
	v_lshl_add_u64 v[148:149], s[10:11], 0, v[132:133]
	s_add_u32 s70, s10, 0x40000
	ds_read_b128 v[204:207], v153 offset:16384
	ds_read_b128 v[208:211], v153 offset:17408
	ds_read_b128 v[212:215], v153 offset:18432
	ds_read_b128 v[216:219], v153 offset:19456
	ds_read_b128 v[220:223], v153 offset:20480
	ds_read_b128 v[224:227], v153 offset:21504
	ds_read_b128 v[228:231], v153 offset:22528
	ds_read_b128 v[232:235], v153 offset:23552
	global_load_lds_dwordx4 v[148:149], off
	v_lshl_add_u64 v[236:237], s[10:11], 0, v[128:129]
	s_mov_b32 m0, s33
	s_addc_u32 s71, s11, 0
	global_load_lds_dwordx4 v[236:237], off
	v_lshl_add_u64 v[238:239], s[70:71], 0, v[132:133]
	s_mov_b32 m0, s46
	v_lshl_add_u64 v[240:241], s[44:45], 0, v[130:131]
	global_load_lds_dwordx4 v[238:239], off
	v_lshl_add_u64 v[238:239], s[70:71], 0, v[128:129]
	s_mov_b32 m0, s47
	s_nop 0
	global_load_lds_dwordx4 v[238:239], off
	v_lshl_add_u64 v[238:239], s[44:45], 0, v[134:135]
	s_mov_b32 m0, s2
	s_nop 0
	global_load_lds_dwordx4 v[238:239], off
	s_mov_b32 m0, s48
	s_nop 0
	global_load_lds_dwordx4 v[240:241], off
	s_waitcnt vmcnt(8)
	s_waitcnt lgkmcnt(0)
	s_barrier
	s_setprio 1
	v_mfma_f32_16x16x32_f16 v[60:63], v[172:175], v[204:207], v[60:63]
	v_mfma_f32_16x16x32_f16 v[56:59], v[180:183], v[204:207], v[56:59]
	v_mfma_f32_16x16x32_f16 v[44:47], v[172:175], v[212:215], v[44:47]
	v_mfma_f32_16x16x32_f16 v[40:43], v[180:183], v[212:215], v[40:43]
	v_mfma_f32_16x16x32_f16 v[28:31], v[172:175], v[220:223], v[28:31]
	v_mfma_f32_16x16x32_f16 v[24:27], v[180:183], v[220:223], v[24:27]
	v_mfma_f32_16x16x32_f16 v[12:15], v[172:175], v[228:231], v[12:15]
	v_mfma_f32_16x16x32_f16 v[8:11], v[180:183], v[228:231], v[8:11]
	v_mfma_f32_16x16x32_f16 v[60:63], v[176:179], v[208:211], v[60:63]
	v_mfma_f32_16x16x32_f16 v[56:59], v[184:187], v[208:211], v[56:59]
	v_mfma_f32_16x16x32_f16 v[44:47], v[176:179], v[216:219], v[44:47]
	v_mfma_f32_16x16x32_f16 v[40:43], v[184:187], v[216:219], v[40:43]
	v_mfma_f32_16x16x32_f16 v[28:31], v[176:179], v[224:227], v[28:31]
	v_mfma_f32_16x16x32_f16 v[24:27], v[184:187], v[224:227], v[24:27]
	v_mfma_f32_16x16x32_f16 v[12:15], v[176:179], v[232:235], v[12:15]
	v_mfma_f32_16x16x32_f16 v[8:11], v[184:187], v[232:235], v[8:11]
	s_setprio 0
	s_setprio 1
	v_mfma_f32_16x16x32_f16 v[52:55], v[188:191], v[204:207], v[52:55]
	v_mfma_f32_16x16x32_f16 v[48:51], v[196:199], v[204:207], v[48:51]
	v_mfma_f32_16x16x32_f16 v[36:39], v[188:191], v[212:215], v[36:39]
	v_mfma_f32_16x16x32_f16 v[32:35], v[196:199], v[212:215], v[32:35]
	v_mfma_f32_16x16x32_f16 v[20:23], v[188:191], v[220:223], v[20:23]
	v_mfma_f32_16x16x32_f16 v[16:19], v[196:199], v[220:223], v[16:19]
	v_mfma_f32_16x16x32_f16 v[4:7], v[188:191], v[228:231], v[4:7]
	v_mfma_f32_16x16x32_f16 v[0:3], v[196:199], v[228:231], v[0:3]
	v_mfma_f32_16x16x32_f16 v[52:55], v[192:195], v[208:211], v[52:55]
	v_mfma_f32_16x16x32_f16 v[48:51], v[200:203], v[208:211], v[48:51]
	v_mfma_f32_16x16x32_f16 v[36:39], v[192:195], v[216:219], v[36:39]
	v_mfma_f32_16x16x32_f16 v[32:35], v[200:203], v[216:219], v[32:35]
	v_mfma_f32_16x16x32_f16 v[20:23], v[192:195], v[224:227], v[20:23]
	v_mfma_f32_16x16x32_f16 v[16:19], v[200:203], v[224:227], v[16:19]
	v_mfma_f32_16x16x32_f16 v[4:7], v[192:195], v[232:235], v[4:7]
	v_mfma_f32_16x16x32_f16 v[0:3], v[200:203], v[232:235], v[0:3]
	s_setprio 0
	s_barrier
; #define PG8_STAGE(bufoff, gbase, voff) do { _Pragma("unroll") for (int _i = 0; _i < 2; ++_i) \
;         __builtin_amdgcn_global_load_lds((const unsigned*)((const char*)(gbase) + (voff)[_i]), (PG8_LAS unsigned*)(lds + (bufoff) + ldsw + _i * 8192), 16, 0, 0); } while (0)
; #define PG8_LDA(dst, b, h) do { _Pragma("unroll") for (int m = 0; m < 4; ++m) _Pragma("unroll") for (int k = 0; k < 2; ++k) dst[m][k] = *(const PG8_LAS bf16x8*)(lds + PG8_SA(b, h) + aoff + m * 2048 + k * 1024); } while (0)
; #define PG8_LDB(dst, b, h) do { _Pragma("unroll") for (int n = 0; n < 2; ++n) _Pragma("unroll") for (int k = 0; k < 2; ++k) dst[n][k] = *(const PG8_LAS bf16x8*)(lds + PG8_SB(b, h) + boff + n * 2048 + k * 1024); } while (0)
; #define PG8_MMA(ai, bj, At, Bt) do { __builtin_amdgcn_s_setprio(1); _Pragma("unroll") for (int m = 0; m < 4; ++m) _Pragma("unroll") for (int n = 0; n < 2; ++n) _Pragma("unroll") for (int k = 0; k < 2; ++k) \
;         acc[ai][bj][m][n] = mma16<F16>(Bt[n][k], At[m][k], acc[ai][bj][m][n]); __builtin_amdgcn_s_setprio(0); } while (0)
; #define PG8_WAIT_V(n) asm volatile("s_waitcnt vmcnt(" #n ")" ::: "memory")
; #define PG8_WAIT_L(n) asm volatile("s_waitcnt lgkmcnt(" #n ")" ::: "memory")
; #define PG8_BAR __builtin_amdgcn_s_barrier()
; #define PG8_SCHED __builtin_amdgcn_sched_barrier(0)
; template <class Epi, class Sched, bool ALIGN_EPI = false, bool SP2 = false, bool F16 = false, bool TOKPERM = false>
; __device__ __forceinline__ void gemm_phase(PG8_LAS unsigned char* lds, const Gemm g, const Sched& S, const Epi& E, int wv) {
;     ...
;             PG8_LDB(B0, 1, 0); PG8_LDB(B1, 1, 1); PG8_SCHED; PG8_LDA(At, 1, 0); PG8_STAGE(PG8_SA(0, 1), a2 + hstep, voffA);
;             PG8_WAIT_V(8); PG8_WAIT_L(0); PG8_BAR; PG8_MMA(0, 0, At, B0); PG8_MMA(0, 1, At, B1); PG8_BAR; PG8_SCHED;
;             PG8_LDA(At, 1, 1); PG8_STAGE(PG8_SB(1, 0), b3, voffB); PG8_STAGE(PG8_SB(1, 1), b3 + hstep, voffB); PG8_STAGE(PG8_SA(1, 0), a3, voffA);
;             PG8_WAIT_V(8); PG8_WAIT_L(0); PG8_BAR; PG8_MMA(1, 0, At, B0); PG8_MMA(1, 1, At, B1); PG8_BAR; PG8_SCHED;
;     ...
;         if constexpr (ALIGN_EPI) { if (wr == 0) PG8_BAR; }
	ds_read_b128 v[172:175], v163
	ds_read_b128 v[176:179], v164
	ds_read_b128 v[180:183], v165
	ds_read_b128 v[184:187], v166
	ds_read_b128 v[188:191], v167
	ds_read_b128 v[192:195], v168
	ds_read_b128 v[196:199], v169
	ds_read_b128 v[200:203], v170
	s_add_u32 s44, s44, 0x40000
	s_addc_u32 s45, s45, 0
	s_mov_b32 m0, s49
	v_lshl_add_u64 v[242:243], s[44:45], 0, v[134:135]
	ds_read_b128 v[204:207], v153 offset:32768
	ds_read_b128 v[208:211], v153 offset:33792
	ds_read_b128 v[212:215], v153 offset:34816
	ds_read_b128 v[216:219], v153 offset:35840
	ds_read_b128 v[220:223], v153 offset:36864
	ds_read_b128 v[224:227], v153 offset:37888
	ds_read_b128 v[228:231], v153 offset:38912
	ds_read_b128 v[232:235], v153 offset:39936
	global_load_lds_dwordx4 v[242:243], off
	v_lshl_add_u64 v[242:243], s[44:45], 0, v[130:131]
	s_mov_b32 m0, s50
	s_nop 0
	global_load_lds_dwordx4 v[242:243], off
	s_waitcnt vmcnt(8)
	s_waitcnt lgkmcnt(0)
	s_barrier
	s_setprio 1
	v_mfma_f32_16x16x32_f16 v[124:127], v[172:175], v[204:207], v[124:127]
	v_mfma_f32_16x16x32_f16 v[116:119], v[180:183], v[204:207], v[116:119]
	v_mfma_f32_16x16x32_f16 v[108:111], v[172:175], v[212:215], v[108:111]
	v_mfma_f32_16x16x32_f16 v[104:107], v[180:183], v[212:215], v[104:107]
	v_mfma_f32_16x16x32_f16 v[92:95], v[172:175], v[220:223], v[92:95]
	v_mfma_f32_16x16x32_f16 v[88:91], v[180:183], v[220:223], v[88:91]
	v_mfma_f32_16x16x32_f16 v[76:79], v[172:175], v[228:231], v[76:79]
	v_mfma_f32_16x16x32_f16 v[72:75], v[180:183], v[228:231], v[72:75]
	v_mfma_f32_16x16x32_f16 v[124:127], v[176:179], v[208:211], v[124:127]
	v_mfma_f32_16x16x32_f16 v[116:119], v[184:187], v[208:211], v[116:119]
	v_mfma_f32_16x16x32_f16 v[108:111], v[176:179], v[216:219], v[108:111]
	v_mfma_f32_16x16x32_f16 v[104:107], v[184:187], v[216:219], v[104:107]
	v_mfma_f32_16x16x32_f16 v[92:95], v[176:179], v[224:227], v[92:95]
	v_mfma_f32_16x16x32_f16 v[88:91], v[184:187], v[224:227], v[88:91]
	v_mfma_f32_16x16x32_f16 v[76:79], v[176:179], v[232:235], v[76:79]
	v_mfma_f32_16x16x32_f16 v[72:75], v[184:187], v[232:235], v[72:75]
	s_setprio 0
	s_setprio 1
	v_mfma_f32_16x16x32_f16 v[120:123], v[188:191], v[204:207], v[120:123]
	v_mfma_f32_16x16x32_f16 v[112:115], v[196:199], v[204:207], v[112:115]
	v_mfma_f32_16x16x32_f16 v[100:103], v[188:191], v[212:215], v[100:103]
	v_mfma_f32_16x16x32_f16 v[96:99], v[196:199], v[212:215], v[96:99]
	v_mfma_f32_16x16x32_f16 v[84:87], v[188:191], v[220:223], v[84:87]
	v_mfma_f32_16x16x32_f16 v[80:83], v[196:199], v[220:223], v[80:83]
	v_mfma_f32_16x16x32_f16 v[68:71], v[188:191], v[228:231], v[68:71]
	v_mfma_f32_16x16x32_f16 v[64:67], v[196:199], v[228:231], v[64:67]
	v_mfma_f32_16x16x32_f16 v[120:123], v[192:195], v[208:211], v[120:123]
	v_mfma_f32_16x16x32_f16 v[112:115], v[200:203], v[208:211], v[112:115]
	v_mfma_f32_16x16x32_f16 v[100:103], v[192:195], v[216:219], v[100:103]
	v_mfma_f32_16x16x32_f16 v[96:99], v[200:203], v[216:219], v[96:99]
	v_mfma_f32_16x16x32_f16 v[84:87], v[192:195], v[224:227], v[84:87]
	v_mfma_f32_16x16x32_f16 v[80:83], v[200:203], v[224:227], v[80:83]
	v_mfma_f32_16x16x32_f16 v[68:71], v[192:195], v[232:235], v[68:71]
	v_mfma_f32_16x16x32_f16 v[64:67], v[200:203], v[232:235], v[64:67]
	s_setprio 0
	s_barrier
	s_mov_b32 m0, s52
	v_lshl_add_u64 v[148:149], v[148:149], 0, s[14:15]
	s_add_u32 s10, s10, 0x40080
	ds_read_b128 v[204:207], v153 offset:49152
	ds_read_b128 v[208:211], v153 offset:50176
	ds_read_b128 v[212:215], v153 offset:51200
	ds_read_b128 v[216:219], v153 offset:52224
	ds_read_b128 v[220:223], v153 offset:53248
	ds_read_b128 v[224:227], v153 offset:54272
	ds_read_b128 v[228:231], v153 offset:55296
	ds_read_b128 v[232:235], v153 offset:56320
	global_load_lds_dwordx4 v[148:149], off
	v_lshl_add_u64 v[148:149], v[236:237], 0, s[14:15]
	s_mov_b32 m0, s53
	s_addc_u32 s11, s11, 0
	global_load_lds_dwordx4 v[148:149], off
	v_lshl_add_u64 v[148:149], s[10:11], 0, v[132:133]
	s_mov_b32 m0, s56
	s_nop 0
	global_load_lds_dwordx4 v[148:149], off
	v_lshl_add_u64 v[148:149], s[10:11], 0, v[128:129]
	s_mov_b32 m0, s57
	s_nop 0
	global_load_lds_dwordx4 v[148:149], off
	v_lshl_add_u64 v[148:149], v[238:239], 0, s[14:15]
	s_mov_b32 m0, s54
	s_nop 0
	global_load_lds_dwordx4 v[148:149], off
	v_lshl_add_u64 v[148:149], v[240:241], 0, s[14:15]
	s_mov_b32 m0, s55
	s_nop 0
	global_load_lds_dwordx4 v[148:149], off
	s_waitcnt vmcnt(8)
	s_waitcnt lgkmcnt(0)
	s_barrier
	s_setprio 1
	v_mfma_f32_16x16x32_f16 v[60:63], v[172:175], v[204:207], v[60:63]
	v_mfma_f32_16x16x32_f16 v[56:59], v[180:183], v[204:207], v[56:59]
	v_mfma_f32_16x16x32_f16 v[44:47], v[172:175], v[212:215], v[44:47]
	v_mfma_f32_16x16x32_f16 v[40:43], v[180:183], v[212:215], v[40:43]
	v_mfma_f32_16x16x32_f16 v[28:31], v[172:175], v[220:223], v[28:31]
	v_mfma_f32_16x16x32_f16 v[24:27], v[180:183], v[220:223], v[24:27]
	v_mfma_f32_16x16x32_f16 v[12:15], v[172:175], v[228:231], v[12:15]
	v_mfma_f32_16x16x32_f16 v[8:11], v[180:183], v[228:231], v[8:11]
	v_mfma_f32_16x16x32_f16 v[60:63], v[176:179], v[208:211], v[60:63]
	v_mfma_f32_16x16x32_f16 v[56:59], v[184:187], v[208:211], v[56:59]
	v_mfma_f32_16x16x32_f16 v[44:47], v[176:179], v[216:219], v[44:47]
	v_mfma_f32_16x16x32_f16 v[40:43], v[184:187], v[216:219], v[40:43]
	v_mfma_f32_16x16x32_f16 v[28:31], v[176:179], v[224:227], v[28:31]
	v_mfma_f32_16x16x32_f16 v[24:27], v[184:187], v[224:227], v[24:27]
	v_mfma_f32_16x16x32_f16 v[12:15], v[176:179], v[232:235], v[12:15]
	v_mfma_f32_16x16x32_f16 v[8:11], v[184:187], v[232:235], v[8:11]
	s_setprio 0
	s_setprio 1
	v_mfma_f32_16x16x32_f16 v[52:55], v[188:191], v[204:207], v[52:55]
	v_mfma_f32_16x16x32_f16 v[48:51], v[196:199], v[204:207], v[48:51]
	v_mfma_f32_16x16x32_f16 v[36:39], v[188:191], v[212:215], v[36:39]
	v_mfma_f32_16x16x32_f16 v[32:35], v[196:199], v[212:215], v[32:35]
	v_mfma_f32_16x16x32_f16 v[20:23], v[188:191], v[220:223], v[20:23]
	v_mfma_f32_16x16x32_f16 v[16:19], v[196:199], v[220:223], v[16:19]
	v_mfma_f32_16x16x32_f16 v[4:7], v[188:191], v[228:231], v[4:7]
	v_mfma_f32_16x16x32_f16 v[0:3], v[196:199], v[228:231], v[0:3]
	v_mfma_f32_16x16x32_f16 v[52:55], v[192:195], v[208:211], v[52:55]
	v_mfma_f32_16x16x32_f16 v[48:51], v[200:203], v[208:211], v[48:51]
	v_mfma_f32_16x16x32_f16 v[36:39], v[192:195], v[216:219], v[36:39]
	v_mfma_f32_16x16x32_f16 v[32:35], v[200:203], v[216:219], v[32:35]
	v_mfma_f32_16x16x32_f16 v[20:23], v[192:195], v[224:227], v[20:23]
	v_mfma_f32_16x16x32_f16 v[16:19], v[200:203], v[224:227], v[16:19]
	v_mfma_f32_16x16x32_f16 v[4:7], v[192:195], v[232:235], v[4:7]
	v_mfma_f32_16x16x32_f16 v[0:3], v[200:203], v[232:235], v[0:3]
	s_setprio 0
	s_barrier
	s_add_i32 s68, s68, 2
	s_add_u32 s8, s8, 0x100
	s_addc_u32 s9, s9, 0
	s_add_u32 s66, s66, 0x100
	s_addc_u32 s67, s67, 0
	s_cmp_gt_u32 s68, 13
	s_cbranch_scc0 .LBB0_1607
	s_and_b64 vcc, exec, s[16:17]
	s_cbranch_vccz .LBB0_1610
	s_barrier

; #define PG8_STAGE(bufoff, gbase, voff) do { _Pragma("unroll") for (int _i = 0; _i < 2; ++_i) \
;         __builtin_amdgcn_global_load_lds((const unsigned*)((const char*)(gbase) + (voff)[_i]), (PG8_LAS unsigned*)(lds + (bufoff) + ldsw + _i * 8192), 16, 0, 0); } while (0)
; #define PG8_LDA(dst, b, h) do { _Pragma("unroll") for (int m = 0; m < 4; ++m) _Pragma("unroll") for (int k = 0; k < 2; ++k) dst[m][k] = *(const PG8_LAS bf16x8*)(lds + PG8_SA(b, h) + aoff + m * 2048 + k * 1024); } while (0)
; #define PG8_LDB(dst, b, h) do { _Pragma("unroll") for (int n = 0; n < 2; ++n) _Pragma("unroll") for (int k = 0; k < 2; ++k) dst[n][k] = *(const PG8_LAS bf16x8*)(lds + PG8_SB(b, h) + boff + n * 2048 + k * 1024); } while (0)
; #define PG8_MMA(ai, bj, At, Bt) do { __builtin_amdgcn_s_setprio(1); _Pragma("unroll") for (int m = 0; m < 4; ++m) _Pragma("unroll") for (int n = 0; n < 2; ++n) _Pragma("unroll") for (int k = 0; k < 2; ++k) \
;         acc[ai][bj][m][n] = mma16<F16>(Bt[n][k], At[m][k], acc[ai][bj][m][n]); __builtin_amdgcn_s_setprio(0); } while (0)
; #define PG8_WAIT_V(n) asm volatile("s_waitcnt vmcnt(" #n ")" ::: "memory")
; #define PG8_WAIT_L(n) asm volatile("s_waitcnt lgkmcnt(" #n ")" ::: "memory")
; #define PG8_BAR __builtin_amdgcn_s_barrier()
; #define PG8_SCHED __builtin_amdgcn_sched_barrier(0)
; template <class Epi, class Sched, bool ALIGN_EPI = false, bool SP2 = false, bool F16 = false, bool TOKPERM = false>
; __device__ __forceinline__ void gemm_phase(PG8_LAS unsigned char* lds, const Gemm g, const Sched& S, const Epi& E, int wv) {
;     ...
;             PG8_LDB(B0, 0, 0); PG8_LDB(B1, 0, 1); PG8_SCHED; PG8_LDA(At, 0, 0); PG8_STAGE(PG8_SA(1, 1), a1 + hstep, voffA);
;             PG8_WAIT_V(8); PG8_WAIT_L(0); PG8_BAR; PG8_MMA(0, 0, At, B0); PG8_MMA(0, 1, At, B1); PG8_BAR; PG8_SCHED;
;             PG8_LDA(At, 0, 1); PG8_STAGE(PG8_SB(0, 0), b2, voffB); PG8_STAGE(PG8_SB(0, 1), b2 + hstep, voffB); PG8_STAGE(PG8_SA(0, 0), a2, voffA);
.LBB0_1687:
	ds_read_b128 v[166:169], v149
	ds_read_b128 v[170:173], v150
	ds_read_b128 v[174:177], v151
	ds_read_b128 v[178:181], v152
	ds_read_b128 v[182:185], v153
	ds_read_b128 v[186:189], v154
	ds_read_b128 v[190:193], v155
	ds_read_b128 v[194:197], v156
	s_add_u32 s10, s8, 0x100
	s_addc_u32 s11, s9, 0
	s_cmp_eq_u32 s53, 40
	s_cselect_b32 s15, s3, s11
	s_cselect_b32 s14, s2, s10
	s_cselect_b32 s13, s5, s52
	s_cselect_b32 s12, s4, s51
	s_mov_b32 m0, s45
	v_lshl_add_u64 v[230:231], s[8:9], 0, v[138:139]
	ds_read_b128 v[198:201], v147
	ds_read_b128 v[202:205], v147 offset:1024
	ds_read_b128 v[206:209], v147 offset:2048
	ds_read_b128 v[210:213], v147 offset:3072
	ds_read_b128 v[214:217], v147 offset:4096
	ds_read_b128 v[218:221], v147 offset:5120
	ds_read_b128 v[222:225], v147 offset:6144
	ds_read_b128 v[226:229], v147 offset:7168
	global_load_lds_dwordx4 v[230:231], off
	v_lshl_add_u64 v[230:231], s[8:9], 0, v[140:141]
	s_mov_b32 m0, s46
	s_nop 0
	global_load_lds_dwordx4 v[230:231], off
	s_waitcnt vmcnt(8)
	s_waitcnt lgkmcnt(0)
	s_barrier
	s_setprio 1
	v_mfma_f32_16x16x32_bf16 v[124:127], v[166:169], v[198:201], v[124:127]
	v_mfma_f32_16x16x32_bf16 v[120:123], v[174:177], v[198:201], v[120:123]
	v_mfma_f32_16x16x32_bf16 v[108:111], v[166:169], v[206:209], v[108:111]
	v_mfma_f32_16x16x32_bf16 v[104:107], v[174:177], v[206:209], v[104:107]
	v_mfma_f32_16x16x32_bf16 v[92:95], v[166:169], v[214:217], v[92:95]
	v_mfma_f32_16x16x32_bf16 v[88:91], v[174:177], v[214:217], v[88:91]
	v_mfma_f32_16x16x32_bf16 v[76:79], v[166:169], v[222:225], v[76:79]
	v_mfma_f32_16x16x32_bf16 v[72:75], v[174:177], v[222:225], v[72:75]
	v_mfma_f32_16x16x32_bf16 v[124:127], v[170:173], v[202:205], v[124:127]
	v_mfma_f32_16x16x32_bf16 v[120:123], v[178:181], v[202:205], v[120:123]
	v_mfma_f32_16x16x32_bf16 v[108:111], v[170:173], v[210:213], v[108:111]
	v_mfma_f32_16x16x32_bf16 v[104:107], v[178:181], v[210:213], v[104:107]
	v_mfma_f32_16x16x32_bf16 v[92:95], v[170:173], v[218:221], v[92:95]
	v_mfma_f32_16x16x32_bf16 v[88:91], v[178:181], v[218:221], v[88:91]
	v_mfma_f32_16x16x32_bf16 v[76:79], v[170:173], v[226:229], v[76:79]
	v_mfma_f32_16x16x32_bf16 v[72:75], v[178:181], v[226:229], v[72:75]
	s_setprio 0
	s_setprio 1
	v_mfma_f32_16x16x32_bf16 v[116:119], v[182:185], v[198:201], v[116:119]
	v_mfma_f32_16x16x32_bf16 v[112:115], v[190:193], v[198:201], v[112:115]
	v_mfma_f32_16x16x32_bf16 v[100:103], v[182:185], v[206:209], v[100:103]
	v_mfma_f32_16x16x32_bf16 v[96:99], v[190:193], v[206:209], v[96:99]
	v_mfma_f32_16x16x32_bf16 v[84:87], v[182:185], v[214:217], v[84:87]
	v_mfma_f32_16x16x32_bf16 v[80:83], v[190:193], v[214:217], v[80:83]
	v_mfma_f32_16x16x32_bf16 v[68:71], v[182:185], v[222:225], v[68:71]
	v_mfma_f32_16x16x32_bf16 v[64:67], v[190:193], v[222:225], v[64:67]
	v_mfma_f32_16x16x32_bf16 v[116:119], v[186:189], v[202:205], v[116:119]
	v_mfma_f32_16x16x32_bf16 v[112:115], v[194:197], v[202:205], v[112:115]
	v_mfma_f32_16x16x32_bf16 v[100:103], v[186:189], v[210:213], v[100:103]
	v_mfma_f32_16x16x32_bf16 v[96:99], v[194:197], v[210:213], v[96:99]
	v_mfma_f32_16x16x32_bf16 v[84:87], v[186:189], v[218:221], v[84:87]
	v_mfma_f32_16x16x32_bf16 v[80:83], v[194:197], v[218:221], v[80:83]
	v_mfma_f32_16x16x32_bf16 v[68:71], v[186:189], v[226:229], v[68:71]
	v_mfma_f32_16x16x32_bf16 v[64:67], v[194:197], v[226:229], v[64:67]
	s_setprio 0
	s_barrier
	s_mov_b32 m0, s21
	v_lshl_add_u64 v[230:231], s[12:13], 0, v[130:131]
	s_add_u32 s8, s12, 0xb0000
	ds_read_b128 v[198:201], v147 offset:16384
	ds_read_b128 v[202:205], v147 offset:17408
	ds_read_b128 v[206:209], v147 offset:18432
	ds_read_b128 v[210:213], v147 offset:19456
	ds_read_b128 v[214:217], v147 offset:20480
	ds_read_b128 v[218:221], v147 offset:21504
	ds_read_b128 v[222:225], v147 offset:22528
	ds_read_b128 v[226:229], v147 offset:23552
	global_load_lds_dwordx4 v[230:231], off
	v_lshl_add_u64 v[232:233], s[12:13], 0, v[134:135]
	s_mov_b32 m0, s22
	s_addc_u32 s9, s13, 0
	global_load_lds_dwordx4 v[232:233], off
	v_lshl_add_u64 v[234:235], s[8:9], 0, v[130:131]
	s_mov_b32 m0, s23
	v_lshl_add_u64 v[236:237], s[14:15], 0, v[132:133]
	global_load_lds_dwordx4 v[234:235], off
	v_lshl_add_u64 v[234:235], s[8:9], 0, v[134:135]
	s_mov_b32 m0, s24
	s_nop 0
	global_load_lds_dwordx4 v[234:235], off
	v_lshl_add_u64 v[234:235], s[14:15], 0, v[128:129]
	s_mov_b32 m0, s20
	s_nop 0
	global_load_lds_dwordx4 v[234:235], off
	s_mov_b32 m0, s25
	s_nop 0
	global_load_lds_dwordx4 v[236:237], off
	s_waitcnt vmcnt(8)
	s_waitcnt lgkmcnt(0)
	s_barrier
; #define PG8_STAGE(bufoff, gbase, voff) do { _Pragma("unroll") for (int _i = 0; _i < 2; ++_i) \
;         __builtin_amdgcn_global_load_lds((const unsigned*)((const char*)(gbase) + (voff)[_i]), (PG8_LAS unsigned*)(lds + (bufoff) + ldsw + _i * 8192), 16, 0, 0); } while (0)
; #define PG8_LDA(dst, b, h) do { _Pragma("unroll") for (int m = 0; m < 4; ++m) _Pragma("unroll") for (int k = 0; k < 2; ++k) dst[m][k] = *(const PG8_LAS bf16x8*)(lds + PG8_SA(b, h) + aoff + m * 2048 + k * 1024); } while (0)
; #define PG8_LDB(dst, b, h) do { _Pragma("unroll") for (int n = 0; n < 2; ++n) _Pragma("unroll") for (int k = 0; k < 2; ++k) dst[n][k] = *(const PG8_LAS bf16x8*)(lds + PG8_SB(b, h) + boff + n * 2048 + k * 1024); } while (0)
; #define PG8_MMA(ai, bj, At, Bt) do { __builtin_amdgcn_s_setprio(1); _Pragma("unroll") for (int m = 0; m < 4; ++m) _Pragma("unroll") for (int n = 0; n < 2; ++n) _Pragma("unroll") for (int k = 0; k < 2; ++k) \
;         acc[ai][bj][m][n] = mma16<F16>(Bt[n][k], At[m][k], acc[ai][bj][m][n]); __builtin_amdgcn_s_setprio(0); } while (0)
; #define PG8_WAIT_V(n) asm volatile("s_waitcnt vmcnt(" #n ")" ::: "memory")
; #define PG8_WAIT_L(n) asm volatile("s_waitcnt lgkmcnt(" #n ")" ::: "memory")
; #define PG8_BAR __builtin_amdgcn_s_barrier()
; #define PG8_SCHED __builtin_amdgcn_sched_barrier(0)
; template <class Epi, class Sched, bool ALIGN_EPI = false, bool SP2 = false, bool F16 = false, bool TOKPERM = false>
; __device__ __forceinline__ void gemm_phase(PG8_LAS unsigned char* lds, const Gemm g, const Sched& S, const Epi& E, int wv) {
;     ...
;             PG8_WAIT_V(8); PG8_WAIT_L(0); PG8_BAR; PG8_MMA(1, 0, At, B0); PG8_MMA(1, 1, At, B1); PG8_BAR; PG8_SCHED;
;             PG8_LDB(B0, 1, 0); PG8_LDB(B1, 1, 1); PG8_SCHED; PG8_LDA(At, 1, 0); PG8_STAGE(PG8_SA(0, 1), a2 + hstep, voffA);
;             PG8_WAIT_V(8); PG8_WAIT_L(0); PG8_BAR; PG8_MMA(0, 0, At, B0); PG8_MMA(0, 1, At, B1); PG8_BAR; PG8_SCHED;
	s_setprio 1
	v_mfma_f32_16x16x32_bf16 v[60:63], v[166:169], v[198:201], v[60:63]
	v_mfma_f32_16x16x32_bf16 v[56:59], v[174:177], v[198:201], v[56:59]
	v_mfma_f32_16x16x32_bf16 v[44:47], v[166:169], v[206:209], v[44:47]
	v_mfma_f32_16x16x32_bf16 v[40:43], v[174:177], v[206:209], v[40:43]
	v_mfma_f32_16x16x32_bf16 v[28:31], v[166:169], v[214:217], v[28:31]
	v_mfma_f32_16x16x32_bf16 v[24:27], v[174:177], v[214:217], v[24:27]
	v_mfma_f32_16x16x32_bf16 v[12:15], v[166:169], v[222:225], v[12:15]
	v_mfma_f32_16x16x32_bf16 v[8:11], v[174:177], v[222:225], v[8:11]
	v_mfma_f32_16x16x32_bf16 v[60:63], v[170:173], v[202:205], v[60:63]
	v_mfma_f32_16x16x32_bf16 v[56:59], v[178:181], v[202:205], v[56:59]
	v_mfma_f32_16x16x32_bf16 v[44:47], v[170:173], v[210:213], v[44:47]
	v_mfma_f32_16x16x32_bf16 v[40:43], v[178:181], v[210:213], v[40:43]
	v_mfma_f32_16x16x32_bf16 v[28:31], v[170:173], v[218:221], v[28:31]
	v_mfma_f32_16x16x32_bf16 v[24:27], v[178:181], v[218:221], v[24:27]
	v_mfma_f32_16x16x32_bf16 v[12:15], v[170:173], v[226:229], v[12:15]
	v_mfma_f32_16x16x32_bf16 v[8:11], v[178:181], v[226:229], v[8:11]
	s_setprio 0
	s_setprio 1
	v_mfma_f32_16x16x32_bf16 v[52:55], v[182:185], v[198:201], v[52:55]
	v_mfma_f32_16x16x32_bf16 v[48:51], v[190:193], v[198:201], v[48:51]
	v_mfma_f32_16x16x32_bf16 v[36:39], v[182:185], v[206:209], v[36:39]
	v_mfma_f32_16x16x32_bf16 v[32:35], v[190:193], v[206:209], v[32:35]
	v_mfma_f32_16x16x32_bf16 v[20:23], v[182:185], v[214:217], v[20:23]
	v_mfma_f32_16x16x32_bf16 v[16:19], v[190:193], v[214:217], v[16:19]
	v_mfma_f32_16x16x32_bf16 v[4:7], v[182:185], v[222:225], v[4:7]
	v_mfma_f32_16x16x32_bf16 v[0:3], v[190:193], v[222:225], v[0:3]
	v_mfma_f32_16x16x32_bf16 v[52:55], v[186:189], v[202:205], v[52:55]
	v_mfma_f32_16x16x32_bf16 v[48:51], v[194:197], v[202:205], v[48:51]
	v_mfma_f32_16x16x32_bf16 v[36:39], v[186:189], v[210:213], v[36:39]
	v_mfma_f32_16x16x32_bf16 v[32:35], v[194:197], v[210:213], v[32:35]
	v_mfma_f32_16x16x32_bf16 v[20:23], v[186:189], v[218:221], v[20:23]
	v_mfma_f32_16x16x32_bf16 v[16:19], v[194:197], v[218:221], v[16:19]
	v_mfma_f32_16x16x32_bf16 v[4:7], v[186:189], v[226:229], v[4:7]
	v_mfma_f32_16x16x32_bf16 v[0:3], v[194:197], v[226:229], v[0:3]
	s_setprio 0
	s_barrier
	ds_read_b128 v[166:169], v157
	ds_read_b128 v[170:173], v158
	ds_read_b128 v[174:177], v159
	ds_read_b128 v[178:181], v160
	ds_read_b128 v[182:185], v161
	ds_read_b128 v[186:189], v162
	ds_read_b128 v[190:193], v163
	ds_read_b128 v[194:197], v164
	s_add_u32 s8, s14, 0xb0000
	s_addc_u32 s9, s15, 0
	s_mov_b32 m0, s27
	v_lshl_add_u64 v[238:239], s[8:9], 0, v[128:129]
	ds_read_b128 v[198:201], v147 offset:32768
	ds_read_b128 v[202:205], v147 offset:33792
	ds_read_b128 v[206:209], v147 offset:34816
	ds_read_b128 v[210:213], v147 offset:35840
	ds_read_b128 v[214:217], v147 offset:36864
	ds_read_b128 v[218:221], v147 offset:37888
	ds_read_b128 v[222:225], v147 offset:38912
	ds_read_b128 v[226:229], v147 offset:39936
	global_load_lds_dwordx4 v[238:239], off
	v_lshl_add_u64 v[238:239], s[8:9], 0, v[132:133]
	s_mov_b32 m0, s29
	s_nop 0
	global_load_lds_dwordx4 v[238:239], off
	s_waitcnt vmcnt(8)
	s_waitcnt lgkmcnt(0)
	s_barrier
	s_setprio 1
	v_mfma_f32_16x16x32_bf16 v[124:127], v[166:169], v[198:201], v[124:127]
	v_mfma_f32_16x16x32_bf16 v[120:123], v[174:177], v[198:201], v[120:123]
	v_mfma_f32_16x16x32_bf16 v[108:111], v[166:169], v[206:209], v[108:111]
	v_mfma_f32_16x16x32_bf16 v[104:107], v[174:177], v[206:209], v[104:107]
	v_mfma_f32_16x16x32_bf16 v[92:95], v[166:169], v[214:217], v[92:95]
	v_mfma_f32_16x16x32_bf16 v[88:91], v[174:177], v[214:217], v[88:91]
	v_mfma_f32_16x16x32_bf16 v[76:79], v[166:169], v[222:225], v[76:79]
	v_mfma_f32_16x16x32_bf16 v[72:75], v[174:177], v[222:225], v[72:75]
	v_mfma_f32_16x16x32_bf16 v[124:127], v[170:173], v[202:205], v[124:127]
	v_mfma_f32_16x16x32_bf16 v[120:123], v[178:181], v[202:205], v[120:123]
	v_mfma_f32_16x16x32_bf16 v[108:111], v[170:173], v[210:213], v[108:111]
	v_mfma_f32_16x16x32_bf16 v[104:107], v[178:181], v[210:213], v[104:107]
	v_mfma_f32_16x16x32_bf16 v[92:95], v[170:173], v[218:221], v[92:95]
	v_mfma_f32_16x16x32_bf16 v[88:91], v[178:181], v[218:221], v[88:91]
	v_mfma_f32_16x16x32_bf16 v[76:79], v[170:173], v[226:229], v[76:79]
	v_mfma_f32_16x16x32_bf16 v[72:75], v[178:181], v[226:229], v[72:75]
	s_setprio 0
	s_setprio 1
	v_mfma_f32_16x16x32_bf16 v[116:119], v[182:185], v[198:201], v[116:119]
	v_mfma_f32_16x16x32_bf16 v[112:115], v[190:193], v[198:201], v[112:115]
	v_mfma_f32_16x16x32_bf16 v[100:103], v[182:185], v[206:209], v[100:103]
	v_mfma_f32_16x16x32_bf16 v[96:99], v[190:193], v[206:209], v[96:99]
	v_mfma_f32_16x16x32_bf16 v[84:87], v[182:185], v[214:217], v[84:87]
	v_mfma_f32_16x16x32_bf16 v[80:83], v[190:193], v[214:217], v[80:83]
	v_mfma_f32_16x16x32_bf16 v[68:71], v[182:185], v[222:225], v[68:71]
	v_mfma_f32_16x16x32_bf16 v[64:67], v[190:193], v[222:225], v[64:67]
	v_mfma_f32_16x16x32_bf16 v[116:119], v[186:189], v[202:205], v[116:119]
	v_mfma_f32_16x16x32_bf16 v[112:115], v[194:197], v[202:205], v[112:115]
	v_mfma_f32_16x16x32_bf16 v[100:103], v[186:189], v[210:213], v[100:103]
	v_mfma_f32_16x16x32_bf16 v[96:99], v[194:197], v[210:213], v[96:99]
	v_mfma_f32_16x16x32_bf16 v[84:87], v[186:189], v[218:221], v[84:87]
	v_mfma_f32_16x16x32_bf16 v[80:83], v[194:197], v[218:221], v[80:83]
	v_mfma_f32_16x16x32_bf16 v[68:71], v[186:189], v[226:229], v[68:71]
	v_mfma_f32_16x16x32_bf16 v[64:67], v[194:197], v[226:229], v[64:67]
	s_setprio 0
	s_barrier
; #define PG8_STAGE(bufoff, gbase, voff) do { _Pragma("unroll") for (int _i = 0; _i < 2; ++_i) \
;         __builtin_amdgcn_global_load_lds((const unsigned*)((const char*)(gbase) + (voff)[_i]), (PG8_LAS unsigned*)(lds + (bufoff) + ldsw + _i * 8192), 16, 0, 0); } while (0)
; #define PG8_LDA(dst, b, h) do { _Pragma("unroll") for (int m = 0; m < 4; ++m) _Pragma("unroll") for (int k = 0; k < 2; ++k) dst[m][k] = *(const PG8_LAS bf16x8*)(lds + PG8_SA(b, h) + aoff + m * 2048 + k * 1024); } while (0)
; #define PG8_MMA(ai, bj, At, Bt) do { __builtin_amdgcn_s_setprio(1); _Pragma("unroll") for (int m = 0; m < 4; ++m) _Pragma("unroll") for (int n = 0; n < 2; ++n) _Pragma("unroll") for (int k = 0; k < 2; ++k) \
;         acc[ai][bj][m][n] = mma16<F16>(Bt[n][k], At[m][k], acc[ai][bj][m][n]); __builtin_amdgcn_s_setprio(0); } while (0)
; #define PG8_WAIT_V(n) asm volatile("s_waitcnt vmcnt(" #n ")" ::: "memory")
; template <class Epi, class Sched, bool ALIGN_EPI = false, bool SP2 = false, bool F16 = false, bool TOKPERM = false>
; __device__ __forceinline__ void gemm_phase(PG8_LAS unsigned char* lds, const Gemm g, const Sched& S, const Epi& E, int wv) {
;     ...
;             PG8_LDA(At, 1, 1); PG8_STAGE(PG8_SB(1, 0), b3, voffB); PG8_STAGE(PG8_SB(1, 1), b3 + hstep, voffB); PG8_STAGE(PG8_SA(1, 0), a3, voffA);
;             PG8_WAIT_V(8); PG8_WAIT_L(0); PG8_BAR; PG8_MMA(1, 0, At, B0); PG8_MMA(1, 1, At, B1); PG8_BAR; PG8_SCHED;
;   __device__ __forceinline__ void operator()(const pg8::f32x4 (&acc)[2][2][4][2], const pg8::Unit& u, int wr, int wc, int fr, int fq) const {
;     ...
;         const int tok = row0 + ai * 128 + m * 16; float ss = 0.f;
; #pragma unroll
;         for (int bj = 0; bj < 2; ++bj) {
;           const unsigned off = (unsigned)tok * DM + colb + 128 * bj;
;           f8_t n = __builtin_convertvector(*(const h8_t*)(x16 + off), f8_t);
; #pragma unroll
;           for (int c = 0; c < 4; ++c) { n[c] += sc * acc[ai][bj][m][0][c]; n[4 + c] += sc * acc[ai][bj][m][1][c]; }
;           if (aux) {
;             *(h8_t*)(x16 + off) = __builtin_convertvector(n, h8_t);
;             ss += ((n[0] * n[0] + n[1] * n[1]) + (n[2] * n[2] + n[3] * n[3])) + ((n[4] * n[4] + n[5] * n[5]) + (n[6] * n[6] + n[7] * n[7]));
;           } else {
;             *(f32x4*)(xout + off) = (f32x4){n[0], n[1], n[2], n[3]}; *(f32x4*)(xout + off + 4) = (f32x4){n[4], n[5], n[6], n[7]};
	s_mov_b32 m0, s33
	v_lshl_add_u64 v[230:231], v[230:231], 0, s[6:7]
	s_add_u32 s8, s12, 0xb0080
	ds_read_b128 v[198:201], v147 offset:49152
	ds_read_b128 v[202:205], v147 offset:50176
	ds_read_b128 v[206:209], v147 offset:51200
	ds_read_b128 v[210:213], v147 offset:52224
	ds_read_b128 v[214:217], v147 offset:53248
	ds_read_b128 v[218:221], v147 offset:54272
	ds_read_b128 v[222:225], v147 offset:55296
	ds_read_b128 v[226:229], v147 offset:56320
	global_load_lds_dwordx4 v[230:231], off
	v_lshl_add_u64 v[230:231], v[232:233], 0, s[6:7]
	s_mov_b32 m0, s34
	s_addc_u32 s9, s13, 0
	global_load_lds_dwordx4 v[230:231], off
	v_lshl_add_u64 v[230:231], s[8:9], 0, v[130:131]
	s_mov_b32 m0, s37
	s_nop 0
	global_load_lds_dwordx4 v[230:231], off
	v_lshl_add_u64 v[230:231], s[8:9], 0, v[134:135]
	s_mov_b32 m0, s42
	s_nop 0
	global_load_lds_dwordx4 v[230:231], off
	v_lshl_add_u64 v[230:231], v[234:235], 0, s[6:7]
	s_mov_b32 m0, s35
	s_nop 0
	global_load_lds_dwordx4 v[230:231], off
	v_lshl_add_u64 v[230:231], v[236:237], 0, s[6:7]
	s_mov_b32 m0, s36
	s_nop 0
	global_load_lds_dwordx4 v[230:231], off
	s_waitcnt vmcnt(8)
	s_waitcnt lgkmcnt(0)
	s_barrier
	s_setprio 1
	v_mfma_f32_16x16x32_bf16 v[60:63], v[166:169], v[198:201], v[60:63]
	v_mfma_f32_16x16x32_bf16 v[56:59], v[174:177], v[198:201], v[56:59]
	v_mfma_f32_16x16x32_bf16 v[44:47], v[166:169], v[206:209], v[44:47]
	v_mfma_f32_16x16x32_bf16 v[40:43], v[174:177], v[206:209], v[40:43]
	v_mfma_f32_16x16x32_bf16 v[28:31], v[166:169], v[214:217], v[28:31]
	v_mfma_f32_16x16x32_bf16 v[24:27], v[174:177], v[214:217], v[24:27]
	v_mfma_f32_16x16x32_bf16 v[12:15], v[166:169], v[222:225], v[12:15]
	v_mfma_f32_16x16x32_bf16 v[8:11], v[174:177], v[222:225], v[8:11]
	v_mfma_f32_16x16x32_bf16 v[60:63], v[170:173], v[202:205], v[60:63]
	v_mfma_f32_16x16x32_bf16 v[56:59], v[178:181], v[202:205], v[56:59]
	v_mfma_f32_16x16x32_bf16 v[44:47], v[170:173], v[210:213], v[44:47]
	v_mfma_f32_16x16x32_bf16 v[40:43], v[178:181], v[210:213], v[40:43]
	v_mfma_f32_16x16x32_bf16 v[28:31], v[170:173], v[218:221], v[28:31]
	v_mfma_f32_16x16x32_bf16 v[24:27], v[178:181], v[218:221], v[24:27]
	v_mfma_f32_16x16x32_bf16 v[12:15], v[170:173], v[226:229], v[12:15]
	v_mfma_f32_16x16x32_bf16 v[8:11], v[178:181], v[226:229], v[8:11]
	s_setprio 0
	s_setprio 1
	v_mfma_f32_16x16x32_bf16 v[52:55], v[182:185], v[198:201], v[52:55]
	v_mfma_f32_16x16x32_bf16 v[48:51], v[190:193], v[198:201], v[48:51]
	v_mfma_f32_16x16x32_bf16 v[36:39], v[182:185], v[206:209], v[36:39]
	v_mfma_f32_16x16x32_bf16 v[32:35], v[190:193], v[206:209], v[32:35]
	v_mfma_f32_16x16x32_bf16 v[20:23], v[182:185], v[214:217], v[20:23]
	v_mfma_f32_16x16x32_bf16 v[16:19], v[190:193], v[214:217], v[16:19]
	v_mfma_f32_16x16x32_bf16 v[4:7], v[182:185], v[222:225], v[4:7]
	v_mfma_f32_16x16x32_bf16 v[0:3], v[190:193], v[222:225], v[0:3]
	v_mfma_f32_16x16x32_bf16 v[52:55], v[186:189], v[202:205], v[52:55]
	v_mfma_f32_16x16x32_bf16 v[48:51], v[194:197], v[202:205], v[48:51]
	v_mfma_f32_16x16x32_bf16 v[36:39], v[186:189], v[210:213], v[36:39]
	v_mfma_f32_16x16x32_bf16 v[32:35], v[194:197], v[210:213], v[32:35]
	v_mfma_f32_16x16x32_bf16 v[20:23], v[186:189], v[218:221], v[20:23]
	v_mfma_f32_16x16x32_bf16 v[16:19], v[194:197], v[218:221], v[16:19]
	v_mfma_f32_16x16x32_bf16 v[4:7], v[186:189], v[226:229], v[4:7]
	v_mfma_f32_16x16x32_bf16 v[0:3], v[194:197], v[226:229], v[0:3]
	s_setprio 0
	s_barrier
	s_add_i32 s53, s53, 2
	s_add_u32 s51, s51, 0x100
	s_addc_u32 s52, s52, 0
	s_cmp_gt_u32 s53, 41
	s_mov_b64 s[8:9], s[10:11]
	s_cbranch_scc0 .LBB0_1687
	v_mov_b32 v136, 0
	s_lshl_b32 s8, s49, 8
	v_lshl_or_b32 v166, s50, 8, v148
	v_add3_u32 v165, s8, v146, v136
	v_add_u32_e32 v136, v166, v136
	v_lshl_add_u32 v136, v165, 10, v136
	v_lshl_add_u64 v[166:167], v[136:137], 1, s[40:41]
	global_load_dwordx4 v[166:169], v[166:167], off
	v_mov_b32_e32 v171, v137
	v_lshl_add_u64 v[172:173], v[136:137], 2, s[30:31]
	v_add_u32_e32 v170, 0x80, v136
	v_lshl_add_u64 v[174:175], v[170:171], 1, s[40:41]
	s_and_b64 vcc, exec, s[0:1]
	s_mov_b32 s50, s47
	s_mov_b32 s49, s48
	s_mov_b64 s[10:11], s[4:5]
	s_mov_b64 s[8:9], s[2:3]
	s_waitcnt vmcnt(0)
	v_cvt_f32_f16_e32 v178, v167
	v_cvt_f32_f16_e32 v182, v166
	v_cvt_f32_f16_sdwa v183, v166 dst_sel:DWORD dst_unused:UNUSED_PAD src0_sel:WORD_1
	v_cvt_f32_f16_sdwa v179, v167 dst_sel:DWORD dst_unused:UNUSED_PAD src0_sel:WORD_1
	v_cvt_f32_f16_e32 v176, v169
	v_cvt_f32_f16_e32 v180, v168
	v_cvt_f32_f16_sdwa v181, v168 dst_sel:DWORD dst_unused:UNUSED_PAD src0_sel:WORD_1
	v_cvt_f32_f16_sdwa v177, v169 dst_sel:DWORD dst_unused:UNUSED_PAD src0_sel:WORD_1
	v_pk_fma_f32 v[124:125], v[124:125], 0.5, v[182:183] op_sel_hi:[1,0,1]
	v_pk_fma_f32 v[126:127], v[126:127], 0.5, v[178:179] op_sel_hi:[1,0,1]
	v_pk_fma_f32 v[120:121], v[120:121], 0.5, v[180:181] op_sel_hi:[1,0,1]
	v_pk_fma_f32 v[122:123], v[122:123], 0.5, v[176:177] op_sel_hi:[1,0,1]
	global_store_dwordx4 v[172:173], v[124:127], off
	global_store_dwordx4 v[172:173], v[120:123], off offset:16
	global_load_dwordx4 v[120:123], v[174:175], off
	v_lshl_add_u64 v[126:127], v[170:171], 2, s[30:31]
	v_mov_b32_e32 v125, v137
	v_add_u32_e32 v124, 0x4000, v136
	v_lshl_add_u64 v[166:167], v[124:125], 1, s[40:41]
	s_waitcnt vmcnt(0)
;   __device__ __forceinline__ void operator()(const pg8::f32x4 (&acc)[2][2][4][2], const pg8::Unit& u, int wr, int wc, int fr, int fq) const {
;     ...
;         const int tok = row0 + ai * 128 + m * 16; float ss = 0.f;
; #pragma unroll
;         for (int bj = 0; bj < 2; ++bj) {
;           const unsigned off = (unsigned)tok * DM + colb + 128 * bj;
;           f8_t n = __builtin_convertvector(*(const h8_t*)(x16 + off), f8_t);
; #pragma unroll
;           for (int c = 0; c < 4; ++c) { n[c] += sc * acc[ai][bj][m][0][c]; n[4 + c] += sc * acc[ai][bj][m][1][c]; }
;           if (aux) {
;             *(h8_t*)(x16 + off) = __builtin_convertvector(n, h8_t);
;             ss += ((n[0] * n[0] + n[1] * n[1]) + (n[2] * n[2] + n[3] * n[3])) + ((n[4] * n[4] + n[5] * n[5]) + (n[6] * n[6] + n[7] * n[7]));
;           } else {
;             *(f32x4*)(xout + off) = (f32x4){n[0], n[1], n[2], n[3]}; *(f32x4*)(xout + off + 4) = (f32x4){n[4], n[5], n[6], n[7]};
;           }
	v_cvt_f32_f16_e32 v170, v121
	v_cvt_f32_f16_e32 v174, v120
	v_cvt_f32_f16_sdwa v175, v120 dst_sel:DWORD dst_unused:UNUSED_PAD src0_sel:WORD_1
	v_cvt_f32_f16_sdwa v171, v121 dst_sel:DWORD dst_unused:UNUSED_PAD src0_sel:WORD_1
	v_cvt_f32_f16_e32 v168, v123
	v_cvt_f32_f16_e32 v172, v122
	v_cvt_f32_f16_sdwa v173, v122 dst_sel:DWORD dst_unused:UNUSED_PAD src0_sel:WORD_1
	v_cvt_f32_f16_sdwa v169, v123 dst_sel:DWORD dst_unused:UNUSED_PAD src0_sel:WORD_1
	v_pk_fma_f32 v[116:117], v[116:117], 0.5, v[174:175] op_sel_hi:[1,0,1]
	v_pk_fma_f32 v[118:119], v[118:119], 0.5, v[170:171] op_sel_hi:[1,0,1]
	v_pk_fma_f32 v[112:113], v[112:113], 0.5, v[172:173] op_sel_hi:[1,0,1]
	v_pk_fma_f32 v[114:115], v[114:115], 0.5, v[168:169] op_sel_hi:[1,0,1]
	global_store_dwordx4 v[126:127], v[116:119], off
	global_store_dwordx4 v[126:127], v[112:115], off offset:16
	global_load_dwordx4 v[112:115], v[166:167], off
	v_lshl_add_u64 v[118:119], v[124:125], 2, s[30:31]
	v_mov_b32_e32 v117, v137
	v_add_u32_e32 v116, 0x4080, v136
	v_lshl_add_u64 v[120:121], v[116:117], 1, s[40:41]
	s_waitcnt vmcnt(0)
	v_cvt_f32_f16_e32 v124, v113
	v_cvt_f32_f16_e32 v166, v112
	v_cvt_f32_f16_sdwa v167, v112 dst_sel:DWORD dst_unused:UNUSED_PAD src0_sel:WORD_1
	v_cvt_f32_f16_sdwa v125, v113 dst_sel:DWORD dst_unused:UNUSED_PAD src0_sel:WORD_1
	v_cvt_f32_f16_e32 v122, v115
	v_cvt_f32_f16_e32 v126, v114
	v_cvt_f32_f16_sdwa v127, v114 dst_sel:DWORD dst_unused:UNUSED_PAD src0_sel:WORD_1
	v_cvt_f32_f16_sdwa v123, v115 dst_sel:DWORD dst_unused:UNUSED_PAD src0_sel:WORD_1
	v_pk_fma_f32 v[108:109], v[108:109], 0.5, v[166:167] op_sel_hi:[1,0,1]
	v_pk_fma_f32 v[110:111], v[110:111], 0.5, v[124:125] op_sel_hi:[1,0,1]
	v_pk_fma_f32 v[104:105], v[104:105], 0.5, v[126:127] op_sel_hi:[1,0,1]
	v_pk_fma_f32 v[106:107], v[106:107], 0.5, v[122:123] op_sel_hi:[1,0,1]
	global_store_dwordx4 v[118:119], v[108:111], off
	global_store_dwordx4 v[118:119], v[104:107], off offset:16
	global_load_dwordx4 v[104:107], v[120:121], off
	v_lshl_add_u64 v[110:111], v[116:117], 2, s[30:31]
	v_mov_b32_e32 v109, v137
	v_add_u32_e32 v108, 0x8000, v136
	v_lshl_add_u64 v[112:113], v[108:109], 1, s[40:41]
	s_waitcnt vmcnt(0)
	v_cvt_f32_f16_e32 v116, v105
	v_cvt_f32_f16_e32 v120, v104
	v_cvt_f32_f16_sdwa v121, v104 dst_sel:DWORD dst_unused:UNUSED_PAD src0_sel:WORD_1
	v_cvt_f32_f16_sdwa v117, v105 dst_sel:DWORD dst_unused:UNUSED_PAD src0_sel:WORD_1
	v_cvt_f32_f16_e32 v114, v107
	v_cvt_f32_f16_e32 v118, v106
	v_cvt_f32_f16_sdwa v119, v106 dst_sel:DWORD dst_unused:UNUSED_PAD src0_sel:WORD_1
	v_cvt_f32_f16_sdwa v115, v107 dst_sel:DWORD dst_unused:UNUSED_PAD src0_sel:WORD_1
	v_pk_fma_f32 v[100:101], v[100:101], 0.5, v[120:121] op_sel_hi:[1,0,1]
	v_pk_fma_f32 v[102:103], v[102:103], 0.5, v[116:117] op_sel_hi:[1,0,1]
	v_pk_fma_f32 v[96:97], v[96:97], 0.5, v[118:119] op_sel_hi:[1,0,1]
	v_pk_fma_f32 v[98:99], v[98:99], 0.5, v[114:115] op_sel_hi:[1,0,1]
	global_store_dwordx4 v[110:111], v[100:103], off
	global_store_dwordx4 v[110:111], v[96:99], off offset:16
	global_load_dwordx4 v[96:99], v[112:113], off
	v_lshl_add_u64 v[102:103], v[108:109], 2, s[30:31]
	v_mov_b32_e32 v101, v137
	v_add_u32_e32 v100, 0x8080, v136
	v_lshl_add_u64 v[104:105], v[100:101], 1, s[40:41]
	s_waitcnt vmcnt(0)
	v_cvt_f32_f16_e32 v108, v97
	v_cvt_f32_f16_e32 v112, v96
	v_cvt_f32_f16_sdwa v113, v96 dst_sel:DWORD dst_unused:UNUSED_PAD src0_sel:WORD_1
	v_cvt_f32_f16_sdwa v109, v97 dst_sel:DWORD dst_unused:UNUSED_PAD src0_sel:WORD_1
	v_cvt_f32_f16_e32 v106, v99
	v_cvt_f32_f16_e32 v110, v98
	v_cvt_f32_f16_sdwa v111, v98 dst_sel:DWORD dst_unused:UNUSED_PAD src0_sel:WORD_1
	v_cvt_f32_f16_sdwa v107, v99 dst_sel:DWORD dst_unused:UNUSED_PAD src0_sel:WORD_1
	v_pk_fma_f32 v[92:93], v[92:93], 0.5, v[112:113] op_sel_hi:[1,0,1]
	v_pk_fma_f32 v[94:95], v[94:95], 0.5, v[108:109] op_sel_hi:[1,0,1]
	v_pk_fma_f32 v[88:89], v[88:89], 0.5, v[110:111] op_sel_hi:[1,0,1]
	v_pk_fma_f32 v[90:91], v[90:91], 0.5, v[106:107] op_sel_hi:[1,0,1]
	global_store_dwordx4 v[102:103], v[92:95], off
	global_store_dwordx4 v[102:103], v[88:91], off offset:16
	global_load_dwordx4 v[88:91], v[104:105], off
	v_lshl_add_u64 v[94:95], v[100:101], 2, s[30:31]
	v_mov_b32_e32 v93, v137
	v_add_u32_e32 v92, 0xc000, v136
	v_lshl_add_u64 v[96:97], v[92:93], 1, s[40:41]
	s_waitcnt vmcnt(0)
	v_cvt_f32_f16_e32 v100, v89
	v_cvt_f32_f16_e32 v104, v88
	v_cvt_f32_f16_sdwa v105, v88 dst_sel:DWORD dst_unused:UNUSED_PAD src0_sel:WORD_1
	v_cvt_f32_f16_sdwa v101, v89 dst_sel:DWORD dst_unused:UNUSED_PAD src0_sel:WORD_1
	v_cvt_f32_f16_e32 v98, v91
	v_cvt_f32_f16_e32 v102, v90
	v_cvt_f32_f16_sdwa v103, v90 dst_sel:DWORD dst_unused:UNUSED_PAD src0_sel:WORD_1
	v_cvt_f32_f16_sdwa v99, v91 dst_sel:DWORD dst_unused:UNUSED_PAD src0_sel:WORD_1
	v_pk_fma_f32 v[84:85], v[84:85], 0.5, v[104:105] op_sel_hi:[1,0,1]
	v_pk_fma_f32 v[86:87], v[86:87], 0.5, v[100:101] op_sel_hi:[1,0,1]
	v_pk_fma_f32 v[80:81], v[80:81], 0.5, v[102:103] op_sel_hi:[1,0,1]
	v_pk_fma_f32 v[82:83], v[82:83], 0.5, v[98:99] op_sel_hi:[1,0,1]
	global_store_dwordx4 v[94:95], v[84:87], off
	global_store_dwordx4 v[94:95], v[80:83], off offset:16
	global_load_dwordx4 v[80:83], v[96:97], off
	v_lshl_add_u64 v[86:87], v[92:93], 2, s[30:31]
	v_mov_b32_e32 v85, v137
	v_add_u32_e32 v84, 0xc080, v136
	v_lshl_add_u64 v[88:89], v[84:85], 1, s[40:41]
	s_waitcnt vmcnt(0)
;   __device__ __forceinline__ void operator()(const pg8::f32x4 (&acc)[2][2][4][2], const pg8::Unit& u, int wr, int wc, int fr, int fq) const {
;     ...
;         const int tok = row0 + ai * 128 + m * 16; float ss = 0.f;
; #pragma unroll
;         for (int bj = 0; bj < 2; ++bj) {
;           const unsigned off = (unsigned)tok * DM + colb + 128 * bj;
;           f8_t n = __builtin_convertvector(*(const h8_t*)(x16 + off), f8_t);
; #pragma unroll
;           for (int c = 0; c < 4; ++c) { n[c] += sc * acc[ai][bj][m][0][c]; n[4 + c] += sc * acc[ai][bj][m][1][c]; }
;           if (aux) {
;             *(h8_t*)(x16 + off) = __builtin_convertvector(n, h8_t);
;             ss += ((n[0] * n[0] + n[1] * n[1]) + (n[2] * n[2] + n[3] * n[3])) + ((n[4] * n[4] + n[5] * n[5]) + (n[6] * n[6] + n[7] * n[7]));
;           } else {
;             *(f32x4*)(xout + off) = (f32x4){n[0], n[1], n[2], n[3]}; *(f32x4*)(xout + off + 4) = (f32x4){n[4], n[5], n[6], n[7]};
;           }
	v_cvt_f32_f16_e32 v92, v81
	v_cvt_f32_f16_e32 v96, v80
	v_cvt_f32_f16_sdwa v97, v80 dst_sel:DWORD dst_unused:UNUSED_PAD src0_sel:WORD_1
	v_cvt_f32_f16_sdwa v93, v81 dst_sel:DWORD dst_unused:UNUSED_PAD src0_sel:WORD_1
	v_cvt_f32_f16_e32 v90, v83
	v_cvt_f32_f16_e32 v94, v82
	v_cvt_f32_f16_sdwa v95, v82 dst_sel:DWORD dst_unused:UNUSED_PAD src0_sel:WORD_1
	v_cvt_f32_f16_sdwa v91, v83 dst_sel:DWORD dst_unused:UNUSED_PAD src0_sel:WORD_1
	v_pk_fma_f32 v[76:77], v[76:77], 0.5, v[96:97] op_sel_hi:[1,0,1]
	v_pk_fma_f32 v[78:79], v[78:79], 0.5, v[92:93] op_sel_hi:[1,0,1]
	v_pk_fma_f32 v[72:73], v[72:73], 0.5, v[94:95] op_sel_hi:[1,0,1]
	v_pk_fma_f32 v[74:75], v[74:75], 0.5, v[90:91] op_sel_hi:[1,0,1]
	global_store_dwordx4 v[86:87], v[76:79], off
	global_store_dwordx4 v[86:87], v[72:75], off offset:16
	global_load_dwordx4 v[72:75], v[88:89], off
	v_lshl_add_u64 v[78:79], v[84:85], 2, s[30:31]
	v_mov_b32_e32 v77, v137
	v_add_u32_e32 v76, 0x20000, v136
	v_lshl_add_u64 v[80:81], v[76:77], 1, s[40:41]
	s_waitcnt vmcnt(0)
	v_cvt_f32_f16_e32 v84, v73
	v_cvt_f32_f16_e32 v88, v72
	v_cvt_f32_f16_sdwa v89, v72 dst_sel:DWORD dst_unused:UNUSED_PAD src0_sel:WORD_1
	v_cvt_f32_f16_sdwa v85, v73 dst_sel:DWORD dst_unused:UNUSED_PAD src0_sel:WORD_1
	v_cvt_f32_f16_e32 v82, v75
	v_cvt_f32_f16_e32 v86, v74
	v_cvt_f32_f16_sdwa v87, v74 dst_sel:DWORD dst_unused:UNUSED_PAD src0_sel:WORD_1
	v_cvt_f32_f16_sdwa v83, v75 dst_sel:DWORD dst_unused:UNUSED_PAD src0_sel:WORD_1
	v_pk_fma_f32 v[68:69], v[68:69], 0.5, v[88:89] op_sel_hi:[1,0,1]
	v_pk_fma_f32 v[70:71], v[70:71], 0.5, v[84:85] op_sel_hi:[1,0,1]
	v_pk_fma_f32 v[64:65], v[64:65], 0.5, v[86:87] op_sel_hi:[1,0,1]
	v_pk_fma_f32 v[66:67], v[66:67], 0.5, v[82:83] op_sel_hi:[1,0,1]
	global_store_dwordx4 v[78:79], v[68:71], off
	global_store_dwordx4 v[78:79], v[64:67], off offset:16
	global_load_dwordx4 v[64:67], v[80:81], off
	v_lshl_add_u64 v[70:71], v[76:77], 2, s[30:31]
	v_mov_b32_e32 v69, v137
	v_add_u32_e32 v68, 0x20080, v136
	v_lshl_add_u64 v[72:73], v[68:69], 1, s[40:41]
	s_waitcnt vmcnt(0)
	v_cvt_f32_f16_e32 v76, v65
	v_cvt_f32_f16_e32 v80, v64
	v_cvt_f32_f16_sdwa v81, v64 dst_sel:DWORD dst_unused:UNUSED_PAD src0_sel:WORD_1
	v_cvt_f32_f16_sdwa v77, v65 dst_sel:DWORD dst_unused:UNUSED_PAD src0_sel:WORD_1
	v_cvt_f32_f16_e32 v74, v67
	v_cvt_f32_f16_e32 v78, v66
	v_cvt_f32_f16_sdwa v79, v66 dst_sel:DWORD dst_unused:UNUSED_PAD src0_sel:WORD_1
	v_cvt_f32_f16_sdwa v75, v67 dst_sel:DWORD dst_unused:UNUSED_PAD src0_sel:WORD_1
	v_pk_fma_f32 v[60:61], v[60:61], 0.5, v[80:81] op_sel_hi:[1,0,1]
	v_pk_fma_f32 v[62:63], v[62:63], 0.5, v[76:77] op_sel_hi:[1,0,1]
	v_pk_fma_f32 v[56:57], v[56:57], 0.5, v[78:79] op_sel_hi:[1,0,1]
	v_pk_fma_f32 v[58:59], v[58:59], 0.5, v[74:75] op_sel_hi:[1,0,1]
	global_store_dwordx4 v[70:71], v[60:63], off
	global_store_dwordx4 v[70:71], v[56:59], off offset:16
	global_load_dwordx4 v[56:59], v[72:73], off
	v_lshl_add_u64 v[62:63], v[68:69], 2, s[30:31]
	v_mov_b32_e32 v61, v137
	v_add_u32_e32 v60, 0x24000, v136
	v_lshl_add_u64 v[64:65], v[60:61], 1, s[40:41]
	s_waitcnt vmcnt(0)
	v_cvt_f32_f16_e32 v68, v57
	v_cvt_f32_f16_e32 v72, v56
	v_cvt_f32_f16_sdwa v73, v56 dst_sel:DWORD dst_unused:UNUSED_PAD src0_sel:WORD_1
	v_cvt_f32_f16_sdwa v69, v57 dst_sel:DWORD dst_unused:UNUSED_PAD src0_sel:WORD_1
	v_cvt_f32_f16_e32 v66, v59
	v_cvt_f32_f16_e32 v70, v58
	v_cvt_f32_f16_sdwa v71, v58 dst_sel:DWORD dst_unused:UNUSED_PAD src0_sel:WORD_1
	v_cvt_f32_f16_sdwa v67, v59 dst_sel:DWORD dst_unused:UNUSED_PAD src0_sel:WORD_1
	v_pk_fma_f32 v[52:53], v[52:53], 0.5, v[72:73] op_sel_hi:[1,0,1]
	v_pk_fma_f32 v[54:55], v[54:55], 0.5, v[68:69] op_sel_hi:[1,0,1]
	v_pk_fma_f32 v[48:49], v[48:49], 0.5, v[70:71] op_sel_hi:[1,0,1]
	v_pk_fma_f32 v[50:51], v[50:51], 0.5, v[66:67] op_sel_hi:[1,0,1]
	global_store_dwordx4 v[62:63], v[52:55], off
	global_store_dwordx4 v[62:63], v[48:51], off offset:16
	global_load_dwordx4 v[48:51], v[64:65], off
	v_lshl_add_u64 v[54:55], v[60:61], 2, s[30:31]
	v_mov_b32_e32 v53, v137
	v_add_u32_e32 v52, 0x24080, v136
	v_lshl_add_u64 v[56:57], v[52:53], 1, s[40:41]
	s_waitcnt vmcnt(0)
	v_cvt_f32_f16_e32 v60, v49
	v_cvt_f32_f16_e32 v64, v48
	v_cvt_f32_f16_sdwa v65, v48 dst_sel:DWORD dst_unused:UNUSED_PAD src0_sel:WORD_1
	v_cvt_f32_f16_sdwa v61, v49 dst_sel:DWORD dst_unused:UNUSED_PAD src0_sel:WORD_1
	v_cvt_f32_f16_e32 v58, v51
	v_cvt_f32_f16_e32 v62, v50
	v_cvt_f32_f16_sdwa v63, v50 dst_sel:DWORD dst_unused:UNUSED_PAD src0_sel:WORD_1
	v_cvt_f32_f16_sdwa v59, v51 dst_sel:DWORD dst_unused:UNUSED_PAD src0_sel:WORD_1
	v_pk_fma_f32 v[44:45], v[44:45], 0.5, v[64:65] op_sel_hi:[1,0,1]
	v_pk_fma_f32 v[46:47], v[46:47], 0.5, v[60:61] op_sel_hi:[1,0,1]
	v_pk_fma_f32 v[40:41], v[40:41], 0.5, v[62:63] op_sel_hi:[1,0,1]
	v_pk_fma_f32 v[42:43], v[42:43], 0.5, v[58:59] op_sel_hi:[1,0,1]
	global_store_dwordx4 v[54:55], v[44:47], off
	global_store_dwordx4 v[54:55], v[40:43], off offset:16
	global_load_dwordx4 v[40:43], v[56:57], off
	v_lshl_add_u64 v[46:47], v[52:53], 2, s[30:31]
	v_mov_b32_e32 v45, v137
	v_add_u32_e32 v44, 0x28000, v136
	v_lshl_add_u64 v[48:49], v[44:45], 1, s[40:41]
	s_waitcnt vmcnt(0)
;   __device__ __forceinline__ void operator()(const pg8::f32x4 (&acc)[2][2][4][2], const pg8::Unit& u, int wr, int wc, int fr, int fq) const {
;     ...
;         const int tok = row0 + ai * 128 + m * 16; float ss = 0.f;
; #pragma unroll
;         for (int bj = 0; bj < 2; ++bj) {
;           const unsigned off = (unsigned)tok * DM + colb + 128 * bj;
;           f8_t n = __builtin_convertvector(*(const h8_t*)(x16 + off), f8_t);
; #pragma unroll
;           for (int c = 0; c < 4; ++c) { n[c] += sc * acc[ai][bj][m][0][c]; n[4 + c] += sc * acc[ai][bj][m][1][c]; }
;           if (aux) {
;             *(h8_t*)(x16 + off) = __builtin_convertvector(n, h8_t);
;             ss += ((n[0] * n[0] + n[1] * n[1]) + (n[2] * n[2] + n[3] * n[3])) + ((n[4] * n[4] + n[5] * n[5]) + (n[6] * n[6] + n[7] * n[7]));
;           } else {
;             *(f32x4*)(xout + off) = (f32x4){n[0], n[1], n[2], n[3]}; *(f32x4*)(xout + off + 4) = (f32x4){n[4], n[5], n[6], n[7]};
;           }
	v_cvt_f32_f16_e32 v52, v41
	v_cvt_f32_f16_e32 v56, v40
	v_cvt_f32_f16_sdwa v57, v40 dst_sel:DWORD dst_unused:UNUSED_PAD src0_sel:WORD_1
	v_cvt_f32_f16_sdwa v53, v41 dst_sel:DWORD dst_unused:UNUSED_PAD src0_sel:WORD_1
	v_cvt_f32_f16_e32 v50, v43
	v_cvt_f32_f16_e32 v54, v42
	v_cvt_f32_f16_sdwa v55, v42 dst_sel:DWORD dst_unused:UNUSED_PAD src0_sel:WORD_1
	v_cvt_f32_f16_sdwa v51, v43 dst_sel:DWORD dst_unused:UNUSED_PAD src0_sel:WORD_1
	v_pk_fma_f32 v[36:37], v[36:37], 0.5, v[56:57] op_sel_hi:[1,0,1]
	v_pk_fma_f32 v[38:39], v[38:39], 0.5, v[52:53] op_sel_hi:[1,0,1]
	v_pk_fma_f32 v[32:33], v[32:33], 0.5, v[54:55] op_sel_hi:[1,0,1]
	v_pk_fma_f32 v[34:35], v[34:35], 0.5, v[50:51] op_sel_hi:[1,0,1]
	global_store_dwordx4 v[46:47], v[36:39], off
	global_store_dwordx4 v[46:47], v[32:35], off offset:16
	global_load_dwordx4 v[32:35], v[48:49], off
	v_lshl_add_u64 v[38:39], v[44:45], 2, s[30:31]
	v_mov_b32_e32 v37, v137
	v_add_u32_e32 v36, 0x28080, v136
	v_lshl_add_u64 v[40:41], v[36:37], 1, s[40:41]
	s_waitcnt vmcnt(0)
	v_cvt_f32_f16_e32 v44, v33
	v_cvt_f32_f16_e32 v48, v32
	v_cvt_f32_f16_sdwa v49, v32 dst_sel:DWORD dst_unused:UNUSED_PAD src0_sel:WORD_1
	v_cvt_f32_f16_sdwa v45, v33 dst_sel:DWORD dst_unused:UNUSED_PAD src0_sel:WORD_1
	v_cvt_f32_f16_e32 v42, v35
	v_cvt_f32_f16_e32 v46, v34
	v_cvt_f32_f16_sdwa v47, v34 dst_sel:DWORD dst_unused:UNUSED_PAD src0_sel:WORD_1
	v_cvt_f32_f16_sdwa v43, v35 dst_sel:DWORD dst_unused:UNUSED_PAD src0_sel:WORD_1
	v_pk_fma_f32 v[28:29], v[28:29], 0.5, v[48:49] op_sel_hi:[1,0,1]
	v_pk_fma_f32 v[30:31], v[30:31], 0.5, v[44:45] op_sel_hi:[1,0,1]
	v_pk_fma_f32 v[24:25], v[24:25], 0.5, v[46:47] op_sel_hi:[1,0,1]
	v_pk_fma_f32 v[26:27], v[26:27], 0.5, v[42:43] op_sel_hi:[1,0,1]
	global_store_dwordx4 v[38:39], v[28:31], off
	global_store_dwordx4 v[38:39], v[24:27], off offset:16
	global_load_dwordx4 v[24:27], v[40:41], off
	v_lshl_add_u64 v[30:31], v[36:37], 2, s[30:31]
	v_mov_b32_e32 v29, v137
	v_add_u32_e32 v28, 0x2c000, v136
	v_lshl_add_u64 v[32:33], v[28:29], 1, s[40:41]
	v_add_u32_e32 v136, 0x2c080, v136
	s_waitcnt vmcnt(0)
	v_cvt_f32_f16_e32 v36, v25
	v_cvt_f32_f16_e32 v40, v24
	v_cvt_f32_f16_sdwa v41, v24 dst_sel:DWORD dst_unused:UNUSED_PAD src0_sel:WORD_1
	v_cvt_f32_f16_sdwa v37, v25 dst_sel:DWORD dst_unused:UNUSED_PAD src0_sel:WORD_1
	v_cvt_f32_f16_e32 v34, v27
	v_cvt_f32_f16_e32 v38, v26
	v_cvt_f32_f16_sdwa v39, v26 dst_sel:DWORD dst_unused:UNUSED_PAD src0_sel:WORD_1
	v_cvt_f32_f16_sdwa v35, v27 dst_sel:DWORD dst_unused:UNUSED_PAD src0_sel:WORD_1
	v_pk_fma_f32 v[20:21], v[20:21], 0.5, v[40:41] op_sel_hi:[1,0,1]
	v_pk_fma_f32 v[22:23], v[22:23], 0.5, v[36:37] op_sel_hi:[1,0,1]
	v_pk_fma_f32 v[16:17], v[16:17], 0.5, v[38:39] op_sel_hi:[1,0,1]
	v_pk_fma_f32 v[18:19], v[18:19], 0.5, v[34:35] op_sel_hi:[1,0,1]
	global_store_dwordx4 v[30:31], v[20:23], off
	global_store_dwordx4 v[30:31], v[16:19], off offset:16
	global_load_dwordx4 v[16:19], v[32:33], off
	v_lshl_add_u64 v[20:21], v[28:29], 2, s[30:31]
	v_lshl_add_u64 v[22:23], v[136:137], 1, s[40:41]
	s_waitcnt vmcnt(0)
	v_cvt_f32_f16_e32 v26, v17
	v_cvt_f32_f16_e32 v30, v16
	v_cvt_f32_f16_sdwa v31, v16 dst_sel:DWORD dst_unused:UNUSED_PAD src0_sel:WORD_1
	v_cvt_f32_f16_sdwa v27, v17 dst_sel:DWORD dst_unused:UNUSED_PAD src0_sel:WORD_1
	v_cvt_f32_f16_e32 v24, v19
	v_cvt_f32_f16_e32 v28, v18
	v_cvt_f32_f16_sdwa v29, v18 dst_sel:DWORD dst_unused:UNUSED_PAD src0_sel:WORD_1
	v_cvt_f32_f16_sdwa v25, v19 dst_sel:DWORD dst_unused:UNUSED_PAD src0_sel:WORD_1
	v_pk_fma_f32 v[12:13], v[12:13], 0.5, v[30:31] op_sel_hi:[1,0,1]
	v_pk_fma_f32 v[14:15], v[14:15], 0.5, v[26:27] op_sel_hi:[1,0,1]
	v_pk_fma_f32 v[8:9], v[8:9], 0.5, v[28:29] op_sel_hi:[1,0,1]
	v_pk_fma_f32 v[10:11], v[10:11], 0.5, v[24:25] op_sel_hi:[1,0,1]
	global_store_dwordx4 v[20:21], v[12:15], off
	global_store_dwordx4 v[20:21], v[8:11], off offset:16
	global_load_dwordx4 v[8:11], v[22:23], off
	v_lshl_add_u64 v[12:13], v[136:137], 2, s[30:31]
	s_waitcnt vmcnt(0)
	v_cvt_f32_f16_e32 v16, v9
	v_cvt_f32_f16_e32 v20, v8
	v_cvt_f32_f16_sdwa v21, v8 dst_sel:DWORD dst_unused:UNUSED_PAD src0_sel:WORD_1
	v_cvt_f32_f16_sdwa v17, v9 dst_sel:DWORD dst_unused:UNUSED_PAD src0_sel:WORD_1
	v_cvt_f32_f16_e32 v14, v11
	v_cvt_f32_f16_e32 v18, v10
	v_cvt_f32_f16_sdwa v19, v10 dst_sel:DWORD dst_unused:UNUSED_PAD src0_sel:WORD_1
	v_cvt_f32_f16_sdwa v15, v11 dst_sel:DWORD dst_unused:UNUSED_PAD src0_sel:WORD_1
	v_pk_fma_f32 v[4:5], v[4:5], 0.5, v[20:21] op_sel_hi:[1,0,1]
	v_pk_fma_f32 v[6:7], v[6:7], 0.5, v[16:17] op_sel_hi:[1,0,1]
	v_pk_fma_f32 v[0:1], v[0:1], 0.5, v[18:19] op_sel_hi:[1,0,1]
	v_pk_fma_f32 v[2:3], v[2:3], 0.5, v[14:15] op_sel_hi:[1,0,1]
	global_store_dwordx4 v[12:13], v[4:7], off
	global_store_dwordx4 v[12:13], v[0:3], off offset:16
	s_cbranch_vccz .LBB0_1676
	s_waitcnt vmcnt(0)
	s_cmpk_gt_u32 s16, 0xff
	s_cbranch_scc1 .LBB0_1691
	s_barrier
